# GEMM phases: M0-hazard s_nop slots filled by neighbouring independent instructions (90 nops fewer)
# baseline (speedup 1.0000x reference)
.LBB0_271:
	s_ashr_i32 s37, s36, 31
	s_lshl_b64 s[38:39], s[36:37], 19
	s_add_u32 s38, s58, s38
	s_addc_u32 s39, s59, s39
	s_and_b64 s[40:41], s[4:5], exec
	s_cselect_b32 s37, s39, s61
	s_cselect_b32 s43, s38, s60
	s_ashr_i32 s35, s34, 31
	s_lshl_b64 s[40:41], s[34:35], 19
	s_add_u32 s40, s66, s40
	s_addc_u32 s41, s67, s41
	s_and_b64 s[64:65], s[4:5], exec
	s_cselect_b32 s35, s41, s63
	s_cselect_b32 s55, s40, s62
	s_add_u32 s60, s60, 0x40080
	s_addc_u32 s61, s61, 0
	s_add_u32 s84, s62, 0x100
	s_addc_u32 s85, s63, 0
	s_mov_b32 s86, -2
	ds_read_b128 v[146:149], v153
	ds_read_b128 v[156:159], v153 offset:1024
	ds_read_b128 v[160:163], v153 offset:2048
	ds_read_b128 v[164:167], v153 offset:3072
	ds_read_b128 v[168:171], v154
	ds_read_b128 v[172:175], v154 offset:1024
	ds_read_b128 v[176:179], v154 offset:2048
	ds_read_b128 v[180:183], v154 offset:3072
	s_add_u32 s62, s60, 0xfffc0080
	s_addc_u32 s63, s61, -1
	s_cmp_eq_u32 s86, 12
	s_cselect_b32 s65, s37, s63
	s_cselect_b32 s64, s43, s62
	s_cselect_b32 s63, s35, s85
	s_cselect_b32 s62, s55, s84
	s_add_i32 m0, s69, 0xc000
	ds_read_b128 v[184:187], v155
	ds_read_b128 v[192:195], v155 offset:1024
	ds_read_b128 v[196:199], v155 offset:2048
	ds_read_b128 v[200:203], v155 offset:3072
	ds_read_b128 v[204:207], v155 offset:4096
	ds_read_b128 v[208:211], v155 offset:5120
	ds_read_b128 v[212:215], v155 offset:6144
	ds_read_b128 v[216:219], v155 offset:7168
	global_load_lds_dwordx4 v138, s[60:61]
	s_add_i32 m0, s69, 0xe000
	v_lshl_add_u64 v[188:189], s[60:61], 0, v[140:141]
	global_load_lds_dwordx4 v[188:189], off
	s_waitcnt vmcnt(8)
	s_waitcnt lgkmcnt(0)
	s_barrier
	v_mfma_f32_16x16x32_bf16 v[124:127], v[146:149], v[184:187], 0
	v_mfma_f32_16x16x32_bf16 v[120:123], v[160:163], v[184:187], 0
	v_mfma_f32_16x16x32_bf16 v[116:119], v[146:149], v[196:199], 0
	v_mfma_f32_16x16x32_bf16 v[108:111], v[160:163], v[196:199], 0
	v_mfma_f32_16x16x32_bf16 v[100:103], v[146:149], v[204:207], 0
	v_mfma_f32_16x16x32_bf16 v[92:95], v[160:163], v[204:207], 0
	v_mfma_f32_16x16x32_bf16 v[84:87], v[146:149], v[212:215], 0
	v_mfma_f32_16x16x32_bf16 v[76:79], v[160:163], v[212:215], 0
	v_mfma_f32_16x16x32_bf16 v[124:127], v[156:159], v[192:195], v[124:127]
	v_mfma_f32_16x16x32_bf16 v[120:123], v[164:167], v[192:195], v[120:123]
	v_mfma_f32_16x16x32_bf16 v[116:119], v[156:159], v[200:203], v[116:119]
	v_mfma_f32_16x16x32_bf16 v[108:111], v[164:167], v[200:203], v[108:111]
	v_mfma_f32_16x16x32_bf16 v[100:103], v[156:159], v[208:211], v[100:103]
	v_mfma_f32_16x16x32_bf16 v[92:95], v[164:167], v[208:211], v[92:95]
	v_mfma_f32_16x16x32_bf16 v[84:87], v[156:159], v[216:219], v[84:87]
	v_mfma_f32_16x16x32_bf16 v[76:79], v[164:167], v[216:219], v[76:79]
	v_mfma_f32_16x16x32_bf16 v[112:115], v[168:171], v[184:187], 0
	v_mfma_f32_16x16x32_bf16 v[104:107], v[176:179], v[184:187], 0
	v_mfma_f32_16x16x32_bf16 v[96:99], v[168:171], v[196:199], 0
	v_mfma_f32_16x16x32_bf16 v[88:91], v[176:179], v[196:199], 0
	v_mfma_f32_16x16x32_bf16 v[80:83], v[168:171], v[204:207], 0
	v_mfma_f32_16x16x32_bf16 v[72:75], v[176:179], v[204:207], 0
	v_mfma_f32_16x16x32_bf16 v[68:71], v[168:171], v[212:215], 0
	v_mfma_f32_16x16x32_bf16 v[64:67], v[176:179], v[212:215], 0
	v_mfma_f32_16x16x32_bf16 v[112:115], v[172:175], v[192:195], v[112:115]
	v_mfma_f32_16x16x32_bf16 v[104:107], v[180:183], v[192:195], v[104:107]
	v_mfma_f32_16x16x32_bf16 v[96:99], v[172:175], v[200:203], v[96:99]
	v_mfma_f32_16x16x32_bf16 v[88:91], v[180:183], v[200:203], v[88:91]
	v_mfma_f32_16x16x32_bf16 v[80:83], v[172:175], v[208:211], v[80:83]
	v_mfma_f32_16x16x32_bf16 v[72:75], v[180:183], v[208:211], v[72:75]
	v_mfma_f32_16x16x32_bf16 v[68:71], v[172:175], v[216:219], v[68:71]
	v_mfma_f32_16x16x32_bf16 v[64:67], v[180:183], v[216:219], v[64:67]
	s_barrier
	s_add_i32 s87, s76, s68
	v_lshl_add_u64 v[188:189], s[62:63], 0, v[132:133]
	s_mov_b32 m0, s87
	ds_read_b128 v[184:187], v155 offset:16384
	ds_read_b128 v[192:195], v155 offset:17408
	ds_read_b128 v[196:199], v155 offset:18432
	ds_read_b128 v[200:203], v155 offset:19456
	ds_read_b128 v[204:207], v155 offset:20480
	ds_read_b128 v[208:211], v155 offset:21504
	ds_read_b128 v[212:215], v155 offset:22528
	ds_read_b128 v[216:219], v155 offset:23552
	global_load_lds_dwordx4 v[188:189], off
	s_add_i32 m0, s87, 0x2000
	s_add_u32 s88, s62, 0x40000
	v_lshl_add_u64 v[220:221], s[62:63], 0, v[128:129]
	s_addc_u32 s89, s63, 0
	s_add_i32 s87, s77, s68
	global_load_lds_dwordx4 v[220:221], off
	s_mov_b32 m0, s87
	v_lshl_add_u64 v[224:225], s[64:65], 0, v[130:131]
	global_load_lds_dwordx4 v132, s[88:89]
	s_add_i32 m0, s87, 0x2000
	v_lshl_add_u64 v[222:223], s[64:65], 0, v[134:135]
	global_load_lds_dwordx4 v128, s[88:89]
	s_mov_b32 m0, s69
	s_nop 0
	global_load_lds_dwordx4 v[222:223], off
	s_mov_b32 m0, s70
	s_nop 0
	global_load_lds_dwordx4 v[224:225], off
	s_waitcnt vmcnt(8)
	s_waitcnt lgkmcnt(0)
	s_barrier
	v_mfma_f32_16x16x32_bf16 v[60:63], v[146:149], v[184:187], 0
	v_mfma_f32_16x16x32_bf16 v[56:59], v[160:163], v[184:187], 0
	v_mfma_f32_16x16x32_bf16 v[52:55], v[146:149], v[196:199], 0
	v_mfma_f32_16x16x32_bf16 v[44:47], v[160:163], v[196:199], 0
	v_mfma_f32_16x16x32_bf16 v[36:39], v[146:149], v[204:207], 0
	v_mfma_f32_16x16x32_bf16 v[28:31], v[160:163], v[204:207], 0
	v_mfma_f32_16x16x32_bf16 v[20:23], v[146:149], v[212:215], 0
	v_mfma_f32_16x16x32_bf16 v[12:15], v[160:163], v[212:215], 0
	v_mfma_f32_16x16x32_bf16 v[60:63], v[156:159], v[192:195], v[60:63]
	v_mfma_f32_16x16x32_bf16 v[56:59], v[164:167], v[192:195], v[56:59]
	v_mfma_f32_16x16x32_bf16 v[52:55], v[156:159], v[200:203], v[52:55]
	v_mfma_f32_16x16x32_bf16 v[44:47], v[164:167], v[200:203], v[44:47]
	v_mfma_f32_16x16x32_bf16 v[36:39], v[156:159], v[208:211], v[36:39]
	v_mfma_f32_16x16x32_bf16 v[28:31], v[164:167], v[208:211], v[28:31]
	v_mfma_f32_16x16x32_bf16 v[20:23], v[156:159], v[216:219], v[20:23]
	v_mfma_f32_16x16x32_bf16 v[12:15], v[164:167], v[216:219], v[12:15]
	v_mfma_f32_16x16x32_bf16 v[48:51], v[168:171], v[184:187], 0
	v_mfma_f32_16x16x32_bf16 v[40:43], v[176:179], v[184:187], 0
	v_mfma_f32_16x16x32_bf16 v[32:35], v[168:171], v[196:199], 0
	v_mfma_f32_16x16x32_bf16 v[24:27], v[176:179], v[196:199], 0
	v_mfma_f32_16x16x32_bf16 v[16:19], v[168:171], v[204:207], 0
	v_mfma_f32_16x16x32_bf16 v[8:11], v[176:179], v[204:207], 0
	v_mfma_f32_16x16x32_bf16 v[4:7], v[168:171], v[212:215], 0
	v_mfma_f32_16x16x32_bf16 v[0:3], v[176:179], v[212:215], 0
	v_mfma_f32_16x16x32_bf16 v[48:51], v[172:175], v[192:195], v[48:51]
	v_mfma_f32_16x16x32_bf16 v[40:43], v[180:183], v[192:195], v[40:43]
	v_mfma_f32_16x16x32_bf16 v[32:35], v[172:175], v[200:203], v[32:35]
	v_mfma_f32_16x16x32_bf16 v[24:27], v[180:183], v[200:203], v[24:27]
	v_mfma_f32_16x16x32_bf16 v[16:19], v[172:175], v[208:211], v[16:19]
	v_mfma_f32_16x16x32_bf16 v[8:11], v[180:183], v[208:211], v[8:11]
	v_mfma_f32_16x16x32_bf16 v[4:7], v[172:175], v[216:219], v[4:7]
	v_mfma_f32_16x16x32_bf16 v[0:3], v[180:183], v[216:219], v[0:3]
	s_barrier
	s_add_i32 s87, 0, 0x18000
	s_add_i32 s88, 0, 0x1c000
	v_add_u32_e32 v164, s87, v151
	v_add_u32_e32 v180, s88, v151
	ds_read_b128 v[146:149], v164
	ds_read_b128 v[156:159], v164 offset:1024
	ds_read_b128 v[160:163], v164 offset:2048
	ds_read_b128 v[164:167], v164 offset:3072
	ds_read_b128 v[168:171], v180
	ds_read_b128 v[172:175], v180 offset:1024
	ds_read_b128 v[176:179], v180 offset:2048
	ds_read_b128 v[180:183], v180 offset:3072
	s_add_u32 s64, s64, 0x40000
	s_addc_u32 s65, s65, 0
	s_mov_b32 m0, s71
	ds_read_b128 v[184:187], v155 offset:32768
	ds_read_b128 v[192:195], v155 offset:33792
	ds_read_b128 v[196:199], v155 offset:34816
	ds_read_b128 v[200:203], v155 offset:35840
	ds_read_b128 v[204:207], v155 offset:36864
	ds_read_b128 v[208:211], v155 offset:37888
	ds_read_b128 v[212:215], v155 offset:38912
	ds_read_b128 v[216:219], v155 offset:39936
	global_load_lds_dwordx4 v134, s[64:65]
	s_mov_b32 m0, s72
	s_nop 0
	global_load_lds_dwordx4 v130, s[64:65]
	s_waitcnt vmcnt(8)
	s_waitcnt lgkmcnt(0)
	s_barrier
	v_mfma_f32_16x16x32_bf16 v[124:127], v[146:149], v[184:187], v[124:127]
	v_mfma_f32_16x16x32_bf16 v[120:123], v[160:163], v[184:187], v[120:123]
	v_mfma_f32_16x16x32_bf16 v[116:119], v[146:149], v[196:199], v[116:119]
	v_mfma_f32_16x16x32_bf16 v[108:111], v[160:163], v[196:199], v[108:111]
	v_mfma_f32_16x16x32_bf16 v[100:103], v[146:149], v[204:207], v[100:103]
	v_mfma_f32_16x16x32_bf16 v[92:95], v[160:163], v[204:207], v[92:95]
	v_mfma_f32_16x16x32_bf16 v[84:87], v[146:149], v[212:215], v[84:87]
	v_mfma_f32_16x16x32_bf16 v[76:79], v[160:163], v[212:215], v[76:79]
	v_mfma_f32_16x16x32_bf16 v[124:127], v[156:159], v[192:195], v[124:127]
	v_mfma_f32_16x16x32_bf16 v[120:123], v[164:167], v[192:195], v[120:123]
	v_mfma_f32_16x16x32_bf16 v[116:119], v[156:159], v[200:203], v[116:119]
	v_mfma_f32_16x16x32_bf16 v[108:111], v[164:167], v[200:203], v[108:111]
	v_mfma_f32_16x16x32_bf16 v[100:103], v[156:159], v[208:211], v[100:103]
	v_mfma_f32_16x16x32_bf16 v[92:95], v[164:167], v[208:211], v[92:95]
	v_mfma_f32_16x16x32_bf16 v[84:87], v[156:159], v[216:219], v[84:87]
	v_mfma_f32_16x16x32_bf16 v[76:79], v[164:167], v[216:219], v[76:79]
	v_mfma_f32_16x16x32_bf16 v[112:115], v[168:171], v[184:187], v[112:115]
	v_mfma_f32_16x16x32_bf16 v[104:107], v[176:179], v[184:187], v[104:107]
	v_mfma_f32_16x16x32_bf16 v[96:99], v[168:171], v[196:199], v[96:99]
	v_mfma_f32_16x16x32_bf16 v[88:91], v[176:179], v[196:199], v[88:91]
	v_mfma_f32_16x16x32_bf16 v[80:83], v[168:171], v[204:207], v[80:83]
	v_mfma_f32_16x16x32_bf16 v[72:75], v[176:179], v[204:207], v[72:75]
	v_mfma_f32_16x16x32_bf16 v[68:71], v[168:171], v[212:215], v[68:71]
	v_mfma_f32_16x16x32_bf16 v[64:67], v[176:179], v[212:215], v[64:67]
	v_mfma_f32_16x16x32_bf16 v[112:115], v[172:175], v[192:195], v[112:115]
	v_mfma_f32_16x16x32_bf16 v[104:107], v[180:183], v[192:195], v[104:107]
	v_mfma_f32_16x16x32_bf16 v[96:99], v[172:175], v[200:203], v[96:99]
	v_mfma_f32_16x16x32_bf16 v[88:91], v[180:183], v[200:203], v[88:91]
	v_mfma_f32_16x16x32_bf16 v[80:83], v[172:175], v[208:211], v[80:83]
	v_mfma_f32_16x16x32_bf16 v[72:75], v[180:183], v[208:211], v[72:75]
	v_mfma_f32_16x16x32_bf16 v[68:71], v[172:175], v[216:219], v[68:71]
	v_mfma_f32_16x16x32_bf16 v[64:67], v[180:183], v[216:219], v[64:67]
	s_barrier
	s_add_i32 s64, s87, s68
	v_lshl_add_u64 v[188:189], v[188:189], 0, s[10:11]
	s_mov_b32 m0, s64
	ds_read_b128 v[184:187], v155 offset:49152
	ds_read_b128 v[192:195], v155 offset:50176
	ds_read_b128 v[196:199], v155 offset:51200
	ds_read_b128 v[200:203], v155 offset:52224
	ds_read_b128 v[204:207], v155 offset:53248
	ds_read_b128 v[208:211], v155 offset:54272
	ds_read_b128 v[212:215], v155 offset:55296
	ds_read_b128 v[216:219], v155 offset:56320
	global_load_lds_dwordx4 v[188:189], off
	s_add_i32 m0, s64, 0x2000
	s_add_u32 s62, s62, 0x40080
	v_lshl_add_u64 v[188:189], v[220:221], 0, s[10:11]
	s_addc_u32 s63, s63, 0
	s_add_i32 s64, s88, s68
	global_load_lds_dwordx4 v[188:189], off
	s_mov_b32 m0, s64
	s_nop 0
	global_load_lds_dwordx4 v132, s[62:63]
	s_add_i32 m0, s64, 0x2000
	v_lshl_add_u64 v[188:189], v[222:223], 0, s[10:11]
	global_load_lds_dwordx4 v128, s[62:63]
	s_mov_b32 m0, s33
	s_nop 0
	global_load_lds_dwordx4 v[188:189], off
	s_mov_b32 m0, s74
	v_lshl_add_u64 v[188:189], v[224:225], 0, s[10:11]
	global_load_lds_dwordx4 v[188:189], off
	s_waitcnt vmcnt(8)
	s_waitcnt lgkmcnt(0)
	s_barrier
	v_mfma_f32_16x16x32_bf16 v[60:63], v[146:149], v[184:187], v[60:63]
	v_mfma_f32_16x16x32_bf16 v[56:59], v[160:163], v[184:187], v[56:59]
	v_mfma_f32_16x16x32_bf16 v[52:55], v[146:149], v[196:199], v[52:55]
	v_mfma_f32_16x16x32_bf16 v[44:47], v[160:163], v[196:199], v[44:47]
	v_mfma_f32_16x16x32_bf16 v[36:39], v[146:149], v[204:207], v[36:39]
	v_mfma_f32_16x16x32_bf16 v[28:31], v[160:163], v[204:207], v[28:31]
	v_mfma_f32_16x16x32_bf16 v[20:23], v[146:149], v[212:215], v[20:23]
	v_mfma_f32_16x16x32_bf16 v[12:15], v[160:163], v[212:215], v[12:15]
	v_mfma_f32_16x16x32_bf16 v[60:63], v[156:159], v[192:195], v[60:63]
	v_mfma_f32_16x16x32_bf16 v[56:59], v[164:167], v[192:195], v[56:59]
	v_mfma_f32_16x16x32_bf16 v[52:55], v[156:159], v[200:203], v[52:55]
	v_mfma_f32_16x16x32_bf16 v[44:47], v[164:167], v[200:203], v[44:47]
	v_mfma_f32_16x16x32_bf16 v[36:39], v[156:159], v[208:211], v[36:39]
	v_mfma_f32_16x16x32_bf16 v[28:31], v[164:167], v[208:211], v[28:31]
	v_mfma_f32_16x16x32_bf16 v[20:23], v[156:159], v[216:219], v[20:23]
	v_mfma_f32_16x16x32_bf16 v[12:15], v[164:167], v[216:219], v[12:15]
	v_mfma_f32_16x16x32_bf16 v[48:51], v[168:171], v[184:187], v[48:51]
	v_mfma_f32_16x16x32_bf16 v[40:43], v[176:179], v[184:187], v[40:43]
	v_mfma_f32_16x16x32_bf16 v[32:35], v[168:171], v[196:199], v[32:35]
	v_mfma_f32_16x16x32_bf16 v[24:27], v[176:179], v[196:199], v[24:27]
	v_mfma_f32_16x16x32_bf16 v[16:19], v[168:171], v[204:207], v[16:19]
	v_mfma_f32_16x16x32_bf16 v[8:11], v[176:179], v[204:207], v[8:11]
	v_mfma_f32_16x16x32_bf16 v[4:7], v[168:171], v[212:215], v[4:7]
	v_mfma_f32_16x16x32_bf16 v[0:3], v[176:179], v[212:215], v[0:3]
	v_mfma_f32_16x16x32_bf16 v[48:51], v[172:175], v[192:195], v[48:51]
	v_mfma_f32_16x16x32_bf16 v[40:43], v[180:183], v[192:195], v[40:43]
	v_mfma_f32_16x16x32_bf16 v[32:35], v[172:175], v[200:203], v[32:35]
	v_mfma_f32_16x16x32_bf16 v[24:27], v[180:183], v[200:203], v[24:27]
	v_mfma_f32_16x16x32_bf16 v[16:19], v[172:175], v[208:211], v[16:19]
	v_mfma_f32_16x16x32_bf16 v[8:11], v[180:183], v[208:211], v[8:11]
	v_mfma_f32_16x16x32_bf16 v[4:7], v[172:175], v[216:219], v[4:7]
	v_mfma_f32_16x16x32_bf16 v[0:3], v[180:183], v[216:219], v[0:3]
	s_barrier
	s_add_i32 s86, s86, 2
	s_add_u32 s60, s60, 0x100
	s_addc_u32 s61, s61, 0
	s_add_u32 s84, s84, 0x100
	s_addc_u32 s85, s85, 0
	s_cmp_gt_u32 s86, 13
	s_cbranch_scc0 .LBB0_272
	s_branch .Lpeel_exit0
.LBB0_272:
	ds_read_b128 v[146:149], v153
	ds_read_b128 v[156:159], v153 offset:1024
	ds_read_b128 v[160:163], v153 offset:2048
	ds_read_b128 v[164:167], v153 offset:3072
	ds_read_b128 v[168:171], v154
	ds_read_b128 v[172:175], v154 offset:1024
	ds_read_b128 v[176:179], v154 offset:2048
	ds_read_b128 v[180:183], v154 offset:3072
	s_add_u32 s62, s60, 0xfffc0080
	s_addc_u32 s63, s61, -1
	s_cmp_eq_u32 s86, 12
	s_cselect_b32 s65, s37, s63
	s_cselect_b32 s64, s43, s62
	s_cselect_b32 s63, s35, s85
	s_cselect_b32 s62, s55, s84
	s_add_i32 m0, s69, 0xc000
	ds_read_b128 v[184:187], v155
	ds_read_b128 v[192:195], v155 offset:1024
	ds_read_b128 v[196:199], v155 offset:2048
	ds_read_b128 v[200:203], v155 offset:3072
	ds_read_b128 v[204:207], v155 offset:4096
	ds_read_b128 v[208:211], v155 offset:5120
	ds_read_b128 v[212:215], v155 offset:6144
	ds_read_b128 v[216:219], v155 offset:7168
	global_load_lds_dwordx4 v138, s[60:61]
	s_add_i32 m0, s69, 0xe000
	v_lshl_add_u64 v[188:189], s[60:61], 0, v[140:141]
	global_load_lds_dwordx4 v[188:189], off
	s_waitcnt vmcnt(8)
	s_waitcnt lgkmcnt(0)
	s_barrier
	v_mfma_f32_16x16x32_bf16 v[124:127], v[146:149], v[184:187], v[124:127]
	v_mfma_f32_16x16x32_bf16 v[120:123], v[160:163], v[184:187], v[120:123]
	v_mfma_f32_16x16x32_bf16 v[116:119], v[146:149], v[196:199], v[116:119]
	v_mfma_f32_16x16x32_bf16 v[108:111], v[160:163], v[196:199], v[108:111]
	v_mfma_f32_16x16x32_bf16 v[100:103], v[146:149], v[204:207], v[100:103]
	v_mfma_f32_16x16x32_bf16 v[92:95], v[160:163], v[204:207], v[92:95]
	v_mfma_f32_16x16x32_bf16 v[84:87], v[146:149], v[212:215], v[84:87]
	v_mfma_f32_16x16x32_bf16 v[76:79], v[160:163], v[212:215], v[76:79]
	v_mfma_f32_16x16x32_bf16 v[124:127], v[156:159], v[192:195], v[124:127]
	v_mfma_f32_16x16x32_bf16 v[120:123], v[164:167], v[192:195], v[120:123]
	v_mfma_f32_16x16x32_bf16 v[116:119], v[156:159], v[200:203], v[116:119]
	v_mfma_f32_16x16x32_bf16 v[108:111], v[164:167], v[200:203], v[108:111]
	v_mfma_f32_16x16x32_bf16 v[100:103], v[156:159], v[208:211], v[100:103]
	v_mfma_f32_16x16x32_bf16 v[92:95], v[164:167], v[208:211], v[92:95]
	v_mfma_f32_16x16x32_bf16 v[84:87], v[156:159], v[216:219], v[84:87]
	v_mfma_f32_16x16x32_bf16 v[76:79], v[164:167], v[216:219], v[76:79]
	v_mfma_f32_16x16x32_bf16 v[112:115], v[168:171], v[184:187], v[112:115]
	v_mfma_f32_16x16x32_bf16 v[104:107], v[176:179], v[184:187], v[104:107]
	v_mfma_f32_16x16x32_bf16 v[96:99], v[168:171], v[196:199], v[96:99]
	v_mfma_f32_16x16x32_bf16 v[88:91], v[176:179], v[196:199], v[88:91]
	v_mfma_f32_16x16x32_bf16 v[80:83], v[168:171], v[204:207], v[80:83]
	v_mfma_f32_16x16x32_bf16 v[72:75], v[176:179], v[204:207], v[72:75]
	v_mfma_f32_16x16x32_bf16 v[68:71], v[168:171], v[212:215], v[68:71]
	v_mfma_f32_16x16x32_bf16 v[64:67], v[176:179], v[212:215], v[64:67]
	v_mfma_f32_16x16x32_bf16 v[112:115], v[172:175], v[192:195], v[112:115]
	v_mfma_f32_16x16x32_bf16 v[104:107], v[180:183], v[192:195], v[104:107]
	v_mfma_f32_16x16x32_bf16 v[96:99], v[172:175], v[200:203], v[96:99]
	v_mfma_f32_16x16x32_bf16 v[88:91], v[180:183], v[200:203], v[88:91]
	v_mfma_f32_16x16x32_bf16 v[80:83], v[172:175], v[208:211], v[80:83]
	v_mfma_f32_16x16x32_bf16 v[72:75], v[180:183], v[208:211], v[72:75]
	v_mfma_f32_16x16x32_bf16 v[68:71], v[172:175], v[216:219], v[68:71]
	v_mfma_f32_16x16x32_bf16 v[64:67], v[180:183], v[216:219], v[64:67]
	s_barrier
	s_add_i32 s87, s76, s68
	v_lshl_add_u64 v[188:189], s[62:63], 0, v[132:133]
	s_mov_b32 m0, s87
	ds_read_b128 v[184:187], v155 offset:16384
	ds_read_b128 v[192:195], v155 offset:17408
	ds_read_b128 v[196:199], v155 offset:18432
	ds_read_b128 v[200:203], v155 offset:19456
	ds_read_b128 v[204:207], v155 offset:20480
	ds_read_b128 v[208:211], v155 offset:21504
	ds_read_b128 v[212:215], v155 offset:22528
	ds_read_b128 v[216:219], v155 offset:23552
	global_load_lds_dwordx4 v[188:189], off
	s_add_i32 m0, s87, 0x2000
	s_add_u32 s88, s62, 0x40000
	v_lshl_add_u64 v[220:221], s[62:63], 0, v[128:129]
	s_addc_u32 s89, s63, 0
	s_add_i32 s87, s77, s68
	global_load_lds_dwordx4 v[220:221], off
	s_mov_b32 m0, s87
	v_lshl_add_u64 v[224:225], s[64:65], 0, v[130:131]
	global_load_lds_dwordx4 v132, s[88:89]
	s_add_i32 m0, s87, 0x2000
	v_lshl_add_u64 v[222:223], s[64:65], 0, v[134:135]
	global_load_lds_dwordx4 v128, s[88:89]
	s_mov_b32 m0, s69
	s_nop 0
	global_load_lds_dwordx4 v[222:223], off
	s_mov_b32 m0, s70
	s_nop 0
	global_load_lds_dwordx4 v[224:225], off
	s_waitcnt vmcnt(8)
	s_waitcnt lgkmcnt(0)
	s_barrier
	v_mfma_f32_16x16x32_bf16 v[60:63], v[146:149], v[184:187], v[60:63]
	v_mfma_f32_16x16x32_bf16 v[56:59], v[160:163], v[184:187], v[56:59]
	v_mfma_f32_16x16x32_bf16 v[52:55], v[146:149], v[196:199], v[52:55]
	v_mfma_f32_16x16x32_bf16 v[44:47], v[160:163], v[196:199], v[44:47]
	v_mfma_f32_16x16x32_bf16 v[36:39], v[146:149], v[204:207], v[36:39]
	v_mfma_f32_16x16x32_bf16 v[28:31], v[160:163], v[204:207], v[28:31]
	v_mfma_f32_16x16x32_bf16 v[20:23], v[146:149], v[212:215], v[20:23]
	v_mfma_f32_16x16x32_bf16 v[12:15], v[160:163], v[212:215], v[12:15]
	v_mfma_f32_16x16x32_bf16 v[60:63], v[156:159], v[192:195], v[60:63]
	v_mfma_f32_16x16x32_bf16 v[56:59], v[164:167], v[192:195], v[56:59]
	v_mfma_f32_16x16x32_bf16 v[52:55], v[156:159], v[200:203], v[52:55]
	v_mfma_f32_16x16x32_bf16 v[44:47], v[164:167], v[200:203], v[44:47]
	v_mfma_f32_16x16x32_bf16 v[36:39], v[156:159], v[208:211], v[36:39]
	v_mfma_f32_16x16x32_bf16 v[28:31], v[164:167], v[208:211], v[28:31]
	v_mfma_f32_16x16x32_bf16 v[20:23], v[156:159], v[216:219], v[20:23]
	v_mfma_f32_16x16x32_bf16 v[12:15], v[164:167], v[216:219], v[12:15]
	v_mfma_f32_16x16x32_bf16 v[48:51], v[168:171], v[184:187], v[48:51]
	v_mfma_f32_16x16x32_bf16 v[40:43], v[176:179], v[184:187], v[40:43]
	v_mfma_f32_16x16x32_bf16 v[32:35], v[168:171], v[196:199], v[32:35]
	v_mfma_f32_16x16x32_bf16 v[24:27], v[176:179], v[196:199], v[24:27]
	v_mfma_f32_16x16x32_bf16 v[16:19], v[168:171], v[204:207], v[16:19]
	v_mfma_f32_16x16x32_bf16 v[8:11], v[176:179], v[204:207], v[8:11]
	v_mfma_f32_16x16x32_bf16 v[4:7], v[168:171], v[212:215], v[4:7]
	v_mfma_f32_16x16x32_bf16 v[0:3], v[176:179], v[212:215], v[0:3]
	v_mfma_f32_16x16x32_bf16 v[48:51], v[172:175], v[192:195], v[48:51]
	v_mfma_f32_16x16x32_bf16 v[40:43], v[180:183], v[192:195], v[40:43]
	v_mfma_f32_16x16x32_bf16 v[32:35], v[172:175], v[200:203], v[32:35]
	v_mfma_f32_16x16x32_bf16 v[24:27], v[180:183], v[200:203], v[24:27]
	v_mfma_f32_16x16x32_bf16 v[16:19], v[172:175], v[208:211], v[16:19]
	v_mfma_f32_16x16x32_bf16 v[8:11], v[180:183], v[208:211], v[8:11]
	v_mfma_f32_16x16x32_bf16 v[4:7], v[172:175], v[216:219], v[4:7]
	v_mfma_f32_16x16x32_bf16 v[0:3], v[180:183], v[216:219], v[0:3]
	s_barrier
	s_add_i32 s87, 0, 0x18000
	s_add_i32 s88, 0, 0x1c000
	v_add_u32_e32 v164, s87, v151
	v_add_u32_e32 v180, s88, v151
	ds_read_b128 v[146:149], v164
	ds_read_b128 v[156:159], v164 offset:1024
	ds_read_b128 v[160:163], v164 offset:2048
	ds_read_b128 v[164:167], v164 offset:3072
	ds_read_b128 v[168:171], v180
	ds_read_b128 v[172:175], v180 offset:1024
	ds_read_b128 v[176:179], v180 offset:2048
	ds_read_b128 v[180:183], v180 offset:3072
	s_add_u32 s64, s64, 0x40000
	s_addc_u32 s65, s65, 0
	s_mov_b32 m0, s71
	ds_read_b128 v[184:187], v155 offset:32768
	ds_read_b128 v[192:195], v155 offset:33792
	ds_read_b128 v[196:199], v155 offset:34816
	ds_read_b128 v[200:203], v155 offset:35840
	ds_read_b128 v[204:207], v155 offset:36864
	ds_read_b128 v[208:211], v155 offset:37888
	ds_read_b128 v[212:215], v155 offset:38912
	ds_read_b128 v[216:219], v155 offset:39936
	global_load_lds_dwordx4 v134, s[64:65]
	s_mov_b32 m0, s72
	s_nop 0
	global_load_lds_dwordx4 v130, s[64:65]
	s_waitcnt vmcnt(8)
	s_waitcnt lgkmcnt(0)
	s_barrier
	v_mfma_f32_16x16x32_bf16 v[124:127], v[146:149], v[184:187], v[124:127]
	v_mfma_f32_16x16x32_bf16 v[120:123], v[160:163], v[184:187], v[120:123]
	v_mfma_f32_16x16x32_bf16 v[116:119], v[146:149], v[196:199], v[116:119]
	v_mfma_f32_16x16x32_bf16 v[108:111], v[160:163], v[196:199], v[108:111]
	v_mfma_f32_16x16x32_bf16 v[100:103], v[146:149], v[204:207], v[100:103]
	v_mfma_f32_16x16x32_bf16 v[92:95], v[160:163], v[204:207], v[92:95]
	v_mfma_f32_16x16x32_bf16 v[84:87], v[146:149], v[212:215], v[84:87]
	v_mfma_f32_16x16x32_bf16 v[76:79], v[160:163], v[212:215], v[76:79]
	v_mfma_f32_16x16x32_bf16 v[124:127], v[156:159], v[192:195], v[124:127]
	v_mfma_f32_16x16x32_bf16 v[120:123], v[164:167], v[192:195], v[120:123]
	v_mfma_f32_16x16x32_bf16 v[116:119], v[156:159], v[200:203], v[116:119]
	v_mfma_f32_16x16x32_bf16 v[108:111], v[164:167], v[200:203], v[108:111]
	v_mfma_f32_16x16x32_bf16 v[100:103], v[156:159], v[208:211], v[100:103]
	v_mfma_f32_16x16x32_bf16 v[92:95], v[164:167], v[208:211], v[92:95]
	v_mfma_f32_16x16x32_bf16 v[84:87], v[156:159], v[216:219], v[84:87]
	v_mfma_f32_16x16x32_bf16 v[76:79], v[164:167], v[216:219], v[76:79]
	v_mfma_f32_16x16x32_bf16 v[112:115], v[168:171], v[184:187], v[112:115]
	v_mfma_f32_16x16x32_bf16 v[104:107], v[176:179], v[184:187], v[104:107]
	v_mfma_f32_16x16x32_bf16 v[96:99], v[168:171], v[196:199], v[96:99]
	v_mfma_f32_16x16x32_bf16 v[88:91], v[176:179], v[196:199], v[88:91]
	v_mfma_f32_16x16x32_bf16 v[80:83], v[168:171], v[204:207], v[80:83]
	v_mfma_f32_16x16x32_bf16 v[72:75], v[176:179], v[204:207], v[72:75]
	v_mfma_f32_16x16x32_bf16 v[68:71], v[168:171], v[212:215], v[68:71]
	v_mfma_f32_16x16x32_bf16 v[64:67], v[176:179], v[212:215], v[64:67]
	v_mfma_f32_16x16x32_bf16 v[112:115], v[172:175], v[192:195], v[112:115]
	v_mfma_f32_16x16x32_bf16 v[104:107], v[180:183], v[192:195], v[104:107]
	v_mfma_f32_16x16x32_bf16 v[96:99], v[172:175], v[200:203], v[96:99]
	v_mfma_f32_16x16x32_bf16 v[88:91], v[180:183], v[200:203], v[88:91]
	v_mfma_f32_16x16x32_bf16 v[80:83], v[172:175], v[208:211], v[80:83]
	v_mfma_f32_16x16x32_bf16 v[72:75], v[180:183], v[208:211], v[72:75]
	v_mfma_f32_16x16x32_bf16 v[68:71], v[172:175], v[216:219], v[68:71]
	v_mfma_f32_16x16x32_bf16 v[64:67], v[180:183], v[216:219], v[64:67]
	s_barrier
	s_add_i32 s64, s87, s68
	v_lshl_add_u64 v[188:189], v[188:189], 0, s[10:11]
	s_mov_b32 m0, s64
	ds_read_b128 v[184:187], v155 offset:49152
	ds_read_b128 v[192:195], v155 offset:50176
	ds_read_b128 v[196:199], v155 offset:51200
	ds_read_b128 v[200:203], v155 offset:52224
	ds_read_b128 v[204:207], v155 offset:53248
	ds_read_b128 v[208:211], v155 offset:54272
	ds_read_b128 v[212:215], v155 offset:55296
	ds_read_b128 v[216:219], v155 offset:56320
	global_load_lds_dwordx4 v[188:189], off
	s_add_i32 m0, s64, 0x2000
	s_add_u32 s62, s62, 0x40080
	v_lshl_add_u64 v[188:189], v[220:221], 0, s[10:11]
	s_addc_u32 s63, s63, 0
	s_add_i32 s64, s88, s68
	global_load_lds_dwordx4 v[188:189], off
	s_mov_b32 m0, s64
	s_nop 0
	global_load_lds_dwordx4 v132, s[62:63]
	s_add_i32 m0, s64, 0x2000
	v_lshl_add_u64 v[188:189], v[222:223], 0, s[10:11]
	global_load_lds_dwordx4 v128, s[62:63]
	s_mov_b32 m0, s33
	s_nop 0
	global_load_lds_dwordx4 v[188:189], off
	s_mov_b32 m0, s74
	v_lshl_add_u64 v[188:189], v[224:225], 0, s[10:11]
	global_load_lds_dwordx4 v[188:189], off
	s_waitcnt vmcnt(8)
	s_waitcnt lgkmcnt(0)
	s_barrier
	v_mfma_f32_16x16x32_bf16 v[60:63], v[146:149], v[184:187], v[60:63]
	v_mfma_f32_16x16x32_bf16 v[56:59], v[160:163], v[184:187], v[56:59]
	v_mfma_f32_16x16x32_bf16 v[52:55], v[146:149], v[196:199], v[52:55]
	v_mfma_f32_16x16x32_bf16 v[44:47], v[160:163], v[196:199], v[44:47]
	v_mfma_f32_16x16x32_bf16 v[36:39], v[146:149], v[204:207], v[36:39]
	v_mfma_f32_16x16x32_bf16 v[28:31], v[160:163], v[204:207], v[28:31]
	v_mfma_f32_16x16x32_bf16 v[20:23], v[146:149], v[212:215], v[20:23]
	v_mfma_f32_16x16x32_bf16 v[12:15], v[160:163], v[212:215], v[12:15]
	v_mfma_f32_16x16x32_bf16 v[60:63], v[156:159], v[192:195], v[60:63]
	v_mfma_f32_16x16x32_bf16 v[56:59], v[164:167], v[192:195], v[56:59]
	v_mfma_f32_16x16x32_bf16 v[52:55], v[156:159], v[200:203], v[52:55]
	v_mfma_f32_16x16x32_bf16 v[44:47], v[164:167], v[200:203], v[44:47]
	v_mfma_f32_16x16x32_bf16 v[36:39], v[156:159], v[208:211], v[36:39]
	v_mfma_f32_16x16x32_bf16 v[28:31], v[164:167], v[208:211], v[28:31]
	v_mfma_f32_16x16x32_bf16 v[20:23], v[156:159], v[216:219], v[20:23]
	v_mfma_f32_16x16x32_bf16 v[12:15], v[164:167], v[216:219], v[12:15]
	v_mfma_f32_16x16x32_bf16 v[48:51], v[168:171], v[184:187], v[48:51]
	v_mfma_f32_16x16x32_bf16 v[40:43], v[176:179], v[184:187], v[40:43]
	v_mfma_f32_16x16x32_bf16 v[32:35], v[168:171], v[196:199], v[32:35]
	v_mfma_f32_16x16x32_bf16 v[24:27], v[176:179], v[196:199], v[24:27]
	v_mfma_f32_16x16x32_bf16 v[16:19], v[168:171], v[204:207], v[16:19]
	v_mfma_f32_16x16x32_bf16 v[8:11], v[176:179], v[204:207], v[8:11]
	v_mfma_f32_16x16x32_bf16 v[4:7], v[168:171], v[212:215], v[4:7]
	v_mfma_f32_16x16x32_bf16 v[0:3], v[176:179], v[212:215], v[0:3]
	v_mfma_f32_16x16x32_bf16 v[48:51], v[172:175], v[192:195], v[48:51]
	v_mfma_f32_16x16x32_bf16 v[40:43], v[180:183], v[192:195], v[40:43]
	v_mfma_f32_16x16x32_bf16 v[32:35], v[172:175], v[200:203], v[32:35]
	v_mfma_f32_16x16x32_bf16 v[24:27], v[180:183], v[200:203], v[24:27]
	v_mfma_f32_16x16x32_bf16 v[16:19], v[172:175], v[208:211], v[16:19]
	v_mfma_f32_16x16x32_bf16 v[8:11], v[180:183], v[208:211], v[8:11]
	v_mfma_f32_16x16x32_bf16 v[4:7], v[172:175], v[216:219], v[4:7]
	v_mfma_f32_16x16x32_bf16 v[0:3], v[180:183], v[216:219], v[0:3]
	s_barrier
	s_add_i32 s86, s86, 2
	s_add_u32 s60, s60, 0x100
	s_addc_u32 s61, s61, 0
	s_add_u32 s84, s84, 0x100
	s_addc_u32 s85, s85, 0
	s_cmp_gt_u32 s86, 13
	s_cbranch_scc0 .LBB0_272

.LBB0_301:
	s_ashr_i32 s27, s26, 31
	s_lshl_b64 s[28:29], s[26:27], 19
	s_add_u32 s28, s43, s28
	s_addc_u32 s29, s52, s29
	s_and_b64 s[30:31], s[4:5], exec
	s_cselect_b32 s27, s29, s37
	s_cselect_b32 s55, s28, s36
	s_ashr_i32 s25, s24, 31
	s_lshl_b64 s[30:31], s[24:25], 19
	s_add_u32 s30, s58, s30
	s_addc_u32 s31, s59, s31
	s_and_b64 s[40:41], s[4:5], exec
	s_cselect_b32 s25, s31, s39
	s_cselect_b32 s72, s30, s38
	s_add_u32 s36, s36, 0x40080
	s_addc_u32 s37, s37, 0
	s_add_u32 s73, s38, 0x100
	s_addc_u32 s74, s39, 0
	s_mov_b32 s75, -2
	ds_read_b128 v[152:155], v149
	ds_read_b128 v[156:159], v149 offset:1024
	ds_read_b128 v[160:163], v149 offset:2048
	ds_read_b128 v[164:167], v149 offset:3072
	ds_read_b128 v[168:171], v150
	ds_read_b128 v[172:175], v150 offset:1024
	ds_read_b128 v[176:179], v150 offset:2048
	ds_read_b128 v[180:183], v150 offset:3072
	s_add_u32 s38, s36, 0xfffc0080
	s_addc_u32 s39, s37, -1
	s_cmp_eq_u32 s75, 12
	s_cselect_b32 s41, s27, s39
	s_cselect_b32 s40, s55, s38
	s_cselect_b32 s39, s25, s74
	s_cselect_b32 s38, s72, s73
	v_lshl_add_u64 v[144:145], s[36:37], 0, v[136:137]
	s_add_i32 m0, s35, 0xc000
	ds_read_b128 v[184:187], v151
	ds_read_b128 v[192:195], v151 offset:1024
	ds_read_b128 v[196:199], v151 offset:2048
	ds_read_b128 v[200:203], v151 offset:3072
	ds_read_b128 v[204:207], v151 offset:4096
	ds_read_b128 v[208:211], v151 offset:5120
	ds_read_b128 v[212:215], v151 offset:6144
	ds_read_b128 v[216:219], v151 offset:7168
	global_load_lds_dwordx4 v[144:145], off
	s_add_i32 m0, s35, 0xe000
	s_nop 0
	global_load_lds_dwordx4 v138, s[36:37]
	s_waitcnt vmcnt(8)
	s_waitcnt lgkmcnt(0)
	s_barrier
	v_mfma_f32_16x16x32_bf16 v[124:127], v[152:155], v[184:187], 0
	v_mfma_f32_16x16x32_bf16 v[120:123], v[160:163], v[184:187], 0
	v_mfma_f32_16x16x32_bf16 v[116:119], v[152:155], v[196:199], 0
	v_mfma_f32_16x16x32_bf16 v[108:111], v[160:163], v[196:199], 0
	v_mfma_f32_16x16x32_bf16 v[100:103], v[152:155], v[204:207], 0
	v_mfma_f32_16x16x32_bf16 v[92:95], v[160:163], v[204:207], 0
	v_mfma_f32_16x16x32_bf16 v[84:87], v[152:155], v[212:215], 0
	v_mfma_f32_16x16x32_bf16 v[76:79], v[160:163], v[212:215], 0
	v_mfma_f32_16x16x32_bf16 v[124:127], v[156:159], v[192:195], v[124:127]
	v_mfma_f32_16x16x32_bf16 v[120:123], v[164:167], v[192:195], v[120:123]
	v_mfma_f32_16x16x32_bf16 v[116:119], v[156:159], v[200:203], v[116:119]
	v_mfma_f32_16x16x32_bf16 v[108:111], v[164:167], v[200:203], v[108:111]
	v_mfma_f32_16x16x32_bf16 v[100:103], v[156:159], v[208:211], v[100:103]
	v_mfma_f32_16x16x32_bf16 v[92:95], v[164:167], v[208:211], v[92:95]
	v_mfma_f32_16x16x32_bf16 v[84:87], v[156:159], v[216:219], v[84:87]
	v_mfma_f32_16x16x32_bf16 v[76:79], v[164:167], v[216:219], v[76:79]
	v_mfma_f32_16x16x32_bf16 v[112:115], v[168:171], v[184:187], 0
	v_mfma_f32_16x16x32_bf16 v[104:107], v[176:179], v[184:187], 0
	v_mfma_f32_16x16x32_bf16 v[96:99], v[168:171], v[196:199], 0
	v_mfma_f32_16x16x32_bf16 v[88:91], v[176:179], v[196:199], 0
	v_mfma_f32_16x16x32_bf16 v[80:83], v[168:171], v[204:207], 0
	v_mfma_f32_16x16x32_bf16 v[72:75], v[176:179], v[204:207], 0
	v_mfma_f32_16x16x32_bf16 v[68:71], v[168:171], v[212:215], 0
	v_mfma_f32_16x16x32_bf16 v[64:67], v[176:179], v[212:215], 0
	v_mfma_f32_16x16x32_bf16 v[112:115], v[172:175], v[192:195], v[112:115]
	v_mfma_f32_16x16x32_bf16 v[104:107], v[180:183], v[192:195], v[104:107]
	v_mfma_f32_16x16x32_bf16 v[96:99], v[172:175], v[200:203], v[96:99]
	v_mfma_f32_16x16x32_bf16 v[88:91], v[180:183], v[200:203], v[88:91]
	v_mfma_f32_16x16x32_bf16 v[80:83], v[172:175], v[208:211], v[80:83]
	v_mfma_f32_16x16x32_bf16 v[72:75], v[180:183], v[208:211], v[72:75]
	v_mfma_f32_16x16x32_bf16 v[68:71], v[172:175], v[216:219], v[68:71]
	v_mfma_f32_16x16x32_bf16 v[64:67], v[180:183], v[216:219], v[64:67]
	s_barrier
	s_add_i32 s76, s66, s53
	v_lshl_add_u64 v[144:145], s[38:39], 0, v[130:131]
	s_mov_b32 m0, s76
	ds_read_b128 v[184:187], v151 offset:16384
	ds_read_b128 v[192:195], v151 offset:17408
	ds_read_b128 v[196:199], v151 offset:18432
	ds_read_b128 v[200:203], v151 offset:19456
	ds_read_b128 v[204:207], v151 offset:20480
	ds_read_b128 v[208:211], v151 offset:21504
	ds_read_b128 v[212:215], v151 offset:22528
	ds_read_b128 v[216:219], v151 offset:23552
	global_load_lds_dwordx4 v[144:145], off
	s_add_i32 m0, s76, 0x2000
	s_add_u32 s76, s38, 0x40000
	v_lshl_add_u64 v[188:189], s[38:39], 0, v[134:135]
	s_addc_u32 s77, s39, 0
	s_add_i32 s80, s67, s53
	global_load_lds_dwordx4 v[188:189], off
	s_mov_b32 m0, s80
	v_lshl_add_u64 v[222:223], s[40:41], 0, v[132:133]
	global_load_lds_dwordx4 v130, s[76:77]
	s_add_i32 m0, s80, 0x2000
	v_lshl_add_u64 v[220:221], s[40:41], 0, v[128:129]
	global_load_lds_dwordx4 v134, s[76:77]
	s_mov_b32 m0, s35
	s_nop 0
	global_load_lds_dwordx4 v[220:221], off
	s_mov_b32 m0, s33
	s_nop 0
	global_load_lds_dwordx4 v[222:223], off
	s_waitcnt vmcnt(8)
	s_waitcnt lgkmcnt(0)
	s_barrier
	v_mfma_f32_16x16x32_bf16 v[60:63], v[152:155], v[184:187], 0
	v_mfma_f32_16x16x32_bf16 v[56:59], v[160:163], v[184:187], 0
	v_mfma_f32_16x16x32_bf16 v[52:55], v[152:155], v[196:199], 0
	v_mfma_f32_16x16x32_bf16 v[44:47], v[160:163], v[196:199], 0
	v_mfma_f32_16x16x32_bf16 v[36:39], v[152:155], v[204:207], 0
	v_mfma_f32_16x16x32_bf16 v[28:31], v[160:163], v[204:207], 0
	v_mfma_f32_16x16x32_bf16 v[20:23], v[152:155], v[212:215], 0
	v_mfma_f32_16x16x32_bf16 v[12:15], v[160:163], v[212:215], 0
	v_mfma_f32_16x16x32_bf16 v[60:63], v[156:159], v[192:195], v[60:63]
	v_mfma_f32_16x16x32_bf16 v[56:59], v[164:167], v[192:195], v[56:59]
	v_mfma_f32_16x16x32_bf16 v[52:55], v[156:159], v[200:203], v[52:55]
	v_mfma_f32_16x16x32_bf16 v[44:47], v[164:167], v[200:203], v[44:47]
	v_mfma_f32_16x16x32_bf16 v[36:39], v[156:159], v[208:211], v[36:39]
	v_mfma_f32_16x16x32_bf16 v[28:31], v[164:167], v[208:211], v[28:31]
	v_mfma_f32_16x16x32_bf16 v[20:23], v[156:159], v[216:219], v[20:23]
	v_mfma_f32_16x16x32_bf16 v[12:15], v[164:167], v[216:219], v[12:15]
	v_mfma_f32_16x16x32_bf16 v[48:51], v[168:171], v[184:187], 0
	v_mfma_f32_16x16x32_bf16 v[40:43], v[176:179], v[184:187], 0
	v_mfma_f32_16x16x32_bf16 v[32:35], v[168:171], v[196:199], 0
	v_mfma_f32_16x16x32_bf16 v[24:27], v[176:179], v[196:199], 0
	v_mfma_f32_16x16x32_bf16 v[16:19], v[168:171], v[204:207], 0
	v_mfma_f32_16x16x32_bf16 v[8:11], v[176:179], v[204:207], 0
	v_mfma_f32_16x16x32_bf16 v[4:7], v[168:171], v[212:215], 0
	v_mfma_f32_16x16x32_bf16 v[0:3], v[176:179], v[212:215], 0
	v_mfma_f32_16x16x32_bf16 v[48:51], v[172:175], v[192:195], v[48:51]
	v_mfma_f32_16x16x32_bf16 v[40:43], v[180:183], v[192:195], v[40:43]
	v_mfma_f32_16x16x32_bf16 v[32:35], v[172:175], v[200:203], v[32:35]
	v_mfma_f32_16x16x32_bf16 v[24:27], v[180:183], v[200:203], v[24:27]
	v_mfma_f32_16x16x32_bf16 v[16:19], v[172:175], v[208:211], v[16:19]
	v_mfma_f32_16x16x32_bf16 v[8:11], v[180:183], v[208:211], v[8:11]
	v_mfma_f32_16x16x32_bf16 v[4:7], v[172:175], v[216:219], v[4:7]
	v_mfma_f32_16x16x32_bf16 v[0:3], v[180:183], v[216:219], v[0:3]
	s_barrier
	s_add_i32 s76, 0, 0x18000
	s_add_i32 s77, 0, 0x1c000
	v_add_u32_e32 v164, s76, v147
	v_add_u32_e32 v180, s77, v147
	ds_read_b128 v[152:155], v164
	ds_read_b128 v[156:159], v164 offset:1024
	ds_read_b128 v[160:163], v164 offset:2048
	ds_read_b128 v[164:167], v164 offset:3072
	ds_read_b128 v[168:171], v180
	ds_read_b128 v[172:175], v180 offset:1024
	ds_read_b128 v[176:179], v180 offset:2048
	ds_read_b128 v[180:183], v180 offset:3072
	s_add_u32 s40, s40, 0x40000
	s_addc_u32 s41, s41, 0
	s_mov_b32 m0, s60
	ds_read_b128 v[184:187], v151 offset:32768
	ds_read_b128 v[192:195], v151 offset:33792
	ds_read_b128 v[196:199], v151 offset:34816
	ds_read_b128 v[200:203], v151 offset:35840
	ds_read_b128 v[204:207], v151 offset:36864
	ds_read_b128 v[208:211], v151 offset:37888
	ds_read_b128 v[212:215], v151 offset:38912
	ds_read_b128 v[216:219], v151 offset:39936
	global_load_lds_dwordx4 v128, s[40:41]
	s_mov_b32 m0, s61
	s_nop 0
	global_load_lds_dwordx4 v132, s[40:41]
	s_waitcnt vmcnt(8)
	s_waitcnt lgkmcnt(0)
	s_barrier
	v_mfma_f32_16x16x32_bf16 v[124:127], v[152:155], v[184:187], v[124:127]
	v_mfma_f32_16x16x32_bf16 v[120:123], v[160:163], v[184:187], v[120:123]
	v_mfma_f32_16x16x32_bf16 v[116:119], v[152:155], v[196:199], v[116:119]
	v_mfma_f32_16x16x32_bf16 v[108:111], v[160:163], v[196:199], v[108:111]
	v_mfma_f32_16x16x32_bf16 v[100:103], v[152:155], v[204:207], v[100:103]
	v_mfma_f32_16x16x32_bf16 v[92:95], v[160:163], v[204:207], v[92:95]
	v_mfma_f32_16x16x32_bf16 v[84:87], v[152:155], v[212:215], v[84:87]
	v_mfma_f32_16x16x32_bf16 v[76:79], v[160:163], v[212:215], v[76:79]
	v_mfma_f32_16x16x32_bf16 v[124:127], v[156:159], v[192:195], v[124:127]
	v_mfma_f32_16x16x32_bf16 v[120:123], v[164:167], v[192:195], v[120:123]
	v_mfma_f32_16x16x32_bf16 v[116:119], v[156:159], v[200:203], v[116:119]
	v_mfma_f32_16x16x32_bf16 v[108:111], v[164:167], v[200:203], v[108:111]
	v_mfma_f32_16x16x32_bf16 v[100:103], v[156:159], v[208:211], v[100:103]
	v_mfma_f32_16x16x32_bf16 v[92:95], v[164:167], v[208:211], v[92:95]
	v_mfma_f32_16x16x32_bf16 v[84:87], v[156:159], v[216:219], v[84:87]
	v_mfma_f32_16x16x32_bf16 v[76:79], v[164:167], v[216:219], v[76:79]
	v_mfma_f32_16x16x32_bf16 v[112:115], v[168:171], v[184:187], v[112:115]
	v_mfma_f32_16x16x32_bf16 v[104:107], v[176:179], v[184:187], v[104:107]
	v_mfma_f32_16x16x32_bf16 v[96:99], v[168:171], v[196:199], v[96:99]
	v_mfma_f32_16x16x32_bf16 v[88:91], v[176:179], v[196:199], v[88:91]
	v_mfma_f32_16x16x32_bf16 v[80:83], v[168:171], v[204:207], v[80:83]
	v_mfma_f32_16x16x32_bf16 v[72:75], v[176:179], v[204:207], v[72:75]
	v_mfma_f32_16x16x32_bf16 v[68:71], v[168:171], v[212:215], v[68:71]
	v_mfma_f32_16x16x32_bf16 v[64:67], v[176:179], v[212:215], v[64:67]
	v_mfma_f32_16x16x32_bf16 v[112:115], v[172:175], v[192:195], v[112:115]
	v_mfma_f32_16x16x32_bf16 v[104:107], v[180:183], v[192:195], v[104:107]
	v_mfma_f32_16x16x32_bf16 v[96:99], v[172:175], v[200:203], v[96:99]
	v_mfma_f32_16x16x32_bf16 v[88:91], v[180:183], v[200:203], v[88:91]
	v_mfma_f32_16x16x32_bf16 v[80:83], v[172:175], v[208:211], v[80:83]
	v_mfma_f32_16x16x32_bf16 v[72:75], v[180:183], v[208:211], v[72:75]
	v_mfma_f32_16x16x32_bf16 v[68:71], v[172:175], v[216:219], v[68:71]
	v_mfma_f32_16x16x32_bf16 v[64:67], v[180:183], v[216:219], v[64:67]
	s_barrier
	s_add_i32 s40, s76, s53
	v_lshl_add_u64 v[144:145], v[144:145], 0, s[12:13]
	s_mov_b32 m0, s40
	ds_read_b128 v[184:187], v151 offset:49152
	ds_read_b128 v[192:195], v151 offset:50176
	ds_read_b128 v[196:199], v151 offset:51200
	ds_read_b128 v[200:203], v151 offset:52224
	ds_read_b128 v[204:207], v151 offset:53248
	ds_read_b128 v[208:211], v151 offset:54272
	ds_read_b128 v[212:215], v151 offset:55296
	ds_read_b128 v[216:219], v151 offset:56320
	global_load_lds_dwordx4 v[144:145], off
	s_add_i32 m0, s40, 0x2000
	s_add_u32 s38, s38, 0x40080
	v_lshl_add_u64 v[144:145], v[188:189], 0, s[12:13]
	s_addc_u32 s39, s39, 0
	s_add_i32 s40, s77, s53
	global_load_lds_dwordx4 v[144:145], off
	s_mov_b32 m0, s40
	s_nop 0
	global_load_lds_dwordx4 v130, s[38:39]
	s_add_i32 m0, s40, 0x2000
	v_lshl_add_u64 v[144:145], v[220:221], 0, s[12:13]
	global_load_lds_dwordx4 v134, s[38:39]
	s_mov_b32 m0, s63
	s_nop 0
	global_load_lds_dwordx4 v[144:145], off
	s_mov_b32 m0, s64
	v_lshl_add_u64 v[144:145], v[222:223], 0, s[12:13]
	global_load_lds_dwordx4 v[144:145], off
	s_waitcnt vmcnt(8)
	s_waitcnt lgkmcnt(0)
	s_barrier
	v_mfma_f32_16x16x32_bf16 v[60:63], v[152:155], v[184:187], v[60:63]
	v_mfma_f32_16x16x32_bf16 v[56:59], v[160:163], v[184:187], v[56:59]
	v_mfma_f32_16x16x32_bf16 v[52:55], v[152:155], v[196:199], v[52:55]
	v_mfma_f32_16x16x32_bf16 v[44:47], v[160:163], v[196:199], v[44:47]
	v_mfma_f32_16x16x32_bf16 v[36:39], v[152:155], v[204:207], v[36:39]
	v_mfma_f32_16x16x32_bf16 v[28:31], v[160:163], v[204:207], v[28:31]
	v_mfma_f32_16x16x32_bf16 v[20:23], v[152:155], v[212:215], v[20:23]
	v_mfma_f32_16x16x32_bf16 v[12:15], v[160:163], v[212:215], v[12:15]
	v_mfma_f32_16x16x32_bf16 v[60:63], v[156:159], v[192:195], v[60:63]
	v_mfma_f32_16x16x32_bf16 v[56:59], v[164:167], v[192:195], v[56:59]
	v_mfma_f32_16x16x32_bf16 v[52:55], v[156:159], v[200:203], v[52:55]
	v_mfma_f32_16x16x32_bf16 v[44:47], v[164:167], v[200:203], v[44:47]
	v_mfma_f32_16x16x32_bf16 v[36:39], v[156:159], v[208:211], v[36:39]
	v_mfma_f32_16x16x32_bf16 v[28:31], v[164:167], v[208:211], v[28:31]
	v_mfma_f32_16x16x32_bf16 v[20:23], v[156:159], v[216:219], v[20:23]
	v_mfma_f32_16x16x32_bf16 v[12:15], v[164:167], v[216:219], v[12:15]
	v_mfma_f32_16x16x32_bf16 v[48:51], v[168:171], v[184:187], v[48:51]
	v_mfma_f32_16x16x32_bf16 v[40:43], v[176:179], v[184:187], v[40:43]
	v_mfma_f32_16x16x32_bf16 v[32:35], v[168:171], v[196:199], v[32:35]
	v_mfma_f32_16x16x32_bf16 v[24:27], v[176:179], v[196:199], v[24:27]
	v_mfma_f32_16x16x32_bf16 v[16:19], v[168:171], v[204:207], v[16:19]
	v_mfma_f32_16x16x32_bf16 v[8:11], v[176:179], v[204:207], v[8:11]
	v_mfma_f32_16x16x32_bf16 v[4:7], v[168:171], v[212:215], v[4:7]
	v_mfma_f32_16x16x32_bf16 v[0:3], v[176:179], v[212:215], v[0:3]
	v_mfma_f32_16x16x32_bf16 v[48:51], v[172:175], v[192:195], v[48:51]
	v_mfma_f32_16x16x32_bf16 v[40:43], v[180:183], v[192:195], v[40:43]
	v_mfma_f32_16x16x32_bf16 v[32:35], v[172:175], v[200:203], v[32:35]
	v_mfma_f32_16x16x32_bf16 v[24:27], v[180:183], v[200:203], v[24:27]
	v_mfma_f32_16x16x32_bf16 v[16:19], v[172:175], v[208:211], v[16:19]
	v_mfma_f32_16x16x32_bf16 v[8:11], v[180:183], v[208:211], v[8:11]
	v_mfma_f32_16x16x32_bf16 v[4:7], v[172:175], v[216:219], v[4:7]
	v_mfma_f32_16x16x32_bf16 v[0:3], v[180:183], v[216:219], v[0:3]
	s_barrier
	s_add_i32 s75, s75, 2
	s_add_u32 s36, s36, 0x100
	s_addc_u32 s37, s37, 0
	s_add_u32 s73, s73, 0x100
	s_addc_u32 s74, s74, 0
	s_cmp_gt_u32 s75, 13
	s_cbranch_scc0 .LBB0_302
	s_branch .Lpeel_exit1
.LBB0_302:
	ds_read_b128 v[152:155], v149
	ds_read_b128 v[156:159], v149 offset:1024
	ds_read_b128 v[160:163], v149 offset:2048
	ds_read_b128 v[164:167], v149 offset:3072
	ds_read_b128 v[168:171], v150
	ds_read_b128 v[172:175], v150 offset:1024
	ds_read_b128 v[176:179], v150 offset:2048
	ds_read_b128 v[180:183], v150 offset:3072
	s_add_u32 s38, s36, 0xfffc0080
	s_addc_u32 s39, s37, -1
	s_cmp_eq_u32 s75, 12
	s_cselect_b32 s41, s27, s39
	s_cselect_b32 s40, s55, s38
	s_cselect_b32 s39, s25, s74
	s_cselect_b32 s38, s72, s73
	v_lshl_add_u64 v[144:145], s[36:37], 0, v[136:137]
	s_add_i32 m0, s35, 0xc000
	ds_read_b128 v[184:187], v151
	ds_read_b128 v[192:195], v151 offset:1024
	ds_read_b128 v[196:199], v151 offset:2048
	ds_read_b128 v[200:203], v151 offset:3072
	ds_read_b128 v[204:207], v151 offset:4096
	ds_read_b128 v[208:211], v151 offset:5120
	ds_read_b128 v[212:215], v151 offset:6144
	ds_read_b128 v[216:219], v151 offset:7168
	global_load_lds_dwordx4 v[144:145], off
	s_add_i32 m0, s35, 0xe000
	s_nop 0
	global_load_lds_dwordx4 v138, s[36:37]
	s_waitcnt vmcnt(8)
	s_waitcnt lgkmcnt(0)
	s_barrier
	v_mfma_f32_16x16x32_bf16 v[124:127], v[152:155], v[184:187], v[124:127]
	v_mfma_f32_16x16x32_bf16 v[120:123], v[160:163], v[184:187], v[120:123]
	v_mfma_f32_16x16x32_bf16 v[116:119], v[152:155], v[196:199], v[116:119]
	v_mfma_f32_16x16x32_bf16 v[108:111], v[160:163], v[196:199], v[108:111]
	v_mfma_f32_16x16x32_bf16 v[100:103], v[152:155], v[204:207], v[100:103]
	v_mfma_f32_16x16x32_bf16 v[92:95], v[160:163], v[204:207], v[92:95]
	v_mfma_f32_16x16x32_bf16 v[84:87], v[152:155], v[212:215], v[84:87]
	v_mfma_f32_16x16x32_bf16 v[76:79], v[160:163], v[212:215], v[76:79]
	v_mfma_f32_16x16x32_bf16 v[124:127], v[156:159], v[192:195], v[124:127]
	v_mfma_f32_16x16x32_bf16 v[120:123], v[164:167], v[192:195], v[120:123]
	v_mfma_f32_16x16x32_bf16 v[116:119], v[156:159], v[200:203], v[116:119]
	v_mfma_f32_16x16x32_bf16 v[108:111], v[164:167], v[200:203], v[108:111]
	v_mfma_f32_16x16x32_bf16 v[100:103], v[156:159], v[208:211], v[100:103]
	v_mfma_f32_16x16x32_bf16 v[92:95], v[164:167], v[208:211], v[92:95]
	v_mfma_f32_16x16x32_bf16 v[84:87], v[156:159], v[216:219], v[84:87]
	v_mfma_f32_16x16x32_bf16 v[76:79], v[164:167], v[216:219], v[76:79]
	v_mfma_f32_16x16x32_bf16 v[112:115], v[168:171], v[184:187], v[112:115]
	v_mfma_f32_16x16x32_bf16 v[104:107], v[176:179], v[184:187], v[104:107]
	v_mfma_f32_16x16x32_bf16 v[96:99], v[168:171], v[196:199], v[96:99]
	v_mfma_f32_16x16x32_bf16 v[88:91], v[176:179], v[196:199], v[88:91]
	v_mfma_f32_16x16x32_bf16 v[80:83], v[168:171], v[204:207], v[80:83]
	v_mfma_f32_16x16x32_bf16 v[72:75], v[176:179], v[204:207], v[72:75]
	v_mfma_f32_16x16x32_bf16 v[68:71], v[168:171], v[212:215], v[68:71]
	v_mfma_f32_16x16x32_bf16 v[64:67], v[176:179], v[212:215], v[64:67]
	v_mfma_f32_16x16x32_bf16 v[112:115], v[172:175], v[192:195], v[112:115]
	v_mfma_f32_16x16x32_bf16 v[104:107], v[180:183], v[192:195], v[104:107]
	v_mfma_f32_16x16x32_bf16 v[96:99], v[172:175], v[200:203], v[96:99]
	v_mfma_f32_16x16x32_bf16 v[88:91], v[180:183], v[200:203], v[88:91]
	v_mfma_f32_16x16x32_bf16 v[80:83], v[172:175], v[208:211], v[80:83]
	v_mfma_f32_16x16x32_bf16 v[72:75], v[180:183], v[208:211], v[72:75]
	v_mfma_f32_16x16x32_bf16 v[68:71], v[172:175], v[216:219], v[68:71]
	v_mfma_f32_16x16x32_bf16 v[64:67], v[180:183], v[216:219], v[64:67]
	s_barrier
	s_add_i32 s76, s66, s53
	v_lshl_add_u64 v[144:145], s[38:39], 0, v[130:131]
	s_mov_b32 m0, s76
	ds_read_b128 v[184:187], v151 offset:16384
	ds_read_b128 v[192:195], v151 offset:17408
	ds_read_b128 v[196:199], v151 offset:18432
	ds_read_b128 v[200:203], v151 offset:19456
	ds_read_b128 v[204:207], v151 offset:20480
	ds_read_b128 v[208:211], v151 offset:21504
	ds_read_b128 v[212:215], v151 offset:22528
	ds_read_b128 v[216:219], v151 offset:23552
	global_load_lds_dwordx4 v[144:145], off
	s_add_i32 m0, s76, 0x2000
	s_add_u32 s76, s38, 0x40000
	v_lshl_add_u64 v[188:189], s[38:39], 0, v[134:135]
	s_addc_u32 s77, s39, 0
	s_add_i32 s80, s67, s53
	global_load_lds_dwordx4 v[188:189], off
	s_mov_b32 m0, s80
	v_lshl_add_u64 v[222:223], s[40:41], 0, v[132:133]
	global_load_lds_dwordx4 v130, s[76:77]
	s_add_i32 m0, s80, 0x2000
	v_lshl_add_u64 v[220:221], s[40:41], 0, v[128:129]
	global_load_lds_dwordx4 v134, s[76:77]
	s_mov_b32 m0, s35
	s_nop 0
	global_load_lds_dwordx4 v[220:221], off
	s_mov_b32 m0, s33
	s_nop 0
	global_load_lds_dwordx4 v[222:223], off
	s_waitcnt vmcnt(8)
	s_waitcnt lgkmcnt(0)
	s_barrier
	v_mfma_f32_16x16x32_bf16 v[60:63], v[152:155], v[184:187], v[60:63]
	v_mfma_f32_16x16x32_bf16 v[56:59], v[160:163], v[184:187], v[56:59]
	v_mfma_f32_16x16x32_bf16 v[52:55], v[152:155], v[196:199], v[52:55]
	v_mfma_f32_16x16x32_bf16 v[44:47], v[160:163], v[196:199], v[44:47]
	v_mfma_f32_16x16x32_bf16 v[36:39], v[152:155], v[204:207], v[36:39]
	v_mfma_f32_16x16x32_bf16 v[28:31], v[160:163], v[204:207], v[28:31]
	v_mfma_f32_16x16x32_bf16 v[20:23], v[152:155], v[212:215], v[20:23]
	v_mfma_f32_16x16x32_bf16 v[12:15], v[160:163], v[212:215], v[12:15]
	v_mfma_f32_16x16x32_bf16 v[60:63], v[156:159], v[192:195], v[60:63]
	v_mfma_f32_16x16x32_bf16 v[56:59], v[164:167], v[192:195], v[56:59]
	v_mfma_f32_16x16x32_bf16 v[52:55], v[156:159], v[200:203], v[52:55]
	v_mfma_f32_16x16x32_bf16 v[44:47], v[164:167], v[200:203], v[44:47]
	v_mfma_f32_16x16x32_bf16 v[36:39], v[156:159], v[208:211], v[36:39]
	v_mfma_f32_16x16x32_bf16 v[28:31], v[164:167], v[208:211], v[28:31]
	v_mfma_f32_16x16x32_bf16 v[20:23], v[156:159], v[216:219], v[20:23]
	v_mfma_f32_16x16x32_bf16 v[12:15], v[164:167], v[216:219], v[12:15]
	v_mfma_f32_16x16x32_bf16 v[48:51], v[168:171], v[184:187], v[48:51]
	v_mfma_f32_16x16x32_bf16 v[40:43], v[176:179], v[184:187], v[40:43]
	v_mfma_f32_16x16x32_bf16 v[32:35], v[168:171], v[196:199], v[32:35]
	v_mfma_f32_16x16x32_bf16 v[24:27], v[176:179], v[196:199], v[24:27]
	v_mfma_f32_16x16x32_bf16 v[16:19], v[168:171], v[204:207], v[16:19]
	v_mfma_f32_16x16x32_bf16 v[8:11], v[176:179], v[204:207], v[8:11]
	v_mfma_f32_16x16x32_bf16 v[4:7], v[168:171], v[212:215], v[4:7]
	v_mfma_f32_16x16x32_bf16 v[0:3], v[176:179], v[212:215], v[0:3]
	v_mfma_f32_16x16x32_bf16 v[48:51], v[172:175], v[192:195], v[48:51]
	v_mfma_f32_16x16x32_bf16 v[40:43], v[180:183], v[192:195], v[40:43]
	v_mfma_f32_16x16x32_bf16 v[32:35], v[172:175], v[200:203], v[32:35]
	v_mfma_f32_16x16x32_bf16 v[24:27], v[180:183], v[200:203], v[24:27]
	v_mfma_f32_16x16x32_bf16 v[16:19], v[172:175], v[208:211], v[16:19]
	v_mfma_f32_16x16x32_bf16 v[8:11], v[180:183], v[208:211], v[8:11]
	v_mfma_f32_16x16x32_bf16 v[4:7], v[172:175], v[216:219], v[4:7]
	v_mfma_f32_16x16x32_bf16 v[0:3], v[180:183], v[216:219], v[0:3]
	s_barrier
	s_add_i32 s76, 0, 0x18000
	s_add_i32 s77, 0, 0x1c000
	v_add_u32_e32 v164, s76, v147
	v_add_u32_e32 v180, s77, v147
	ds_read_b128 v[152:155], v164
	ds_read_b128 v[156:159], v164 offset:1024
	ds_read_b128 v[160:163], v164 offset:2048
	ds_read_b128 v[164:167], v164 offset:3072
	ds_read_b128 v[168:171], v180
	ds_read_b128 v[172:175], v180 offset:1024
	ds_read_b128 v[176:179], v180 offset:2048
	ds_read_b128 v[180:183], v180 offset:3072
	s_add_u32 s40, s40, 0x40000
	s_addc_u32 s41, s41, 0
	s_mov_b32 m0, s60
	ds_read_b128 v[184:187], v151 offset:32768
	ds_read_b128 v[192:195], v151 offset:33792
	ds_read_b128 v[196:199], v151 offset:34816
	ds_read_b128 v[200:203], v151 offset:35840
	ds_read_b128 v[204:207], v151 offset:36864
	ds_read_b128 v[208:211], v151 offset:37888
	ds_read_b128 v[212:215], v151 offset:38912
	ds_read_b128 v[216:219], v151 offset:39936
	global_load_lds_dwordx4 v128, s[40:41]
	s_mov_b32 m0, s61
	s_nop 0
	global_load_lds_dwordx4 v132, s[40:41]
	s_waitcnt vmcnt(8)
	s_waitcnt lgkmcnt(0)
	s_barrier
	v_mfma_f32_16x16x32_bf16 v[124:127], v[152:155], v[184:187], v[124:127]
	v_mfma_f32_16x16x32_bf16 v[120:123], v[160:163], v[184:187], v[120:123]
	v_mfma_f32_16x16x32_bf16 v[116:119], v[152:155], v[196:199], v[116:119]
	v_mfma_f32_16x16x32_bf16 v[108:111], v[160:163], v[196:199], v[108:111]
	v_mfma_f32_16x16x32_bf16 v[100:103], v[152:155], v[204:207], v[100:103]
	v_mfma_f32_16x16x32_bf16 v[92:95], v[160:163], v[204:207], v[92:95]
	v_mfma_f32_16x16x32_bf16 v[84:87], v[152:155], v[212:215], v[84:87]
	v_mfma_f32_16x16x32_bf16 v[76:79], v[160:163], v[212:215], v[76:79]
	v_mfma_f32_16x16x32_bf16 v[124:127], v[156:159], v[192:195], v[124:127]
	v_mfma_f32_16x16x32_bf16 v[120:123], v[164:167], v[192:195], v[120:123]
	v_mfma_f32_16x16x32_bf16 v[116:119], v[156:159], v[200:203], v[116:119]
	v_mfma_f32_16x16x32_bf16 v[108:111], v[164:167], v[200:203], v[108:111]
	v_mfma_f32_16x16x32_bf16 v[100:103], v[156:159], v[208:211], v[100:103]
	v_mfma_f32_16x16x32_bf16 v[92:95], v[164:167], v[208:211], v[92:95]
	v_mfma_f32_16x16x32_bf16 v[84:87], v[156:159], v[216:219], v[84:87]
	v_mfma_f32_16x16x32_bf16 v[76:79], v[164:167], v[216:219], v[76:79]
	v_mfma_f32_16x16x32_bf16 v[112:115], v[168:171], v[184:187], v[112:115]
	v_mfma_f32_16x16x32_bf16 v[104:107], v[176:179], v[184:187], v[104:107]
	v_mfma_f32_16x16x32_bf16 v[96:99], v[168:171], v[196:199], v[96:99]
	v_mfma_f32_16x16x32_bf16 v[88:91], v[176:179], v[196:199], v[88:91]
	v_mfma_f32_16x16x32_bf16 v[80:83], v[168:171], v[204:207], v[80:83]
	v_mfma_f32_16x16x32_bf16 v[72:75], v[176:179], v[204:207], v[72:75]
	v_mfma_f32_16x16x32_bf16 v[68:71], v[168:171], v[212:215], v[68:71]
	v_mfma_f32_16x16x32_bf16 v[64:67], v[176:179], v[212:215], v[64:67]
	v_mfma_f32_16x16x32_bf16 v[112:115], v[172:175], v[192:195], v[112:115]
	v_mfma_f32_16x16x32_bf16 v[104:107], v[180:183], v[192:195], v[104:107]
	v_mfma_f32_16x16x32_bf16 v[96:99], v[172:175], v[200:203], v[96:99]
	v_mfma_f32_16x16x32_bf16 v[88:91], v[180:183], v[200:203], v[88:91]
	v_mfma_f32_16x16x32_bf16 v[80:83], v[172:175], v[208:211], v[80:83]
	v_mfma_f32_16x16x32_bf16 v[72:75], v[180:183], v[208:211], v[72:75]
	v_mfma_f32_16x16x32_bf16 v[68:71], v[172:175], v[216:219], v[68:71]
	v_mfma_f32_16x16x32_bf16 v[64:67], v[180:183], v[216:219], v[64:67]
	s_barrier
	s_add_i32 s40, s76, s53
	v_lshl_add_u64 v[144:145], v[144:145], 0, s[12:13]
	s_mov_b32 m0, s40
	ds_read_b128 v[184:187], v151 offset:49152
	ds_read_b128 v[192:195], v151 offset:50176
	ds_read_b128 v[196:199], v151 offset:51200
	ds_read_b128 v[200:203], v151 offset:52224
	ds_read_b128 v[204:207], v151 offset:53248
	ds_read_b128 v[208:211], v151 offset:54272
	ds_read_b128 v[212:215], v151 offset:55296
	ds_read_b128 v[216:219], v151 offset:56320
	global_load_lds_dwordx4 v[144:145], off
	s_add_i32 m0, s40, 0x2000
	s_add_u32 s38, s38, 0x40080
	v_lshl_add_u64 v[144:145], v[188:189], 0, s[12:13]
	s_addc_u32 s39, s39, 0
	s_add_i32 s40, s77, s53
	global_load_lds_dwordx4 v[144:145], off
	s_mov_b32 m0, s40
	s_nop 0
	global_load_lds_dwordx4 v130, s[38:39]
	s_add_i32 m0, s40, 0x2000
	v_lshl_add_u64 v[144:145], v[220:221], 0, s[12:13]
	global_load_lds_dwordx4 v134, s[38:39]
	s_mov_b32 m0, s63
	s_nop 0
	global_load_lds_dwordx4 v[144:145], off
	s_mov_b32 m0, s64
	v_lshl_add_u64 v[144:145], v[222:223], 0, s[12:13]
	global_load_lds_dwordx4 v[144:145], off
	s_waitcnt vmcnt(8)
	s_waitcnt lgkmcnt(0)
	s_barrier
	v_mfma_f32_16x16x32_bf16 v[60:63], v[152:155], v[184:187], v[60:63]
	v_mfma_f32_16x16x32_bf16 v[56:59], v[160:163], v[184:187], v[56:59]
	v_mfma_f32_16x16x32_bf16 v[52:55], v[152:155], v[196:199], v[52:55]
	v_mfma_f32_16x16x32_bf16 v[44:47], v[160:163], v[196:199], v[44:47]
	v_mfma_f32_16x16x32_bf16 v[36:39], v[152:155], v[204:207], v[36:39]
	v_mfma_f32_16x16x32_bf16 v[28:31], v[160:163], v[204:207], v[28:31]
	v_mfma_f32_16x16x32_bf16 v[20:23], v[152:155], v[212:215], v[20:23]
	v_mfma_f32_16x16x32_bf16 v[12:15], v[160:163], v[212:215], v[12:15]
	v_mfma_f32_16x16x32_bf16 v[60:63], v[156:159], v[192:195], v[60:63]
	v_mfma_f32_16x16x32_bf16 v[56:59], v[164:167], v[192:195], v[56:59]
	v_mfma_f32_16x16x32_bf16 v[52:55], v[156:159], v[200:203], v[52:55]
	v_mfma_f32_16x16x32_bf16 v[44:47], v[164:167], v[200:203], v[44:47]
	v_mfma_f32_16x16x32_bf16 v[36:39], v[156:159], v[208:211], v[36:39]
	v_mfma_f32_16x16x32_bf16 v[28:31], v[164:167], v[208:211], v[28:31]
	v_mfma_f32_16x16x32_bf16 v[20:23], v[156:159], v[216:219], v[20:23]
	v_mfma_f32_16x16x32_bf16 v[12:15], v[164:167], v[216:219], v[12:15]
	v_mfma_f32_16x16x32_bf16 v[48:51], v[168:171], v[184:187], v[48:51]
	v_mfma_f32_16x16x32_bf16 v[40:43], v[176:179], v[184:187], v[40:43]
	v_mfma_f32_16x16x32_bf16 v[32:35], v[168:171], v[196:199], v[32:35]
	v_mfma_f32_16x16x32_bf16 v[24:27], v[176:179], v[196:199], v[24:27]
	v_mfma_f32_16x16x32_bf16 v[16:19], v[168:171], v[204:207], v[16:19]
	v_mfma_f32_16x16x32_bf16 v[8:11], v[176:179], v[204:207], v[8:11]
	v_mfma_f32_16x16x32_bf16 v[4:7], v[168:171], v[212:215], v[4:7]
	v_mfma_f32_16x16x32_bf16 v[0:3], v[176:179], v[212:215], v[0:3]
	v_mfma_f32_16x16x32_bf16 v[48:51], v[172:175], v[192:195], v[48:51]
	v_mfma_f32_16x16x32_bf16 v[40:43], v[180:183], v[192:195], v[40:43]
	v_mfma_f32_16x16x32_bf16 v[32:35], v[172:175], v[200:203], v[32:35]
	v_mfma_f32_16x16x32_bf16 v[24:27], v[180:183], v[200:203], v[24:27]
	v_mfma_f32_16x16x32_bf16 v[16:19], v[172:175], v[208:211], v[16:19]
	v_mfma_f32_16x16x32_bf16 v[8:11], v[180:183], v[208:211], v[8:11]
	v_mfma_f32_16x16x32_bf16 v[4:7], v[172:175], v[216:219], v[4:7]
	v_mfma_f32_16x16x32_bf16 v[0:3], v[180:183], v[216:219], v[0:3]
	s_barrier
	s_add_i32 s75, s75, 2
	s_add_u32 s36, s36, 0x100
	s_addc_u32 s37, s37, 0
	s_add_u32 s73, s73, 0x100
	s_addc_u32 s74, s74, 0
	s_cmp_gt_u32 s75, 13
	s_cbranch_scc0 .LBB0_302

.LBB0_699:
	s_ashr_i32 s25, s24, 31
	s_lshl_b64 s[26:27], s[24:25], 19
	s_add_u32 s26, s58, s26
	s_addc_u32 s27, s59, s27
	s_and_b64 s[28:29], s[4:5], exec
	s_cselect_b32 s25, s27, s35
	s_cselect_b32 s55, s26, s34
	s_ashr_i32 s23, s22, 31
	s_lshl_b64 s[28:29], s[22:23], 19
	s_add_u32 s28, s43, s28
	s_addc_u32 s29, s52, s29
	s_and_b64 s[40:41], s[4:5], exec
	s_cselect_b32 s23, s29, s39
	s_cselect_b32 s72, s28, s38
	s_add_u32 s34, s34, 0x40080
	s_addc_u32 s35, s35, 0
	s_add_u32 s73, s38, 0x100
	s_addc_u32 s74, s39, 0
	s_mov_b32 s75, -2
	ds_read_b128 v[152:155], v149
	ds_read_b128 v[156:159], v149 offset:1024
	ds_read_b128 v[160:163], v149 offset:2048
	ds_read_b128 v[164:167], v149 offset:3072
	ds_read_b128 v[168:171], v150
	ds_read_b128 v[172:175], v150 offset:1024
	ds_read_b128 v[176:179], v150 offset:2048
	ds_read_b128 v[180:183], v150 offset:3072
	s_add_u32 s38, s34, 0xfffc0080
	s_addc_u32 s39, s35, -1
	s_cmp_eq_u32 s75, 12
	s_cselect_b32 s41, s25, s39
	s_cselect_b32 s40, s55, s38
	s_cselect_b32 s39, s23, s74
	s_cselect_b32 s38, s72, s73
	s_add_i32 m0, s31, 0xc000
	ds_read_b128 v[184:187], v151
	ds_read_b128 v[192:195], v151 offset:1024
	ds_read_b128 v[196:199], v151 offset:2048
	ds_read_b128 v[200:203], v151 offset:3072
	ds_read_b128 v[204:207], v151 offset:4096
	ds_read_b128 v[208:211], v151 offset:5120
	ds_read_b128 v[212:215], v151 offset:6144
	ds_read_b128 v[216:219], v151 offset:7168
	global_load_lds_dwordx4 v136, s[34:35]
	s_add_i32 m0, s31, 0xe000
	s_nop 0
	global_load_lds_dwordx4 v138, s[34:35]
	s_waitcnt vmcnt(8)
	s_waitcnt lgkmcnt(0)
	s_barrier
	v_mfma_f32_16x16x32_bf16 v[124:127], v[152:155], v[184:187], 0
	v_mfma_f32_16x16x32_bf16 v[120:123], v[160:163], v[184:187], 0
	v_mfma_f32_16x16x32_bf16 v[116:119], v[152:155], v[196:199], 0
	v_mfma_f32_16x16x32_bf16 v[108:111], v[160:163], v[196:199], 0
	v_mfma_f32_16x16x32_bf16 v[100:103], v[152:155], v[204:207], 0
	v_mfma_f32_16x16x32_bf16 v[92:95], v[160:163], v[204:207], 0
	v_mfma_f32_16x16x32_bf16 v[84:87], v[152:155], v[212:215], 0
	v_mfma_f32_16x16x32_bf16 v[76:79], v[160:163], v[212:215], 0
	v_mfma_f32_16x16x32_bf16 v[124:127], v[156:159], v[192:195], v[124:127]
	v_mfma_f32_16x16x32_bf16 v[120:123], v[164:167], v[192:195], v[120:123]
	v_mfma_f32_16x16x32_bf16 v[116:119], v[156:159], v[200:203], v[116:119]
	v_mfma_f32_16x16x32_bf16 v[108:111], v[164:167], v[200:203], v[108:111]
	v_mfma_f32_16x16x32_bf16 v[100:103], v[156:159], v[208:211], v[100:103]
	v_mfma_f32_16x16x32_bf16 v[92:95], v[164:167], v[208:211], v[92:95]
	v_mfma_f32_16x16x32_bf16 v[84:87], v[156:159], v[216:219], v[84:87]
	v_mfma_f32_16x16x32_bf16 v[76:79], v[164:167], v[216:219], v[76:79]
	v_mfma_f32_16x16x32_bf16 v[112:115], v[168:171], v[184:187], 0
	v_mfma_f32_16x16x32_bf16 v[104:107], v[176:179], v[184:187], 0
	v_mfma_f32_16x16x32_bf16 v[96:99], v[168:171], v[196:199], 0
	v_mfma_f32_16x16x32_bf16 v[88:91], v[176:179], v[196:199], 0
	v_mfma_f32_16x16x32_bf16 v[80:83], v[168:171], v[204:207], 0
	v_mfma_f32_16x16x32_bf16 v[72:75], v[176:179], v[204:207], 0
	v_mfma_f32_16x16x32_bf16 v[68:71], v[168:171], v[212:215], 0
	v_mfma_f32_16x16x32_bf16 v[64:67], v[176:179], v[212:215], 0
	v_mfma_f32_16x16x32_bf16 v[112:115], v[172:175], v[192:195], v[112:115]
	v_mfma_f32_16x16x32_bf16 v[104:107], v[180:183], v[192:195], v[104:107]
	v_mfma_f32_16x16x32_bf16 v[96:99], v[172:175], v[200:203], v[96:99]
	v_mfma_f32_16x16x32_bf16 v[88:91], v[180:183], v[200:203], v[88:91]
	v_mfma_f32_16x16x32_bf16 v[80:83], v[172:175], v[208:211], v[80:83]
	v_mfma_f32_16x16x32_bf16 v[72:75], v[180:183], v[208:211], v[72:75]
	v_mfma_f32_16x16x32_bf16 v[68:71], v[172:175], v[216:219], v[68:71]
	v_mfma_f32_16x16x32_bf16 v[64:67], v[180:183], v[216:219], v[64:67]
	s_barrier
	s_add_i32 s76, s66, s53
	v_lshl_add_u64 v[144:145], s[38:39], 0, v[130:131]
	s_mov_b32 m0, s76
	ds_read_b128 v[184:187], v151 offset:16384
	ds_read_b128 v[192:195], v151 offset:17408
	ds_read_b128 v[196:199], v151 offset:18432
	ds_read_b128 v[200:203], v151 offset:19456
	ds_read_b128 v[204:207], v151 offset:20480
	ds_read_b128 v[208:211], v151 offset:21504
	ds_read_b128 v[212:215], v151 offset:22528
	ds_read_b128 v[216:219], v151 offset:23552
	global_load_lds_dwordx4 v[144:145], off
	s_add_i32 m0, s76, 0x2000
	s_add_u32 s76, s38, 0x40000
	v_lshl_add_u64 v[188:189], s[38:39], 0, v[134:135]
	s_addc_u32 s77, s39, 0
	s_add_i32 s79, s67, s53
	global_load_lds_dwordx4 v[188:189], off
	s_mov_b32 m0, s79
	v_lshl_add_u64 v[222:223], s[40:41], 0, v[132:133]
	global_load_lds_dwordx4 v130, s[76:77]
	s_add_i32 m0, s79, 0x2000
	v_lshl_add_u64 v[220:221], s[40:41], 0, v[128:129]
	global_load_lds_dwordx4 v134, s[76:77]
	s_mov_b32 m0, s31
	s_nop 0
	global_load_lds_dwordx4 v[220:221], off
	s_mov_b32 m0, s33
	s_nop 0
	global_load_lds_dwordx4 v[222:223], off
	s_waitcnt vmcnt(8)
	s_waitcnt lgkmcnt(0)
	s_barrier
	v_mfma_f32_16x16x32_bf16 v[60:63], v[152:155], v[184:187], 0
	v_mfma_f32_16x16x32_bf16 v[56:59], v[160:163], v[184:187], 0
	v_mfma_f32_16x16x32_bf16 v[52:55], v[152:155], v[196:199], 0
	v_mfma_f32_16x16x32_bf16 v[44:47], v[160:163], v[196:199], 0
	v_mfma_f32_16x16x32_bf16 v[36:39], v[152:155], v[204:207], 0
	v_mfma_f32_16x16x32_bf16 v[28:31], v[160:163], v[204:207], 0
	v_mfma_f32_16x16x32_bf16 v[20:23], v[152:155], v[212:215], 0
	v_mfma_f32_16x16x32_bf16 v[12:15], v[160:163], v[212:215], 0
	v_mfma_f32_16x16x32_bf16 v[60:63], v[156:159], v[192:195], v[60:63]
	v_mfma_f32_16x16x32_bf16 v[56:59], v[164:167], v[192:195], v[56:59]
	v_mfma_f32_16x16x32_bf16 v[52:55], v[156:159], v[200:203], v[52:55]
	v_mfma_f32_16x16x32_bf16 v[44:47], v[164:167], v[200:203], v[44:47]
	v_mfma_f32_16x16x32_bf16 v[36:39], v[156:159], v[208:211], v[36:39]
	v_mfma_f32_16x16x32_bf16 v[28:31], v[164:167], v[208:211], v[28:31]
	v_mfma_f32_16x16x32_bf16 v[20:23], v[156:159], v[216:219], v[20:23]
	v_mfma_f32_16x16x32_bf16 v[12:15], v[164:167], v[216:219], v[12:15]
	v_mfma_f32_16x16x32_bf16 v[48:51], v[168:171], v[184:187], 0
	v_mfma_f32_16x16x32_bf16 v[40:43], v[176:179], v[184:187], 0
	v_mfma_f32_16x16x32_bf16 v[32:35], v[168:171], v[196:199], 0
	v_mfma_f32_16x16x32_bf16 v[24:27], v[176:179], v[196:199], 0
	v_mfma_f32_16x16x32_bf16 v[16:19], v[168:171], v[204:207], 0
	v_mfma_f32_16x16x32_bf16 v[8:11], v[176:179], v[204:207], 0
	v_mfma_f32_16x16x32_bf16 v[4:7], v[168:171], v[212:215], 0
	v_mfma_f32_16x16x32_bf16 v[0:3], v[176:179], v[212:215], 0
	v_mfma_f32_16x16x32_bf16 v[48:51], v[172:175], v[192:195], v[48:51]
	v_mfma_f32_16x16x32_bf16 v[40:43], v[180:183], v[192:195], v[40:43]
	v_mfma_f32_16x16x32_bf16 v[32:35], v[172:175], v[200:203], v[32:35]
	v_mfma_f32_16x16x32_bf16 v[24:27], v[180:183], v[200:203], v[24:27]
	v_mfma_f32_16x16x32_bf16 v[16:19], v[172:175], v[208:211], v[16:19]
	v_mfma_f32_16x16x32_bf16 v[8:11], v[180:183], v[208:211], v[8:11]
	v_mfma_f32_16x16x32_bf16 v[4:7], v[172:175], v[216:219], v[4:7]
	v_mfma_f32_16x16x32_bf16 v[0:3], v[180:183], v[216:219], v[0:3]
	s_barrier
	s_add_i32 s76, 0, 0x18000
	s_add_i32 s77, 0, 0x1c000
	v_add_u32_e32 v164, s76, v147
	v_add_u32_e32 v180, s77, v147
	ds_read_b128 v[152:155], v164
	ds_read_b128 v[156:159], v164 offset:1024
	ds_read_b128 v[160:163], v164 offset:2048
	ds_read_b128 v[164:167], v164 offset:3072
	ds_read_b128 v[168:171], v180
	ds_read_b128 v[172:175], v180 offset:1024
	ds_read_b128 v[176:179], v180 offset:2048
	ds_read_b128 v[180:183], v180 offset:3072
	s_add_u32 s40, s40, 0x40000
	s_addc_u32 s41, s41, 0
	s_mov_b32 m0, s60
	ds_read_b128 v[184:187], v151 offset:32768
	ds_read_b128 v[192:195], v151 offset:33792
	ds_read_b128 v[196:199], v151 offset:34816
	ds_read_b128 v[200:203], v151 offset:35840
	ds_read_b128 v[204:207], v151 offset:36864
	ds_read_b128 v[208:211], v151 offset:37888
	ds_read_b128 v[212:215], v151 offset:38912
	ds_read_b128 v[216:219], v151 offset:39936
	global_load_lds_dwordx4 v128, s[40:41]
	s_mov_b32 m0, s61
	s_nop 0
	global_load_lds_dwordx4 v132, s[40:41]
	s_waitcnt vmcnt(8)
	s_waitcnt lgkmcnt(0)
	s_barrier
	v_mfma_f32_16x16x32_bf16 v[124:127], v[152:155], v[184:187], v[124:127]
	v_mfma_f32_16x16x32_bf16 v[120:123], v[160:163], v[184:187], v[120:123]
	v_mfma_f32_16x16x32_bf16 v[116:119], v[152:155], v[196:199], v[116:119]
	v_mfma_f32_16x16x32_bf16 v[108:111], v[160:163], v[196:199], v[108:111]
	v_mfma_f32_16x16x32_bf16 v[100:103], v[152:155], v[204:207], v[100:103]
	v_mfma_f32_16x16x32_bf16 v[92:95], v[160:163], v[204:207], v[92:95]
	v_mfma_f32_16x16x32_bf16 v[84:87], v[152:155], v[212:215], v[84:87]
	v_mfma_f32_16x16x32_bf16 v[76:79], v[160:163], v[212:215], v[76:79]
	v_mfma_f32_16x16x32_bf16 v[124:127], v[156:159], v[192:195], v[124:127]
	v_mfma_f32_16x16x32_bf16 v[120:123], v[164:167], v[192:195], v[120:123]
	v_mfma_f32_16x16x32_bf16 v[116:119], v[156:159], v[200:203], v[116:119]
	v_mfma_f32_16x16x32_bf16 v[108:111], v[164:167], v[200:203], v[108:111]
	v_mfma_f32_16x16x32_bf16 v[100:103], v[156:159], v[208:211], v[100:103]
	v_mfma_f32_16x16x32_bf16 v[92:95], v[164:167], v[208:211], v[92:95]
	v_mfma_f32_16x16x32_bf16 v[84:87], v[156:159], v[216:219], v[84:87]
	v_mfma_f32_16x16x32_bf16 v[76:79], v[164:167], v[216:219], v[76:79]
	v_mfma_f32_16x16x32_bf16 v[112:115], v[168:171], v[184:187], v[112:115]
	v_mfma_f32_16x16x32_bf16 v[104:107], v[176:179], v[184:187], v[104:107]
	v_mfma_f32_16x16x32_bf16 v[96:99], v[168:171], v[196:199], v[96:99]
	v_mfma_f32_16x16x32_bf16 v[88:91], v[176:179], v[196:199], v[88:91]
	v_mfma_f32_16x16x32_bf16 v[80:83], v[168:171], v[204:207], v[80:83]
	v_mfma_f32_16x16x32_bf16 v[72:75], v[176:179], v[204:207], v[72:75]
	v_mfma_f32_16x16x32_bf16 v[68:71], v[168:171], v[212:215], v[68:71]
	v_mfma_f32_16x16x32_bf16 v[64:67], v[176:179], v[212:215], v[64:67]
	v_mfma_f32_16x16x32_bf16 v[112:115], v[172:175], v[192:195], v[112:115]
	v_mfma_f32_16x16x32_bf16 v[104:107], v[180:183], v[192:195], v[104:107]
	v_mfma_f32_16x16x32_bf16 v[96:99], v[172:175], v[200:203], v[96:99]
	v_mfma_f32_16x16x32_bf16 v[88:91], v[180:183], v[200:203], v[88:91]
	v_mfma_f32_16x16x32_bf16 v[80:83], v[172:175], v[208:211], v[80:83]
	v_mfma_f32_16x16x32_bf16 v[72:75], v[180:183], v[208:211], v[72:75]
	v_mfma_f32_16x16x32_bf16 v[68:71], v[172:175], v[216:219], v[68:71]
	v_mfma_f32_16x16x32_bf16 v[64:67], v[180:183], v[216:219], v[64:67]
	s_barrier
	s_add_i32 s40, s76, s53
	v_lshl_add_u64 v[144:145], v[144:145], 0, s[12:13]
	s_mov_b32 m0, s40
	ds_read_b128 v[184:187], v151 offset:49152
	ds_read_b128 v[192:195], v151 offset:50176
	ds_read_b128 v[196:199], v151 offset:51200
	ds_read_b128 v[200:203], v151 offset:52224
	ds_read_b128 v[204:207], v151 offset:53248
	ds_read_b128 v[208:211], v151 offset:54272
	ds_read_b128 v[212:215], v151 offset:55296
	ds_read_b128 v[216:219], v151 offset:56320
	global_load_lds_dwordx4 v[144:145], off
	s_add_i32 m0, s40, 0x2000
	s_add_u32 s38, s38, 0x40080
	v_lshl_add_u64 v[144:145], v[188:189], 0, s[12:13]
	s_addc_u32 s39, s39, 0
	s_add_i32 s40, s77, s53
	global_load_lds_dwordx4 v[144:145], off
	s_mov_b32 m0, s40
	s_nop 0
	global_load_lds_dwordx4 v130, s[38:39]
	s_add_i32 m0, s40, 0x2000
	v_lshl_add_u64 v[144:145], v[220:221], 0, s[12:13]
	global_load_lds_dwordx4 v134, s[38:39]
	s_mov_b32 m0, s63
	s_nop 0
	global_load_lds_dwordx4 v[144:145], off
	s_mov_b32 m0, s64
	v_lshl_add_u64 v[144:145], v[222:223], 0, s[12:13]
	global_load_lds_dwordx4 v[144:145], off
	s_waitcnt vmcnt(8)
	s_waitcnt lgkmcnt(0)
	s_barrier
	v_mfma_f32_16x16x32_bf16 v[60:63], v[152:155], v[184:187], v[60:63]
	v_mfma_f32_16x16x32_bf16 v[56:59], v[160:163], v[184:187], v[56:59]
	v_mfma_f32_16x16x32_bf16 v[52:55], v[152:155], v[196:199], v[52:55]
	v_mfma_f32_16x16x32_bf16 v[44:47], v[160:163], v[196:199], v[44:47]
	v_mfma_f32_16x16x32_bf16 v[36:39], v[152:155], v[204:207], v[36:39]
	v_mfma_f32_16x16x32_bf16 v[28:31], v[160:163], v[204:207], v[28:31]
	v_mfma_f32_16x16x32_bf16 v[20:23], v[152:155], v[212:215], v[20:23]
	v_mfma_f32_16x16x32_bf16 v[12:15], v[160:163], v[212:215], v[12:15]
	v_mfma_f32_16x16x32_bf16 v[60:63], v[156:159], v[192:195], v[60:63]
	v_mfma_f32_16x16x32_bf16 v[56:59], v[164:167], v[192:195], v[56:59]
	v_mfma_f32_16x16x32_bf16 v[52:55], v[156:159], v[200:203], v[52:55]
	v_mfma_f32_16x16x32_bf16 v[44:47], v[164:167], v[200:203], v[44:47]
	v_mfma_f32_16x16x32_bf16 v[36:39], v[156:159], v[208:211], v[36:39]
	v_mfma_f32_16x16x32_bf16 v[28:31], v[164:167], v[208:211], v[28:31]
	v_mfma_f32_16x16x32_bf16 v[20:23], v[156:159], v[216:219], v[20:23]
	v_mfma_f32_16x16x32_bf16 v[12:15], v[164:167], v[216:219], v[12:15]
	v_mfma_f32_16x16x32_bf16 v[48:51], v[168:171], v[184:187], v[48:51]
	v_mfma_f32_16x16x32_bf16 v[40:43], v[176:179], v[184:187], v[40:43]
	v_mfma_f32_16x16x32_bf16 v[32:35], v[168:171], v[196:199], v[32:35]
	v_mfma_f32_16x16x32_bf16 v[24:27], v[176:179], v[196:199], v[24:27]
	v_mfma_f32_16x16x32_bf16 v[16:19], v[168:171], v[204:207], v[16:19]
	v_mfma_f32_16x16x32_bf16 v[8:11], v[176:179], v[204:207], v[8:11]
	v_mfma_f32_16x16x32_bf16 v[4:7], v[168:171], v[212:215], v[4:7]
	v_mfma_f32_16x16x32_bf16 v[0:3], v[176:179], v[212:215], v[0:3]
	v_mfma_f32_16x16x32_bf16 v[48:51], v[172:175], v[192:195], v[48:51]
	v_mfma_f32_16x16x32_bf16 v[40:43], v[180:183], v[192:195], v[40:43]
	v_mfma_f32_16x16x32_bf16 v[32:35], v[172:175], v[200:203], v[32:35]
	v_mfma_f32_16x16x32_bf16 v[24:27], v[180:183], v[200:203], v[24:27]
	v_mfma_f32_16x16x32_bf16 v[16:19], v[172:175], v[208:211], v[16:19]
	v_mfma_f32_16x16x32_bf16 v[8:11], v[180:183], v[208:211], v[8:11]
	v_mfma_f32_16x16x32_bf16 v[4:7], v[172:175], v[216:219], v[4:7]
	v_mfma_f32_16x16x32_bf16 v[0:3], v[180:183], v[216:219], v[0:3]
	s_barrier
	s_add_i32 s75, s75, 2
	s_add_u32 s34, s34, 0x100
	s_addc_u32 s35, s35, 0
	s_add_u32 s73, s73, 0x100
	s_addc_u32 s74, s74, 0
	s_cmp_gt_u32 s75, 13
	s_cbranch_scc0 .LBB0_700
	s_branch .Lpeel_exit2
.LBB0_700:
	ds_read_b128 v[152:155], v149
	ds_read_b128 v[156:159], v149 offset:1024
	ds_read_b128 v[160:163], v149 offset:2048
	ds_read_b128 v[164:167], v149 offset:3072
	ds_read_b128 v[168:171], v150
	ds_read_b128 v[172:175], v150 offset:1024
	ds_read_b128 v[176:179], v150 offset:2048
	ds_read_b128 v[180:183], v150 offset:3072
	s_add_u32 s38, s34, 0xfffc0080
	s_addc_u32 s39, s35, -1
	s_cmp_eq_u32 s75, 12
	s_cselect_b32 s41, s25, s39
	s_cselect_b32 s40, s55, s38
	s_cselect_b32 s39, s23, s74
	s_cselect_b32 s38, s72, s73
	s_add_i32 m0, s31, 0xc000
	ds_read_b128 v[184:187], v151
	ds_read_b128 v[192:195], v151 offset:1024
	ds_read_b128 v[196:199], v151 offset:2048
	ds_read_b128 v[200:203], v151 offset:3072
	ds_read_b128 v[204:207], v151 offset:4096
	ds_read_b128 v[208:211], v151 offset:5120
	ds_read_b128 v[212:215], v151 offset:6144
	ds_read_b128 v[216:219], v151 offset:7168
	global_load_lds_dwordx4 v136, s[34:35]
	s_add_i32 m0, s31, 0xe000
	s_nop 0
	global_load_lds_dwordx4 v138, s[34:35]
	s_waitcnt vmcnt(8)
	s_waitcnt lgkmcnt(0)
	s_barrier
	v_mfma_f32_16x16x32_bf16 v[124:127], v[152:155], v[184:187], v[124:127]
	v_mfma_f32_16x16x32_bf16 v[120:123], v[160:163], v[184:187], v[120:123]
	v_mfma_f32_16x16x32_bf16 v[116:119], v[152:155], v[196:199], v[116:119]
	v_mfma_f32_16x16x32_bf16 v[108:111], v[160:163], v[196:199], v[108:111]
	v_mfma_f32_16x16x32_bf16 v[100:103], v[152:155], v[204:207], v[100:103]
	v_mfma_f32_16x16x32_bf16 v[92:95], v[160:163], v[204:207], v[92:95]
	v_mfma_f32_16x16x32_bf16 v[84:87], v[152:155], v[212:215], v[84:87]
	v_mfma_f32_16x16x32_bf16 v[76:79], v[160:163], v[212:215], v[76:79]
	v_mfma_f32_16x16x32_bf16 v[124:127], v[156:159], v[192:195], v[124:127]
	v_mfma_f32_16x16x32_bf16 v[120:123], v[164:167], v[192:195], v[120:123]
	v_mfma_f32_16x16x32_bf16 v[116:119], v[156:159], v[200:203], v[116:119]
	v_mfma_f32_16x16x32_bf16 v[108:111], v[164:167], v[200:203], v[108:111]
	v_mfma_f32_16x16x32_bf16 v[100:103], v[156:159], v[208:211], v[100:103]
	v_mfma_f32_16x16x32_bf16 v[92:95], v[164:167], v[208:211], v[92:95]
	v_mfma_f32_16x16x32_bf16 v[84:87], v[156:159], v[216:219], v[84:87]
	v_mfma_f32_16x16x32_bf16 v[76:79], v[164:167], v[216:219], v[76:79]
	v_mfma_f32_16x16x32_bf16 v[112:115], v[168:171], v[184:187], v[112:115]
	v_mfma_f32_16x16x32_bf16 v[104:107], v[176:179], v[184:187], v[104:107]
	v_mfma_f32_16x16x32_bf16 v[96:99], v[168:171], v[196:199], v[96:99]
	v_mfma_f32_16x16x32_bf16 v[88:91], v[176:179], v[196:199], v[88:91]
	v_mfma_f32_16x16x32_bf16 v[80:83], v[168:171], v[204:207], v[80:83]
	v_mfma_f32_16x16x32_bf16 v[72:75], v[176:179], v[204:207], v[72:75]
	v_mfma_f32_16x16x32_bf16 v[68:71], v[168:171], v[212:215], v[68:71]
	v_mfma_f32_16x16x32_bf16 v[64:67], v[176:179], v[212:215], v[64:67]
	v_mfma_f32_16x16x32_bf16 v[112:115], v[172:175], v[192:195], v[112:115]
	v_mfma_f32_16x16x32_bf16 v[104:107], v[180:183], v[192:195], v[104:107]
	v_mfma_f32_16x16x32_bf16 v[96:99], v[172:175], v[200:203], v[96:99]
	v_mfma_f32_16x16x32_bf16 v[88:91], v[180:183], v[200:203], v[88:91]
	v_mfma_f32_16x16x32_bf16 v[80:83], v[172:175], v[208:211], v[80:83]
	v_mfma_f32_16x16x32_bf16 v[72:75], v[180:183], v[208:211], v[72:75]
	v_mfma_f32_16x16x32_bf16 v[68:71], v[172:175], v[216:219], v[68:71]
	v_mfma_f32_16x16x32_bf16 v[64:67], v[180:183], v[216:219], v[64:67]
	s_barrier
	s_add_i32 s76, s66, s53
	v_lshl_add_u64 v[144:145], s[38:39], 0, v[130:131]
	s_mov_b32 m0, s76
	ds_read_b128 v[184:187], v151 offset:16384
	ds_read_b128 v[192:195], v151 offset:17408
	ds_read_b128 v[196:199], v151 offset:18432
	ds_read_b128 v[200:203], v151 offset:19456
	ds_read_b128 v[204:207], v151 offset:20480
	ds_read_b128 v[208:211], v151 offset:21504
	ds_read_b128 v[212:215], v151 offset:22528
	ds_read_b128 v[216:219], v151 offset:23552
	global_load_lds_dwordx4 v[144:145], off
	s_add_i32 m0, s76, 0x2000
	s_add_u32 s76, s38, 0x40000
	v_lshl_add_u64 v[188:189], s[38:39], 0, v[134:135]
	s_addc_u32 s77, s39, 0
	s_add_i32 s79, s67, s53
	global_load_lds_dwordx4 v[188:189], off
	s_mov_b32 m0, s79
	v_lshl_add_u64 v[222:223], s[40:41], 0, v[132:133]
	global_load_lds_dwordx4 v130, s[76:77]
	s_add_i32 m0, s79, 0x2000
	v_lshl_add_u64 v[220:221], s[40:41], 0, v[128:129]
	global_load_lds_dwordx4 v134, s[76:77]
	s_mov_b32 m0, s31
	s_nop 0
	global_load_lds_dwordx4 v[220:221], off
	s_mov_b32 m0, s33
	s_nop 0
	global_load_lds_dwordx4 v[222:223], off
	s_waitcnt vmcnt(8)
	s_waitcnt lgkmcnt(0)
	s_barrier
	v_mfma_f32_16x16x32_bf16 v[60:63], v[152:155], v[184:187], v[60:63]
	v_mfma_f32_16x16x32_bf16 v[56:59], v[160:163], v[184:187], v[56:59]
	v_mfma_f32_16x16x32_bf16 v[52:55], v[152:155], v[196:199], v[52:55]
	v_mfma_f32_16x16x32_bf16 v[44:47], v[160:163], v[196:199], v[44:47]
	v_mfma_f32_16x16x32_bf16 v[36:39], v[152:155], v[204:207], v[36:39]
	v_mfma_f32_16x16x32_bf16 v[28:31], v[160:163], v[204:207], v[28:31]
	v_mfma_f32_16x16x32_bf16 v[20:23], v[152:155], v[212:215], v[20:23]
	v_mfma_f32_16x16x32_bf16 v[12:15], v[160:163], v[212:215], v[12:15]
	v_mfma_f32_16x16x32_bf16 v[60:63], v[156:159], v[192:195], v[60:63]
	v_mfma_f32_16x16x32_bf16 v[56:59], v[164:167], v[192:195], v[56:59]
	v_mfma_f32_16x16x32_bf16 v[52:55], v[156:159], v[200:203], v[52:55]
	v_mfma_f32_16x16x32_bf16 v[44:47], v[164:167], v[200:203], v[44:47]
	v_mfma_f32_16x16x32_bf16 v[36:39], v[156:159], v[208:211], v[36:39]
	v_mfma_f32_16x16x32_bf16 v[28:31], v[164:167], v[208:211], v[28:31]
	v_mfma_f32_16x16x32_bf16 v[20:23], v[156:159], v[216:219], v[20:23]
	v_mfma_f32_16x16x32_bf16 v[12:15], v[164:167], v[216:219], v[12:15]
	v_mfma_f32_16x16x32_bf16 v[48:51], v[168:171], v[184:187], v[48:51]
	v_mfma_f32_16x16x32_bf16 v[40:43], v[176:179], v[184:187], v[40:43]
	v_mfma_f32_16x16x32_bf16 v[32:35], v[168:171], v[196:199], v[32:35]
	v_mfma_f32_16x16x32_bf16 v[24:27], v[176:179], v[196:199], v[24:27]
	v_mfma_f32_16x16x32_bf16 v[16:19], v[168:171], v[204:207], v[16:19]
	v_mfma_f32_16x16x32_bf16 v[8:11], v[176:179], v[204:207], v[8:11]
	v_mfma_f32_16x16x32_bf16 v[4:7], v[168:171], v[212:215], v[4:7]
	v_mfma_f32_16x16x32_bf16 v[0:3], v[176:179], v[212:215], v[0:3]
	v_mfma_f32_16x16x32_bf16 v[48:51], v[172:175], v[192:195], v[48:51]
	v_mfma_f32_16x16x32_bf16 v[40:43], v[180:183], v[192:195], v[40:43]
	v_mfma_f32_16x16x32_bf16 v[32:35], v[172:175], v[200:203], v[32:35]
	v_mfma_f32_16x16x32_bf16 v[24:27], v[180:183], v[200:203], v[24:27]
	v_mfma_f32_16x16x32_bf16 v[16:19], v[172:175], v[208:211], v[16:19]
	v_mfma_f32_16x16x32_bf16 v[8:11], v[180:183], v[208:211], v[8:11]
	v_mfma_f32_16x16x32_bf16 v[4:7], v[172:175], v[216:219], v[4:7]
	v_mfma_f32_16x16x32_bf16 v[0:3], v[180:183], v[216:219], v[0:3]
	s_barrier
	s_add_i32 s76, 0, 0x18000
	s_add_i32 s77, 0, 0x1c000
	v_add_u32_e32 v164, s76, v147
	v_add_u32_e32 v180, s77, v147
	ds_read_b128 v[152:155], v164
	ds_read_b128 v[156:159], v164 offset:1024
	ds_read_b128 v[160:163], v164 offset:2048
	ds_read_b128 v[164:167], v164 offset:3072
	ds_read_b128 v[168:171], v180
	ds_read_b128 v[172:175], v180 offset:1024
	ds_read_b128 v[176:179], v180 offset:2048
	ds_read_b128 v[180:183], v180 offset:3072
	s_add_u32 s40, s40, 0x40000
	s_addc_u32 s41, s41, 0
	s_mov_b32 m0, s60
	ds_read_b128 v[184:187], v151 offset:32768
	ds_read_b128 v[192:195], v151 offset:33792
	ds_read_b128 v[196:199], v151 offset:34816
	ds_read_b128 v[200:203], v151 offset:35840
	ds_read_b128 v[204:207], v151 offset:36864
	ds_read_b128 v[208:211], v151 offset:37888
	ds_read_b128 v[212:215], v151 offset:38912
	ds_read_b128 v[216:219], v151 offset:39936
	global_load_lds_dwordx4 v128, s[40:41]
	s_mov_b32 m0, s61
	s_nop 0
	global_load_lds_dwordx4 v132, s[40:41]
	s_waitcnt vmcnt(8)
	s_waitcnt lgkmcnt(0)
	s_barrier
	v_mfma_f32_16x16x32_bf16 v[124:127], v[152:155], v[184:187], v[124:127]
	v_mfma_f32_16x16x32_bf16 v[120:123], v[160:163], v[184:187], v[120:123]
	v_mfma_f32_16x16x32_bf16 v[116:119], v[152:155], v[196:199], v[116:119]
	v_mfma_f32_16x16x32_bf16 v[108:111], v[160:163], v[196:199], v[108:111]
	v_mfma_f32_16x16x32_bf16 v[100:103], v[152:155], v[204:207], v[100:103]
	v_mfma_f32_16x16x32_bf16 v[92:95], v[160:163], v[204:207], v[92:95]
	v_mfma_f32_16x16x32_bf16 v[84:87], v[152:155], v[212:215], v[84:87]
	v_mfma_f32_16x16x32_bf16 v[76:79], v[160:163], v[212:215], v[76:79]
	v_mfma_f32_16x16x32_bf16 v[124:127], v[156:159], v[192:195], v[124:127]
	v_mfma_f32_16x16x32_bf16 v[120:123], v[164:167], v[192:195], v[120:123]
	v_mfma_f32_16x16x32_bf16 v[116:119], v[156:159], v[200:203], v[116:119]
	v_mfma_f32_16x16x32_bf16 v[108:111], v[164:167], v[200:203], v[108:111]
	v_mfma_f32_16x16x32_bf16 v[100:103], v[156:159], v[208:211], v[100:103]
	v_mfma_f32_16x16x32_bf16 v[92:95], v[164:167], v[208:211], v[92:95]
	v_mfma_f32_16x16x32_bf16 v[84:87], v[156:159], v[216:219], v[84:87]
	v_mfma_f32_16x16x32_bf16 v[76:79], v[164:167], v[216:219], v[76:79]
	v_mfma_f32_16x16x32_bf16 v[112:115], v[168:171], v[184:187], v[112:115]
	v_mfma_f32_16x16x32_bf16 v[104:107], v[176:179], v[184:187], v[104:107]
	v_mfma_f32_16x16x32_bf16 v[96:99], v[168:171], v[196:199], v[96:99]
	v_mfma_f32_16x16x32_bf16 v[88:91], v[176:179], v[196:199], v[88:91]
	v_mfma_f32_16x16x32_bf16 v[80:83], v[168:171], v[204:207], v[80:83]
	v_mfma_f32_16x16x32_bf16 v[72:75], v[176:179], v[204:207], v[72:75]
	v_mfma_f32_16x16x32_bf16 v[68:71], v[168:171], v[212:215], v[68:71]
	v_mfma_f32_16x16x32_bf16 v[64:67], v[176:179], v[212:215], v[64:67]
	v_mfma_f32_16x16x32_bf16 v[112:115], v[172:175], v[192:195], v[112:115]
	v_mfma_f32_16x16x32_bf16 v[104:107], v[180:183], v[192:195], v[104:107]
	v_mfma_f32_16x16x32_bf16 v[96:99], v[172:175], v[200:203], v[96:99]
	v_mfma_f32_16x16x32_bf16 v[88:91], v[180:183], v[200:203], v[88:91]
	v_mfma_f32_16x16x32_bf16 v[80:83], v[172:175], v[208:211], v[80:83]
	v_mfma_f32_16x16x32_bf16 v[72:75], v[180:183], v[208:211], v[72:75]
	v_mfma_f32_16x16x32_bf16 v[68:71], v[172:175], v[216:219], v[68:71]
	v_mfma_f32_16x16x32_bf16 v[64:67], v[180:183], v[216:219], v[64:67]
	s_barrier
	s_add_i32 s40, s76, s53
	v_lshl_add_u64 v[144:145], v[144:145], 0, s[12:13]
	s_mov_b32 m0, s40
	ds_read_b128 v[184:187], v151 offset:49152
	ds_read_b128 v[192:195], v151 offset:50176
	ds_read_b128 v[196:199], v151 offset:51200
	ds_read_b128 v[200:203], v151 offset:52224
	ds_read_b128 v[204:207], v151 offset:53248
	ds_read_b128 v[208:211], v151 offset:54272
	ds_read_b128 v[212:215], v151 offset:55296
	ds_read_b128 v[216:219], v151 offset:56320
	global_load_lds_dwordx4 v[144:145], off
	s_add_i32 m0, s40, 0x2000
	s_add_u32 s38, s38, 0x40080
	v_lshl_add_u64 v[144:145], v[188:189], 0, s[12:13]
	s_addc_u32 s39, s39, 0
	s_add_i32 s40, s77, s53
	global_load_lds_dwordx4 v[144:145], off
	s_mov_b32 m0, s40
	s_nop 0
	global_load_lds_dwordx4 v130, s[38:39]
	s_add_i32 m0, s40, 0x2000
	v_lshl_add_u64 v[144:145], v[220:221], 0, s[12:13]
	global_load_lds_dwordx4 v134, s[38:39]
	s_mov_b32 m0, s63
	s_nop 0
	global_load_lds_dwordx4 v[144:145], off
	s_mov_b32 m0, s64
	v_lshl_add_u64 v[144:145], v[222:223], 0, s[12:13]
	global_load_lds_dwordx4 v[144:145], off
	s_waitcnt vmcnt(8)
	s_waitcnt lgkmcnt(0)
	s_barrier
	v_mfma_f32_16x16x32_bf16 v[60:63], v[152:155], v[184:187], v[60:63]
	v_mfma_f32_16x16x32_bf16 v[56:59], v[160:163], v[184:187], v[56:59]
	v_mfma_f32_16x16x32_bf16 v[52:55], v[152:155], v[196:199], v[52:55]
	v_mfma_f32_16x16x32_bf16 v[44:47], v[160:163], v[196:199], v[44:47]
	v_mfma_f32_16x16x32_bf16 v[36:39], v[152:155], v[204:207], v[36:39]
	v_mfma_f32_16x16x32_bf16 v[28:31], v[160:163], v[204:207], v[28:31]
	v_mfma_f32_16x16x32_bf16 v[20:23], v[152:155], v[212:215], v[20:23]
	v_mfma_f32_16x16x32_bf16 v[12:15], v[160:163], v[212:215], v[12:15]
	v_mfma_f32_16x16x32_bf16 v[60:63], v[156:159], v[192:195], v[60:63]
	v_mfma_f32_16x16x32_bf16 v[56:59], v[164:167], v[192:195], v[56:59]
	v_mfma_f32_16x16x32_bf16 v[52:55], v[156:159], v[200:203], v[52:55]
	v_mfma_f32_16x16x32_bf16 v[44:47], v[164:167], v[200:203], v[44:47]
	v_mfma_f32_16x16x32_bf16 v[36:39], v[156:159], v[208:211], v[36:39]
	v_mfma_f32_16x16x32_bf16 v[28:31], v[164:167], v[208:211], v[28:31]
	v_mfma_f32_16x16x32_bf16 v[20:23], v[156:159], v[216:219], v[20:23]
	v_mfma_f32_16x16x32_bf16 v[12:15], v[164:167], v[216:219], v[12:15]
	v_mfma_f32_16x16x32_bf16 v[48:51], v[168:171], v[184:187], v[48:51]
	v_mfma_f32_16x16x32_bf16 v[40:43], v[176:179], v[184:187], v[40:43]
	v_mfma_f32_16x16x32_bf16 v[32:35], v[168:171], v[196:199], v[32:35]
	v_mfma_f32_16x16x32_bf16 v[24:27], v[176:179], v[196:199], v[24:27]
	v_mfma_f32_16x16x32_bf16 v[16:19], v[168:171], v[204:207], v[16:19]
	v_mfma_f32_16x16x32_bf16 v[8:11], v[176:179], v[204:207], v[8:11]
	v_mfma_f32_16x16x32_bf16 v[4:7], v[168:171], v[212:215], v[4:7]
	v_mfma_f32_16x16x32_bf16 v[0:3], v[176:179], v[212:215], v[0:3]
	v_mfma_f32_16x16x32_bf16 v[48:51], v[172:175], v[192:195], v[48:51]
	v_mfma_f32_16x16x32_bf16 v[40:43], v[180:183], v[192:195], v[40:43]
	v_mfma_f32_16x16x32_bf16 v[32:35], v[172:175], v[200:203], v[32:35]
	v_mfma_f32_16x16x32_bf16 v[24:27], v[180:183], v[200:203], v[24:27]
	v_mfma_f32_16x16x32_bf16 v[16:19], v[172:175], v[208:211], v[16:19]
	v_mfma_f32_16x16x32_bf16 v[8:11], v[180:183], v[208:211], v[8:11]
	v_mfma_f32_16x16x32_bf16 v[4:7], v[172:175], v[216:219], v[4:7]
	v_mfma_f32_16x16x32_bf16 v[0:3], v[180:183], v[216:219], v[0:3]
	s_barrier
	s_add_i32 s75, s75, 2
	s_add_u32 s34, s34, 0x100
	s_addc_u32 s35, s35, 0
	s_add_u32 s73, s73, 0x100
	s_addc_u32 s74, s74, 0
	s_cmp_gt_u32 s75, 13
	s_cbranch_scc0 .LBB0_700

.LBB0_836:
	s_ashr_i32 s25, s24, 31
	s_lshl_b64 s[26:27], s[24:25], 19
	s_add_u32 s26, s58, s26
	s_addc_u32 s27, s59, s27
	s_and_b64 s[28:29], s[4:5], exec
	s_cselect_b32 s25, s27, s35
	s_cselect_b32 s54, s26, s34
	s_ashr_i32 s23, s22, 31
	s_lshl_b64 s[28:29], s[22:23], 19
	s_add_u32 s28, s61, s28
	s_addc_u32 s29, s62, s29
	s_and_b64 s[42:43], s[4:5], exec
	s_cselect_b32 s23, s29, s41
	s_cselect_b32 s55, s28, s40
	s_add_u32 s34, s34, 0x40080
	s_addc_u32 s35, s35, 0
	s_add_u32 s75, s40, 0x100
	s_addc_u32 s76, s41, 0
	s_mov_b32 s77, -2
	ds_read_b128 v[152:155], v149
	ds_read_b128 v[156:159], v149 offset:1024
	ds_read_b128 v[160:163], v149 offset:2048
	ds_read_b128 v[164:167], v149 offset:3072
	ds_read_b128 v[168:171], v150
	ds_read_b128 v[172:175], v150 offset:1024
	ds_read_b128 v[176:179], v150 offset:2048
	ds_read_b128 v[180:183], v150 offset:3072
	s_add_u32 s40, s34, 0xfffc0080
	s_addc_u32 s41, s35, -1
	s_cmp_eq_u32 s77, 12
	s_cselect_b32 s43, s25, s41
	s_cselect_b32 s42, s54, s40
	s_cselect_b32 s41, s23, s76
	s_cselect_b32 s40, s55, s75
	s_add_i32 m0, s31, 0xc000
	ds_read_b128 v[184:187], v151
	ds_read_b128 v[192:195], v151 offset:1024
	ds_read_b128 v[196:199], v151 offset:2048
	ds_read_b128 v[200:203], v151 offset:3072
	ds_read_b128 v[204:207], v151 offset:4096
	ds_read_b128 v[208:211], v151 offset:5120
	ds_read_b128 v[212:215], v151 offset:6144
	ds_read_b128 v[216:219], v151 offset:7168
	global_load_lds_dwordx4 v136, s[34:35]
	s_add_i32 m0, s31, 0xe000
	s_nop 0
	global_load_lds_dwordx4 v138, s[34:35]
	s_waitcnt vmcnt(8)
	s_waitcnt lgkmcnt(0)
	s_barrier
	v_mfma_f32_16x16x32_bf16 v[124:127], v[152:155], v[184:187], 0
	v_mfma_f32_16x16x32_bf16 v[120:123], v[160:163], v[184:187], 0
	v_mfma_f32_16x16x32_bf16 v[108:111], v[152:155], v[196:199], 0
	v_mfma_f32_16x16x32_bf16 v[104:107], v[160:163], v[196:199], 0
	v_mfma_f32_16x16x32_bf16 v[92:95], v[152:155], v[204:207], 0
	v_mfma_f32_16x16x32_bf16 v[88:91], v[160:163], v[204:207], 0
	v_mfma_f32_16x16x32_bf16 v[76:79], v[152:155], v[212:215], 0
	v_mfma_f32_16x16x32_bf16 v[72:75], v[160:163], v[212:215], 0
	v_mfma_f32_16x16x32_bf16 v[124:127], v[156:159], v[192:195], v[124:127]
	v_mfma_f32_16x16x32_bf16 v[120:123], v[164:167], v[192:195], v[120:123]
	v_mfma_f32_16x16x32_bf16 v[108:111], v[156:159], v[200:203], v[108:111]
	v_mfma_f32_16x16x32_bf16 v[104:107], v[164:167], v[200:203], v[104:107]
	v_mfma_f32_16x16x32_bf16 v[92:95], v[156:159], v[208:211], v[92:95]
	v_mfma_f32_16x16x32_bf16 v[88:91], v[164:167], v[208:211], v[88:91]
	v_mfma_f32_16x16x32_bf16 v[76:79], v[156:159], v[216:219], v[76:79]
	v_mfma_f32_16x16x32_bf16 v[72:75], v[164:167], v[216:219], v[72:75]
	v_mfma_f32_16x16x32_bf16 v[116:119], v[168:171], v[184:187], 0
	v_mfma_f32_16x16x32_bf16 v[112:115], v[176:179], v[184:187], 0
	v_mfma_f32_16x16x32_bf16 v[100:103], v[168:171], v[196:199], 0
	v_mfma_f32_16x16x32_bf16 v[96:99], v[176:179], v[196:199], 0
	v_mfma_f32_16x16x32_bf16 v[84:87], v[168:171], v[204:207], 0
	v_mfma_f32_16x16x32_bf16 v[80:83], v[176:179], v[204:207], 0
	v_mfma_f32_16x16x32_bf16 v[68:71], v[168:171], v[212:215], 0
	v_mfma_f32_16x16x32_bf16 v[64:67], v[176:179], v[212:215], 0
	v_mfma_f32_16x16x32_bf16 v[116:119], v[172:175], v[192:195], v[116:119]
	v_mfma_f32_16x16x32_bf16 v[112:115], v[180:183], v[192:195], v[112:115]
	v_mfma_f32_16x16x32_bf16 v[100:103], v[172:175], v[200:203], v[100:103]
	v_mfma_f32_16x16x32_bf16 v[96:99], v[180:183], v[200:203], v[96:99]
	v_mfma_f32_16x16x32_bf16 v[84:87], v[172:175], v[208:211], v[84:87]
	v_mfma_f32_16x16x32_bf16 v[80:83], v[180:183], v[208:211], v[80:83]
	v_mfma_f32_16x16x32_bf16 v[68:71], v[172:175], v[216:219], v[68:71]
	v_mfma_f32_16x16x32_bf16 v[64:67], v[180:183], v[216:219], v[64:67]
	s_barrier
	s_add_i32 s79, s69, s63
	v_lshl_add_u64 v[144:145], s[40:41], 0, v[130:131]
	s_mov_b32 m0, s79
	ds_read_b128 v[184:187], v151 offset:16384
	ds_read_b128 v[192:195], v151 offset:17408
	ds_read_b128 v[196:199], v151 offset:18432
	ds_read_b128 v[200:203], v151 offset:19456
	ds_read_b128 v[204:207], v151 offset:20480
	ds_read_b128 v[208:211], v151 offset:21504
	ds_read_b128 v[212:215], v151 offset:22528
	ds_read_b128 v[216:219], v151 offset:23552
	global_load_lds_dwordx4 v[144:145], off
	s_add_i32 m0, s79, 0x2000
	s_add_u32 s80, s40, 0x40000
	v_lshl_add_u64 v[188:189], s[40:41], 0, v[134:135]
	s_addc_u32 s81, s41, 0
	s_add_i32 s79, s70, s63
	global_load_lds_dwordx4 v[188:189], off
	s_mov_b32 m0, s79
	v_lshl_add_u64 v[222:223], s[42:43], 0, v[132:133]
	global_load_lds_dwordx4 v130, s[80:81]
	s_add_i32 m0, s79, 0x2000
	v_lshl_add_u64 v[220:221], s[42:43], 0, v[128:129]
	global_load_lds_dwordx4 v134, s[80:81]
	s_mov_b32 m0, s31
	s_nop 0
	global_load_lds_dwordx4 v[220:221], off
	s_mov_b32 m0, s64
	s_nop 0
	global_load_lds_dwordx4 v[222:223], off
	s_waitcnt vmcnt(8)
	s_waitcnt lgkmcnt(0)
	s_barrier
	v_mfma_f32_16x16x32_bf16 v[60:63], v[152:155], v[184:187], 0
	v_mfma_f32_16x16x32_bf16 v[56:59], v[160:163], v[184:187], 0
	v_mfma_f32_16x16x32_bf16 v[44:47], v[152:155], v[196:199], 0
	v_mfma_f32_16x16x32_bf16 v[40:43], v[160:163], v[196:199], 0
	v_mfma_f32_16x16x32_bf16 v[28:31], v[152:155], v[204:207], 0
	v_mfma_f32_16x16x32_bf16 v[24:27], v[160:163], v[204:207], 0
	v_mfma_f32_16x16x32_bf16 v[12:15], v[152:155], v[212:215], 0
	v_mfma_f32_16x16x32_bf16 v[8:11], v[160:163], v[212:215], 0
	v_mfma_f32_16x16x32_bf16 v[60:63], v[156:159], v[192:195], v[60:63]
	v_mfma_f32_16x16x32_bf16 v[56:59], v[164:167], v[192:195], v[56:59]
	v_mfma_f32_16x16x32_bf16 v[44:47], v[156:159], v[200:203], v[44:47]
	v_mfma_f32_16x16x32_bf16 v[40:43], v[164:167], v[200:203], v[40:43]
	v_mfma_f32_16x16x32_bf16 v[28:31], v[156:159], v[208:211], v[28:31]
	v_mfma_f32_16x16x32_bf16 v[24:27], v[164:167], v[208:211], v[24:27]
	v_mfma_f32_16x16x32_bf16 v[12:15], v[156:159], v[216:219], v[12:15]
	v_mfma_f32_16x16x32_bf16 v[8:11], v[164:167], v[216:219], v[8:11]
	v_mfma_f32_16x16x32_bf16 v[52:55], v[168:171], v[184:187], 0
	v_mfma_f32_16x16x32_bf16 v[48:51], v[176:179], v[184:187], 0
	v_mfma_f32_16x16x32_bf16 v[36:39], v[168:171], v[196:199], 0
	v_mfma_f32_16x16x32_bf16 v[32:35], v[176:179], v[196:199], 0
	v_mfma_f32_16x16x32_bf16 v[20:23], v[168:171], v[204:207], 0
	v_mfma_f32_16x16x32_bf16 v[16:19], v[176:179], v[204:207], 0
	v_mfma_f32_16x16x32_bf16 v[4:7], v[168:171], v[212:215], 0
	v_mfma_f32_16x16x32_bf16 v[0:3], v[176:179], v[212:215], 0
	v_mfma_f32_16x16x32_bf16 v[52:55], v[172:175], v[192:195], v[52:55]
	v_mfma_f32_16x16x32_bf16 v[48:51], v[180:183], v[192:195], v[48:51]
	v_mfma_f32_16x16x32_bf16 v[36:39], v[172:175], v[200:203], v[36:39]
	v_mfma_f32_16x16x32_bf16 v[32:35], v[180:183], v[200:203], v[32:35]
	v_mfma_f32_16x16x32_bf16 v[20:23], v[172:175], v[208:211], v[20:23]
	v_mfma_f32_16x16x32_bf16 v[16:19], v[180:183], v[208:211], v[16:19]
	v_mfma_f32_16x16x32_bf16 v[4:7], v[172:175], v[216:219], v[4:7]
	v_mfma_f32_16x16x32_bf16 v[0:3], v[180:183], v[216:219], v[0:3]
	s_barrier
	s_add_i32 s79, 0, 0x18000
	s_add_i32 s80, 0, 0x1c000
	v_add_u32_e32 v164, s79, v147
	v_add_u32_e32 v180, s80, v147
	ds_read_b128 v[152:155], v164
	ds_read_b128 v[156:159], v164 offset:1024
	ds_read_b128 v[160:163], v164 offset:2048
	ds_read_b128 v[164:167], v164 offset:3072
	ds_read_b128 v[168:171], v180
	ds_read_b128 v[172:175], v180 offset:1024
	ds_read_b128 v[176:179], v180 offset:2048
	ds_read_b128 v[180:183], v180 offset:3072
	s_add_u32 s42, s42, 0x40000
	s_addc_u32 s43, s43, 0
	s_mov_b32 m0, s65
	ds_read_b128 v[184:187], v151 offset:32768
	ds_read_b128 v[192:195], v151 offset:33792
	ds_read_b128 v[196:199], v151 offset:34816
	ds_read_b128 v[200:203], v151 offset:35840
	ds_read_b128 v[204:207], v151 offset:36864
	ds_read_b128 v[208:211], v151 offset:37888
	ds_read_b128 v[212:215], v151 offset:38912
	ds_read_b128 v[216:219], v151 offset:39936
	global_load_lds_dwordx4 v128, s[42:43]
	s_mov_b32 m0, s66
	s_nop 0
	global_load_lds_dwordx4 v132, s[42:43]
	s_waitcnt vmcnt(8)
	s_waitcnt lgkmcnt(0)
	s_barrier
	v_mfma_f32_16x16x32_bf16 v[124:127], v[152:155], v[184:187], v[124:127]
	v_mfma_f32_16x16x32_bf16 v[120:123], v[160:163], v[184:187], v[120:123]
	v_mfma_f32_16x16x32_bf16 v[108:111], v[152:155], v[196:199], v[108:111]
	v_mfma_f32_16x16x32_bf16 v[104:107], v[160:163], v[196:199], v[104:107]
	v_mfma_f32_16x16x32_bf16 v[92:95], v[152:155], v[204:207], v[92:95]
	v_mfma_f32_16x16x32_bf16 v[88:91], v[160:163], v[204:207], v[88:91]
	v_mfma_f32_16x16x32_bf16 v[76:79], v[152:155], v[212:215], v[76:79]
	v_mfma_f32_16x16x32_bf16 v[72:75], v[160:163], v[212:215], v[72:75]
	v_mfma_f32_16x16x32_bf16 v[124:127], v[156:159], v[192:195], v[124:127]
	v_mfma_f32_16x16x32_bf16 v[120:123], v[164:167], v[192:195], v[120:123]
	v_mfma_f32_16x16x32_bf16 v[108:111], v[156:159], v[200:203], v[108:111]
	v_mfma_f32_16x16x32_bf16 v[104:107], v[164:167], v[200:203], v[104:107]
	v_mfma_f32_16x16x32_bf16 v[92:95], v[156:159], v[208:211], v[92:95]
	v_mfma_f32_16x16x32_bf16 v[88:91], v[164:167], v[208:211], v[88:91]
	v_mfma_f32_16x16x32_bf16 v[76:79], v[156:159], v[216:219], v[76:79]
	v_mfma_f32_16x16x32_bf16 v[72:75], v[164:167], v[216:219], v[72:75]
	v_mfma_f32_16x16x32_bf16 v[116:119], v[168:171], v[184:187], v[116:119]
	v_mfma_f32_16x16x32_bf16 v[112:115], v[176:179], v[184:187], v[112:115]
	v_mfma_f32_16x16x32_bf16 v[100:103], v[168:171], v[196:199], v[100:103]
	v_mfma_f32_16x16x32_bf16 v[96:99], v[176:179], v[196:199], v[96:99]
	v_mfma_f32_16x16x32_bf16 v[84:87], v[168:171], v[204:207], v[84:87]
	v_mfma_f32_16x16x32_bf16 v[80:83], v[176:179], v[204:207], v[80:83]
	v_mfma_f32_16x16x32_bf16 v[68:71], v[168:171], v[212:215], v[68:71]
	v_mfma_f32_16x16x32_bf16 v[64:67], v[176:179], v[212:215], v[64:67]
	v_mfma_f32_16x16x32_bf16 v[116:119], v[172:175], v[192:195], v[116:119]
	v_mfma_f32_16x16x32_bf16 v[112:115], v[180:183], v[192:195], v[112:115]
	v_mfma_f32_16x16x32_bf16 v[100:103], v[172:175], v[200:203], v[100:103]
	v_mfma_f32_16x16x32_bf16 v[96:99], v[180:183], v[200:203], v[96:99]
	v_mfma_f32_16x16x32_bf16 v[84:87], v[172:175], v[208:211], v[84:87]
	v_mfma_f32_16x16x32_bf16 v[80:83], v[180:183], v[208:211], v[80:83]
	v_mfma_f32_16x16x32_bf16 v[68:71], v[172:175], v[216:219], v[68:71]
	v_mfma_f32_16x16x32_bf16 v[64:67], v[180:183], v[216:219], v[64:67]
	s_barrier
	s_add_i32 s42, s79, s63
	v_lshl_add_u64 v[144:145], v[144:145], 0, s[10:11]
	s_mov_b32 m0, s42
	ds_read_b128 v[184:187], v151 offset:49152
	ds_read_b128 v[192:195], v151 offset:50176
	ds_read_b128 v[196:199], v151 offset:51200
	ds_read_b128 v[200:203], v151 offset:52224
	ds_read_b128 v[204:207], v151 offset:53248
	ds_read_b128 v[208:211], v151 offset:54272
	ds_read_b128 v[212:215], v151 offset:55296
	ds_read_b128 v[216:219], v151 offset:56320
	global_load_lds_dwordx4 v[144:145], off
	s_add_i32 m0, s42, 0x2000
	s_add_u32 s40, s40, 0x40080
	v_lshl_add_u64 v[144:145], v[188:189], 0, s[10:11]
	s_addc_u32 s41, s41, 0
	s_add_i32 s42, s80, s63
	global_load_lds_dwordx4 v[144:145], off
	s_mov_b32 m0, s42
	s_nop 0
	global_load_lds_dwordx4 v130, s[40:41]
	s_add_i32 m0, s42, 0x2000
	v_lshl_add_u64 v[144:145], v[220:221], 0, s[10:11]
	global_load_lds_dwordx4 v134, s[40:41]
	s_mov_b32 m0, s52
	s_nop 0
	global_load_lds_dwordx4 v[144:145], off
	s_mov_b32 m0, s53
	v_lshl_add_u64 v[144:145], v[222:223], 0, s[10:11]
	global_load_lds_dwordx4 v[144:145], off
	s_waitcnt vmcnt(8)
	s_waitcnt lgkmcnt(0)
	s_barrier
	v_mfma_f32_16x16x32_bf16 v[60:63], v[152:155], v[184:187], v[60:63]
	v_mfma_f32_16x16x32_bf16 v[56:59], v[160:163], v[184:187], v[56:59]
	v_mfma_f32_16x16x32_bf16 v[44:47], v[152:155], v[196:199], v[44:47]
	v_mfma_f32_16x16x32_bf16 v[40:43], v[160:163], v[196:199], v[40:43]
	v_mfma_f32_16x16x32_bf16 v[28:31], v[152:155], v[204:207], v[28:31]
	v_mfma_f32_16x16x32_bf16 v[24:27], v[160:163], v[204:207], v[24:27]
	v_mfma_f32_16x16x32_bf16 v[12:15], v[152:155], v[212:215], v[12:15]
	v_mfma_f32_16x16x32_bf16 v[8:11], v[160:163], v[212:215], v[8:11]
	v_mfma_f32_16x16x32_bf16 v[60:63], v[156:159], v[192:195], v[60:63]
	v_mfma_f32_16x16x32_bf16 v[56:59], v[164:167], v[192:195], v[56:59]
	v_mfma_f32_16x16x32_bf16 v[44:47], v[156:159], v[200:203], v[44:47]
	v_mfma_f32_16x16x32_bf16 v[40:43], v[164:167], v[200:203], v[40:43]
	v_mfma_f32_16x16x32_bf16 v[28:31], v[156:159], v[208:211], v[28:31]
	v_mfma_f32_16x16x32_bf16 v[24:27], v[164:167], v[208:211], v[24:27]
	v_mfma_f32_16x16x32_bf16 v[12:15], v[156:159], v[216:219], v[12:15]
	v_mfma_f32_16x16x32_bf16 v[8:11], v[164:167], v[216:219], v[8:11]
	v_mfma_f32_16x16x32_bf16 v[52:55], v[168:171], v[184:187], v[52:55]
	v_mfma_f32_16x16x32_bf16 v[48:51], v[176:179], v[184:187], v[48:51]
	v_mfma_f32_16x16x32_bf16 v[36:39], v[168:171], v[196:199], v[36:39]
	v_mfma_f32_16x16x32_bf16 v[32:35], v[176:179], v[196:199], v[32:35]
	v_mfma_f32_16x16x32_bf16 v[20:23], v[168:171], v[204:207], v[20:23]
	v_mfma_f32_16x16x32_bf16 v[16:19], v[176:179], v[204:207], v[16:19]
	v_mfma_f32_16x16x32_bf16 v[4:7], v[168:171], v[212:215], v[4:7]
	v_mfma_f32_16x16x32_bf16 v[0:3], v[176:179], v[212:215], v[0:3]
	v_mfma_f32_16x16x32_bf16 v[52:55], v[172:175], v[192:195], v[52:55]
	v_mfma_f32_16x16x32_bf16 v[48:51], v[180:183], v[192:195], v[48:51]
	v_mfma_f32_16x16x32_bf16 v[36:39], v[172:175], v[200:203], v[36:39]
	v_mfma_f32_16x16x32_bf16 v[32:35], v[180:183], v[200:203], v[32:35]
	v_mfma_f32_16x16x32_bf16 v[20:23], v[172:175], v[208:211], v[20:23]
	v_mfma_f32_16x16x32_bf16 v[16:19], v[180:183], v[208:211], v[16:19]
	v_mfma_f32_16x16x32_bf16 v[4:7], v[172:175], v[216:219], v[4:7]
	v_mfma_f32_16x16x32_bf16 v[0:3], v[180:183], v[216:219], v[0:3]
	s_barrier
	s_add_i32 s77, s77, 2
	s_add_u32 s34, s34, 0x100
	s_addc_u32 s35, s35, 0
	s_add_u32 s75, s75, 0x100
	s_addc_u32 s76, s76, 0
	s_cmp_gt_u32 s77, 13
	s_cbranch_scc0 .LBB0_837
	s_branch .Lpeel_exit3
.LBB0_837:
	ds_read_b128 v[152:155], v149
	ds_read_b128 v[156:159], v149 offset:1024
	ds_read_b128 v[160:163], v149 offset:2048
	ds_read_b128 v[164:167], v149 offset:3072
	ds_read_b128 v[168:171], v150
	ds_read_b128 v[172:175], v150 offset:1024
	ds_read_b128 v[176:179], v150 offset:2048
	ds_read_b128 v[180:183], v150 offset:3072
	s_add_u32 s40, s34, 0xfffc0080
	s_addc_u32 s41, s35, -1
	s_cmp_eq_u32 s77, 12
	s_cselect_b32 s43, s25, s41
	s_cselect_b32 s42, s54, s40
	s_cselect_b32 s41, s23, s76
	s_cselect_b32 s40, s55, s75
	s_add_i32 m0, s31, 0xc000
	ds_read_b128 v[184:187], v151
	ds_read_b128 v[192:195], v151 offset:1024
	ds_read_b128 v[196:199], v151 offset:2048
	ds_read_b128 v[200:203], v151 offset:3072
	ds_read_b128 v[204:207], v151 offset:4096
	ds_read_b128 v[208:211], v151 offset:5120
	ds_read_b128 v[212:215], v151 offset:6144
	ds_read_b128 v[216:219], v151 offset:7168
	global_load_lds_dwordx4 v136, s[34:35]
	s_add_i32 m0, s31, 0xe000
	s_nop 0
	global_load_lds_dwordx4 v138, s[34:35]
	s_waitcnt vmcnt(8)
	s_waitcnt lgkmcnt(0)
	s_barrier
	v_mfma_f32_16x16x32_bf16 v[124:127], v[152:155], v[184:187], v[124:127]
	v_mfma_f32_16x16x32_bf16 v[120:123], v[160:163], v[184:187], v[120:123]
	v_mfma_f32_16x16x32_bf16 v[108:111], v[152:155], v[196:199], v[108:111]
	v_mfma_f32_16x16x32_bf16 v[104:107], v[160:163], v[196:199], v[104:107]
	v_mfma_f32_16x16x32_bf16 v[92:95], v[152:155], v[204:207], v[92:95]
	v_mfma_f32_16x16x32_bf16 v[88:91], v[160:163], v[204:207], v[88:91]
	v_mfma_f32_16x16x32_bf16 v[76:79], v[152:155], v[212:215], v[76:79]
	v_mfma_f32_16x16x32_bf16 v[72:75], v[160:163], v[212:215], v[72:75]
	v_mfma_f32_16x16x32_bf16 v[124:127], v[156:159], v[192:195], v[124:127]
	v_mfma_f32_16x16x32_bf16 v[120:123], v[164:167], v[192:195], v[120:123]
	v_mfma_f32_16x16x32_bf16 v[108:111], v[156:159], v[200:203], v[108:111]
	v_mfma_f32_16x16x32_bf16 v[104:107], v[164:167], v[200:203], v[104:107]
	v_mfma_f32_16x16x32_bf16 v[92:95], v[156:159], v[208:211], v[92:95]
	v_mfma_f32_16x16x32_bf16 v[88:91], v[164:167], v[208:211], v[88:91]
	v_mfma_f32_16x16x32_bf16 v[76:79], v[156:159], v[216:219], v[76:79]
	v_mfma_f32_16x16x32_bf16 v[72:75], v[164:167], v[216:219], v[72:75]
	v_mfma_f32_16x16x32_bf16 v[116:119], v[168:171], v[184:187], v[116:119]
	v_mfma_f32_16x16x32_bf16 v[112:115], v[176:179], v[184:187], v[112:115]
	v_mfma_f32_16x16x32_bf16 v[100:103], v[168:171], v[196:199], v[100:103]
	v_mfma_f32_16x16x32_bf16 v[96:99], v[176:179], v[196:199], v[96:99]
	v_mfma_f32_16x16x32_bf16 v[84:87], v[168:171], v[204:207], v[84:87]
	v_mfma_f32_16x16x32_bf16 v[80:83], v[176:179], v[204:207], v[80:83]
	v_mfma_f32_16x16x32_bf16 v[68:71], v[168:171], v[212:215], v[68:71]
	v_mfma_f32_16x16x32_bf16 v[64:67], v[176:179], v[212:215], v[64:67]
	v_mfma_f32_16x16x32_bf16 v[116:119], v[172:175], v[192:195], v[116:119]
	v_mfma_f32_16x16x32_bf16 v[112:115], v[180:183], v[192:195], v[112:115]
	v_mfma_f32_16x16x32_bf16 v[100:103], v[172:175], v[200:203], v[100:103]
	v_mfma_f32_16x16x32_bf16 v[96:99], v[180:183], v[200:203], v[96:99]
	v_mfma_f32_16x16x32_bf16 v[84:87], v[172:175], v[208:211], v[84:87]
	v_mfma_f32_16x16x32_bf16 v[80:83], v[180:183], v[208:211], v[80:83]
	v_mfma_f32_16x16x32_bf16 v[68:71], v[172:175], v[216:219], v[68:71]
	v_mfma_f32_16x16x32_bf16 v[64:67], v[180:183], v[216:219], v[64:67]
	s_barrier
	s_add_i32 s79, s69, s63
	v_lshl_add_u64 v[144:145], s[40:41], 0, v[130:131]
	s_mov_b32 m0, s79
	ds_read_b128 v[184:187], v151 offset:16384
	ds_read_b128 v[192:195], v151 offset:17408
	ds_read_b128 v[196:199], v151 offset:18432
	ds_read_b128 v[200:203], v151 offset:19456
	ds_read_b128 v[204:207], v151 offset:20480
	ds_read_b128 v[208:211], v151 offset:21504
	ds_read_b128 v[212:215], v151 offset:22528
	ds_read_b128 v[216:219], v151 offset:23552
	global_load_lds_dwordx4 v[144:145], off
	s_add_i32 m0, s79, 0x2000
	s_add_u32 s80, s40, 0x40000
	v_lshl_add_u64 v[188:189], s[40:41], 0, v[134:135]
	s_addc_u32 s81, s41, 0
	s_add_i32 s79, s70, s63
	global_load_lds_dwordx4 v[188:189], off
	s_mov_b32 m0, s79
	v_lshl_add_u64 v[222:223], s[42:43], 0, v[132:133]
	global_load_lds_dwordx4 v130, s[80:81]
	s_add_i32 m0, s79, 0x2000
	v_lshl_add_u64 v[220:221], s[42:43], 0, v[128:129]
	global_load_lds_dwordx4 v134, s[80:81]
	s_mov_b32 m0, s31
	s_nop 0
	global_load_lds_dwordx4 v[220:221], off
	s_mov_b32 m0, s64
	s_nop 0
	global_load_lds_dwordx4 v[222:223], off
	s_waitcnt vmcnt(8)
	s_waitcnt lgkmcnt(0)
	s_barrier
	v_mfma_f32_16x16x32_bf16 v[60:63], v[152:155], v[184:187], v[60:63]
	v_mfma_f32_16x16x32_bf16 v[56:59], v[160:163], v[184:187], v[56:59]
	v_mfma_f32_16x16x32_bf16 v[44:47], v[152:155], v[196:199], v[44:47]
	v_mfma_f32_16x16x32_bf16 v[40:43], v[160:163], v[196:199], v[40:43]
	v_mfma_f32_16x16x32_bf16 v[28:31], v[152:155], v[204:207], v[28:31]
	v_mfma_f32_16x16x32_bf16 v[24:27], v[160:163], v[204:207], v[24:27]
	v_mfma_f32_16x16x32_bf16 v[12:15], v[152:155], v[212:215], v[12:15]
	v_mfma_f32_16x16x32_bf16 v[8:11], v[160:163], v[212:215], v[8:11]
	v_mfma_f32_16x16x32_bf16 v[60:63], v[156:159], v[192:195], v[60:63]
	v_mfma_f32_16x16x32_bf16 v[56:59], v[164:167], v[192:195], v[56:59]
	v_mfma_f32_16x16x32_bf16 v[44:47], v[156:159], v[200:203], v[44:47]
	v_mfma_f32_16x16x32_bf16 v[40:43], v[164:167], v[200:203], v[40:43]
	v_mfma_f32_16x16x32_bf16 v[28:31], v[156:159], v[208:211], v[28:31]
	v_mfma_f32_16x16x32_bf16 v[24:27], v[164:167], v[208:211], v[24:27]
	v_mfma_f32_16x16x32_bf16 v[12:15], v[156:159], v[216:219], v[12:15]
	v_mfma_f32_16x16x32_bf16 v[8:11], v[164:167], v[216:219], v[8:11]
	v_mfma_f32_16x16x32_bf16 v[52:55], v[168:171], v[184:187], v[52:55]
	v_mfma_f32_16x16x32_bf16 v[48:51], v[176:179], v[184:187], v[48:51]
	v_mfma_f32_16x16x32_bf16 v[36:39], v[168:171], v[196:199], v[36:39]
	v_mfma_f32_16x16x32_bf16 v[32:35], v[176:179], v[196:199], v[32:35]
	v_mfma_f32_16x16x32_bf16 v[20:23], v[168:171], v[204:207], v[20:23]
	v_mfma_f32_16x16x32_bf16 v[16:19], v[176:179], v[204:207], v[16:19]
	v_mfma_f32_16x16x32_bf16 v[4:7], v[168:171], v[212:215], v[4:7]
	v_mfma_f32_16x16x32_bf16 v[0:3], v[176:179], v[212:215], v[0:3]
	v_mfma_f32_16x16x32_bf16 v[52:55], v[172:175], v[192:195], v[52:55]
	v_mfma_f32_16x16x32_bf16 v[48:51], v[180:183], v[192:195], v[48:51]
	v_mfma_f32_16x16x32_bf16 v[36:39], v[172:175], v[200:203], v[36:39]
	v_mfma_f32_16x16x32_bf16 v[32:35], v[180:183], v[200:203], v[32:35]
	v_mfma_f32_16x16x32_bf16 v[20:23], v[172:175], v[208:211], v[20:23]
	v_mfma_f32_16x16x32_bf16 v[16:19], v[180:183], v[208:211], v[16:19]
	v_mfma_f32_16x16x32_bf16 v[4:7], v[172:175], v[216:219], v[4:7]
	v_mfma_f32_16x16x32_bf16 v[0:3], v[180:183], v[216:219], v[0:3]
	s_barrier
	s_add_i32 s79, 0, 0x18000
	s_add_i32 s80, 0, 0x1c000
	v_add_u32_e32 v164, s79, v147
	v_add_u32_e32 v180, s80, v147
	ds_read_b128 v[152:155], v164
	ds_read_b128 v[156:159], v164 offset:1024
	ds_read_b128 v[160:163], v164 offset:2048
	ds_read_b128 v[164:167], v164 offset:3072
	ds_read_b128 v[168:171], v180
	ds_read_b128 v[172:175], v180 offset:1024
	ds_read_b128 v[176:179], v180 offset:2048
	ds_read_b128 v[180:183], v180 offset:3072
	s_add_u32 s42, s42, 0x40000
	s_addc_u32 s43, s43, 0
	s_mov_b32 m0, s65
	ds_read_b128 v[184:187], v151 offset:32768
	ds_read_b128 v[192:195], v151 offset:33792
	ds_read_b128 v[196:199], v151 offset:34816
	ds_read_b128 v[200:203], v151 offset:35840
	ds_read_b128 v[204:207], v151 offset:36864
	ds_read_b128 v[208:211], v151 offset:37888
	ds_read_b128 v[212:215], v151 offset:38912
	ds_read_b128 v[216:219], v151 offset:39936
	global_load_lds_dwordx4 v128, s[42:43]
	s_mov_b32 m0, s66
	s_nop 0
	global_load_lds_dwordx4 v132, s[42:43]
	s_waitcnt vmcnt(8)
	s_waitcnt lgkmcnt(0)
	s_barrier
	v_mfma_f32_16x16x32_bf16 v[124:127], v[152:155], v[184:187], v[124:127]
	v_mfma_f32_16x16x32_bf16 v[120:123], v[160:163], v[184:187], v[120:123]
	v_mfma_f32_16x16x32_bf16 v[108:111], v[152:155], v[196:199], v[108:111]
	v_mfma_f32_16x16x32_bf16 v[104:107], v[160:163], v[196:199], v[104:107]
	v_mfma_f32_16x16x32_bf16 v[92:95], v[152:155], v[204:207], v[92:95]
	v_mfma_f32_16x16x32_bf16 v[88:91], v[160:163], v[204:207], v[88:91]
	v_mfma_f32_16x16x32_bf16 v[76:79], v[152:155], v[212:215], v[76:79]
	v_mfma_f32_16x16x32_bf16 v[72:75], v[160:163], v[212:215], v[72:75]
	v_mfma_f32_16x16x32_bf16 v[124:127], v[156:159], v[192:195], v[124:127]
	v_mfma_f32_16x16x32_bf16 v[120:123], v[164:167], v[192:195], v[120:123]
	v_mfma_f32_16x16x32_bf16 v[108:111], v[156:159], v[200:203], v[108:111]
	v_mfma_f32_16x16x32_bf16 v[104:107], v[164:167], v[200:203], v[104:107]
	v_mfma_f32_16x16x32_bf16 v[92:95], v[156:159], v[208:211], v[92:95]
	v_mfma_f32_16x16x32_bf16 v[88:91], v[164:167], v[208:211], v[88:91]
	v_mfma_f32_16x16x32_bf16 v[76:79], v[156:159], v[216:219], v[76:79]
	v_mfma_f32_16x16x32_bf16 v[72:75], v[164:167], v[216:219], v[72:75]
	v_mfma_f32_16x16x32_bf16 v[116:119], v[168:171], v[184:187], v[116:119]
	v_mfma_f32_16x16x32_bf16 v[112:115], v[176:179], v[184:187], v[112:115]
	v_mfma_f32_16x16x32_bf16 v[100:103], v[168:171], v[196:199], v[100:103]
	v_mfma_f32_16x16x32_bf16 v[96:99], v[176:179], v[196:199], v[96:99]
	v_mfma_f32_16x16x32_bf16 v[84:87], v[168:171], v[204:207], v[84:87]
	v_mfma_f32_16x16x32_bf16 v[80:83], v[176:179], v[204:207], v[80:83]
	v_mfma_f32_16x16x32_bf16 v[68:71], v[168:171], v[212:215], v[68:71]
	v_mfma_f32_16x16x32_bf16 v[64:67], v[176:179], v[212:215], v[64:67]
	v_mfma_f32_16x16x32_bf16 v[116:119], v[172:175], v[192:195], v[116:119]
	v_mfma_f32_16x16x32_bf16 v[112:115], v[180:183], v[192:195], v[112:115]
	v_mfma_f32_16x16x32_bf16 v[100:103], v[172:175], v[200:203], v[100:103]
	v_mfma_f32_16x16x32_bf16 v[96:99], v[180:183], v[200:203], v[96:99]
	v_mfma_f32_16x16x32_bf16 v[84:87], v[172:175], v[208:211], v[84:87]
	v_mfma_f32_16x16x32_bf16 v[80:83], v[180:183], v[208:211], v[80:83]
	v_mfma_f32_16x16x32_bf16 v[68:71], v[172:175], v[216:219], v[68:71]
	v_mfma_f32_16x16x32_bf16 v[64:67], v[180:183], v[216:219], v[64:67]
	s_barrier
	s_add_i32 s42, s79, s63
	v_lshl_add_u64 v[144:145], v[144:145], 0, s[10:11]
	s_mov_b32 m0, s42
	ds_read_b128 v[184:187], v151 offset:49152
	ds_read_b128 v[192:195], v151 offset:50176
	ds_read_b128 v[196:199], v151 offset:51200
	ds_read_b128 v[200:203], v151 offset:52224
	ds_read_b128 v[204:207], v151 offset:53248
	ds_read_b128 v[208:211], v151 offset:54272
	ds_read_b128 v[212:215], v151 offset:55296
	ds_read_b128 v[216:219], v151 offset:56320
	global_load_lds_dwordx4 v[144:145], off
	s_add_i32 m0, s42, 0x2000
	s_add_u32 s40, s40, 0x40080
	v_lshl_add_u64 v[144:145], v[188:189], 0, s[10:11]
	s_addc_u32 s41, s41, 0
	s_add_i32 s42, s80, s63
	global_load_lds_dwordx4 v[144:145], off
	s_mov_b32 m0, s42
	s_nop 0
	global_load_lds_dwordx4 v130, s[40:41]
	s_add_i32 m0, s42, 0x2000
	v_lshl_add_u64 v[144:145], v[220:221], 0, s[10:11]
	global_load_lds_dwordx4 v134, s[40:41]
	s_mov_b32 m0, s52
	s_nop 0
	global_load_lds_dwordx4 v[144:145], off
	s_mov_b32 m0, s53
	v_lshl_add_u64 v[144:145], v[222:223], 0, s[10:11]
	global_load_lds_dwordx4 v[144:145], off
	s_waitcnt vmcnt(8)
	s_waitcnt lgkmcnt(0)
	s_barrier
	v_mfma_f32_16x16x32_bf16 v[60:63], v[152:155], v[184:187], v[60:63]
	v_mfma_f32_16x16x32_bf16 v[56:59], v[160:163], v[184:187], v[56:59]
	v_mfma_f32_16x16x32_bf16 v[44:47], v[152:155], v[196:199], v[44:47]
	v_mfma_f32_16x16x32_bf16 v[40:43], v[160:163], v[196:199], v[40:43]
	v_mfma_f32_16x16x32_bf16 v[28:31], v[152:155], v[204:207], v[28:31]
	v_mfma_f32_16x16x32_bf16 v[24:27], v[160:163], v[204:207], v[24:27]
	v_mfma_f32_16x16x32_bf16 v[12:15], v[152:155], v[212:215], v[12:15]
	v_mfma_f32_16x16x32_bf16 v[8:11], v[160:163], v[212:215], v[8:11]
	v_mfma_f32_16x16x32_bf16 v[60:63], v[156:159], v[192:195], v[60:63]
	v_mfma_f32_16x16x32_bf16 v[56:59], v[164:167], v[192:195], v[56:59]
	v_mfma_f32_16x16x32_bf16 v[44:47], v[156:159], v[200:203], v[44:47]
	v_mfma_f32_16x16x32_bf16 v[40:43], v[164:167], v[200:203], v[40:43]
	v_mfma_f32_16x16x32_bf16 v[28:31], v[156:159], v[208:211], v[28:31]
	v_mfma_f32_16x16x32_bf16 v[24:27], v[164:167], v[208:211], v[24:27]
	v_mfma_f32_16x16x32_bf16 v[12:15], v[156:159], v[216:219], v[12:15]
	v_mfma_f32_16x16x32_bf16 v[8:11], v[164:167], v[216:219], v[8:11]
	v_mfma_f32_16x16x32_bf16 v[52:55], v[168:171], v[184:187], v[52:55]
	v_mfma_f32_16x16x32_bf16 v[48:51], v[176:179], v[184:187], v[48:51]
	v_mfma_f32_16x16x32_bf16 v[36:39], v[168:171], v[196:199], v[36:39]
	v_mfma_f32_16x16x32_bf16 v[32:35], v[176:179], v[196:199], v[32:35]
	v_mfma_f32_16x16x32_bf16 v[20:23], v[168:171], v[204:207], v[20:23]
	v_mfma_f32_16x16x32_bf16 v[16:19], v[176:179], v[204:207], v[16:19]
	v_mfma_f32_16x16x32_bf16 v[4:7], v[168:171], v[212:215], v[4:7]
	v_mfma_f32_16x16x32_bf16 v[0:3], v[176:179], v[212:215], v[0:3]
	v_mfma_f32_16x16x32_bf16 v[52:55], v[172:175], v[192:195], v[52:55]
	v_mfma_f32_16x16x32_bf16 v[48:51], v[180:183], v[192:195], v[48:51]
	v_mfma_f32_16x16x32_bf16 v[36:39], v[172:175], v[200:203], v[36:39]
	v_mfma_f32_16x16x32_bf16 v[32:35], v[180:183], v[200:203], v[32:35]
	v_mfma_f32_16x16x32_bf16 v[20:23], v[172:175], v[208:211], v[20:23]
	v_mfma_f32_16x16x32_bf16 v[16:19], v[180:183], v[208:211], v[16:19]
	v_mfma_f32_16x16x32_bf16 v[4:7], v[172:175], v[216:219], v[4:7]
	v_mfma_f32_16x16x32_bf16 v[0:3], v[180:183], v[216:219], v[0:3]
	s_barrier
	s_add_i32 s77, s77, 2
	s_add_u32 s34, s34, 0x100
	s_addc_u32 s35, s35, 0
	s_add_u32 s75, s75, 0x100
	s_addc_u32 s76, s76, 0
	s_cmp_gt_u32 s77, 13
	s_cbranch_scc0 .LBB0_837

.LBB0_915:
	s_ashr_i32 s25, s24, 31
	s_lshl_b64 s[26:27], s[24:25], 21
	s_add_u32 s26, s56, s26
	s_addc_u32 s27, s57, s27
	s_and_b64 s[28:29], s[4:5], exec
	s_cselect_b32 s25, s27, s35
	s_cselect_b32 s55, s26, s34
	s_ashr_i32 s23, s22, 31
	s_lshl_b64 s[28:29], s[22:23], 21
	s_add_u32 s28, s53, s28
	s_addc_u32 s29, s60, s29
	s_and_b64 s[42:43], s[4:5], exec
	s_cselect_b32 s23, s29, s41
	s_cselect_b32 s74, s28, s40
	s_add_u32 s34, s34, 0x100080
	s_addc_u32 s35, s35, 0
	s_add_u32 s75, s40, 0x100
	s_addc_u32 s76, s41, 0
	s_mov_b32 s77, -2
	ds_read_b128 v[152:155], v149
	ds_read_b128 v[156:159], v149 offset:1024
	ds_read_b128 v[160:163], v149 offset:2048
	ds_read_b128 v[164:167], v149 offset:3072
	ds_read_b128 v[168:171], v150
	ds_read_b128 v[172:175], v150 offset:1024
	ds_read_b128 v[176:179], v150 offset:2048
	ds_read_b128 v[180:183], v150 offset:3072
	s_add_u32 s40, s34, 0xfff00080
	s_addc_u32 s41, s35, -1
	s_cmp_eq_u32 s77, 60
	s_cselect_b32 s43, s25, s41
	s_cselect_b32 s42, s55, s40
	s_cselect_b32 s41, s23, s76
	s_cselect_b32 s40, s74, s75
	s_add_i32 m0, s31, 0xc000
	ds_read_b128 v[184:187], v151
	ds_read_b128 v[192:195], v151 offset:1024
	ds_read_b128 v[196:199], v151 offset:2048
	ds_read_b128 v[200:203], v151 offset:3072
	ds_read_b128 v[204:207], v151 offset:4096
	ds_read_b128 v[208:211], v151 offset:5120
	ds_read_b128 v[212:215], v151 offset:6144
	ds_read_b128 v[216:219], v151 offset:7168
	global_load_lds_dwordx4 v136, s[34:35]
	s_add_i32 m0, s31, 0xe000
	s_nop 0
	global_load_lds_dwordx4 v138, s[34:35]
	s_waitcnt vmcnt(8)
	s_waitcnt lgkmcnt(0)
	s_barrier
	v_mfma_f32_16x16x32_bf16 v[124:127], v[152:155], v[184:187], 0
	v_mfma_f32_16x16x32_bf16 v[120:123], v[160:163], v[184:187], 0
	v_mfma_f32_16x16x32_bf16 v[116:119], v[152:155], v[196:199], 0
	v_mfma_f32_16x16x32_bf16 v[108:111], v[160:163], v[196:199], 0
	v_mfma_f32_16x16x32_bf16 v[100:103], v[152:155], v[204:207], 0
	v_mfma_f32_16x16x32_bf16 v[92:95], v[160:163], v[204:207], 0
	v_mfma_f32_16x16x32_bf16 v[84:87], v[152:155], v[212:215], 0
	v_mfma_f32_16x16x32_bf16 v[76:79], v[160:163], v[212:215], 0
	v_mfma_f32_16x16x32_bf16 v[124:127], v[156:159], v[192:195], v[124:127]
	v_mfma_f32_16x16x32_bf16 v[120:123], v[164:167], v[192:195], v[120:123]
	v_mfma_f32_16x16x32_bf16 v[116:119], v[156:159], v[200:203], v[116:119]
	v_mfma_f32_16x16x32_bf16 v[108:111], v[164:167], v[200:203], v[108:111]
	v_mfma_f32_16x16x32_bf16 v[100:103], v[156:159], v[208:211], v[100:103]
	v_mfma_f32_16x16x32_bf16 v[92:95], v[164:167], v[208:211], v[92:95]
	v_mfma_f32_16x16x32_bf16 v[84:87], v[156:159], v[216:219], v[84:87]
	v_mfma_f32_16x16x32_bf16 v[76:79], v[164:167], v[216:219], v[76:79]
	v_mfma_f32_16x16x32_bf16 v[112:115], v[168:171], v[184:187], 0
	v_mfma_f32_16x16x32_bf16 v[104:107], v[176:179], v[184:187], 0
	v_mfma_f32_16x16x32_bf16 v[96:99], v[168:171], v[196:199], 0
	v_mfma_f32_16x16x32_bf16 v[88:91], v[176:179], v[196:199], 0
	v_mfma_f32_16x16x32_bf16 v[80:83], v[168:171], v[204:207], 0
	v_mfma_f32_16x16x32_bf16 v[72:75], v[176:179], v[204:207], 0
	v_mfma_f32_16x16x32_bf16 v[68:71], v[168:171], v[212:215], 0
	v_mfma_f32_16x16x32_bf16 v[64:67], v[176:179], v[212:215], 0
	v_mfma_f32_16x16x32_bf16 v[112:115], v[172:175], v[192:195], v[112:115]
	v_mfma_f32_16x16x32_bf16 v[104:107], v[180:183], v[192:195], v[104:107]
	v_mfma_f32_16x16x32_bf16 v[96:99], v[172:175], v[200:203], v[96:99]
	v_mfma_f32_16x16x32_bf16 v[88:91], v[180:183], v[200:203], v[88:91]
	v_mfma_f32_16x16x32_bf16 v[80:83], v[172:175], v[208:211], v[80:83]
	v_mfma_f32_16x16x32_bf16 v[72:75], v[180:183], v[208:211], v[72:75]
	v_mfma_f32_16x16x32_bf16 v[68:71], v[172:175], v[216:219], v[68:71]
	v_mfma_f32_16x16x32_bf16 v[64:67], v[180:183], v[216:219], v[64:67]
	s_barrier
	s_add_i32 s79, s68, s61
	v_lshl_add_u64 v[144:145], s[40:41], 0, v[130:131]
	s_mov_b32 m0, s79
	ds_read_b128 v[184:187], v151 offset:16384
	ds_read_b128 v[192:195], v151 offset:17408
	ds_read_b128 v[196:199], v151 offset:18432
	ds_read_b128 v[200:203], v151 offset:19456
	ds_read_b128 v[204:207], v151 offset:20480
	ds_read_b128 v[208:211], v151 offset:21504
	ds_read_b128 v[212:215], v151 offset:22528
	ds_read_b128 v[216:219], v151 offset:23552
	global_load_lds_dwordx4 v[144:145], off
	s_add_i32 m0, s79, 0x2000
	s_add_u32 s80, s40, 0x100000
	v_lshl_add_u64 v[188:189], s[40:41], 0, v[134:135]
	s_addc_u32 s81, s41, 0
	s_add_i32 s79, s69, s61
	global_load_lds_dwordx4 v[188:189], off
	s_mov_b32 m0, s79
	v_lshl_add_u64 v[222:223], s[42:43], 0, v[132:133]
	global_load_lds_dwordx4 v130, s[80:81]
	s_add_i32 m0, s79, 0x2000
	v_lshl_add_u64 v[220:221], s[42:43], 0, v[128:129]
	global_load_lds_dwordx4 v134, s[80:81]
	s_mov_b32 m0, s31
	s_nop 0
	global_load_lds_dwordx4 v[220:221], off
	s_mov_b32 m0, s33
	s_nop 0
	global_load_lds_dwordx4 v[222:223], off
	s_waitcnt vmcnt(8)
	s_waitcnt lgkmcnt(0)
	s_barrier
	v_mfma_f32_16x16x32_bf16 v[60:63], v[152:155], v[184:187], 0
	v_mfma_f32_16x16x32_bf16 v[56:59], v[160:163], v[184:187], 0
	v_mfma_f32_16x16x32_bf16 v[52:55], v[152:155], v[196:199], 0
	v_mfma_f32_16x16x32_bf16 v[44:47], v[160:163], v[196:199], 0
	v_mfma_f32_16x16x32_bf16 v[36:39], v[152:155], v[204:207], 0
	v_mfma_f32_16x16x32_bf16 v[28:31], v[160:163], v[204:207], 0
	v_mfma_f32_16x16x32_bf16 v[20:23], v[152:155], v[212:215], 0
	v_mfma_f32_16x16x32_bf16 v[12:15], v[160:163], v[212:215], 0
	v_mfma_f32_16x16x32_bf16 v[60:63], v[156:159], v[192:195], v[60:63]
	v_mfma_f32_16x16x32_bf16 v[56:59], v[164:167], v[192:195], v[56:59]
	v_mfma_f32_16x16x32_bf16 v[52:55], v[156:159], v[200:203], v[52:55]
	v_mfma_f32_16x16x32_bf16 v[44:47], v[164:167], v[200:203], v[44:47]
	v_mfma_f32_16x16x32_bf16 v[36:39], v[156:159], v[208:211], v[36:39]
	v_mfma_f32_16x16x32_bf16 v[28:31], v[164:167], v[208:211], v[28:31]
	v_mfma_f32_16x16x32_bf16 v[20:23], v[156:159], v[216:219], v[20:23]
	v_mfma_f32_16x16x32_bf16 v[12:15], v[164:167], v[216:219], v[12:15]
	v_mfma_f32_16x16x32_bf16 v[48:51], v[168:171], v[184:187], 0
	v_mfma_f32_16x16x32_bf16 v[40:43], v[176:179], v[184:187], 0
	v_mfma_f32_16x16x32_bf16 v[32:35], v[168:171], v[196:199], 0
	v_mfma_f32_16x16x32_bf16 v[24:27], v[176:179], v[196:199], 0
	v_mfma_f32_16x16x32_bf16 v[16:19], v[168:171], v[204:207], 0
	v_mfma_f32_16x16x32_bf16 v[8:11], v[176:179], v[204:207], 0
	v_mfma_f32_16x16x32_bf16 v[4:7], v[168:171], v[212:215], 0
	v_mfma_f32_16x16x32_bf16 v[0:3], v[176:179], v[212:215], 0
	v_mfma_f32_16x16x32_bf16 v[48:51], v[172:175], v[192:195], v[48:51]
	v_mfma_f32_16x16x32_bf16 v[40:43], v[180:183], v[192:195], v[40:43]
	v_mfma_f32_16x16x32_bf16 v[32:35], v[172:175], v[200:203], v[32:35]
	v_mfma_f32_16x16x32_bf16 v[24:27], v[180:183], v[200:203], v[24:27]
	v_mfma_f32_16x16x32_bf16 v[16:19], v[172:175], v[208:211], v[16:19]
	v_mfma_f32_16x16x32_bf16 v[8:11], v[180:183], v[208:211], v[8:11]
	v_mfma_f32_16x16x32_bf16 v[4:7], v[172:175], v[216:219], v[4:7]
	v_mfma_f32_16x16x32_bf16 v[0:3], v[180:183], v[216:219], v[0:3]
	s_barrier
	s_add_i32 s79, 0, 0x18000
	s_add_i32 s80, 0, 0x1c000
	v_add_u32_e32 v164, s79, v147
	v_add_u32_e32 v180, s80, v147
	ds_read_b128 v[152:155], v164
	ds_read_b128 v[156:159], v164 offset:1024
	ds_read_b128 v[160:163], v164 offset:2048
	ds_read_b128 v[164:167], v164 offset:3072
	ds_read_b128 v[168:171], v180
	ds_read_b128 v[172:175], v180 offset:1024
	ds_read_b128 v[176:179], v180 offset:2048
	ds_read_b128 v[180:183], v180 offset:3072
	s_add_u32 s42, s42, 0x100000
	s_addc_u32 s43, s43, 0
	s_mov_b32 m0, s62
	ds_read_b128 v[184:187], v151 offset:32768
	ds_read_b128 v[192:195], v151 offset:33792
	ds_read_b128 v[196:199], v151 offset:34816
	ds_read_b128 v[200:203], v151 offset:35840
	ds_read_b128 v[204:207], v151 offset:36864
	ds_read_b128 v[208:211], v151 offset:37888
	ds_read_b128 v[212:215], v151 offset:38912
	ds_read_b128 v[216:219], v151 offset:39936
	global_load_lds_dwordx4 v128, s[42:43]
	s_mov_b32 m0, s63
	s_nop 0
	global_load_lds_dwordx4 v132, s[42:43]
	s_waitcnt vmcnt(8)
	s_waitcnt lgkmcnt(0)
	s_barrier
	v_mfma_f32_16x16x32_bf16 v[124:127], v[152:155], v[184:187], v[124:127]
	v_mfma_f32_16x16x32_bf16 v[120:123], v[160:163], v[184:187], v[120:123]
	v_mfma_f32_16x16x32_bf16 v[116:119], v[152:155], v[196:199], v[116:119]
	v_mfma_f32_16x16x32_bf16 v[108:111], v[160:163], v[196:199], v[108:111]
	v_mfma_f32_16x16x32_bf16 v[100:103], v[152:155], v[204:207], v[100:103]
	v_mfma_f32_16x16x32_bf16 v[92:95], v[160:163], v[204:207], v[92:95]
	v_mfma_f32_16x16x32_bf16 v[84:87], v[152:155], v[212:215], v[84:87]
	v_mfma_f32_16x16x32_bf16 v[76:79], v[160:163], v[212:215], v[76:79]
	v_mfma_f32_16x16x32_bf16 v[124:127], v[156:159], v[192:195], v[124:127]
	v_mfma_f32_16x16x32_bf16 v[120:123], v[164:167], v[192:195], v[120:123]
	v_mfma_f32_16x16x32_bf16 v[116:119], v[156:159], v[200:203], v[116:119]
	v_mfma_f32_16x16x32_bf16 v[108:111], v[164:167], v[200:203], v[108:111]
	v_mfma_f32_16x16x32_bf16 v[100:103], v[156:159], v[208:211], v[100:103]
	v_mfma_f32_16x16x32_bf16 v[92:95], v[164:167], v[208:211], v[92:95]
	v_mfma_f32_16x16x32_bf16 v[84:87], v[156:159], v[216:219], v[84:87]
	v_mfma_f32_16x16x32_bf16 v[76:79], v[164:167], v[216:219], v[76:79]
	v_mfma_f32_16x16x32_bf16 v[112:115], v[168:171], v[184:187], v[112:115]
	v_mfma_f32_16x16x32_bf16 v[104:107], v[176:179], v[184:187], v[104:107]
	v_mfma_f32_16x16x32_bf16 v[96:99], v[168:171], v[196:199], v[96:99]
	v_mfma_f32_16x16x32_bf16 v[88:91], v[176:179], v[196:199], v[88:91]
	v_mfma_f32_16x16x32_bf16 v[80:83], v[168:171], v[204:207], v[80:83]
	v_mfma_f32_16x16x32_bf16 v[72:75], v[176:179], v[204:207], v[72:75]
	v_mfma_f32_16x16x32_bf16 v[68:71], v[168:171], v[212:215], v[68:71]
	v_mfma_f32_16x16x32_bf16 v[64:67], v[176:179], v[212:215], v[64:67]
	v_mfma_f32_16x16x32_bf16 v[112:115], v[172:175], v[192:195], v[112:115]
	v_mfma_f32_16x16x32_bf16 v[104:107], v[180:183], v[192:195], v[104:107]
	v_mfma_f32_16x16x32_bf16 v[96:99], v[172:175], v[200:203], v[96:99]
	v_mfma_f32_16x16x32_bf16 v[88:91], v[180:183], v[200:203], v[88:91]
	v_mfma_f32_16x16x32_bf16 v[80:83], v[172:175], v[208:211], v[80:83]
	v_mfma_f32_16x16x32_bf16 v[72:75], v[180:183], v[208:211], v[72:75]
	v_mfma_f32_16x16x32_bf16 v[68:71], v[172:175], v[216:219], v[68:71]
	v_mfma_f32_16x16x32_bf16 v[64:67], v[180:183], v[216:219], v[64:67]
	s_barrier
	s_add_i32 s42, s79, s61
	v_lshl_add_u64 v[144:145], v[144:145], 0, s[10:11]
	s_mov_b32 m0, s42
	ds_read_b128 v[184:187], v151 offset:49152
	ds_read_b128 v[192:195], v151 offset:50176
	ds_read_b128 v[196:199], v151 offset:51200
	ds_read_b128 v[200:203], v151 offset:52224
	ds_read_b128 v[204:207], v151 offset:53248
	ds_read_b128 v[208:211], v151 offset:54272
	ds_read_b128 v[212:215], v151 offset:55296
	ds_read_b128 v[216:219], v151 offset:56320
	global_load_lds_dwordx4 v[144:145], off
	s_add_i32 m0, s42, 0x2000
	s_add_u32 s40, s40, 0x100080
	v_lshl_add_u64 v[144:145], v[188:189], 0, s[10:11]
	s_addc_u32 s41, s41, 0
	s_add_i32 s42, s80, s61
	global_load_lds_dwordx4 v[144:145], off
	s_mov_b32 m0, s42
	s_nop 0
	global_load_lds_dwordx4 v130, s[40:41]
	s_add_i32 m0, s42, 0x2000
	v_lshl_add_u64 v[144:145], v[220:221], 0, s[10:11]
	global_load_lds_dwordx4 v134, s[40:41]
	s_mov_b32 m0, s65
	s_nop 0
	global_load_lds_dwordx4 v[144:145], off
	s_mov_b32 m0, s66
	v_lshl_add_u64 v[144:145], v[222:223], 0, s[10:11]
	global_load_lds_dwordx4 v[144:145], off
	s_waitcnt vmcnt(8)
	s_waitcnt lgkmcnt(0)
	s_barrier
	v_mfma_f32_16x16x32_bf16 v[60:63], v[152:155], v[184:187], v[60:63]
	v_mfma_f32_16x16x32_bf16 v[56:59], v[160:163], v[184:187], v[56:59]
	v_mfma_f32_16x16x32_bf16 v[52:55], v[152:155], v[196:199], v[52:55]
	v_mfma_f32_16x16x32_bf16 v[44:47], v[160:163], v[196:199], v[44:47]
	v_mfma_f32_16x16x32_bf16 v[36:39], v[152:155], v[204:207], v[36:39]
	v_mfma_f32_16x16x32_bf16 v[28:31], v[160:163], v[204:207], v[28:31]
	v_mfma_f32_16x16x32_bf16 v[20:23], v[152:155], v[212:215], v[20:23]
	v_mfma_f32_16x16x32_bf16 v[12:15], v[160:163], v[212:215], v[12:15]
	v_mfma_f32_16x16x32_bf16 v[60:63], v[156:159], v[192:195], v[60:63]
	v_mfma_f32_16x16x32_bf16 v[56:59], v[164:167], v[192:195], v[56:59]
	v_mfma_f32_16x16x32_bf16 v[52:55], v[156:159], v[200:203], v[52:55]
	v_mfma_f32_16x16x32_bf16 v[44:47], v[164:167], v[200:203], v[44:47]
	v_mfma_f32_16x16x32_bf16 v[36:39], v[156:159], v[208:211], v[36:39]
	v_mfma_f32_16x16x32_bf16 v[28:31], v[164:167], v[208:211], v[28:31]
	v_mfma_f32_16x16x32_bf16 v[20:23], v[156:159], v[216:219], v[20:23]
	v_mfma_f32_16x16x32_bf16 v[12:15], v[164:167], v[216:219], v[12:15]
	v_mfma_f32_16x16x32_bf16 v[48:51], v[168:171], v[184:187], v[48:51]
	v_mfma_f32_16x16x32_bf16 v[40:43], v[176:179], v[184:187], v[40:43]
	v_mfma_f32_16x16x32_bf16 v[32:35], v[168:171], v[196:199], v[32:35]
	v_mfma_f32_16x16x32_bf16 v[24:27], v[176:179], v[196:199], v[24:27]
	v_mfma_f32_16x16x32_bf16 v[16:19], v[168:171], v[204:207], v[16:19]
	v_mfma_f32_16x16x32_bf16 v[8:11], v[176:179], v[204:207], v[8:11]
	v_mfma_f32_16x16x32_bf16 v[4:7], v[168:171], v[212:215], v[4:7]
	v_mfma_f32_16x16x32_bf16 v[0:3], v[176:179], v[212:215], v[0:3]
	v_mfma_f32_16x16x32_bf16 v[48:51], v[172:175], v[192:195], v[48:51]
	v_mfma_f32_16x16x32_bf16 v[40:43], v[180:183], v[192:195], v[40:43]
	v_mfma_f32_16x16x32_bf16 v[32:35], v[172:175], v[200:203], v[32:35]
	v_mfma_f32_16x16x32_bf16 v[24:27], v[180:183], v[200:203], v[24:27]
	v_mfma_f32_16x16x32_bf16 v[16:19], v[172:175], v[208:211], v[16:19]
	v_mfma_f32_16x16x32_bf16 v[8:11], v[180:183], v[208:211], v[8:11]
	v_mfma_f32_16x16x32_bf16 v[4:7], v[172:175], v[216:219], v[4:7]
	v_mfma_f32_16x16x32_bf16 v[0:3], v[180:183], v[216:219], v[0:3]
	s_barrier
	s_add_i32 s77, s77, 2
	s_add_u32 s34, s34, 0x100
	s_addc_u32 s35, s35, 0
	s_add_u32 s75, s75, 0x100
	s_addc_u32 s76, s76, 0
	s_cmp_gt_u32 s77, 61
	s_cbranch_scc0 .LBB0_916
	s_branch .Lpeel_exit4
.LBB0_916:
	ds_read_b128 v[152:155], v149
	ds_read_b128 v[156:159], v149 offset:1024
	ds_read_b128 v[160:163], v149 offset:2048
	ds_read_b128 v[164:167], v149 offset:3072
	ds_read_b128 v[168:171], v150
	ds_read_b128 v[172:175], v150 offset:1024
	ds_read_b128 v[176:179], v150 offset:2048
	ds_read_b128 v[180:183], v150 offset:3072
	s_add_u32 s40, s34, 0xfff00080
	s_addc_u32 s41, s35, -1
	s_cmp_eq_u32 s77, 60
	s_cselect_b32 s43, s25, s41
	s_cselect_b32 s42, s55, s40
	s_cselect_b32 s41, s23, s76
	s_cselect_b32 s40, s74, s75
	s_add_i32 m0, s31, 0xc000
	ds_read_b128 v[184:187], v151
	ds_read_b128 v[192:195], v151 offset:1024
	ds_read_b128 v[196:199], v151 offset:2048
	ds_read_b128 v[200:203], v151 offset:3072
	ds_read_b128 v[204:207], v151 offset:4096
	ds_read_b128 v[208:211], v151 offset:5120
	ds_read_b128 v[212:215], v151 offset:6144
	ds_read_b128 v[216:219], v151 offset:7168
	global_load_lds_dwordx4 v136, s[34:35]
	s_add_i32 m0, s31, 0xe000
	s_nop 0
	global_load_lds_dwordx4 v138, s[34:35]
	s_waitcnt vmcnt(8)
	s_waitcnt lgkmcnt(0)
	s_barrier
	v_mfma_f32_16x16x32_bf16 v[124:127], v[152:155], v[184:187], v[124:127]
	v_mfma_f32_16x16x32_bf16 v[120:123], v[160:163], v[184:187], v[120:123]
	v_mfma_f32_16x16x32_bf16 v[116:119], v[152:155], v[196:199], v[116:119]
	v_mfma_f32_16x16x32_bf16 v[108:111], v[160:163], v[196:199], v[108:111]
	v_mfma_f32_16x16x32_bf16 v[100:103], v[152:155], v[204:207], v[100:103]
	v_mfma_f32_16x16x32_bf16 v[92:95], v[160:163], v[204:207], v[92:95]
	v_mfma_f32_16x16x32_bf16 v[84:87], v[152:155], v[212:215], v[84:87]
	v_mfma_f32_16x16x32_bf16 v[76:79], v[160:163], v[212:215], v[76:79]
	v_mfma_f32_16x16x32_bf16 v[124:127], v[156:159], v[192:195], v[124:127]
	v_mfma_f32_16x16x32_bf16 v[120:123], v[164:167], v[192:195], v[120:123]
	v_mfma_f32_16x16x32_bf16 v[116:119], v[156:159], v[200:203], v[116:119]
	v_mfma_f32_16x16x32_bf16 v[108:111], v[164:167], v[200:203], v[108:111]
	v_mfma_f32_16x16x32_bf16 v[100:103], v[156:159], v[208:211], v[100:103]
	v_mfma_f32_16x16x32_bf16 v[92:95], v[164:167], v[208:211], v[92:95]
	v_mfma_f32_16x16x32_bf16 v[84:87], v[156:159], v[216:219], v[84:87]
	v_mfma_f32_16x16x32_bf16 v[76:79], v[164:167], v[216:219], v[76:79]
	v_mfma_f32_16x16x32_bf16 v[112:115], v[168:171], v[184:187], v[112:115]
	v_mfma_f32_16x16x32_bf16 v[104:107], v[176:179], v[184:187], v[104:107]
	v_mfma_f32_16x16x32_bf16 v[96:99], v[168:171], v[196:199], v[96:99]
	v_mfma_f32_16x16x32_bf16 v[88:91], v[176:179], v[196:199], v[88:91]
	v_mfma_f32_16x16x32_bf16 v[80:83], v[168:171], v[204:207], v[80:83]
	v_mfma_f32_16x16x32_bf16 v[72:75], v[176:179], v[204:207], v[72:75]
	v_mfma_f32_16x16x32_bf16 v[68:71], v[168:171], v[212:215], v[68:71]
	v_mfma_f32_16x16x32_bf16 v[64:67], v[176:179], v[212:215], v[64:67]
	v_mfma_f32_16x16x32_bf16 v[112:115], v[172:175], v[192:195], v[112:115]
	v_mfma_f32_16x16x32_bf16 v[104:107], v[180:183], v[192:195], v[104:107]
	v_mfma_f32_16x16x32_bf16 v[96:99], v[172:175], v[200:203], v[96:99]
	v_mfma_f32_16x16x32_bf16 v[88:91], v[180:183], v[200:203], v[88:91]
	v_mfma_f32_16x16x32_bf16 v[80:83], v[172:175], v[208:211], v[80:83]
	v_mfma_f32_16x16x32_bf16 v[72:75], v[180:183], v[208:211], v[72:75]
	v_mfma_f32_16x16x32_bf16 v[68:71], v[172:175], v[216:219], v[68:71]
	v_mfma_f32_16x16x32_bf16 v[64:67], v[180:183], v[216:219], v[64:67]
	s_barrier
	s_add_i32 s79, s68, s61
	v_lshl_add_u64 v[144:145], s[40:41], 0, v[130:131]
	s_mov_b32 m0, s79
	ds_read_b128 v[184:187], v151 offset:16384
	ds_read_b128 v[192:195], v151 offset:17408
	ds_read_b128 v[196:199], v151 offset:18432
	ds_read_b128 v[200:203], v151 offset:19456
	ds_read_b128 v[204:207], v151 offset:20480
	ds_read_b128 v[208:211], v151 offset:21504
	ds_read_b128 v[212:215], v151 offset:22528
	ds_read_b128 v[216:219], v151 offset:23552
	global_load_lds_dwordx4 v[144:145], off
	s_add_i32 m0, s79, 0x2000
	s_add_u32 s80, s40, 0x100000
	v_lshl_add_u64 v[188:189], s[40:41], 0, v[134:135]
	s_addc_u32 s81, s41, 0
	s_add_i32 s79, s69, s61
	global_load_lds_dwordx4 v[188:189], off
	s_mov_b32 m0, s79
	v_lshl_add_u64 v[222:223], s[42:43], 0, v[132:133]
	global_load_lds_dwordx4 v130, s[80:81]
	s_add_i32 m0, s79, 0x2000
	v_lshl_add_u64 v[220:221], s[42:43], 0, v[128:129]
	global_load_lds_dwordx4 v134, s[80:81]
	s_mov_b32 m0, s31
	s_nop 0
	global_load_lds_dwordx4 v[220:221], off
	s_mov_b32 m0, s33
	s_nop 0
	global_load_lds_dwordx4 v[222:223], off
	s_waitcnt vmcnt(8)
	s_waitcnt lgkmcnt(0)
	s_barrier
	v_mfma_f32_16x16x32_bf16 v[60:63], v[152:155], v[184:187], v[60:63]
	v_mfma_f32_16x16x32_bf16 v[56:59], v[160:163], v[184:187], v[56:59]
	v_mfma_f32_16x16x32_bf16 v[52:55], v[152:155], v[196:199], v[52:55]
	v_mfma_f32_16x16x32_bf16 v[44:47], v[160:163], v[196:199], v[44:47]
	v_mfma_f32_16x16x32_bf16 v[36:39], v[152:155], v[204:207], v[36:39]
	v_mfma_f32_16x16x32_bf16 v[28:31], v[160:163], v[204:207], v[28:31]
	v_mfma_f32_16x16x32_bf16 v[20:23], v[152:155], v[212:215], v[20:23]
	v_mfma_f32_16x16x32_bf16 v[12:15], v[160:163], v[212:215], v[12:15]
	v_mfma_f32_16x16x32_bf16 v[60:63], v[156:159], v[192:195], v[60:63]
	v_mfma_f32_16x16x32_bf16 v[56:59], v[164:167], v[192:195], v[56:59]
	v_mfma_f32_16x16x32_bf16 v[52:55], v[156:159], v[200:203], v[52:55]
	v_mfma_f32_16x16x32_bf16 v[44:47], v[164:167], v[200:203], v[44:47]
	v_mfma_f32_16x16x32_bf16 v[36:39], v[156:159], v[208:211], v[36:39]
	v_mfma_f32_16x16x32_bf16 v[28:31], v[164:167], v[208:211], v[28:31]
	v_mfma_f32_16x16x32_bf16 v[20:23], v[156:159], v[216:219], v[20:23]
	v_mfma_f32_16x16x32_bf16 v[12:15], v[164:167], v[216:219], v[12:15]
	v_mfma_f32_16x16x32_bf16 v[48:51], v[168:171], v[184:187], v[48:51]
	v_mfma_f32_16x16x32_bf16 v[40:43], v[176:179], v[184:187], v[40:43]
	v_mfma_f32_16x16x32_bf16 v[32:35], v[168:171], v[196:199], v[32:35]
	v_mfma_f32_16x16x32_bf16 v[24:27], v[176:179], v[196:199], v[24:27]
	v_mfma_f32_16x16x32_bf16 v[16:19], v[168:171], v[204:207], v[16:19]
	v_mfma_f32_16x16x32_bf16 v[8:11], v[176:179], v[204:207], v[8:11]
	v_mfma_f32_16x16x32_bf16 v[4:7], v[168:171], v[212:215], v[4:7]
	v_mfma_f32_16x16x32_bf16 v[0:3], v[176:179], v[212:215], v[0:3]
	v_mfma_f32_16x16x32_bf16 v[48:51], v[172:175], v[192:195], v[48:51]
	v_mfma_f32_16x16x32_bf16 v[40:43], v[180:183], v[192:195], v[40:43]
	v_mfma_f32_16x16x32_bf16 v[32:35], v[172:175], v[200:203], v[32:35]
	v_mfma_f32_16x16x32_bf16 v[24:27], v[180:183], v[200:203], v[24:27]
	v_mfma_f32_16x16x32_bf16 v[16:19], v[172:175], v[208:211], v[16:19]
	v_mfma_f32_16x16x32_bf16 v[8:11], v[180:183], v[208:211], v[8:11]
	v_mfma_f32_16x16x32_bf16 v[4:7], v[172:175], v[216:219], v[4:7]
	v_mfma_f32_16x16x32_bf16 v[0:3], v[180:183], v[216:219], v[0:3]
	s_barrier
	s_add_i32 s79, 0, 0x18000
	s_add_i32 s80, 0, 0x1c000
	v_add_u32_e32 v164, s79, v147
	v_add_u32_e32 v180, s80, v147
	ds_read_b128 v[152:155], v164
	ds_read_b128 v[156:159], v164 offset:1024
	ds_read_b128 v[160:163], v164 offset:2048
	ds_read_b128 v[164:167], v164 offset:3072
	ds_read_b128 v[168:171], v180
	ds_read_b128 v[172:175], v180 offset:1024
	ds_read_b128 v[176:179], v180 offset:2048
	ds_read_b128 v[180:183], v180 offset:3072
	s_add_u32 s42, s42, 0x100000
	s_addc_u32 s43, s43, 0
	s_mov_b32 m0, s62
	ds_read_b128 v[184:187], v151 offset:32768
	ds_read_b128 v[192:195], v151 offset:33792
	ds_read_b128 v[196:199], v151 offset:34816
	ds_read_b128 v[200:203], v151 offset:35840
	ds_read_b128 v[204:207], v151 offset:36864
	ds_read_b128 v[208:211], v151 offset:37888
	ds_read_b128 v[212:215], v151 offset:38912
	ds_read_b128 v[216:219], v151 offset:39936
	global_load_lds_dwordx4 v128, s[42:43]
	s_mov_b32 m0, s63
	s_nop 0
	global_load_lds_dwordx4 v132, s[42:43]
	s_waitcnt vmcnt(8)
	s_waitcnt lgkmcnt(0)
	s_barrier
	v_mfma_f32_16x16x32_bf16 v[124:127], v[152:155], v[184:187], v[124:127]
	v_mfma_f32_16x16x32_bf16 v[120:123], v[160:163], v[184:187], v[120:123]
	v_mfma_f32_16x16x32_bf16 v[116:119], v[152:155], v[196:199], v[116:119]
	v_mfma_f32_16x16x32_bf16 v[108:111], v[160:163], v[196:199], v[108:111]
	v_mfma_f32_16x16x32_bf16 v[100:103], v[152:155], v[204:207], v[100:103]
	v_mfma_f32_16x16x32_bf16 v[92:95], v[160:163], v[204:207], v[92:95]
	v_mfma_f32_16x16x32_bf16 v[84:87], v[152:155], v[212:215], v[84:87]
	v_mfma_f32_16x16x32_bf16 v[76:79], v[160:163], v[212:215], v[76:79]
	v_mfma_f32_16x16x32_bf16 v[124:127], v[156:159], v[192:195], v[124:127]
	v_mfma_f32_16x16x32_bf16 v[120:123], v[164:167], v[192:195], v[120:123]
	v_mfma_f32_16x16x32_bf16 v[116:119], v[156:159], v[200:203], v[116:119]
	v_mfma_f32_16x16x32_bf16 v[108:111], v[164:167], v[200:203], v[108:111]
	v_mfma_f32_16x16x32_bf16 v[100:103], v[156:159], v[208:211], v[100:103]
	v_mfma_f32_16x16x32_bf16 v[92:95], v[164:167], v[208:211], v[92:95]
	v_mfma_f32_16x16x32_bf16 v[84:87], v[156:159], v[216:219], v[84:87]
	v_mfma_f32_16x16x32_bf16 v[76:79], v[164:167], v[216:219], v[76:79]
	v_mfma_f32_16x16x32_bf16 v[112:115], v[168:171], v[184:187], v[112:115]
	v_mfma_f32_16x16x32_bf16 v[104:107], v[176:179], v[184:187], v[104:107]
	v_mfma_f32_16x16x32_bf16 v[96:99], v[168:171], v[196:199], v[96:99]
	v_mfma_f32_16x16x32_bf16 v[88:91], v[176:179], v[196:199], v[88:91]
	v_mfma_f32_16x16x32_bf16 v[80:83], v[168:171], v[204:207], v[80:83]
	v_mfma_f32_16x16x32_bf16 v[72:75], v[176:179], v[204:207], v[72:75]
	v_mfma_f32_16x16x32_bf16 v[68:71], v[168:171], v[212:215], v[68:71]
	v_mfma_f32_16x16x32_bf16 v[64:67], v[176:179], v[212:215], v[64:67]
	v_mfma_f32_16x16x32_bf16 v[112:115], v[172:175], v[192:195], v[112:115]
	v_mfma_f32_16x16x32_bf16 v[104:107], v[180:183], v[192:195], v[104:107]
	v_mfma_f32_16x16x32_bf16 v[96:99], v[172:175], v[200:203], v[96:99]
	v_mfma_f32_16x16x32_bf16 v[88:91], v[180:183], v[200:203], v[88:91]
	v_mfma_f32_16x16x32_bf16 v[80:83], v[172:175], v[208:211], v[80:83]
	v_mfma_f32_16x16x32_bf16 v[72:75], v[180:183], v[208:211], v[72:75]
	v_mfma_f32_16x16x32_bf16 v[68:71], v[172:175], v[216:219], v[68:71]
	v_mfma_f32_16x16x32_bf16 v[64:67], v[180:183], v[216:219], v[64:67]
	s_barrier
	s_add_i32 s42, s79, s61
	v_lshl_add_u64 v[144:145], v[144:145], 0, s[10:11]
	s_mov_b32 m0, s42
	ds_read_b128 v[184:187], v151 offset:49152
	ds_read_b128 v[192:195], v151 offset:50176
	ds_read_b128 v[196:199], v151 offset:51200
	ds_read_b128 v[200:203], v151 offset:52224
	ds_read_b128 v[204:207], v151 offset:53248
	ds_read_b128 v[208:211], v151 offset:54272
	ds_read_b128 v[212:215], v151 offset:55296
	ds_read_b128 v[216:219], v151 offset:56320
	global_load_lds_dwordx4 v[144:145], off
	s_add_i32 m0, s42, 0x2000
	s_add_u32 s40, s40, 0x100080
	v_lshl_add_u64 v[144:145], v[188:189], 0, s[10:11]
	s_addc_u32 s41, s41, 0
	s_add_i32 s42, s80, s61
	global_load_lds_dwordx4 v[144:145], off
	s_mov_b32 m0, s42
	s_nop 0
	global_load_lds_dwordx4 v130, s[40:41]
	s_add_i32 m0, s42, 0x2000
	v_lshl_add_u64 v[144:145], v[220:221], 0, s[10:11]
	global_load_lds_dwordx4 v134, s[40:41]
	s_mov_b32 m0, s65
	s_nop 0
	global_load_lds_dwordx4 v[144:145], off
	s_mov_b32 m0, s66
	v_lshl_add_u64 v[144:145], v[222:223], 0, s[10:11]
	global_load_lds_dwordx4 v[144:145], off
	s_waitcnt vmcnt(8)
	s_waitcnt lgkmcnt(0)
	s_barrier
	v_mfma_f32_16x16x32_bf16 v[60:63], v[152:155], v[184:187], v[60:63]
	v_mfma_f32_16x16x32_bf16 v[56:59], v[160:163], v[184:187], v[56:59]
	v_mfma_f32_16x16x32_bf16 v[52:55], v[152:155], v[196:199], v[52:55]
	v_mfma_f32_16x16x32_bf16 v[44:47], v[160:163], v[196:199], v[44:47]
	v_mfma_f32_16x16x32_bf16 v[36:39], v[152:155], v[204:207], v[36:39]
	v_mfma_f32_16x16x32_bf16 v[28:31], v[160:163], v[204:207], v[28:31]
	v_mfma_f32_16x16x32_bf16 v[20:23], v[152:155], v[212:215], v[20:23]
	v_mfma_f32_16x16x32_bf16 v[12:15], v[160:163], v[212:215], v[12:15]
	v_mfma_f32_16x16x32_bf16 v[60:63], v[156:159], v[192:195], v[60:63]
	v_mfma_f32_16x16x32_bf16 v[56:59], v[164:167], v[192:195], v[56:59]
	v_mfma_f32_16x16x32_bf16 v[52:55], v[156:159], v[200:203], v[52:55]
	v_mfma_f32_16x16x32_bf16 v[44:47], v[164:167], v[200:203], v[44:47]
	v_mfma_f32_16x16x32_bf16 v[36:39], v[156:159], v[208:211], v[36:39]
	v_mfma_f32_16x16x32_bf16 v[28:31], v[164:167], v[208:211], v[28:31]
	v_mfma_f32_16x16x32_bf16 v[20:23], v[156:159], v[216:219], v[20:23]
	v_mfma_f32_16x16x32_bf16 v[12:15], v[164:167], v[216:219], v[12:15]
	v_mfma_f32_16x16x32_bf16 v[48:51], v[168:171], v[184:187], v[48:51]
	v_mfma_f32_16x16x32_bf16 v[40:43], v[176:179], v[184:187], v[40:43]
	v_mfma_f32_16x16x32_bf16 v[32:35], v[168:171], v[196:199], v[32:35]
	v_mfma_f32_16x16x32_bf16 v[24:27], v[176:179], v[196:199], v[24:27]
	v_mfma_f32_16x16x32_bf16 v[16:19], v[168:171], v[204:207], v[16:19]
	v_mfma_f32_16x16x32_bf16 v[8:11], v[176:179], v[204:207], v[8:11]
	v_mfma_f32_16x16x32_bf16 v[4:7], v[168:171], v[212:215], v[4:7]
	v_mfma_f32_16x16x32_bf16 v[0:3], v[176:179], v[212:215], v[0:3]
	v_mfma_f32_16x16x32_bf16 v[48:51], v[172:175], v[192:195], v[48:51]
	v_mfma_f32_16x16x32_bf16 v[40:43], v[180:183], v[192:195], v[40:43]
	v_mfma_f32_16x16x32_bf16 v[32:35], v[172:175], v[200:203], v[32:35]
	v_mfma_f32_16x16x32_bf16 v[24:27], v[180:183], v[200:203], v[24:27]
	v_mfma_f32_16x16x32_bf16 v[16:19], v[172:175], v[208:211], v[16:19]
	v_mfma_f32_16x16x32_bf16 v[8:11], v[180:183], v[208:211], v[8:11]
	v_mfma_f32_16x16x32_bf16 v[4:7], v[172:175], v[216:219], v[4:7]
	v_mfma_f32_16x16x32_bf16 v[0:3], v[180:183], v[216:219], v[0:3]
	s_barrier
	s_add_i32 s77, s77, 2
	s_add_u32 s34, s34, 0x100
	s_addc_u32 s35, s35, 0
	s_add_u32 s75, s75, 0x100
	s_addc_u32 s76, s76, 0
	s_cmp_gt_u32 s77, 61
	s_cbranch_scc0 .LBB0_916

.LBB0_1052:
	s_ashr_i32 s27, s26, 31
	s_lshl_b64 s[28:29], s[26:27], 19
	s_add_u32 s28, s58, s28
	s_addc_u32 s29, s59, s29
	s_and_b64 s[30:31], s[4:5], exec
	s_cselect_b32 s27, s29, s43
	s_cselect_b32 s55, s28, s42
	s_ashr_i32 s25, s24, 31
	s_lshl_b64 s[30:31], s[24:25], 19
	s_add_u32 s30, s53, s30
	s_addc_u32 s31, s64, s31
	s_and_b64 s[62:63], s[4:5], exec
	s_cselect_b32 s25, s31, s61
	s_cselect_b32 s79, s30, s60
	s_add_u32 s42, s42, 0x40080
	s_addc_u32 s43, s43, 0
	s_add_u32 s80, s60, 0x100
	s_addc_u32 s81, s61, 0
	s_mov_b32 s82, -2
	ds_read_b128 v[152:155], v149
	ds_read_b128 v[156:159], v149 offset:1024
	ds_read_b128 v[160:163], v149 offset:2048
	ds_read_b128 v[164:167], v149 offset:3072
	ds_read_b128 v[168:171], v150
	ds_read_b128 v[172:175], v150 offset:1024
	ds_read_b128 v[176:179], v150 offset:2048
	ds_read_b128 v[180:183], v150 offset:3072
	s_add_u32 s60, s42, 0xfffc0080
	s_addc_u32 s61, s43, -1
	s_cmp_eq_u32 s82, 12
	s_cselect_b32 s63, s27, s61
	s_cselect_b32 s62, s55, s60
	s_cselect_b32 s61, s25, s81
	s_cselect_b32 s60, s79, s80
	s_add_i32 m0, s35, 0xc000
	ds_read_b128 v[184:187], v151
	ds_read_b128 v[192:195], v151 offset:1024
	ds_read_b128 v[196:199], v151 offset:2048
	ds_read_b128 v[200:203], v151 offset:3072
	ds_read_b128 v[204:207], v151 offset:4096
	ds_read_b128 v[208:211], v151 offset:5120
	ds_read_b128 v[212:215], v151 offset:6144
	ds_read_b128 v[216:219], v151 offset:7168
	global_load_lds_dwordx4 v136, s[42:43]
	s_add_i32 m0, s35, 0xe000
	s_nop 0
	global_load_lds_dwordx4 v138, s[42:43]
	s_waitcnt vmcnt(8)
	s_waitcnt lgkmcnt(0)
	s_barrier
	v_mfma_f32_16x16x32_bf16 v[124:127], v[152:155], v[184:187], 0
	v_mfma_f32_16x16x32_bf16 v[120:123], v[160:163], v[184:187], 0
	v_mfma_f32_16x16x32_bf16 v[116:119], v[152:155], v[196:199], 0
	v_mfma_f32_16x16x32_bf16 v[108:111], v[160:163], v[196:199], 0
	v_mfma_f32_16x16x32_bf16 v[100:103], v[152:155], v[204:207], 0
	v_mfma_f32_16x16x32_bf16 v[92:95], v[160:163], v[204:207], 0
	v_mfma_f32_16x16x32_bf16 v[84:87], v[152:155], v[212:215], 0
	v_mfma_f32_16x16x32_bf16 v[76:79], v[160:163], v[212:215], 0
	v_mfma_f32_16x16x32_bf16 v[124:127], v[156:159], v[192:195], v[124:127]
	v_mfma_f32_16x16x32_bf16 v[120:123], v[164:167], v[192:195], v[120:123]
	v_mfma_f32_16x16x32_bf16 v[116:119], v[156:159], v[200:203], v[116:119]
	v_mfma_f32_16x16x32_bf16 v[108:111], v[164:167], v[200:203], v[108:111]
	v_mfma_f32_16x16x32_bf16 v[100:103], v[156:159], v[208:211], v[100:103]
	v_mfma_f32_16x16x32_bf16 v[92:95], v[164:167], v[208:211], v[92:95]
	v_mfma_f32_16x16x32_bf16 v[84:87], v[156:159], v[216:219], v[84:87]
	v_mfma_f32_16x16x32_bf16 v[76:79], v[164:167], v[216:219], v[76:79]
	v_mfma_f32_16x16x32_bf16 v[112:115], v[168:171], v[184:187], 0
	v_mfma_f32_16x16x32_bf16 v[104:107], v[176:179], v[184:187], 0
	v_mfma_f32_16x16x32_bf16 v[96:99], v[168:171], v[196:199], 0
	v_mfma_f32_16x16x32_bf16 v[88:91], v[176:179], v[196:199], 0
	v_mfma_f32_16x16x32_bf16 v[80:83], v[168:171], v[204:207], 0
	v_mfma_f32_16x16x32_bf16 v[72:75], v[176:179], v[204:207], 0
	v_mfma_f32_16x16x32_bf16 v[68:71], v[168:171], v[212:215], 0
	v_mfma_f32_16x16x32_bf16 v[64:67], v[176:179], v[212:215], 0
	v_mfma_f32_16x16x32_bf16 v[112:115], v[172:175], v[192:195], v[112:115]
	v_mfma_f32_16x16x32_bf16 v[104:107], v[180:183], v[192:195], v[104:107]
	v_mfma_f32_16x16x32_bf16 v[96:99], v[172:175], v[200:203], v[96:99]
	v_mfma_f32_16x16x32_bf16 v[88:91], v[180:183], v[200:203], v[88:91]
	v_mfma_f32_16x16x32_bf16 v[80:83], v[172:175], v[208:211], v[80:83]
	v_mfma_f32_16x16x32_bf16 v[72:75], v[180:183], v[208:211], v[72:75]
	v_mfma_f32_16x16x32_bf16 v[68:71], v[172:175], v[216:219], v[68:71]
	v_mfma_f32_16x16x32_bf16 v[64:67], v[180:183], v[216:219], v[64:67]
	s_barrier
	s_add_i32 s83, s72, s65
	v_lshl_add_u64 v[144:145], s[60:61], 0, v[130:131]
	s_mov_b32 m0, s83
	ds_read_b128 v[184:187], v151 offset:16384
	ds_read_b128 v[192:195], v151 offset:17408
	ds_read_b128 v[196:199], v151 offset:18432
	ds_read_b128 v[200:203], v151 offset:19456
	ds_read_b128 v[204:207], v151 offset:20480
	ds_read_b128 v[208:211], v151 offset:21504
	ds_read_b128 v[212:215], v151 offset:22528
	ds_read_b128 v[216:219], v151 offset:23552
	global_load_lds_dwordx4 v[144:145], off
	s_add_i32 m0, s83, 0x2000
	s_add_u32 s84, s60, 0x40000
	v_lshl_add_u64 v[188:189], s[60:61], 0, v[134:135]
	s_addc_u32 s85, s61, 0
	s_add_i32 s83, s73, s65
	global_load_lds_dwordx4 v[188:189], off
	s_mov_b32 m0, s83
	v_lshl_add_u64 v[222:223], s[62:63], 0, v[132:133]
	global_load_lds_dwordx4 v130, s[84:85]
	s_add_i32 m0, s83, 0x2000
	v_lshl_add_u64 v[220:221], s[62:63], 0, v[128:129]
	global_load_lds_dwordx4 v134, s[84:85]
	s_mov_b32 m0, s35
	s_nop 0
	global_load_lds_dwordx4 v[220:221], off
	s_mov_b32 m0, s33
	s_nop 0
	global_load_lds_dwordx4 v[222:223], off
	s_waitcnt vmcnt(8)
	s_waitcnt lgkmcnt(0)
	s_barrier
	v_mfma_f32_16x16x32_bf16 v[60:63], v[152:155], v[184:187], 0
	v_mfma_f32_16x16x32_bf16 v[56:59], v[160:163], v[184:187], 0
	v_mfma_f32_16x16x32_bf16 v[52:55], v[152:155], v[196:199], 0
	v_mfma_f32_16x16x32_bf16 v[44:47], v[160:163], v[196:199], 0
	v_mfma_f32_16x16x32_bf16 v[36:39], v[152:155], v[204:207], 0
	v_mfma_f32_16x16x32_bf16 v[28:31], v[160:163], v[204:207], 0
	v_mfma_f32_16x16x32_bf16 v[20:23], v[152:155], v[212:215], 0
	v_mfma_f32_16x16x32_bf16 v[12:15], v[160:163], v[212:215], 0
	v_mfma_f32_16x16x32_bf16 v[60:63], v[156:159], v[192:195], v[60:63]
	v_mfma_f32_16x16x32_bf16 v[56:59], v[164:167], v[192:195], v[56:59]
	v_mfma_f32_16x16x32_bf16 v[52:55], v[156:159], v[200:203], v[52:55]
	v_mfma_f32_16x16x32_bf16 v[44:47], v[164:167], v[200:203], v[44:47]
	v_mfma_f32_16x16x32_bf16 v[36:39], v[156:159], v[208:211], v[36:39]
	v_mfma_f32_16x16x32_bf16 v[28:31], v[164:167], v[208:211], v[28:31]
	v_mfma_f32_16x16x32_bf16 v[20:23], v[156:159], v[216:219], v[20:23]
	v_mfma_f32_16x16x32_bf16 v[12:15], v[164:167], v[216:219], v[12:15]
	v_mfma_f32_16x16x32_bf16 v[48:51], v[168:171], v[184:187], 0
	v_mfma_f32_16x16x32_bf16 v[40:43], v[176:179], v[184:187], 0
	v_mfma_f32_16x16x32_bf16 v[32:35], v[168:171], v[196:199], 0
	v_mfma_f32_16x16x32_bf16 v[24:27], v[176:179], v[196:199], 0
	v_mfma_f32_16x16x32_bf16 v[16:19], v[168:171], v[204:207], 0
	v_mfma_f32_16x16x32_bf16 v[8:11], v[176:179], v[204:207], 0
	v_mfma_f32_16x16x32_bf16 v[4:7], v[168:171], v[212:215], 0
	v_mfma_f32_16x16x32_bf16 v[0:3], v[176:179], v[212:215], 0
	v_mfma_f32_16x16x32_bf16 v[48:51], v[172:175], v[192:195], v[48:51]
	v_mfma_f32_16x16x32_bf16 v[40:43], v[180:183], v[192:195], v[40:43]
	v_mfma_f32_16x16x32_bf16 v[32:35], v[172:175], v[200:203], v[32:35]
	v_mfma_f32_16x16x32_bf16 v[24:27], v[180:183], v[200:203], v[24:27]
	v_mfma_f32_16x16x32_bf16 v[16:19], v[172:175], v[208:211], v[16:19]
	v_mfma_f32_16x16x32_bf16 v[8:11], v[180:183], v[208:211], v[8:11]
	v_mfma_f32_16x16x32_bf16 v[4:7], v[172:175], v[216:219], v[4:7]
	v_mfma_f32_16x16x32_bf16 v[0:3], v[180:183], v[216:219], v[0:3]
	s_barrier
	s_add_i32 s83, 0, 0x18000
	s_add_i32 s84, 0, 0x1c000
	v_add_u32_e32 v164, s83, v147
	v_add_u32_e32 v180, s84, v147
	ds_read_b128 v[152:155], v164
	ds_read_b128 v[156:159], v164 offset:1024
	ds_read_b128 v[160:163], v164 offset:2048
	ds_read_b128 v[164:167], v164 offset:3072
	ds_read_b128 v[168:171], v180
	ds_read_b128 v[172:175], v180 offset:1024
	ds_read_b128 v[176:179], v180 offset:2048
	ds_read_b128 v[180:183], v180 offset:3072
	s_add_u32 s62, s62, 0x40000
	s_addc_u32 s63, s63, 0
	s_mov_b32 m0, s66
	ds_read_b128 v[184:187], v151 offset:32768
	ds_read_b128 v[192:195], v151 offset:33792
	ds_read_b128 v[196:199], v151 offset:34816
	ds_read_b128 v[200:203], v151 offset:35840
	ds_read_b128 v[204:207], v151 offset:36864
	ds_read_b128 v[208:211], v151 offset:37888
	ds_read_b128 v[212:215], v151 offset:38912
	ds_read_b128 v[216:219], v151 offset:39936
	global_load_lds_dwordx4 v128, s[62:63]
	s_mov_b32 m0, s67
	s_nop 0
	global_load_lds_dwordx4 v132, s[62:63]
	s_waitcnt vmcnt(8)
	s_waitcnt lgkmcnt(0)
	s_barrier
	v_mfma_f32_16x16x32_bf16 v[124:127], v[152:155], v[184:187], v[124:127]
	v_mfma_f32_16x16x32_bf16 v[120:123], v[160:163], v[184:187], v[120:123]
	v_mfma_f32_16x16x32_bf16 v[116:119], v[152:155], v[196:199], v[116:119]
	v_mfma_f32_16x16x32_bf16 v[108:111], v[160:163], v[196:199], v[108:111]
	v_mfma_f32_16x16x32_bf16 v[100:103], v[152:155], v[204:207], v[100:103]
	v_mfma_f32_16x16x32_bf16 v[92:95], v[160:163], v[204:207], v[92:95]
	v_mfma_f32_16x16x32_bf16 v[84:87], v[152:155], v[212:215], v[84:87]
	v_mfma_f32_16x16x32_bf16 v[76:79], v[160:163], v[212:215], v[76:79]
	v_mfma_f32_16x16x32_bf16 v[124:127], v[156:159], v[192:195], v[124:127]
	v_mfma_f32_16x16x32_bf16 v[120:123], v[164:167], v[192:195], v[120:123]
	v_mfma_f32_16x16x32_bf16 v[116:119], v[156:159], v[200:203], v[116:119]
	v_mfma_f32_16x16x32_bf16 v[108:111], v[164:167], v[200:203], v[108:111]
	v_mfma_f32_16x16x32_bf16 v[100:103], v[156:159], v[208:211], v[100:103]
	v_mfma_f32_16x16x32_bf16 v[92:95], v[164:167], v[208:211], v[92:95]
	v_mfma_f32_16x16x32_bf16 v[84:87], v[156:159], v[216:219], v[84:87]
	v_mfma_f32_16x16x32_bf16 v[76:79], v[164:167], v[216:219], v[76:79]
	v_mfma_f32_16x16x32_bf16 v[112:115], v[168:171], v[184:187], v[112:115]
	v_mfma_f32_16x16x32_bf16 v[104:107], v[176:179], v[184:187], v[104:107]
	v_mfma_f32_16x16x32_bf16 v[96:99], v[168:171], v[196:199], v[96:99]
	v_mfma_f32_16x16x32_bf16 v[88:91], v[176:179], v[196:199], v[88:91]
	v_mfma_f32_16x16x32_bf16 v[80:83], v[168:171], v[204:207], v[80:83]
	v_mfma_f32_16x16x32_bf16 v[72:75], v[176:179], v[204:207], v[72:75]
	v_mfma_f32_16x16x32_bf16 v[68:71], v[168:171], v[212:215], v[68:71]
	v_mfma_f32_16x16x32_bf16 v[64:67], v[176:179], v[212:215], v[64:67]
	v_mfma_f32_16x16x32_bf16 v[112:115], v[172:175], v[192:195], v[112:115]
	v_mfma_f32_16x16x32_bf16 v[104:107], v[180:183], v[192:195], v[104:107]
	v_mfma_f32_16x16x32_bf16 v[96:99], v[172:175], v[200:203], v[96:99]
	v_mfma_f32_16x16x32_bf16 v[88:91], v[180:183], v[200:203], v[88:91]
	v_mfma_f32_16x16x32_bf16 v[80:83], v[172:175], v[208:211], v[80:83]
	v_mfma_f32_16x16x32_bf16 v[72:75], v[180:183], v[208:211], v[72:75]
	v_mfma_f32_16x16x32_bf16 v[68:71], v[172:175], v[216:219], v[68:71]
	v_mfma_f32_16x16x32_bf16 v[64:67], v[180:183], v[216:219], v[64:67]
	s_barrier
	s_add_i32 s62, s83, s65
	v_lshl_add_u64 v[144:145], v[144:145], 0, s[12:13]
	s_mov_b32 m0, s62
	ds_read_b128 v[184:187], v151 offset:49152
	ds_read_b128 v[192:195], v151 offset:50176
	ds_read_b128 v[196:199], v151 offset:51200
	ds_read_b128 v[200:203], v151 offset:52224
	ds_read_b128 v[204:207], v151 offset:53248
	ds_read_b128 v[208:211], v151 offset:54272
	ds_read_b128 v[212:215], v151 offset:55296
	ds_read_b128 v[216:219], v151 offset:56320
	global_load_lds_dwordx4 v[144:145], off
	s_add_i32 m0, s62, 0x2000
	s_add_u32 s60, s60, 0x40080
	v_lshl_add_u64 v[144:145], v[188:189], 0, s[12:13]
	s_addc_u32 s61, s61, 0
	s_add_i32 s62, s84, s65
	global_load_lds_dwordx4 v[144:145], off
	s_mov_b32 m0, s62
	s_nop 0
	global_load_lds_dwordx4 v130, s[60:61]
	s_add_i32 m0, s62, 0x2000
	v_lshl_add_u64 v[144:145], v[220:221], 0, s[12:13]
	global_load_lds_dwordx4 v134, s[60:61]
	s_mov_b32 m0, s69
	s_nop 0
	global_load_lds_dwordx4 v[144:145], off
	s_mov_b32 m0, s70
	v_lshl_add_u64 v[144:145], v[222:223], 0, s[12:13]
	global_load_lds_dwordx4 v[144:145], off
	s_waitcnt vmcnt(8)
	s_waitcnt lgkmcnt(0)
	s_barrier
	v_mfma_f32_16x16x32_bf16 v[60:63], v[152:155], v[184:187], v[60:63]
	v_mfma_f32_16x16x32_bf16 v[56:59], v[160:163], v[184:187], v[56:59]
	v_mfma_f32_16x16x32_bf16 v[52:55], v[152:155], v[196:199], v[52:55]
	v_mfma_f32_16x16x32_bf16 v[44:47], v[160:163], v[196:199], v[44:47]
	v_mfma_f32_16x16x32_bf16 v[36:39], v[152:155], v[204:207], v[36:39]
	v_mfma_f32_16x16x32_bf16 v[28:31], v[160:163], v[204:207], v[28:31]
	v_mfma_f32_16x16x32_bf16 v[20:23], v[152:155], v[212:215], v[20:23]
	v_mfma_f32_16x16x32_bf16 v[12:15], v[160:163], v[212:215], v[12:15]
	v_mfma_f32_16x16x32_bf16 v[60:63], v[156:159], v[192:195], v[60:63]
	v_mfma_f32_16x16x32_bf16 v[56:59], v[164:167], v[192:195], v[56:59]
	v_mfma_f32_16x16x32_bf16 v[52:55], v[156:159], v[200:203], v[52:55]
	v_mfma_f32_16x16x32_bf16 v[44:47], v[164:167], v[200:203], v[44:47]
	v_mfma_f32_16x16x32_bf16 v[36:39], v[156:159], v[208:211], v[36:39]
	v_mfma_f32_16x16x32_bf16 v[28:31], v[164:167], v[208:211], v[28:31]
	v_mfma_f32_16x16x32_bf16 v[20:23], v[156:159], v[216:219], v[20:23]
	v_mfma_f32_16x16x32_bf16 v[12:15], v[164:167], v[216:219], v[12:15]
	v_mfma_f32_16x16x32_bf16 v[48:51], v[168:171], v[184:187], v[48:51]
	v_mfma_f32_16x16x32_bf16 v[40:43], v[176:179], v[184:187], v[40:43]
	v_mfma_f32_16x16x32_bf16 v[32:35], v[168:171], v[196:199], v[32:35]
	v_mfma_f32_16x16x32_bf16 v[24:27], v[176:179], v[196:199], v[24:27]
	v_mfma_f32_16x16x32_bf16 v[16:19], v[168:171], v[204:207], v[16:19]
	v_mfma_f32_16x16x32_bf16 v[8:11], v[176:179], v[204:207], v[8:11]
	v_mfma_f32_16x16x32_bf16 v[4:7], v[168:171], v[212:215], v[4:7]
	v_mfma_f32_16x16x32_bf16 v[0:3], v[176:179], v[212:215], v[0:3]
	v_mfma_f32_16x16x32_bf16 v[48:51], v[172:175], v[192:195], v[48:51]
	v_mfma_f32_16x16x32_bf16 v[40:43], v[180:183], v[192:195], v[40:43]
	v_mfma_f32_16x16x32_bf16 v[32:35], v[172:175], v[200:203], v[32:35]
	v_mfma_f32_16x16x32_bf16 v[24:27], v[180:183], v[200:203], v[24:27]
	v_mfma_f32_16x16x32_bf16 v[16:19], v[172:175], v[208:211], v[16:19]
	v_mfma_f32_16x16x32_bf16 v[8:11], v[180:183], v[208:211], v[8:11]
	v_mfma_f32_16x16x32_bf16 v[4:7], v[172:175], v[216:219], v[4:7]
	v_mfma_f32_16x16x32_bf16 v[0:3], v[180:183], v[216:219], v[0:3]
	s_barrier
	s_add_i32 s82, s82, 2
	s_add_u32 s42, s42, 0x100
	s_addc_u32 s43, s43, 0
	s_add_u32 s80, s80, 0x100
	s_addc_u32 s81, s81, 0
	s_cmp_gt_u32 s82, 13
	s_cbranch_scc0 .LBB0_1053
	s_branch .Lpeel_exit5
.LBB0_1053:
	ds_read_b128 v[152:155], v149
	ds_read_b128 v[156:159], v149 offset:1024
	ds_read_b128 v[160:163], v149 offset:2048
	ds_read_b128 v[164:167], v149 offset:3072
	ds_read_b128 v[168:171], v150
	ds_read_b128 v[172:175], v150 offset:1024
	ds_read_b128 v[176:179], v150 offset:2048
	ds_read_b128 v[180:183], v150 offset:3072
	s_add_u32 s60, s42, 0xfffc0080
	s_addc_u32 s61, s43, -1
	s_cmp_eq_u32 s82, 12
	s_cselect_b32 s63, s27, s61
	s_cselect_b32 s62, s55, s60
	s_cselect_b32 s61, s25, s81
	s_cselect_b32 s60, s79, s80
	s_add_i32 m0, s35, 0xc000
	ds_read_b128 v[184:187], v151
	ds_read_b128 v[192:195], v151 offset:1024
	ds_read_b128 v[196:199], v151 offset:2048
	ds_read_b128 v[200:203], v151 offset:3072
	ds_read_b128 v[204:207], v151 offset:4096
	ds_read_b128 v[208:211], v151 offset:5120
	ds_read_b128 v[212:215], v151 offset:6144
	ds_read_b128 v[216:219], v151 offset:7168
	global_load_lds_dwordx4 v136, s[42:43]
	s_add_i32 m0, s35, 0xe000
	s_nop 0
	global_load_lds_dwordx4 v138, s[42:43]
	s_waitcnt vmcnt(8)
	s_waitcnt lgkmcnt(0)
	s_barrier
	v_mfma_f32_16x16x32_bf16 v[124:127], v[152:155], v[184:187], v[124:127]
	v_mfma_f32_16x16x32_bf16 v[120:123], v[160:163], v[184:187], v[120:123]
	v_mfma_f32_16x16x32_bf16 v[116:119], v[152:155], v[196:199], v[116:119]
	v_mfma_f32_16x16x32_bf16 v[108:111], v[160:163], v[196:199], v[108:111]
	v_mfma_f32_16x16x32_bf16 v[100:103], v[152:155], v[204:207], v[100:103]
	v_mfma_f32_16x16x32_bf16 v[92:95], v[160:163], v[204:207], v[92:95]
	v_mfma_f32_16x16x32_bf16 v[84:87], v[152:155], v[212:215], v[84:87]
	v_mfma_f32_16x16x32_bf16 v[76:79], v[160:163], v[212:215], v[76:79]
	v_mfma_f32_16x16x32_bf16 v[124:127], v[156:159], v[192:195], v[124:127]
	v_mfma_f32_16x16x32_bf16 v[120:123], v[164:167], v[192:195], v[120:123]
	v_mfma_f32_16x16x32_bf16 v[116:119], v[156:159], v[200:203], v[116:119]
	v_mfma_f32_16x16x32_bf16 v[108:111], v[164:167], v[200:203], v[108:111]
	v_mfma_f32_16x16x32_bf16 v[100:103], v[156:159], v[208:211], v[100:103]
	v_mfma_f32_16x16x32_bf16 v[92:95], v[164:167], v[208:211], v[92:95]
	v_mfma_f32_16x16x32_bf16 v[84:87], v[156:159], v[216:219], v[84:87]
	v_mfma_f32_16x16x32_bf16 v[76:79], v[164:167], v[216:219], v[76:79]
	v_mfma_f32_16x16x32_bf16 v[112:115], v[168:171], v[184:187], v[112:115]
	v_mfma_f32_16x16x32_bf16 v[104:107], v[176:179], v[184:187], v[104:107]
	v_mfma_f32_16x16x32_bf16 v[96:99], v[168:171], v[196:199], v[96:99]
	v_mfma_f32_16x16x32_bf16 v[88:91], v[176:179], v[196:199], v[88:91]
	v_mfma_f32_16x16x32_bf16 v[80:83], v[168:171], v[204:207], v[80:83]
	v_mfma_f32_16x16x32_bf16 v[72:75], v[176:179], v[204:207], v[72:75]
	v_mfma_f32_16x16x32_bf16 v[68:71], v[168:171], v[212:215], v[68:71]
	v_mfma_f32_16x16x32_bf16 v[64:67], v[176:179], v[212:215], v[64:67]
	v_mfma_f32_16x16x32_bf16 v[112:115], v[172:175], v[192:195], v[112:115]
	v_mfma_f32_16x16x32_bf16 v[104:107], v[180:183], v[192:195], v[104:107]
	v_mfma_f32_16x16x32_bf16 v[96:99], v[172:175], v[200:203], v[96:99]
	v_mfma_f32_16x16x32_bf16 v[88:91], v[180:183], v[200:203], v[88:91]
	v_mfma_f32_16x16x32_bf16 v[80:83], v[172:175], v[208:211], v[80:83]
	v_mfma_f32_16x16x32_bf16 v[72:75], v[180:183], v[208:211], v[72:75]
	v_mfma_f32_16x16x32_bf16 v[68:71], v[172:175], v[216:219], v[68:71]
	v_mfma_f32_16x16x32_bf16 v[64:67], v[180:183], v[216:219], v[64:67]
	s_barrier
	s_add_i32 s83, s72, s65
	v_lshl_add_u64 v[144:145], s[60:61], 0, v[130:131]
	s_mov_b32 m0, s83
	ds_read_b128 v[184:187], v151 offset:16384
	ds_read_b128 v[192:195], v151 offset:17408
	ds_read_b128 v[196:199], v151 offset:18432
	ds_read_b128 v[200:203], v151 offset:19456
	ds_read_b128 v[204:207], v151 offset:20480
	ds_read_b128 v[208:211], v151 offset:21504
	ds_read_b128 v[212:215], v151 offset:22528
	ds_read_b128 v[216:219], v151 offset:23552
	global_load_lds_dwordx4 v[144:145], off
	s_add_i32 m0, s83, 0x2000
	s_add_u32 s84, s60, 0x40000
	v_lshl_add_u64 v[188:189], s[60:61], 0, v[134:135]
	s_addc_u32 s85, s61, 0
	s_add_i32 s83, s73, s65
	global_load_lds_dwordx4 v[188:189], off
	s_mov_b32 m0, s83
	v_lshl_add_u64 v[222:223], s[62:63], 0, v[132:133]
	global_load_lds_dwordx4 v130, s[84:85]
	s_add_i32 m0, s83, 0x2000
	v_lshl_add_u64 v[220:221], s[62:63], 0, v[128:129]
	global_load_lds_dwordx4 v134, s[84:85]
	s_mov_b32 m0, s35
	s_nop 0
	global_load_lds_dwordx4 v[220:221], off
	s_mov_b32 m0, s33
	s_nop 0
	global_load_lds_dwordx4 v[222:223], off
	s_waitcnt vmcnt(8)
	s_waitcnt lgkmcnt(0)
	s_barrier
	v_mfma_f32_16x16x32_bf16 v[60:63], v[152:155], v[184:187], v[60:63]
	v_mfma_f32_16x16x32_bf16 v[56:59], v[160:163], v[184:187], v[56:59]
	v_mfma_f32_16x16x32_bf16 v[52:55], v[152:155], v[196:199], v[52:55]
	v_mfma_f32_16x16x32_bf16 v[44:47], v[160:163], v[196:199], v[44:47]
	v_mfma_f32_16x16x32_bf16 v[36:39], v[152:155], v[204:207], v[36:39]
	v_mfma_f32_16x16x32_bf16 v[28:31], v[160:163], v[204:207], v[28:31]
	v_mfma_f32_16x16x32_bf16 v[20:23], v[152:155], v[212:215], v[20:23]
	v_mfma_f32_16x16x32_bf16 v[12:15], v[160:163], v[212:215], v[12:15]
	v_mfma_f32_16x16x32_bf16 v[60:63], v[156:159], v[192:195], v[60:63]
	v_mfma_f32_16x16x32_bf16 v[56:59], v[164:167], v[192:195], v[56:59]
	v_mfma_f32_16x16x32_bf16 v[52:55], v[156:159], v[200:203], v[52:55]
	v_mfma_f32_16x16x32_bf16 v[44:47], v[164:167], v[200:203], v[44:47]
	v_mfma_f32_16x16x32_bf16 v[36:39], v[156:159], v[208:211], v[36:39]
	v_mfma_f32_16x16x32_bf16 v[28:31], v[164:167], v[208:211], v[28:31]
	v_mfma_f32_16x16x32_bf16 v[20:23], v[156:159], v[216:219], v[20:23]
	v_mfma_f32_16x16x32_bf16 v[12:15], v[164:167], v[216:219], v[12:15]
	v_mfma_f32_16x16x32_bf16 v[48:51], v[168:171], v[184:187], v[48:51]
	v_mfma_f32_16x16x32_bf16 v[40:43], v[176:179], v[184:187], v[40:43]
	v_mfma_f32_16x16x32_bf16 v[32:35], v[168:171], v[196:199], v[32:35]
	v_mfma_f32_16x16x32_bf16 v[24:27], v[176:179], v[196:199], v[24:27]
	v_mfma_f32_16x16x32_bf16 v[16:19], v[168:171], v[204:207], v[16:19]
	v_mfma_f32_16x16x32_bf16 v[8:11], v[176:179], v[204:207], v[8:11]
	v_mfma_f32_16x16x32_bf16 v[4:7], v[168:171], v[212:215], v[4:7]
	v_mfma_f32_16x16x32_bf16 v[0:3], v[176:179], v[212:215], v[0:3]
	v_mfma_f32_16x16x32_bf16 v[48:51], v[172:175], v[192:195], v[48:51]
	v_mfma_f32_16x16x32_bf16 v[40:43], v[180:183], v[192:195], v[40:43]
	v_mfma_f32_16x16x32_bf16 v[32:35], v[172:175], v[200:203], v[32:35]
	v_mfma_f32_16x16x32_bf16 v[24:27], v[180:183], v[200:203], v[24:27]
	v_mfma_f32_16x16x32_bf16 v[16:19], v[172:175], v[208:211], v[16:19]
	v_mfma_f32_16x16x32_bf16 v[8:11], v[180:183], v[208:211], v[8:11]
	v_mfma_f32_16x16x32_bf16 v[4:7], v[172:175], v[216:219], v[4:7]
	v_mfma_f32_16x16x32_bf16 v[0:3], v[180:183], v[216:219], v[0:3]
	s_barrier
	s_add_i32 s83, 0, 0x18000
	s_add_i32 s84, 0, 0x1c000
	v_add_u32_e32 v164, s83, v147
	v_add_u32_e32 v180, s84, v147
	ds_read_b128 v[152:155], v164
	ds_read_b128 v[156:159], v164 offset:1024
	ds_read_b128 v[160:163], v164 offset:2048
	ds_read_b128 v[164:167], v164 offset:3072
	ds_read_b128 v[168:171], v180
	ds_read_b128 v[172:175], v180 offset:1024
	ds_read_b128 v[176:179], v180 offset:2048
	ds_read_b128 v[180:183], v180 offset:3072
	s_add_u32 s62, s62, 0x40000
	s_addc_u32 s63, s63, 0
	s_mov_b32 m0, s66
	ds_read_b128 v[184:187], v151 offset:32768
	ds_read_b128 v[192:195], v151 offset:33792
	ds_read_b128 v[196:199], v151 offset:34816
	ds_read_b128 v[200:203], v151 offset:35840
	ds_read_b128 v[204:207], v151 offset:36864
	ds_read_b128 v[208:211], v151 offset:37888
	ds_read_b128 v[212:215], v151 offset:38912
	ds_read_b128 v[216:219], v151 offset:39936
	global_load_lds_dwordx4 v128, s[62:63]
	s_mov_b32 m0, s67
	s_nop 0
	global_load_lds_dwordx4 v132, s[62:63]
	s_waitcnt vmcnt(8)
	s_waitcnt lgkmcnt(0)
	s_barrier
	v_mfma_f32_16x16x32_bf16 v[124:127], v[152:155], v[184:187], v[124:127]
	v_mfma_f32_16x16x32_bf16 v[120:123], v[160:163], v[184:187], v[120:123]
	v_mfma_f32_16x16x32_bf16 v[116:119], v[152:155], v[196:199], v[116:119]
	v_mfma_f32_16x16x32_bf16 v[108:111], v[160:163], v[196:199], v[108:111]
	v_mfma_f32_16x16x32_bf16 v[100:103], v[152:155], v[204:207], v[100:103]
	v_mfma_f32_16x16x32_bf16 v[92:95], v[160:163], v[204:207], v[92:95]
	v_mfma_f32_16x16x32_bf16 v[84:87], v[152:155], v[212:215], v[84:87]
	v_mfma_f32_16x16x32_bf16 v[76:79], v[160:163], v[212:215], v[76:79]
	v_mfma_f32_16x16x32_bf16 v[124:127], v[156:159], v[192:195], v[124:127]
	v_mfma_f32_16x16x32_bf16 v[120:123], v[164:167], v[192:195], v[120:123]
	v_mfma_f32_16x16x32_bf16 v[116:119], v[156:159], v[200:203], v[116:119]
	v_mfma_f32_16x16x32_bf16 v[108:111], v[164:167], v[200:203], v[108:111]
	v_mfma_f32_16x16x32_bf16 v[100:103], v[156:159], v[208:211], v[100:103]
	v_mfma_f32_16x16x32_bf16 v[92:95], v[164:167], v[208:211], v[92:95]
	v_mfma_f32_16x16x32_bf16 v[84:87], v[156:159], v[216:219], v[84:87]
	v_mfma_f32_16x16x32_bf16 v[76:79], v[164:167], v[216:219], v[76:79]
	v_mfma_f32_16x16x32_bf16 v[112:115], v[168:171], v[184:187], v[112:115]
	v_mfma_f32_16x16x32_bf16 v[104:107], v[176:179], v[184:187], v[104:107]
	v_mfma_f32_16x16x32_bf16 v[96:99], v[168:171], v[196:199], v[96:99]
	v_mfma_f32_16x16x32_bf16 v[88:91], v[176:179], v[196:199], v[88:91]
	v_mfma_f32_16x16x32_bf16 v[80:83], v[168:171], v[204:207], v[80:83]
	v_mfma_f32_16x16x32_bf16 v[72:75], v[176:179], v[204:207], v[72:75]
	v_mfma_f32_16x16x32_bf16 v[68:71], v[168:171], v[212:215], v[68:71]
	v_mfma_f32_16x16x32_bf16 v[64:67], v[176:179], v[212:215], v[64:67]
	v_mfma_f32_16x16x32_bf16 v[112:115], v[172:175], v[192:195], v[112:115]
	v_mfma_f32_16x16x32_bf16 v[104:107], v[180:183], v[192:195], v[104:107]
	v_mfma_f32_16x16x32_bf16 v[96:99], v[172:175], v[200:203], v[96:99]
	v_mfma_f32_16x16x32_bf16 v[88:91], v[180:183], v[200:203], v[88:91]
	v_mfma_f32_16x16x32_bf16 v[80:83], v[172:175], v[208:211], v[80:83]
	v_mfma_f32_16x16x32_bf16 v[72:75], v[180:183], v[208:211], v[72:75]
	v_mfma_f32_16x16x32_bf16 v[68:71], v[172:175], v[216:219], v[68:71]
	v_mfma_f32_16x16x32_bf16 v[64:67], v[180:183], v[216:219], v[64:67]
	s_barrier
	s_add_i32 s62, s83, s65
	v_lshl_add_u64 v[144:145], v[144:145], 0, s[12:13]
	s_mov_b32 m0, s62
	ds_read_b128 v[184:187], v151 offset:49152
	ds_read_b128 v[192:195], v151 offset:50176
	ds_read_b128 v[196:199], v151 offset:51200
	ds_read_b128 v[200:203], v151 offset:52224
	ds_read_b128 v[204:207], v151 offset:53248
	ds_read_b128 v[208:211], v151 offset:54272
	ds_read_b128 v[212:215], v151 offset:55296
	ds_read_b128 v[216:219], v151 offset:56320
	global_load_lds_dwordx4 v[144:145], off
	s_add_i32 m0, s62, 0x2000
	s_add_u32 s60, s60, 0x40080
	v_lshl_add_u64 v[144:145], v[188:189], 0, s[12:13]
	s_addc_u32 s61, s61, 0
	s_add_i32 s62, s84, s65
	global_load_lds_dwordx4 v[144:145], off
	s_mov_b32 m0, s62
	s_nop 0
	global_load_lds_dwordx4 v130, s[60:61]
	s_add_i32 m0, s62, 0x2000
	v_lshl_add_u64 v[144:145], v[220:221], 0, s[12:13]
	global_load_lds_dwordx4 v134, s[60:61]
	s_mov_b32 m0, s69
	s_nop 0
	global_load_lds_dwordx4 v[144:145], off
	s_mov_b32 m0, s70
	v_lshl_add_u64 v[144:145], v[222:223], 0, s[12:13]
	global_load_lds_dwordx4 v[144:145], off
	s_waitcnt vmcnt(8)
	s_waitcnt lgkmcnt(0)
	s_barrier
	v_mfma_f32_16x16x32_bf16 v[60:63], v[152:155], v[184:187], v[60:63]
	v_mfma_f32_16x16x32_bf16 v[56:59], v[160:163], v[184:187], v[56:59]
	v_mfma_f32_16x16x32_bf16 v[52:55], v[152:155], v[196:199], v[52:55]
	v_mfma_f32_16x16x32_bf16 v[44:47], v[160:163], v[196:199], v[44:47]
	v_mfma_f32_16x16x32_bf16 v[36:39], v[152:155], v[204:207], v[36:39]
	v_mfma_f32_16x16x32_bf16 v[28:31], v[160:163], v[204:207], v[28:31]
	v_mfma_f32_16x16x32_bf16 v[20:23], v[152:155], v[212:215], v[20:23]
	v_mfma_f32_16x16x32_bf16 v[12:15], v[160:163], v[212:215], v[12:15]
	v_mfma_f32_16x16x32_bf16 v[60:63], v[156:159], v[192:195], v[60:63]
	v_mfma_f32_16x16x32_bf16 v[56:59], v[164:167], v[192:195], v[56:59]
	v_mfma_f32_16x16x32_bf16 v[52:55], v[156:159], v[200:203], v[52:55]
	v_mfma_f32_16x16x32_bf16 v[44:47], v[164:167], v[200:203], v[44:47]
	v_mfma_f32_16x16x32_bf16 v[36:39], v[156:159], v[208:211], v[36:39]
	v_mfma_f32_16x16x32_bf16 v[28:31], v[164:167], v[208:211], v[28:31]
	v_mfma_f32_16x16x32_bf16 v[20:23], v[156:159], v[216:219], v[20:23]
	v_mfma_f32_16x16x32_bf16 v[12:15], v[164:167], v[216:219], v[12:15]
	v_mfma_f32_16x16x32_bf16 v[48:51], v[168:171], v[184:187], v[48:51]
	v_mfma_f32_16x16x32_bf16 v[40:43], v[176:179], v[184:187], v[40:43]
	v_mfma_f32_16x16x32_bf16 v[32:35], v[168:171], v[196:199], v[32:35]
	v_mfma_f32_16x16x32_bf16 v[24:27], v[176:179], v[196:199], v[24:27]
	v_mfma_f32_16x16x32_bf16 v[16:19], v[168:171], v[204:207], v[16:19]
	v_mfma_f32_16x16x32_bf16 v[8:11], v[176:179], v[204:207], v[8:11]
	v_mfma_f32_16x16x32_bf16 v[4:7], v[168:171], v[212:215], v[4:7]
	v_mfma_f32_16x16x32_bf16 v[0:3], v[176:179], v[212:215], v[0:3]
	v_mfma_f32_16x16x32_bf16 v[48:51], v[172:175], v[192:195], v[48:51]
	v_mfma_f32_16x16x32_bf16 v[40:43], v[180:183], v[192:195], v[40:43]
	v_mfma_f32_16x16x32_bf16 v[32:35], v[172:175], v[200:203], v[32:35]
	v_mfma_f32_16x16x32_bf16 v[24:27], v[180:183], v[200:203], v[24:27]
	v_mfma_f32_16x16x32_bf16 v[16:19], v[172:175], v[208:211], v[16:19]
	v_mfma_f32_16x16x32_bf16 v[8:11], v[180:183], v[208:211], v[8:11]
	v_mfma_f32_16x16x32_bf16 v[4:7], v[172:175], v[216:219], v[4:7]
	v_mfma_f32_16x16x32_bf16 v[0:3], v[180:183], v[216:219], v[0:3]
	s_barrier
	s_add_i32 s82, s82, 2
	s_add_u32 s42, s42, 0x100
	s_addc_u32 s43, s43, 0
	s_add_u32 s80, s80, 0x100
	s_addc_u32 s81, s81, 0
	s_cmp_gt_u32 s82, 13
	s_cbranch_scc0 .LBB0_1053

.LBB0_1076:
	s_ashr_i32 s27, s26, 31
	s_lshl_b64 s[28:29], s[26:27], 19
	s_add_u32 s28, s40, s28
	s_addc_u32 s29, s41, s29
	s_and_b64 s[30:31], s[4:5], exec
	s_cselect_b32 s27, s29, s43
	s_cselect_b32 s55, s28, s42
	s_ashr_i32 s25, s24, 31
	s_lshl_b64 s[30:31], s[24:25], 19
	s_add_u32 s30, s53, s30
	s_addc_u32 s31, s64, s31
	s_and_b64 s[62:63], s[4:5], exec
	s_cselect_b32 s25, s31, s61
	s_cselect_b32 s79, s30, s60
	s_add_u32 s42, s42, 0x40080
	s_addc_u32 s43, s43, 0
	s_add_u32 s80, s60, 0x100
	s_addc_u32 s81, s61, 0
	s_mov_b32 s82, -2
	ds_read_b128 v[152:155], v149
	ds_read_b128 v[156:159], v149 offset:1024
	ds_read_b128 v[160:163], v149 offset:2048
	ds_read_b128 v[164:167], v149 offset:3072
	ds_read_b128 v[168:171], v150
	ds_read_b128 v[172:175], v150 offset:1024
	ds_read_b128 v[176:179], v150 offset:2048
	ds_read_b128 v[180:183], v150 offset:3072
	s_add_u32 s60, s42, 0xfffc0080
	s_addc_u32 s61, s43, -1
	s_cmp_eq_u32 s82, 12
	s_cselect_b32 s63, s27, s61
	s_cselect_b32 s62, s55, s60
	s_cselect_b32 s61, s25, s81
	s_cselect_b32 s60, s79, s80
	s_add_i32 m0, s35, 0xc000
	ds_read_b128 v[184:187], v151
	ds_read_b128 v[192:195], v151 offset:1024
	ds_read_b128 v[196:199], v151 offset:2048
	ds_read_b128 v[200:203], v151 offset:3072
	ds_read_b128 v[204:207], v151 offset:4096
	ds_read_b128 v[208:211], v151 offset:5120
	ds_read_b128 v[212:215], v151 offset:6144
	ds_read_b128 v[216:219], v151 offset:7168
	global_load_lds_dwordx4 v136, s[42:43]
	s_add_i32 m0, s35, 0xe000
	s_nop 0
	global_load_lds_dwordx4 v138, s[42:43]
	s_waitcnt vmcnt(8)
	s_waitcnt lgkmcnt(0)
	s_barrier
	v_mfma_f32_16x16x32_bf16 v[124:127], v[152:155], v[184:187], 0
	v_mfma_f32_16x16x32_bf16 v[120:123], v[160:163], v[184:187], 0
	v_mfma_f32_16x16x32_bf16 v[116:119], v[152:155], v[196:199], 0
	v_mfma_f32_16x16x32_bf16 v[108:111], v[160:163], v[196:199], 0
	v_mfma_f32_16x16x32_bf16 v[100:103], v[152:155], v[204:207], 0
	v_mfma_f32_16x16x32_bf16 v[92:95], v[160:163], v[204:207], 0
	v_mfma_f32_16x16x32_bf16 v[84:87], v[152:155], v[212:215], 0
	v_mfma_f32_16x16x32_bf16 v[76:79], v[160:163], v[212:215], 0
	v_mfma_f32_16x16x32_bf16 v[124:127], v[156:159], v[192:195], v[124:127]
	v_mfma_f32_16x16x32_bf16 v[120:123], v[164:167], v[192:195], v[120:123]
	v_mfma_f32_16x16x32_bf16 v[116:119], v[156:159], v[200:203], v[116:119]
	v_mfma_f32_16x16x32_bf16 v[108:111], v[164:167], v[200:203], v[108:111]
	v_mfma_f32_16x16x32_bf16 v[100:103], v[156:159], v[208:211], v[100:103]
	v_mfma_f32_16x16x32_bf16 v[92:95], v[164:167], v[208:211], v[92:95]
	v_mfma_f32_16x16x32_bf16 v[84:87], v[156:159], v[216:219], v[84:87]
	v_mfma_f32_16x16x32_bf16 v[76:79], v[164:167], v[216:219], v[76:79]
	v_mfma_f32_16x16x32_bf16 v[112:115], v[168:171], v[184:187], 0
	v_mfma_f32_16x16x32_bf16 v[104:107], v[176:179], v[184:187], 0
	v_mfma_f32_16x16x32_bf16 v[96:99], v[168:171], v[196:199], 0
	v_mfma_f32_16x16x32_bf16 v[88:91], v[176:179], v[196:199], 0
	v_mfma_f32_16x16x32_bf16 v[80:83], v[168:171], v[204:207], 0
	v_mfma_f32_16x16x32_bf16 v[72:75], v[176:179], v[204:207], 0
	v_mfma_f32_16x16x32_bf16 v[68:71], v[168:171], v[212:215], 0
	v_mfma_f32_16x16x32_bf16 v[64:67], v[176:179], v[212:215], 0
	v_mfma_f32_16x16x32_bf16 v[112:115], v[172:175], v[192:195], v[112:115]
	v_mfma_f32_16x16x32_bf16 v[104:107], v[180:183], v[192:195], v[104:107]
	v_mfma_f32_16x16x32_bf16 v[96:99], v[172:175], v[200:203], v[96:99]
	v_mfma_f32_16x16x32_bf16 v[88:91], v[180:183], v[200:203], v[88:91]
	v_mfma_f32_16x16x32_bf16 v[80:83], v[172:175], v[208:211], v[80:83]
	v_mfma_f32_16x16x32_bf16 v[72:75], v[180:183], v[208:211], v[72:75]
	v_mfma_f32_16x16x32_bf16 v[68:71], v[172:175], v[216:219], v[68:71]
	v_mfma_f32_16x16x32_bf16 v[64:67], v[180:183], v[216:219], v[64:67]
	s_barrier
	s_add_i32 s83, s72, s65
	v_lshl_add_u64 v[144:145], s[60:61], 0, v[130:131]
	s_mov_b32 m0, s83
	ds_read_b128 v[184:187], v151 offset:16384
	ds_read_b128 v[192:195], v151 offset:17408
	ds_read_b128 v[196:199], v151 offset:18432
	ds_read_b128 v[200:203], v151 offset:19456
	ds_read_b128 v[204:207], v151 offset:20480
	ds_read_b128 v[208:211], v151 offset:21504
	ds_read_b128 v[212:215], v151 offset:22528
	ds_read_b128 v[216:219], v151 offset:23552
	global_load_lds_dwordx4 v[144:145], off
	s_add_i32 m0, s83, 0x2000
	s_add_u32 s84, s60, 0x40000
	v_lshl_add_u64 v[188:189], s[60:61], 0, v[134:135]
	s_addc_u32 s85, s61, 0
	s_add_i32 s83, s73, s65
	global_load_lds_dwordx4 v[188:189], off
	s_mov_b32 m0, s83
	v_lshl_add_u64 v[222:223], s[62:63], 0, v[132:133]
	global_load_lds_dwordx4 v130, s[84:85]
	s_add_i32 m0, s83, 0x2000
	v_lshl_add_u64 v[220:221], s[62:63], 0, v[128:129]
	global_load_lds_dwordx4 v134, s[84:85]
	s_mov_b32 m0, s35
	s_nop 0
	global_load_lds_dwordx4 v[220:221], off
	s_mov_b32 m0, s33
	s_nop 0
	global_load_lds_dwordx4 v[222:223], off
	s_waitcnt vmcnt(8)
	s_waitcnt lgkmcnt(0)
	s_barrier
	v_mfma_f32_16x16x32_bf16 v[60:63], v[152:155], v[184:187], 0
	v_mfma_f32_16x16x32_bf16 v[56:59], v[160:163], v[184:187], 0
	v_mfma_f32_16x16x32_bf16 v[52:55], v[152:155], v[196:199], 0
	v_mfma_f32_16x16x32_bf16 v[44:47], v[160:163], v[196:199], 0
	v_mfma_f32_16x16x32_bf16 v[36:39], v[152:155], v[204:207], 0
	v_mfma_f32_16x16x32_bf16 v[28:31], v[160:163], v[204:207], 0
	v_mfma_f32_16x16x32_bf16 v[20:23], v[152:155], v[212:215], 0
	v_mfma_f32_16x16x32_bf16 v[12:15], v[160:163], v[212:215], 0
	v_mfma_f32_16x16x32_bf16 v[60:63], v[156:159], v[192:195], v[60:63]
	v_mfma_f32_16x16x32_bf16 v[56:59], v[164:167], v[192:195], v[56:59]
	v_mfma_f32_16x16x32_bf16 v[52:55], v[156:159], v[200:203], v[52:55]
	v_mfma_f32_16x16x32_bf16 v[44:47], v[164:167], v[200:203], v[44:47]
	v_mfma_f32_16x16x32_bf16 v[36:39], v[156:159], v[208:211], v[36:39]
	v_mfma_f32_16x16x32_bf16 v[28:31], v[164:167], v[208:211], v[28:31]
	v_mfma_f32_16x16x32_bf16 v[20:23], v[156:159], v[216:219], v[20:23]
	v_mfma_f32_16x16x32_bf16 v[12:15], v[164:167], v[216:219], v[12:15]
	v_mfma_f32_16x16x32_bf16 v[48:51], v[168:171], v[184:187], 0
	v_mfma_f32_16x16x32_bf16 v[40:43], v[176:179], v[184:187], 0
	v_mfma_f32_16x16x32_bf16 v[32:35], v[168:171], v[196:199], 0
	v_mfma_f32_16x16x32_bf16 v[24:27], v[176:179], v[196:199], 0
	v_mfma_f32_16x16x32_bf16 v[16:19], v[168:171], v[204:207], 0
	v_mfma_f32_16x16x32_bf16 v[8:11], v[176:179], v[204:207], 0
	v_mfma_f32_16x16x32_bf16 v[4:7], v[168:171], v[212:215], 0
	v_mfma_f32_16x16x32_bf16 v[0:3], v[176:179], v[212:215], 0
	v_mfma_f32_16x16x32_bf16 v[48:51], v[172:175], v[192:195], v[48:51]
	v_mfma_f32_16x16x32_bf16 v[40:43], v[180:183], v[192:195], v[40:43]
	v_mfma_f32_16x16x32_bf16 v[32:35], v[172:175], v[200:203], v[32:35]
	v_mfma_f32_16x16x32_bf16 v[24:27], v[180:183], v[200:203], v[24:27]
	v_mfma_f32_16x16x32_bf16 v[16:19], v[172:175], v[208:211], v[16:19]
	v_mfma_f32_16x16x32_bf16 v[8:11], v[180:183], v[208:211], v[8:11]
	v_mfma_f32_16x16x32_bf16 v[4:7], v[172:175], v[216:219], v[4:7]
	v_mfma_f32_16x16x32_bf16 v[0:3], v[180:183], v[216:219], v[0:3]
	s_barrier
	s_add_i32 s83, 0, 0x18000
	s_add_i32 s84, 0, 0x1c000
	v_add_u32_e32 v164, s83, v147
	v_add_u32_e32 v180, s84, v147
	ds_read_b128 v[152:155], v164
	ds_read_b128 v[156:159], v164 offset:1024
	ds_read_b128 v[160:163], v164 offset:2048
	ds_read_b128 v[164:167], v164 offset:3072
	ds_read_b128 v[168:171], v180
	ds_read_b128 v[172:175], v180 offset:1024
	ds_read_b128 v[176:179], v180 offset:2048
	ds_read_b128 v[180:183], v180 offset:3072
	s_add_u32 s62, s62, 0x40000
	s_addc_u32 s63, s63, 0
	s_mov_b32 m0, s66
	ds_read_b128 v[184:187], v151 offset:32768
	ds_read_b128 v[192:195], v151 offset:33792
	ds_read_b128 v[196:199], v151 offset:34816
	ds_read_b128 v[200:203], v151 offset:35840
	ds_read_b128 v[204:207], v151 offset:36864
	ds_read_b128 v[208:211], v151 offset:37888
	ds_read_b128 v[212:215], v151 offset:38912
	ds_read_b128 v[216:219], v151 offset:39936
	global_load_lds_dwordx4 v128, s[62:63]
	s_mov_b32 m0, s67
	s_nop 0
	global_load_lds_dwordx4 v132, s[62:63]
	s_waitcnt vmcnt(8)
	s_waitcnt lgkmcnt(0)
	s_barrier
	v_mfma_f32_16x16x32_bf16 v[124:127], v[152:155], v[184:187], v[124:127]
	v_mfma_f32_16x16x32_bf16 v[120:123], v[160:163], v[184:187], v[120:123]
	v_mfma_f32_16x16x32_bf16 v[116:119], v[152:155], v[196:199], v[116:119]
	v_mfma_f32_16x16x32_bf16 v[108:111], v[160:163], v[196:199], v[108:111]
	v_mfma_f32_16x16x32_bf16 v[100:103], v[152:155], v[204:207], v[100:103]
	v_mfma_f32_16x16x32_bf16 v[92:95], v[160:163], v[204:207], v[92:95]
	v_mfma_f32_16x16x32_bf16 v[84:87], v[152:155], v[212:215], v[84:87]
	v_mfma_f32_16x16x32_bf16 v[76:79], v[160:163], v[212:215], v[76:79]
	v_mfma_f32_16x16x32_bf16 v[124:127], v[156:159], v[192:195], v[124:127]
	v_mfma_f32_16x16x32_bf16 v[120:123], v[164:167], v[192:195], v[120:123]
	v_mfma_f32_16x16x32_bf16 v[116:119], v[156:159], v[200:203], v[116:119]
	v_mfma_f32_16x16x32_bf16 v[108:111], v[164:167], v[200:203], v[108:111]
	v_mfma_f32_16x16x32_bf16 v[100:103], v[156:159], v[208:211], v[100:103]
	v_mfma_f32_16x16x32_bf16 v[92:95], v[164:167], v[208:211], v[92:95]
	v_mfma_f32_16x16x32_bf16 v[84:87], v[156:159], v[216:219], v[84:87]
	v_mfma_f32_16x16x32_bf16 v[76:79], v[164:167], v[216:219], v[76:79]
	v_mfma_f32_16x16x32_bf16 v[112:115], v[168:171], v[184:187], v[112:115]
	v_mfma_f32_16x16x32_bf16 v[104:107], v[176:179], v[184:187], v[104:107]
	v_mfma_f32_16x16x32_bf16 v[96:99], v[168:171], v[196:199], v[96:99]
	v_mfma_f32_16x16x32_bf16 v[88:91], v[176:179], v[196:199], v[88:91]
	v_mfma_f32_16x16x32_bf16 v[80:83], v[168:171], v[204:207], v[80:83]
	v_mfma_f32_16x16x32_bf16 v[72:75], v[176:179], v[204:207], v[72:75]
	v_mfma_f32_16x16x32_bf16 v[68:71], v[168:171], v[212:215], v[68:71]
	v_mfma_f32_16x16x32_bf16 v[64:67], v[176:179], v[212:215], v[64:67]
	v_mfma_f32_16x16x32_bf16 v[112:115], v[172:175], v[192:195], v[112:115]
	v_mfma_f32_16x16x32_bf16 v[104:107], v[180:183], v[192:195], v[104:107]
	v_mfma_f32_16x16x32_bf16 v[96:99], v[172:175], v[200:203], v[96:99]
	v_mfma_f32_16x16x32_bf16 v[88:91], v[180:183], v[200:203], v[88:91]
	v_mfma_f32_16x16x32_bf16 v[80:83], v[172:175], v[208:211], v[80:83]
	v_mfma_f32_16x16x32_bf16 v[72:75], v[180:183], v[208:211], v[72:75]
	v_mfma_f32_16x16x32_bf16 v[68:71], v[172:175], v[216:219], v[68:71]
	v_mfma_f32_16x16x32_bf16 v[64:67], v[180:183], v[216:219], v[64:67]
	s_barrier
	s_add_i32 s62, s83, s65
	v_lshl_add_u64 v[144:145], v[144:145], 0, s[12:13]
	s_mov_b32 m0, s62
	ds_read_b128 v[184:187], v151 offset:49152
	ds_read_b128 v[192:195], v151 offset:50176
	ds_read_b128 v[196:199], v151 offset:51200
	ds_read_b128 v[200:203], v151 offset:52224
	ds_read_b128 v[204:207], v151 offset:53248
	ds_read_b128 v[208:211], v151 offset:54272
	ds_read_b128 v[212:215], v151 offset:55296
	ds_read_b128 v[216:219], v151 offset:56320
	global_load_lds_dwordx4 v[144:145], off
	s_add_i32 m0, s62, 0x2000
	s_add_u32 s60, s60, 0x40080
	v_lshl_add_u64 v[144:145], v[188:189], 0, s[12:13]
	s_addc_u32 s61, s61, 0
	s_add_i32 s62, s84, s65
	global_load_lds_dwordx4 v[144:145], off
	s_mov_b32 m0, s62
	s_nop 0
	global_load_lds_dwordx4 v130, s[60:61]
	s_add_i32 m0, s62, 0x2000
	v_lshl_add_u64 v[144:145], v[220:221], 0, s[12:13]
	global_load_lds_dwordx4 v134, s[60:61]
	s_mov_b32 m0, s69
	s_nop 0
	global_load_lds_dwordx4 v[144:145], off
	s_mov_b32 m0, s70
	v_lshl_add_u64 v[144:145], v[222:223], 0, s[12:13]
	global_load_lds_dwordx4 v[144:145], off
	s_waitcnt vmcnt(8)
	s_waitcnt lgkmcnt(0)
	s_barrier
	v_mfma_f32_16x16x32_bf16 v[60:63], v[152:155], v[184:187], v[60:63]
	v_mfma_f32_16x16x32_bf16 v[56:59], v[160:163], v[184:187], v[56:59]
	v_mfma_f32_16x16x32_bf16 v[52:55], v[152:155], v[196:199], v[52:55]
	v_mfma_f32_16x16x32_bf16 v[44:47], v[160:163], v[196:199], v[44:47]
	v_mfma_f32_16x16x32_bf16 v[36:39], v[152:155], v[204:207], v[36:39]
	v_mfma_f32_16x16x32_bf16 v[28:31], v[160:163], v[204:207], v[28:31]
	v_mfma_f32_16x16x32_bf16 v[20:23], v[152:155], v[212:215], v[20:23]
	v_mfma_f32_16x16x32_bf16 v[12:15], v[160:163], v[212:215], v[12:15]
	v_mfma_f32_16x16x32_bf16 v[60:63], v[156:159], v[192:195], v[60:63]
	v_mfma_f32_16x16x32_bf16 v[56:59], v[164:167], v[192:195], v[56:59]
	v_mfma_f32_16x16x32_bf16 v[52:55], v[156:159], v[200:203], v[52:55]
	v_mfma_f32_16x16x32_bf16 v[44:47], v[164:167], v[200:203], v[44:47]
	v_mfma_f32_16x16x32_bf16 v[36:39], v[156:159], v[208:211], v[36:39]
	v_mfma_f32_16x16x32_bf16 v[28:31], v[164:167], v[208:211], v[28:31]
	v_mfma_f32_16x16x32_bf16 v[20:23], v[156:159], v[216:219], v[20:23]
	v_mfma_f32_16x16x32_bf16 v[12:15], v[164:167], v[216:219], v[12:15]
	v_mfma_f32_16x16x32_bf16 v[48:51], v[168:171], v[184:187], v[48:51]
	v_mfma_f32_16x16x32_bf16 v[40:43], v[176:179], v[184:187], v[40:43]
	v_mfma_f32_16x16x32_bf16 v[32:35], v[168:171], v[196:199], v[32:35]
	v_mfma_f32_16x16x32_bf16 v[24:27], v[176:179], v[196:199], v[24:27]
	v_mfma_f32_16x16x32_bf16 v[16:19], v[168:171], v[204:207], v[16:19]
	v_mfma_f32_16x16x32_bf16 v[8:11], v[176:179], v[204:207], v[8:11]
	v_mfma_f32_16x16x32_bf16 v[4:7], v[168:171], v[212:215], v[4:7]
	v_mfma_f32_16x16x32_bf16 v[0:3], v[176:179], v[212:215], v[0:3]
	v_mfma_f32_16x16x32_bf16 v[48:51], v[172:175], v[192:195], v[48:51]
	v_mfma_f32_16x16x32_bf16 v[40:43], v[180:183], v[192:195], v[40:43]
	v_mfma_f32_16x16x32_bf16 v[32:35], v[172:175], v[200:203], v[32:35]
	v_mfma_f32_16x16x32_bf16 v[24:27], v[180:183], v[200:203], v[24:27]
	v_mfma_f32_16x16x32_bf16 v[16:19], v[172:175], v[208:211], v[16:19]
	v_mfma_f32_16x16x32_bf16 v[8:11], v[180:183], v[208:211], v[8:11]
	v_mfma_f32_16x16x32_bf16 v[4:7], v[172:175], v[216:219], v[4:7]
	v_mfma_f32_16x16x32_bf16 v[0:3], v[180:183], v[216:219], v[0:3]
	s_barrier
	s_add_i32 s82, s82, 2
	s_add_u32 s42, s42, 0x100
	s_addc_u32 s43, s43, 0
	s_add_u32 s80, s80, 0x100
	s_addc_u32 s81, s81, 0
	s_cmp_gt_u32 s82, 13
	s_cbranch_scc0 .LBB0_1077
	s_branch .Lpeel_exit6

.LBB0_1221:
	s_ashr_i32 s21, s20, 31
	s_lshl_b64 s[22:23], s[20:21], 17
	s_add_u32 s22, s70, s22
	s_addc_u32 s23, s71, s23
	s_and_b64 s[24:25], s[0:1], exec
	s_cselect_b32 s21, s23, s31
	s_cselect_b32 s55, s22, s30
	s_ashr_i32 s19, s18, 31
	s_lshl_b64 s[24:25], s[18:19], 17
	s_add_u32 s24, s53, s24
	s_addc_u32 s25, s72, s25
	s_and_b64 s[34:35], s[0:1], exec
	s_cselect_b32 s19, s25, s29
	s_cselect_b32 s85, s24, s28
	s_mov_b32 s60, 0
	s_mov_b64 s[34:35], -1
	s_mov_b64 s[42:43], 0
	s_add_u32 s61, s30, s60
	s_addc_u32 s66, s31, 0
	s_add_u32 s64, s61, 0x100
	s_addc_u32 s65, s66, 0
	s_and_b64 s[62:63], s[42:43], exec
	s_cselect_b32 s63, s21, s65
	s_cselect_b32 s62, s55, s64
	s_add_u32 s60, s28, s60
	s_addc_u32 s64, s29, 0
	s_add_u32 s60, s60, 0x100
	s_addc_u32 s64, s64, 0
	s_and_b64 s[42:43], s[42:43], exec
	s_cselect_b32 s65, s19, s64
	s_cselect_b32 s64, s85, s60
	s_add_u32 s68, s61, 0x10080
	ds_read_b128 v[148:151], v145
	ds_read_b128 v[152:155], v145 offset:1024
	ds_read_b128 v[156:159], v145 offset:2048
	ds_read_b128 v[160:163], v145 offset:3072
	ds_read_b128 v[164:167], v146
	ds_read_b128 v[168:171], v146 offset:1024
	ds_read_b128 v[172:175], v146 offset:2048
	ds_read_b128 v[176:179], v146 offset:3072
	s_addc_u32 s69, s66, 0
	s_add_i32 s95, s81, s73
	s_add_i32 m0, s27, 0xc000
	s_add_i32 s96, s27, 0xe000
	s_add_i32 s92, s95, 0x2000
	s_add_u32 s66, s64, 0x10000
	s_addc_u32 s67, s65, 0
	s_add_i32 s94, s82, s73
	s_add_i32 s93, s94, 0x2000
	s_add_i32 s91, 0, 0x18000
	s_add_i32 s90, 0, 0x1c000
	s_add_u32 s60, s62, 0x10000
	s_addc_u32 s61, s63, 0
	s_add_i32 s89, s91, s73
	s_add_i32 s87, s89, 0x2000
	s_add_u32 s42, s64, 0x10080
	s_addc_u32 s43, s65, 0
	s_add_i32 s88, s90, s73
	s_add_i32 s86, s88, 0x2000
	ds_read_b128 v[180:183], v147
	ds_read_b128 v[184:187], v147 offset:1024
	ds_read_b128 v[192:195], v147 offset:2048
	ds_read_b128 v[196:199], v147 offset:3072
	ds_read_b128 v[200:203], v147 offset:4096
	ds_read_b128 v[204:207], v147 offset:5120
	ds_read_b128 v[208:211], v147 offset:6144
	ds_read_b128 v[212:215], v147 offset:7168
	global_load_lds_dwordx4 v128, s[68:69]
	s_mov_b32 m0, s96
	s_nop 0
	global_load_lds_dwordx4 v132, s[68:69]
	s_waitcnt vmcnt(8)
	s_waitcnt lgkmcnt(0)
	s_barrier
	v_mfma_f32_16x16x32_bf16 v[124:127], v[148:151], v[180:183], 0
	v_mfma_f32_16x16x32_bf16 v[120:123], v[156:159], v[180:183], 0
	v_mfma_f32_16x16x32_bf16 v[116:119], v[148:151], v[192:195], 0
	v_mfma_f32_16x16x32_bf16 v[108:111], v[156:159], v[192:195], 0
	v_mfma_f32_16x16x32_bf16 v[100:103], v[148:151], v[200:203], 0
	v_mfma_f32_16x16x32_bf16 v[92:95], v[156:159], v[200:203], 0
	v_mfma_f32_16x16x32_bf16 v[84:87], v[148:151], v[208:211], 0
	v_mfma_f32_16x16x32_bf16 v[76:79], v[156:159], v[208:211], 0
	v_mfma_f32_16x16x32_bf16 v[124:127], v[152:155], v[184:187], v[124:127]
	v_mfma_f32_16x16x32_bf16 v[120:123], v[160:163], v[184:187], v[120:123]
	v_mfma_f32_16x16x32_bf16 v[116:119], v[152:155], v[196:199], v[116:119]
	v_mfma_f32_16x16x32_bf16 v[108:111], v[160:163], v[196:199], v[108:111]
	v_mfma_f32_16x16x32_bf16 v[100:103], v[152:155], v[204:207], v[100:103]
	v_mfma_f32_16x16x32_bf16 v[92:95], v[160:163], v[204:207], v[92:95]
	v_mfma_f32_16x16x32_bf16 v[84:87], v[152:155], v[212:215], v[84:87]
	v_mfma_f32_16x16x32_bf16 v[76:79], v[160:163], v[212:215], v[76:79]
	v_mfma_f32_16x16x32_bf16 v[112:115], v[164:167], v[180:183], 0
	v_mfma_f32_16x16x32_bf16 v[104:107], v[172:175], v[180:183], 0
	v_mfma_f32_16x16x32_bf16 v[96:99], v[164:167], v[192:195], 0
	v_mfma_f32_16x16x32_bf16 v[88:91], v[172:175], v[192:195], 0
	v_mfma_f32_16x16x32_bf16 v[80:83], v[164:167], v[200:203], 0
	v_mfma_f32_16x16x32_bf16 v[72:75], v[172:175], v[200:203], 0
	v_mfma_f32_16x16x32_bf16 v[68:71], v[164:167], v[208:211], 0
	v_mfma_f32_16x16x32_bf16 v[64:67], v[172:175], v[208:211], 0
	v_mfma_f32_16x16x32_bf16 v[112:115], v[168:171], v[184:187], v[112:115]
	v_mfma_f32_16x16x32_bf16 v[104:107], v[176:179], v[184:187], v[104:107]
	v_mfma_f32_16x16x32_bf16 v[96:99], v[168:171], v[196:199], v[96:99]
	v_mfma_f32_16x16x32_bf16 v[88:91], v[176:179], v[196:199], v[88:91]
	v_mfma_f32_16x16x32_bf16 v[80:83], v[168:171], v[204:207], v[80:83]
	v_mfma_f32_16x16x32_bf16 v[72:75], v[176:179], v[204:207], v[72:75]
	v_mfma_f32_16x16x32_bf16 v[68:71], v[168:171], v[212:215], v[68:71]
	v_mfma_f32_16x16x32_bf16 v[64:67], v[176:179], v[212:215], v[64:67]
	s_barrier
	s_mov_b32 m0, s95
	v_lshl_add_u64 v[140:141], s[64:65], 0, v[130:131]
	ds_read_b128 v[180:183], v147 offset:16384
	ds_read_b128 v[184:187], v147 offset:17408
	ds_read_b128 v[192:195], v147 offset:18432
	ds_read_b128 v[196:199], v147 offset:19456
	ds_read_b128 v[200:203], v147 offset:20480
	ds_read_b128 v[204:207], v147 offset:21504
	ds_read_b128 v[208:211], v147 offset:22528
	ds_read_b128 v[212:215], v147 offset:23552
	global_load_lds_dwordx4 v[140:141], off
	s_mov_b32 m0, s92
	v_lshl_add_u64 v[188:189], s[64:65], 0, v[134:135]
	global_load_lds_dwordx4 v[188:189], off
	s_mov_b32 m0, s94
	v_lshl_add_u64 v[218:219], s[62:63], 0, v[132:133]
	global_load_lds_dwordx4 v130, s[66:67]
	s_mov_b32 m0, s93
	v_lshl_add_u64 v[216:217], s[62:63], 0, v[128:129]
	global_load_lds_dwordx4 v134, s[66:67]
	s_mov_b32 m0, s27
	s_nop 0
	global_load_lds_dwordx4 v[216:217], off
	s_mov_b32 m0, s33
	s_nop 0
	global_load_lds_dwordx4 v[218:219], off
	s_waitcnt vmcnt(8)
	s_waitcnt lgkmcnt(0)
	s_barrier
	v_mfma_f32_16x16x32_bf16 v[60:63], v[148:151], v[180:183], 0
	v_mfma_f32_16x16x32_bf16 v[56:59], v[156:159], v[180:183], 0
	v_mfma_f32_16x16x32_bf16 v[52:55], v[148:151], v[192:195], 0
	v_mfma_f32_16x16x32_bf16 v[44:47], v[156:159], v[192:195], 0
	v_mfma_f32_16x16x32_bf16 v[36:39], v[148:151], v[200:203], 0
	v_mfma_f32_16x16x32_bf16 v[28:31], v[156:159], v[200:203], 0
	v_mfma_f32_16x16x32_bf16 v[20:23], v[148:151], v[208:211], 0
	v_mfma_f32_16x16x32_bf16 v[12:15], v[156:159], v[208:211], 0
	v_mfma_f32_16x16x32_bf16 v[60:63], v[152:155], v[184:187], v[60:63]
	v_mfma_f32_16x16x32_bf16 v[56:59], v[160:163], v[184:187], v[56:59]
	v_mfma_f32_16x16x32_bf16 v[52:55], v[152:155], v[196:199], v[52:55]
	v_mfma_f32_16x16x32_bf16 v[44:47], v[160:163], v[196:199], v[44:47]
	v_mfma_f32_16x16x32_bf16 v[36:39], v[152:155], v[204:207], v[36:39]
	v_mfma_f32_16x16x32_bf16 v[28:31], v[160:163], v[204:207], v[28:31]
	v_mfma_f32_16x16x32_bf16 v[20:23], v[152:155], v[212:215], v[20:23]
	v_mfma_f32_16x16x32_bf16 v[12:15], v[160:163], v[212:215], v[12:15]
	v_mfma_f32_16x16x32_bf16 v[48:51], v[164:167], v[180:183], 0
	v_mfma_f32_16x16x32_bf16 v[40:43], v[172:175], v[180:183], 0
	v_mfma_f32_16x16x32_bf16 v[32:35], v[164:167], v[192:195], 0
	v_mfma_f32_16x16x32_bf16 v[24:27], v[172:175], v[192:195], 0
	v_mfma_f32_16x16x32_bf16 v[16:19], v[164:167], v[200:203], 0
	v_mfma_f32_16x16x32_bf16 v[8:11], v[172:175], v[200:203], 0
	v_mfma_f32_16x16x32_bf16 v[4:7], v[164:167], v[208:211], 0
	v_mfma_f32_16x16x32_bf16 v[0:3], v[172:175], v[208:211], 0
	v_mfma_f32_16x16x32_bf16 v[48:51], v[168:171], v[184:187], v[48:51]
	v_mfma_f32_16x16x32_bf16 v[40:43], v[176:179], v[184:187], v[40:43]
	v_mfma_f32_16x16x32_bf16 v[32:35], v[168:171], v[196:199], v[32:35]
	v_mfma_f32_16x16x32_bf16 v[24:27], v[176:179], v[196:199], v[24:27]
	v_mfma_f32_16x16x32_bf16 v[16:19], v[168:171], v[204:207], v[16:19]
	v_mfma_f32_16x16x32_bf16 v[8:11], v[176:179], v[204:207], v[8:11]
	v_mfma_f32_16x16x32_bf16 v[4:7], v[168:171], v[212:215], v[4:7]
	v_mfma_f32_16x16x32_bf16 v[0:3], v[176:179], v[212:215], v[0:3]
	s_barrier
	v_add_u32_e32 v160, s91, v143
	v_add_u32_e32 v176, s90, v143
	ds_read_b128 v[148:151], v160
	ds_read_b128 v[152:155], v160 offset:1024
	ds_read_b128 v[156:159], v160 offset:2048
	ds_read_b128 v[160:163], v160 offset:3072
	ds_read_b128 v[164:167], v176
	ds_read_b128 v[168:171], v176 offset:1024
	ds_read_b128 v[172:175], v176 offset:2048
	ds_read_b128 v[176:179], v176 offset:3072
	s_mov_b32 m0, s74
	ds_read_b128 v[180:183], v147 offset:32768
	ds_read_b128 v[184:187], v147 offset:33792
	ds_read_b128 v[192:195], v147 offset:34816
	ds_read_b128 v[196:199], v147 offset:35840
	ds_read_b128 v[200:203], v147 offset:36864
	ds_read_b128 v[204:207], v147 offset:37888
	ds_read_b128 v[208:211], v147 offset:38912
	ds_read_b128 v[212:215], v147 offset:39936
	global_load_lds_dwordx4 v128, s[60:61]
	s_mov_b32 m0, s75
	s_nop 0
	global_load_lds_dwordx4 v132, s[60:61]
	s_waitcnt vmcnt(8)
	s_waitcnt lgkmcnt(0)
	s_barrier
	v_mfma_f32_16x16x32_bf16 v[124:127], v[148:151], v[180:183], v[124:127]
	v_mfma_f32_16x16x32_bf16 v[120:123], v[156:159], v[180:183], v[120:123]
	v_mfma_f32_16x16x32_bf16 v[116:119], v[148:151], v[192:195], v[116:119]
	v_mfma_f32_16x16x32_bf16 v[108:111], v[156:159], v[192:195], v[108:111]
	v_mfma_f32_16x16x32_bf16 v[100:103], v[148:151], v[200:203], v[100:103]
	v_mfma_f32_16x16x32_bf16 v[92:95], v[156:159], v[200:203], v[92:95]
	v_mfma_f32_16x16x32_bf16 v[84:87], v[148:151], v[208:211], v[84:87]
	v_mfma_f32_16x16x32_bf16 v[76:79], v[156:159], v[208:211], v[76:79]
	v_mfma_f32_16x16x32_bf16 v[124:127], v[152:155], v[184:187], v[124:127]
	v_mfma_f32_16x16x32_bf16 v[120:123], v[160:163], v[184:187], v[120:123]
	v_mfma_f32_16x16x32_bf16 v[116:119], v[152:155], v[196:199], v[116:119]
	v_mfma_f32_16x16x32_bf16 v[108:111], v[160:163], v[196:199], v[108:111]
	v_mfma_f32_16x16x32_bf16 v[100:103], v[152:155], v[204:207], v[100:103]
	v_mfma_f32_16x16x32_bf16 v[92:95], v[160:163], v[204:207], v[92:95]
	v_mfma_f32_16x16x32_bf16 v[84:87], v[152:155], v[212:215], v[84:87]
	v_mfma_f32_16x16x32_bf16 v[76:79], v[160:163], v[212:215], v[76:79]
	v_mfma_f32_16x16x32_bf16 v[112:115], v[164:167], v[180:183], v[112:115]
	v_mfma_f32_16x16x32_bf16 v[104:107], v[172:175], v[180:183], v[104:107]
	v_mfma_f32_16x16x32_bf16 v[96:99], v[164:167], v[192:195], v[96:99]
	v_mfma_f32_16x16x32_bf16 v[88:91], v[172:175], v[192:195], v[88:91]
	v_mfma_f32_16x16x32_bf16 v[80:83], v[164:167], v[200:203], v[80:83]
	v_mfma_f32_16x16x32_bf16 v[72:75], v[172:175], v[200:203], v[72:75]
	v_mfma_f32_16x16x32_bf16 v[68:71], v[164:167], v[208:211], v[68:71]
	v_mfma_f32_16x16x32_bf16 v[64:67], v[172:175], v[208:211], v[64:67]
	v_mfma_f32_16x16x32_bf16 v[112:115], v[168:171], v[184:187], v[112:115]
	v_mfma_f32_16x16x32_bf16 v[104:107], v[176:179], v[184:187], v[104:107]
	v_mfma_f32_16x16x32_bf16 v[96:99], v[168:171], v[196:199], v[96:99]
	v_mfma_f32_16x16x32_bf16 v[88:91], v[176:179], v[196:199], v[88:91]
	v_mfma_f32_16x16x32_bf16 v[80:83], v[168:171], v[204:207], v[80:83]
	v_mfma_f32_16x16x32_bf16 v[72:75], v[176:179], v[204:207], v[72:75]
	v_mfma_f32_16x16x32_bf16 v[68:71], v[168:171], v[212:215], v[68:71]
	v_mfma_f32_16x16x32_bf16 v[64:67], v[176:179], v[212:215], v[64:67]
	s_barrier
	s_mov_b32 m0, s89
	v_lshl_add_u64 v[140:141], v[140:141], 0, s[12:13]
	ds_read_b128 v[180:183], v147 offset:49152
	ds_read_b128 v[184:187], v147 offset:50176
	ds_read_b128 v[192:195], v147 offset:51200
	ds_read_b128 v[196:199], v147 offset:52224
	ds_read_b128 v[200:203], v147 offset:53248
	ds_read_b128 v[204:207], v147 offset:54272
	ds_read_b128 v[208:211], v147 offset:55296
	ds_read_b128 v[212:215], v147 offset:56320
	global_load_lds_dwordx4 v[140:141], off
	s_mov_b32 m0, s87
	v_lshl_add_u64 v[140:141], v[188:189], 0, s[12:13]
	global_load_lds_dwordx4 v[140:141], off
	s_mov_b32 m0, s88
	s_nop 0
	global_load_lds_dwordx4 v130, s[42:43]
	s_mov_b32 m0, s86
	v_lshl_add_u64 v[140:141], v[216:217], 0, s[12:13]
	global_load_lds_dwordx4 v134, s[42:43]
	s_mov_b32 m0, s77
	s_nop 0
	global_load_lds_dwordx4 v[140:141], off
	s_mov_b32 m0, s79
	v_lshl_add_u64 v[140:141], v[218:219], 0, s[12:13]
	global_load_lds_dwordx4 v[140:141], off
	s_waitcnt vmcnt(8)
	s_waitcnt lgkmcnt(0)
	s_barrier
	v_mfma_f32_16x16x32_bf16 v[60:63], v[148:151], v[180:183], v[60:63]
	v_mfma_f32_16x16x32_bf16 v[56:59], v[156:159], v[180:183], v[56:59]
	v_mfma_f32_16x16x32_bf16 v[52:55], v[148:151], v[192:195], v[52:55]
	v_mfma_f32_16x16x32_bf16 v[44:47], v[156:159], v[192:195], v[44:47]
	v_mfma_f32_16x16x32_bf16 v[36:39], v[148:151], v[200:203], v[36:39]
	v_mfma_f32_16x16x32_bf16 v[28:31], v[156:159], v[200:203], v[28:31]
	v_mfma_f32_16x16x32_bf16 v[20:23], v[148:151], v[208:211], v[20:23]
	v_mfma_f32_16x16x32_bf16 v[12:15], v[156:159], v[208:211], v[12:15]
	v_mfma_f32_16x16x32_bf16 v[60:63], v[152:155], v[184:187], v[60:63]
	v_mfma_f32_16x16x32_bf16 v[56:59], v[160:163], v[184:187], v[56:59]
	v_mfma_f32_16x16x32_bf16 v[52:55], v[152:155], v[196:199], v[52:55]
	v_mfma_f32_16x16x32_bf16 v[44:47], v[160:163], v[196:199], v[44:47]
	v_mfma_f32_16x16x32_bf16 v[36:39], v[152:155], v[204:207], v[36:39]
	v_mfma_f32_16x16x32_bf16 v[28:31], v[160:163], v[204:207], v[28:31]
	v_mfma_f32_16x16x32_bf16 v[20:23], v[152:155], v[212:215], v[20:23]
	v_mfma_f32_16x16x32_bf16 v[12:15], v[160:163], v[212:215], v[12:15]
	v_mfma_f32_16x16x32_bf16 v[48:51], v[164:167], v[180:183], v[48:51]
	v_mfma_f32_16x16x32_bf16 v[40:43], v[172:175], v[180:183], v[40:43]
	v_mfma_f32_16x16x32_bf16 v[32:35], v[164:167], v[192:195], v[32:35]
	v_mfma_f32_16x16x32_bf16 v[24:27], v[172:175], v[192:195], v[24:27]
	v_mfma_f32_16x16x32_bf16 v[16:19], v[164:167], v[200:203], v[16:19]
	v_mfma_f32_16x16x32_bf16 v[8:11], v[172:175], v[200:203], v[8:11]
	v_mfma_f32_16x16x32_bf16 v[4:7], v[164:167], v[208:211], v[4:7]
	v_mfma_f32_16x16x32_bf16 v[0:3], v[172:175], v[208:211], v[0:3]
	v_mfma_f32_16x16x32_bf16 v[48:51], v[168:171], v[184:187], v[48:51]
	v_mfma_f32_16x16x32_bf16 v[40:43], v[176:179], v[184:187], v[40:43]
	v_mfma_f32_16x16x32_bf16 v[32:35], v[168:171], v[196:199], v[32:35]
	v_mfma_f32_16x16x32_bf16 v[24:27], v[176:179], v[196:199], v[24:27]
	v_mfma_f32_16x16x32_bf16 v[16:19], v[168:171], v[204:207], v[16:19]
	v_mfma_f32_16x16x32_bf16 v[8:11], v[176:179], v[204:207], v[8:11]
	v_mfma_f32_16x16x32_bf16 v[4:7], v[168:171], v[212:215], v[4:7]
	v_mfma_f32_16x16x32_bf16 v[0:3], v[176:179], v[212:215], v[0:3]
	s_barrier
	s_movk_i32 s60, 0x100
	s_andn2_b64 vcc, exec, s[34:35]
	s_mov_b64 s[42:43], -1
	s_mov_b64 s[34:35], 0
	s_cbranch_vccz .LBB0_1222
	s_branch .Lpeel_exit7
.LBB0_1222:
	s_add_u32 s61, s30, s60
	s_addc_u32 s66, s31, 0
	s_add_u32 s64, s61, 0x100
	s_addc_u32 s65, s66, 0
	s_and_b64 s[62:63], s[42:43], exec
	s_cselect_b32 s63, s21, s65
	s_cselect_b32 s62, s55, s64
	s_add_u32 s60, s28, s60
	s_addc_u32 s64, s29, 0
	s_add_u32 s60, s60, 0x100
	s_addc_u32 s64, s64, 0
	s_and_b64 s[42:43], s[42:43], exec
	s_cselect_b32 s65, s19, s64
	s_cselect_b32 s64, s85, s60
	s_add_u32 s68, s61, 0x10080
	ds_read_b128 v[148:151], v145
	ds_read_b128 v[152:155], v145 offset:1024
	ds_read_b128 v[156:159], v145 offset:2048
	ds_read_b128 v[160:163], v145 offset:3072
	ds_read_b128 v[164:167], v146
	ds_read_b128 v[168:171], v146 offset:1024
	ds_read_b128 v[172:175], v146 offset:2048
	ds_read_b128 v[176:179], v146 offset:3072
	s_addc_u32 s69, s66, 0
	s_add_i32 s95, s81, s73
	s_add_i32 m0, s27, 0xc000
	s_add_i32 s96, s27, 0xe000
	s_add_i32 s92, s95, 0x2000
	s_add_u32 s66, s64, 0x10000
	s_addc_u32 s67, s65, 0
	s_add_i32 s94, s82, s73
	s_add_i32 s93, s94, 0x2000
	s_add_i32 s91, 0, 0x18000
	s_add_i32 s90, 0, 0x1c000
	s_add_u32 s60, s62, 0x10000
	s_addc_u32 s61, s63, 0
	s_add_i32 s89, s91, s73
	s_add_i32 s87, s89, 0x2000
	s_add_u32 s42, s64, 0x10080
	s_addc_u32 s43, s65, 0
	s_add_i32 s88, s90, s73
	s_add_i32 s86, s88, 0x2000
	ds_read_b128 v[180:183], v147
	ds_read_b128 v[184:187], v147 offset:1024
	ds_read_b128 v[192:195], v147 offset:2048
	ds_read_b128 v[196:199], v147 offset:3072
	ds_read_b128 v[200:203], v147 offset:4096
	ds_read_b128 v[204:207], v147 offset:5120
	ds_read_b128 v[208:211], v147 offset:6144
	ds_read_b128 v[212:215], v147 offset:7168
	global_load_lds_dwordx4 v128, s[68:69]
	s_mov_b32 m0, s96
	s_nop 0
	global_load_lds_dwordx4 v132, s[68:69]
	s_waitcnt vmcnt(8)
	s_waitcnt lgkmcnt(0)
	s_barrier
	v_mfma_f32_16x16x32_bf16 v[124:127], v[148:151], v[180:183], v[124:127]
	v_mfma_f32_16x16x32_bf16 v[120:123], v[156:159], v[180:183], v[120:123]
	v_mfma_f32_16x16x32_bf16 v[116:119], v[148:151], v[192:195], v[116:119]
	v_mfma_f32_16x16x32_bf16 v[108:111], v[156:159], v[192:195], v[108:111]
	v_mfma_f32_16x16x32_bf16 v[100:103], v[148:151], v[200:203], v[100:103]
	v_mfma_f32_16x16x32_bf16 v[92:95], v[156:159], v[200:203], v[92:95]
	v_mfma_f32_16x16x32_bf16 v[84:87], v[148:151], v[208:211], v[84:87]
	v_mfma_f32_16x16x32_bf16 v[76:79], v[156:159], v[208:211], v[76:79]
	v_mfma_f32_16x16x32_bf16 v[124:127], v[152:155], v[184:187], v[124:127]
	v_mfma_f32_16x16x32_bf16 v[120:123], v[160:163], v[184:187], v[120:123]
	v_mfma_f32_16x16x32_bf16 v[116:119], v[152:155], v[196:199], v[116:119]
	v_mfma_f32_16x16x32_bf16 v[108:111], v[160:163], v[196:199], v[108:111]
	v_mfma_f32_16x16x32_bf16 v[100:103], v[152:155], v[204:207], v[100:103]
	v_mfma_f32_16x16x32_bf16 v[92:95], v[160:163], v[204:207], v[92:95]
	v_mfma_f32_16x16x32_bf16 v[84:87], v[152:155], v[212:215], v[84:87]
	v_mfma_f32_16x16x32_bf16 v[76:79], v[160:163], v[212:215], v[76:79]
	v_mfma_f32_16x16x32_bf16 v[112:115], v[164:167], v[180:183], v[112:115]
	v_mfma_f32_16x16x32_bf16 v[104:107], v[172:175], v[180:183], v[104:107]
	v_mfma_f32_16x16x32_bf16 v[96:99], v[164:167], v[192:195], v[96:99]
	v_mfma_f32_16x16x32_bf16 v[88:91], v[172:175], v[192:195], v[88:91]
	v_mfma_f32_16x16x32_bf16 v[80:83], v[164:167], v[200:203], v[80:83]
	v_mfma_f32_16x16x32_bf16 v[72:75], v[172:175], v[200:203], v[72:75]
	v_mfma_f32_16x16x32_bf16 v[68:71], v[164:167], v[208:211], v[68:71]
	v_mfma_f32_16x16x32_bf16 v[64:67], v[172:175], v[208:211], v[64:67]
	v_mfma_f32_16x16x32_bf16 v[112:115], v[168:171], v[184:187], v[112:115]
	v_mfma_f32_16x16x32_bf16 v[104:107], v[176:179], v[184:187], v[104:107]
	v_mfma_f32_16x16x32_bf16 v[96:99], v[168:171], v[196:199], v[96:99]
	v_mfma_f32_16x16x32_bf16 v[88:91], v[176:179], v[196:199], v[88:91]
	v_mfma_f32_16x16x32_bf16 v[80:83], v[168:171], v[204:207], v[80:83]
	v_mfma_f32_16x16x32_bf16 v[72:75], v[176:179], v[204:207], v[72:75]
	v_mfma_f32_16x16x32_bf16 v[68:71], v[168:171], v[212:215], v[68:71]
	v_mfma_f32_16x16x32_bf16 v[64:67], v[176:179], v[212:215], v[64:67]
	s_barrier
	s_mov_b32 m0, s95
	v_lshl_add_u64 v[140:141], s[64:65], 0, v[130:131]
	ds_read_b128 v[180:183], v147 offset:16384
	ds_read_b128 v[184:187], v147 offset:17408
	ds_read_b128 v[192:195], v147 offset:18432
	ds_read_b128 v[196:199], v147 offset:19456
	ds_read_b128 v[200:203], v147 offset:20480
	ds_read_b128 v[204:207], v147 offset:21504
	ds_read_b128 v[208:211], v147 offset:22528
	ds_read_b128 v[212:215], v147 offset:23552
	global_load_lds_dwordx4 v[140:141], off
	s_mov_b32 m0, s92
	v_lshl_add_u64 v[188:189], s[64:65], 0, v[134:135]
	global_load_lds_dwordx4 v[188:189], off
	s_mov_b32 m0, s94
	v_lshl_add_u64 v[218:219], s[62:63], 0, v[132:133]
	global_load_lds_dwordx4 v130, s[66:67]
	s_mov_b32 m0, s93
	v_lshl_add_u64 v[216:217], s[62:63], 0, v[128:129]
	global_load_lds_dwordx4 v134, s[66:67]
	s_mov_b32 m0, s27
	s_nop 0
	global_load_lds_dwordx4 v[216:217], off
	s_mov_b32 m0, s33
	s_nop 0
	global_load_lds_dwordx4 v[218:219], off
	s_waitcnt vmcnt(8)
	s_waitcnt lgkmcnt(0)
	s_barrier
	v_mfma_f32_16x16x32_bf16 v[60:63], v[148:151], v[180:183], v[60:63]
	v_mfma_f32_16x16x32_bf16 v[56:59], v[156:159], v[180:183], v[56:59]
	v_mfma_f32_16x16x32_bf16 v[52:55], v[148:151], v[192:195], v[52:55]
	v_mfma_f32_16x16x32_bf16 v[44:47], v[156:159], v[192:195], v[44:47]
	v_mfma_f32_16x16x32_bf16 v[36:39], v[148:151], v[200:203], v[36:39]
	v_mfma_f32_16x16x32_bf16 v[28:31], v[156:159], v[200:203], v[28:31]
	v_mfma_f32_16x16x32_bf16 v[20:23], v[148:151], v[208:211], v[20:23]
	v_mfma_f32_16x16x32_bf16 v[12:15], v[156:159], v[208:211], v[12:15]
	v_mfma_f32_16x16x32_bf16 v[60:63], v[152:155], v[184:187], v[60:63]
	v_mfma_f32_16x16x32_bf16 v[56:59], v[160:163], v[184:187], v[56:59]
	v_mfma_f32_16x16x32_bf16 v[52:55], v[152:155], v[196:199], v[52:55]
	v_mfma_f32_16x16x32_bf16 v[44:47], v[160:163], v[196:199], v[44:47]
	v_mfma_f32_16x16x32_bf16 v[36:39], v[152:155], v[204:207], v[36:39]
	v_mfma_f32_16x16x32_bf16 v[28:31], v[160:163], v[204:207], v[28:31]
	v_mfma_f32_16x16x32_bf16 v[20:23], v[152:155], v[212:215], v[20:23]
	v_mfma_f32_16x16x32_bf16 v[12:15], v[160:163], v[212:215], v[12:15]
	v_mfma_f32_16x16x32_bf16 v[48:51], v[164:167], v[180:183], v[48:51]
	v_mfma_f32_16x16x32_bf16 v[40:43], v[172:175], v[180:183], v[40:43]
	v_mfma_f32_16x16x32_bf16 v[32:35], v[164:167], v[192:195], v[32:35]
	v_mfma_f32_16x16x32_bf16 v[24:27], v[172:175], v[192:195], v[24:27]
	v_mfma_f32_16x16x32_bf16 v[16:19], v[164:167], v[200:203], v[16:19]
	v_mfma_f32_16x16x32_bf16 v[8:11], v[172:175], v[200:203], v[8:11]
	v_mfma_f32_16x16x32_bf16 v[4:7], v[164:167], v[208:211], v[4:7]
	v_mfma_f32_16x16x32_bf16 v[0:3], v[172:175], v[208:211], v[0:3]
	v_mfma_f32_16x16x32_bf16 v[48:51], v[168:171], v[184:187], v[48:51]
	v_mfma_f32_16x16x32_bf16 v[40:43], v[176:179], v[184:187], v[40:43]
	v_mfma_f32_16x16x32_bf16 v[32:35], v[168:171], v[196:199], v[32:35]
	v_mfma_f32_16x16x32_bf16 v[24:27], v[176:179], v[196:199], v[24:27]
	v_mfma_f32_16x16x32_bf16 v[16:19], v[168:171], v[204:207], v[16:19]
	v_mfma_f32_16x16x32_bf16 v[8:11], v[176:179], v[204:207], v[8:11]
	v_mfma_f32_16x16x32_bf16 v[4:7], v[168:171], v[212:215], v[4:7]
	v_mfma_f32_16x16x32_bf16 v[0:3], v[176:179], v[212:215], v[0:3]
	s_barrier
	v_add_u32_e32 v160, s91, v143
	v_add_u32_e32 v176, s90, v143
	ds_read_b128 v[148:151], v160
	ds_read_b128 v[152:155], v160 offset:1024
	ds_read_b128 v[156:159], v160 offset:2048
	ds_read_b128 v[160:163], v160 offset:3072
	ds_read_b128 v[164:167], v176
	ds_read_b128 v[168:171], v176 offset:1024
	ds_read_b128 v[172:175], v176 offset:2048
	ds_read_b128 v[176:179], v176 offset:3072
	s_mov_b32 m0, s74
	ds_read_b128 v[180:183], v147 offset:32768
	ds_read_b128 v[184:187], v147 offset:33792
	ds_read_b128 v[192:195], v147 offset:34816
	ds_read_b128 v[196:199], v147 offset:35840
	ds_read_b128 v[200:203], v147 offset:36864
	ds_read_b128 v[204:207], v147 offset:37888
	ds_read_b128 v[208:211], v147 offset:38912
	ds_read_b128 v[212:215], v147 offset:39936
	global_load_lds_dwordx4 v128, s[60:61]
	s_mov_b32 m0, s75
	s_nop 0
	global_load_lds_dwordx4 v132, s[60:61]
	s_waitcnt vmcnt(8)
	s_waitcnt lgkmcnt(0)
	s_barrier
	v_mfma_f32_16x16x32_bf16 v[124:127], v[148:151], v[180:183], v[124:127]
	v_mfma_f32_16x16x32_bf16 v[120:123], v[156:159], v[180:183], v[120:123]
	v_mfma_f32_16x16x32_bf16 v[116:119], v[148:151], v[192:195], v[116:119]
	v_mfma_f32_16x16x32_bf16 v[108:111], v[156:159], v[192:195], v[108:111]
	v_mfma_f32_16x16x32_bf16 v[100:103], v[148:151], v[200:203], v[100:103]
	v_mfma_f32_16x16x32_bf16 v[92:95], v[156:159], v[200:203], v[92:95]
	v_mfma_f32_16x16x32_bf16 v[84:87], v[148:151], v[208:211], v[84:87]
	v_mfma_f32_16x16x32_bf16 v[76:79], v[156:159], v[208:211], v[76:79]
	v_mfma_f32_16x16x32_bf16 v[124:127], v[152:155], v[184:187], v[124:127]
	v_mfma_f32_16x16x32_bf16 v[120:123], v[160:163], v[184:187], v[120:123]
	v_mfma_f32_16x16x32_bf16 v[116:119], v[152:155], v[196:199], v[116:119]
	v_mfma_f32_16x16x32_bf16 v[108:111], v[160:163], v[196:199], v[108:111]
	v_mfma_f32_16x16x32_bf16 v[100:103], v[152:155], v[204:207], v[100:103]
	v_mfma_f32_16x16x32_bf16 v[92:95], v[160:163], v[204:207], v[92:95]
	v_mfma_f32_16x16x32_bf16 v[84:87], v[152:155], v[212:215], v[84:87]
	v_mfma_f32_16x16x32_bf16 v[76:79], v[160:163], v[212:215], v[76:79]
	v_mfma_f32_16x16x32_bf16 v[112:115], v[164:167], v[180:183], v[112:115]
	v_mfma_f32_16x16x32_bf16 v[104:107], v[172:175], v[180:183], v[104:107]
	v_mfma_f32_16x16x32_bf16 v[96:99], v[164:167], v[192:195], v[96:99]
	v_mfma_f32_16x16x32_bf16 v[88:91], v[172:175], v[192:195], v[88:91]
	v_mfma_f32_16x16x32_bf16 v[80:83], v[164:167], v[200:203], v[80:83]
	v_mfma_f32_16x16x32_bf16 v[72:75], v[172:175], v[200:203], v[72:75]
	v_mfma_f32_16x16x32_bf16 v[68:71], v[164:167], v[208:211], v[68:71]
	v_mfma_f32_16x16x32_bf16 v[64:67], v[172:175], v[208:211], v[64:67]
	v_mfma_f32_16x16x32_bf16 v[112:115], v[168:171], v[184:187], v[112:115]
	v_mfma_f32_16x16x32_bf16 v[104:107], v[176:179], v[184:187], v[104:107]
	v_mfma_f32_16x16x32_bf16 v[96:99], v[168:171], v[196:199], v[96:99]
	v_mfma_f32_16x16x32_bf16 v[88:91], v[176:179], v[196:199], v[88:91]
	v_mfma_f32_16x16x32_bf16 v[80:83], v[168:171], v[204:207], v[80:83]
	v_mfma_f32_16x16x32_bf16 v[72:75], v[176:179], v[204:207], v[72:75]
	v_mfma_f32_16x16x32_bf16 v[68:71], v[168:171], v[212:215], v[68:71]
	v_mfma_f32_16x16x32_bf16 v[64:67], v[176:179], v[212:215], v[64:67]
	s_barrier
	s_mov_b32 m0, s89
	v_lshl_add_u64 v[140:141], v[140:141], 0, s[12:13]
	ds_read_b128 v[180:183], v147 offset:49152
	ds_read_b128 v[184:187], v147 offset:50176
	ds_read_b128 v[192:195], v147 offset:51200
	ds_read_b128 v[196:199], v147 offset:52224
	ds_read_b128 v[200:203], v147 offset:53248
	ds_read_b128 v[204:207], v147 offset:54272
	ds_read_b128 v[208:211], v147 offset:55296
	ds_read_b128 v[212:215], v147 offset:56320
	global_load_lds_dwordx4 v[140:141], off
	s_mov_b32 m0, s87
	v_lshl_add_u64 v[140:141], v[188:189], 0, s[12:13]
	global_load_lds_dwordx4 v[140:141], off
	s_mov_b32 m0, s88
	s_nop 0
	global_load_lds_dwordx4 v130, s[42:43]
	s_mov_b32 m0, s86
	v_lshl_add_u64 v[140:141], v[216:217], 0, s[12:13]
	global_load_lds_dwordx4 v134, s[42:43]
	s_mov_b32 m0, s77
	s_nop 0
	global_load_lds_dwordx4 v[140:141], off
	s_mov_b32 m0, s79
	v_lshl_add_u64 v[140:141], v[218:219], 0, s[12:13]
	global_load_lds_dwordx4 v[140:141], off
	s_waitcnt vmcnt(8)
	s_waitcnt lgkmcnt(0)
	s_barrier
	v_mfma_f32_16x16x32_bf16 v[60:63], v[148:151], v[180:183], v[60:63]
	v_mfma_f32_16x16x32_bf16 v[56:59], v[156:159], v[180:183], v[56:59]
	v_mfma_f32_16x16x32_bf16 v[52:55], v[148:151], v[192:195], v[52:55]
	v_mfma_f32_16x16x32_bf16 v[44:47], v[156:159], v[192:195], v[44:47]
	v_mfma_f32_16x16x32_bf16 v[36:39], v[148:151], v[200:203], v[36:39]
	v_mfma_f32_16x16x32_bf16 v[28:31], v[156:159], v[200:203], v[28:31]
	v_mfma_f32_16x16x32_bf16 v[20:23], v[148:151], v[208:211], v[20:23]
	v_mfma_f32_16x16x32_bf16 v[12:15], v[156:159], v[208:211], v[12:15]
	v_mfma_f32_16x16x32_bf16 v[60:63], v[152:155], v[184:187], v[60:63]
	v_mfma_f32_16x16x32_bf16 v[56:59], v[160:163], v[184:187], v[56:59]
	v_mfma_f32_16x16x32_bf16 v[52:55], v[152:155], v[196:199], v[52:55]
	v_mfma_f32_16x16x32_bf16 v[44:47], v[160:163], v[196:199], v[44:47]
	v_mfma_f32_16x16x32_bf16 v[36:39], v[152:155], v[204:207], v[36:39]
	v_mfma_f32_16x16x32_bf16 v[28:31], v[160:163], v[204:207], v[28:31]
	v_mfma_f32_16x16x32_bf16 v[20:23], v[152:155], v[212:215], v[20:23]
	v_mfma_f32_16x16x32_bf16 v[12:15], v[160:163], v[212:215], v[12:15]
	v_mfma_f32_16x16x32_bf16 v[48:51], v[164:167], v[180:183], v[48:51]
	v_mfma_f32_16x16x32_bf16 v[40:43], v[172:175], v[180:183], v[40:43]
	v_mfma_f32_16x16x32_bf16 v[32:35], v[164:167], v[192:195], v[32:35]
	v_mfma_f32_16x16x32_bf16 v[24:27], v[172:175], v[192:195], v[24:27]
	v_mfma_f32_16x16x32_bf16 v[16:19], v[164:167], v[200:203], v[16:19]
	v_mfma_f32_16x16x32_bf16 v[8:11], v[172:175], v[200:203], v[8:11]
	v_mfma_f32_16x16x32_bf16 v[4:7], v[164:167], v[208:211], v[4:7]
	v_mfma_f32_16x16x32_bf16 v[0:3], v[172:175], v[208:211], v[0:3]
	v_mfma_f32_16x16x32_bf16 v[48:51], v[168:171], v[184:187], v[48:51]
	v_mfma_f32_16x16x32_bf16 v[40:43], v[176:179], v[184:187], v[40:43]
	v_mfma_f32_16x16x32_bf16 v[32:35], v[168:171], v[196:199], v[32:35]
	v_mfma_f32_16x16x32_bf16 v[24:27], v[176:179], v[196:199], v[24:27]
	v_mfma_f32_16x16x32_bf16 v[16:19], v[168:171], v[204:207], v[16:19]
	v_mfma_f32_16x16x32_bf16 v[8:11], v[176:179], v[204:207], v[8:11]
	v_mfma_f32_16x16x32_bf16 v[4:7], v[168:171], v[212:215], v[4:7]
	v_mfma_f32_16x16x32_bf16 v[0:3], v[176:179], v[212:215], v[0:3]
	s_barrier
	s_movk_i32 s60, 0x100
	s_andn2_b64 vcc, exec, s[34:35]
	s_mov_b64 s[42:43], -1
	s_mov_b64 s[34:35], 0
	s_cbranch_vccz .LBB0_1222

.LBB0_1245:
	s_ashr_i32 s21, s20, 31
	s_lshl_b64 s[22:23], s[20:21], 17
	s_add_u32 s22, s52, s22
	s_addc_u32 s23, s53, s23
	s_and_b64 s[24:25], s[0:1], exec
	s_cselect_b32 s21, s23, s31
	s_cselect_b32 s55, s22, s30
	s_ashr_i32 s19, s18, 31
	s_lshl_b64 s[24:25], s[18:19], 17
	s_add_u32 s24, s70, s24
	s_addc_u32 s25, s71, s25
	s_and_b64 s[34:35], s[0:1], exec
	s_cselect_b32 s19, s25, s29
	s_cselect_b32 s86, s24, s28
	s_mov_b32 s60, 0
	s_mov_b64 s[34:35], -1
	s_mov_b64 s[42:43], 0
	s_add_u32 s61, s30, s60
	s_addc_u32 s66, s31, 0
	s_add_u32 s64, s61, 0x100
	s_addc_u32 s65, s66, 0
	s_and_b64 s[62:63], s[42:43], exec
	s_cselect_b32 s63, s21, s65
	s_cselect_b32 s62, s55, s64
	s_add_u32 s60, s28, s60
	s_addc_u32 s64, s29, 0
	s_add_u32 s60, s60, 0x100
	s_addc_u32 s64, s64, 0
	s_and_b64 s[42:43], s[42:43], exec
	s_cselect_b32 s65, s19, s64
	s_cselect_b32 s64, s86, s60
	s_add_u32 s68, s61, 0x10080
	ds_read_b128 v[148:151], v145
	ds_read_b128 v[152:155], v145 offset:1024
	ds_read_b128 v[156:159], v145 offset:2048
	ds_read_b128 v[160:163], v145 offset:3072
	ds_read_b128 v[164:167], v146
	ds_read_b128 v[168:171], v146 offset:1024
	ds_read_b128 v[172:175], v146 offset:2048
	ds_read_b128 v[176:179], v146 offset:3072
	s_addc_u32 s69, s66, 0
	s_add_i32 s96, s81, s73
	s_add_i32 m0, s27, 0xc000
	s_add_i32 s97, s27, 0xe000
	s_add_i32 s93, s96, 0x2000
	s_add_u32 s66, s64, 0x10000
	s_addc_u32 s67, s65, 0
	s_add_i32 s95, s82, s73
	s_add_i32 s94, s95, 0x2000
	s_add_i32 s92, 0, 0x18000
	s_add_i32 s91, 0, 0x1c000
	s_add_u32 s60, s62, 0x10000
	s_addc_u32 s61, s63, 0
	s_add_i32 s90, s92, s73
	s_add_i32 s88, s90, 0x2000
	s_add_u32 s42, s64, 0x10080
	s_addc_u32 s43, s65, 0
	s_add_i32 s89, s91, s73
	s_add_i32 s87, s89, 0x2000
	ds_read_b128 v[180:183], v147
	ds_read_b128 v[184:187], v147 offset:1024
	ds_read_b128 v[192:195], v147 offset:2048
	ds_read_b128 v[196:199], v147 offset:3072
	ds_read_b128 v[200:203], v147 offset:4096
	ds_read_b128 v[204:207], v147 offset:5120
	ds_read_b128 v[208:211], v147 offset:6144
	ds_read_b128 v[212:215], v147 offset:7168
	global_load_lds_dwordx4 v128, s[68:69]
	s_mov_b32 m0, s97
	s_nop 0
	global_load_lds_dwordx4 v132, s[68:69]
	s_waitcnt vmcnt(8)
	s_waitcnt lgkmcnt(0)
	s_barrier
	v_mfma_f32_16x16x32_bf16 v[124:127], v[148:151], v[180:183], 0
	v_mfma_f32_16x16x32_bf16 v[120:123], v[156:159], v[180:183], 0
	v_mfma_f32_16x16x32_bf16 v[116:119], v[148:151], v[192:195], 0
	v_mfma_f32_16x16x32_bf16 v[108:111], v[156:159], v[192:195], 0
	v_mfma_f32_16x16x32_bf16 v[100:103], v[148:151], v[200:203], 0
	v_mfma_f32_16x16x32_bf16 v[92:95], v[156:159], v[200:203], 0
	v_mfma_f32_16x16x32_bf16 v[84:87], v[148:151], v[208:211], 0
	v_mfma_f32_16x16x32_bf16 v[76:79], v[156:159], v[208:211], 0
	v_mfma_f32_16x16x32_bf16 v[124:127], v[152:155], v[184:187], v[124:127]
	v_mfma_f32_16x16x32_bf16 v[120:123], v[160:163], v[184:187], v[120:123]
	v_mfma_f32_16x16x32_bf16 v[116:119], v[152:155], v[196:199], v[116:119]
	v_mfma_f32_16x16x32_bf16 v[108:111], v[160:163], v[196:199], v[108:111]
	v_mfma_f32_16x16x32_bf16 v[100:103], v[152:155], v[204:207], v[100:103]
	v_mfma_f32_16x16x32_bf16 v[92:95], v[160:163], v[204:207], v[92:95]
	v_mfma_f32_16x16x32_bf16 v[84:87], v[152:155], v[212:215], v[84:87]
	v_mfma_f32_16x16x32_bf16 v[76:79], v[160:163], v[212:215], v[76:79]
	v_mfma_f32_16x16x32_bf16 v[112:115], v[164:167], v[180:183], 0
	v_mfma_f32_16x16x32_bf16 v[104:107], v[172:175], v[180:183], 0
	v_mfma_f32_16x16x32_bf16 v[96:99], v[164:167], v[192:195], 0
	v_mfma_f32_16x16x32_bf16 v[88:91], v[172:175], v[192:195], 0
	v_mfma_f32_16x16x32_bf16 v[80:83], v[164:167], v[200:203], 0
	v_mfma_f32_16x16x32_bf16 v[72:75], v[172:175], v[200:203], 0
	v_mfma_f32_16x16x32_bf16 v[68:71], v[164:167], v[208:211], 0
	v_mfma_f32_16x16x32_bf16 v[64:67], v[172:175], v[208:211], 0
	v_mfma_f32_16x16x32_bf16 v[112:115], v[168:171], v[184:187], v[112:115]
	v_mfma_f32_16x16x32_bf16 v[104:107], v[176:179], v[184:187], v[104:107]
	v_mfma_f32_16x16x32_bf16 v[96:99], v[168:171], v[196:199], v[96:99]
	v_mfma_f32_16x16x32_bf16 v[88:91], v[176:179], v[196:199], v[88:91]
	v_mfma_f32_16x16x32_bf16 v[80:83], v[168:171], v[204:207], v[80:83]
	v_mfma_f32_16x16x32_bf16 v[72:75], v[176:179], v[204:207], v[72:75]
	v_mfma_f32_16x16x32_bf16 v[68:71], v[168:171], v[212:215], v[68:71]
	v_mfma_f32_16x16x32_bf16 v[64:67], v[176:179], v[212:215], v[64:67]
	s_barrier
	s_mov_b32 m0, s96
	v_lshl_add_u64 v[140:141], s[64:65], 0, v[130:131]
	ds_read_b128 v[180:183], v147 offset:16384
	ds_read_b128 v[184:187], v147 offset:17408
	ds_read_b128 v[192:195], v147 offset:18432
	ds_read_b128 v[196:199], v147 offset:19456
	ds_read_b128 v[200:203], v147 offset:20480
	ds_read_b128 v[204:207], v147 offset:21504
	ds_read_b128 v[208:211], v147 offset:22528
	ds_read_b128 v[212:215], v147 offset:23552
	global_load_lds_dwordx4 v[140:141], off
	s_mov_b32 m0, s93
	v_lshl_add_u64 v[188:189], s[64:65], 0, v[134:135]
	global_load_lds_dwordx4 v[188:189], off
	s_mov_b32 m0, s95
	v_lshl_add_u64 v[218:219], s[62:63], 0, v[132:133]
	global_load_lds_dwordx4 v130, s[66:67]
	s_mov_b32 m0, s94
	v_lshl_add_u64 v[216:217], s[62:63], 0, v[128:129]
	global_load_lds_dwordx4 v134, s[66:67]
	s_mov_b32 m0, s27
	s_nop 0
	global_load_lds_dwordx4 v[216:217], off
	s_mov_b32 m0, s33
	s_nop 0
	global_load_lds_dwordx4 v[218:219], off
	s_waitcnt vmcnt(8)
	s_waitcnt lgkmcnt(0)
	s_barrier
	v_mfma_f32_16x16x32_bf16 v[60:63], v[148:151], v[180:183], 0
	v_mfma_f32_16x16x32_bf16 v[56:59], v[156:159], v[180:183], 0
	v_mfma_f32_16x16x32_bf16 v[52:55], v[148:151], v[192:195], 0
	v_mfma_f32_16x16x32_bf16 v[44:47], v[156:159], v[192:195], 0
	v_mfma_f32_16x16x32_bf16 v[36:39], v[148:151], v[200:203], 0
	v_mfma_f32_16x16x32_bf16 v[28:31], v[156:159], v[200:203], 0
	v_mfma_f32_16x16x32_bf16 v[20:23], v[148:151], v[208:211], 0
	v_mfma_f32_16x16x32_bf16 v[12:15], v[156:159], v[208:211], 0
	v_mfma_f32_16x16x32_bf16 v[60:63], v[152:155], v[184:187], v[60:63]
	v_mfma_f32_16x16x32_bf16 v[56:59], v[160:163], v[184:187], v[56:59]
	v_mfma_f32_16x16x32_bf16 v[52:55], v[152:155], v[196:199], v[52:55]
	v_mfma_f32_16x16x32_bf16 v[44:47], v[160:163], v[196:199], v[44:47]
	v_mfma_f32_16x16x32_bf16 v[36:39], v[152:155], v[204:207], v[36:39]
	v_mfma_f32_16x16x32_bf16 v[28:31], v[160:163], v[204:207], v[28:31]
	v_mfma_f32_16x16x32_bf16 v[20:23], v[152:155], v[212:215], v[20:23]
	v_mfma_f32_16x16x32_bf16 v[12:15], v[160:163], v[212:215], v[12:15]
	v_mfma_f32_16x16x32_bf16 v[48:51], v[164:167], v[180:183], 0
	v_mfma_f32_16x16x32_bf16 v[40:43], v[172:175], v[180:183], 0
	v_mfma_f32_16x16x32_bf16 v[32:35], v[164:167], v[192:195], 0
	v_mfma_f32_16x16x32_bf16 v[24:27], v[172:175], v[192:195], 0
	v_mfma_f32_16x16x32_bf16 v[16:19], v[164:167], v[200:203], 0
	v_mfma_f32_16x16x32_bf16 v[8:11], v[172:175], v[200:203], 0
	v_mfma_f32_16x16x32_bf16 v[4:7], v[164:167], v[208:211], 0
	v_mfma_f32_16x16x32_bf16 v[0:3], v[172:175], v[208:211], 0
	v_mfma_f32_16x16x32_bf16 v[48:51], v[168:171], v[184:187], v[48:51]
	v_mfma_f32_16x16x32_bf16 v[40:43], v[176:179], v[184:187], v[40:43]
	v_mfma_f32_16x16x32_bf16 v[32:35], v[168:171], v[196:199], v[32:35]
	v_mfma_f32_16x16x32_bf16 v[24:27], v[176:179], v[196:199], v[24:27]
	v_mfma_f32_16x16x32_bf16 v[16:19], v[168:171], v[204:207], v[16:19]
	v_mfma_f32_16x16x32_bf16 v[8:11], v[176:179], v[204:207], v[8:11]
	v_mfma_f32_16x16x32_bf16 v[4:7], v[168:171], v[212:215], v[4:7]
	v_mfma_f32_16x16x32_bf16 v[0:3], v[176:179], v[212:215], v[0:3]
	s_barrier
	v_add_u32_e32 v160, s92, v143
	v_add_u32_e32 v176, s91, v143
	ds_read_b128 v[148:151], v160
	ds_read_b128 v[152:155], v160 offset:1024
	ds_read_b128 v[156:159], v160 offset:2048
	ds_read_b128 v[160:163], v160 offset:3072
	ds_read_b128 v[164:167], v176
	ds_read_b128 v[168:171], v176 offset:1024
	ds_read_b128 v[172:175], v176 offset:2048
	ds_read_b128 v[176:179], v176 offset:3072
	s_mov_b32 m0, s74
	ds_read_b128 v[180:183], v147 offset:32768
	ds_read_b128 v[184:187], v147 offset:33792
	ds_read_b128 v[192:195], v147 offset:34816
	ds_read_b128 v[196:199], v147 offset:35840
	ds_read_b128 v[200:203], v147 offset:36864
	ds_read_b128 v[204:207], v147 offset:37888
	ds_read_b128 v[208:211], v147 offset:38912
	ds_read_b128 v[212:215], v147 offset:39936
	global_load_lds_dwordx4 v128, s[60:61]
	s_mov_b32 m0, s75
	s_nop 0
	global_load_lds_dwordx4 v132, s[60:61]
	s_waitcnt vmcnt(8)
	s_waitcnt lgkmcnt(0)
	s_barrier
	v_mfma_f32_16x16x32_bf16 v[124:127], v[148:151], v[180:183], v[124:127]
	v_mfma_f32_16x16x32_bf16 v[120:123], v[156:159], v[180:183], v[120:123]
	v_mfma_f32_16x16x32_bf16 v[116:119], v[148:151], v[192:195], v[116:119]
	v_mfma_f32_16x16x32_bf16 v[108:111], v[156:159], v[192:195], v[108:111]
	v_mfma_f32_16x16x32_bf16 v[100:103], v[148:151], v[200:203], v[100:103]
	v_mfma_f32_16x16x32_bf16 v[92:95], v[156:159], v[200:203], v[92:95]
	v_mfma_f32_16x16x32_bf16 v[84:87], v[148:151], v[208:211], v[84:87]
	v_mfma_f32_16x16x32_bf16 v[76:79], v[156:159], v[208:211], v[76:79]
	v_mfma_f32_16x16x32_bf16 v[124:127], v[152:155], v[184:187], v[124:127]
	v_mfma_f32_16x16x32_bf16 v[120:123], v[160:163], v[184:187], v[120:123]
	v_mfma_f32_16x16x32_bf16 v[116:119], v[152:155], v[196:199], v[116:119]
	v_mfma_f32_16x16x32_bf16 v[108:111], v[160:163], v[196:199], v[108:111]
	v_mfma_f32_16x16x32_bf16 v[100:103], v[152:155], v[204:207], v[100:103]
	v_mfma_f32_16x16x32_bf16 v[92:95], v[160:163], v[204:207], v[92:95]
	v_mfma_f32_16x16x32_bf16 v[84:87], v[152:155], v[212:215], v[84:87]
	v_mfma_f32_16x16x32_bf16 v[76:79], v[160:163], v[212:215], v[76:79]
	v_mfma_f32_16x16x32_bf16 v[112:115], v[164:167], v[180:183], v[112:115]
	v_mfma_f32_16x16x32_bf16 v[104:107], v[172:175], v[180:183], v[104:107]
	v_mfma_f32_16x16x32_bf16 v[96:99], v[164:167], v[192:195], v[96:99]
	v_mfma_f32_16x16x32_bf16 v[88:91], v[172:175], v[192:195], v[88:91]
	v_mfma_f32_16x16x32_bf16 v[80:83], v[164:167], v[200:203], v[80:83]
	v_mfma_f32_16x16x32_bf16 v[72:75], v[172:175], v[200:203], v[72:75]
	v_mfma_f32_16x16x32_bf16 v[68:71], v[164:167], v[208:211], v[68:71]
	v_mfma_f32_16x16x32_bf16 v[64:67], v[172:175], v[208:211], v[64:67]
	v_mfma_f32_16x16x32_bf16 v[112:115], v[168:171], v[184:187], v[112:115]
	v_mfma_f32_16x16x32_bf16 v[104:107], v[176:179], v[184:187], v[104:107]
	v_mfma_f32_16x16x32_bf16 v[96:99], v[168:171], v[196:199], v[96:99]
	v_mfma_f32_16x16x32_bf16 v[88:91], v[176:179], v[196:199], v[88:91]
	v_mfma_f32_16x16x32_bf16 v[80:83], v[168:171], v[204:207], v[80:83]
	v_mfma_f32_16x16x32_bf16 v[72:75], v[176:179], v[204:207], v[72:75]
	v_mfma_f32_16x16x32_bf16 v[68:71], v[168:171], v[212:215], v[68:71]
	v_mfma_f32_16x16x32_bf16 v[64:67], v[176:179], v[212:215], v[64:67]
	s_barrier
	s_mov_b32 m0, s90
	v_lshl_add_u64 v[140:141], v[140:141], 0, s[10:11]
	ds_read_b128 v[180:183], v147 offset:49152
	ds_read_b128 v[184:187], v147 offset:50176
	ds_read_b128 v[192:195], v147 offset:51200
	ds_read_b128 v[196:199], v147 offset:52224
	ds_read_b128 v[200:203], v147 offset:53248
	ds_read_b128 v[204:207], v147 offset:54272
	ds_read_b128 v[208:211], v147 offset:55296
	ds_read_b128 v[212:215], v147 offset:56320
	global_load_lds_dwordx4 v[140:141], off
	s_mov_b32 m0, s88
	v_lshl_add_u64 v[140:141], v[188:189], 0, s[10:11]
	global_load_lds_dwordx4 v[140:141], off
	s_mov_b32 m0, s89
	s_nop 0
	global_load_lds_dwordx4 v130, s[42:43]
	s_mov_b32 m0, s87
	v_lshl_add_u64 v[140:141], v[216:217], 0, s[10:11]
	global_load_lds_dwordx4 v134, s[42:43]
	s_mov_b32 m0, s77
	s_nop 0
	global_load_lds_dwordx4 v[140:141], off
	s_mov_b32 m0, s79
	v_lshl_add_u64 v[140:141], v[218:219], 0, s[10:11]
	global_load_lds_dwordx4 v[140:141], off
	s_waitcnt vmcnt(8)
	s_waitcnt lgkmcnt(0)
	s_barrier
	v_mfma_f32_16x16x32_bf16 v[60:63], v[148:151], v[180:183], v[60:63]
	v_mfma_f32_16x16x32_bf16 v[56:59], v[156:159], v[180:183], v[56:59]
	v_mfma_f32_16x16x32_bf16 v[52:55], v[148:151], v[192:195], v[52:55]
	v_mfma_f32_16x16x32_bf16 v[44:47], v[156:159], v[192:195], v[44:47]
	v_mfma_f32_16x16x32_bf16 v[36:39], v[148:151], v[200:203], v[36:39]
	v_mfma_f32_16x16x32_bf16 v[28:31], v[156:159], v[200:203], v[28:31]
	v_mfma_f32_16x16x32_bf16 v[20:23], v[148:151], v[208:211], v[20:23]
	v_mfma_f32_16x16x32_bf16 v[12:15], v[156:159], v[208:211], v[12:15]
	v_mfma_f32_16x16x32_bf16 v[60:63], v[152:155], v[184:187], v[60:63]
	v_mfma_f32_16x16x32_bf16 v[56:59], v[160:163], v[184:187], v[56:59]
	v_mfma_f32_16x16x32_bf16 v[52:55], v[152:155], v[196:199], v[52:55]
	v_mfma_f32_16x16x32_bf16 v[44:47], v[160:163], v[196:199], v[44:47]
	v_mfma_f32_16x16x32_bf16 v[36:39], v[152:155], v[204:207], v[36:39]
	v_mfma_f32_16x16x32_bf16 v[28:31], v[160:163], v[204:207], v[28:31]
	v_mfma_f32_16x16x32_bf16 v[20:23], v[152:155], v[212:215], v[20:23]
	v_mfma_f32_16x16x32_bf16 v[12:15], v[160:163], v[212:215], v[12:15]
	v_mfma_f32_16x16x32_bf16 v[48:51], v[164:167], v[180:183], v[48:51]
	v_mfma_f32_16x16x32_bf16 v[40:43], v[172:175], v[180:183], v[40:43]
	v_mfma_f32_16x16x32_bf16 v[32:35], v[164:167], v[192:195], v[32:35]
	v_mfma_f32_16x16x32_bf16 v[24:27], v[172:175], v[192:195], v[24:27]
	v_mfma_f32_16x16x32_bf16 v[16:19], v[164:167], v[200:203], v[16:19]
	v_mfma_f32_16x16x32_bf16 v[8:11], v[172:175], v[200:203], v[8:11]
	v_mfma_f32_16x16x32_bf16 v[4:7], v[164:167], v[208:211], v[4:7]
	v_mfma_f32_16x16x32_bf16 v[0:3], v[172:175], v[208:211], v[0:3]
	v_mfma_f32_16x16x32_bf16 v[48:51], v[168:171], v[184:187], v[48:51]
	v_mfma_f32_16x16x32_bf16 v[40:43], v[176:179], v[184:187], v[40:43]
	v_mfma_f32_16x16x32_bf16 v[32:35], v[168:171], v[196:199], v[32:35]
	v_mfma_f32_16x16x32_bf16 v[24:27], v[176:179], v[196:199], v[24:27]
	v_mfma_f32_16x16x32_bf16 v[16:19], v[168:171], v[204:207], v[16:19]
	v_mfma_f32_16x16x32_bf16 v[8:11], v[176:179], v[204:207], v[8:11]
	v_mfma_f32_16x16x32_bf16 v[4:7], v[168:171], v[212:215], v[4:7]
	v_mfma_f32_16x16x32_bf16 v[0:3], v[176:179], v[212:215], v[0:3]
	s_barrier
	s_movk_i32 s60, 0x100
	s_andn2_b64 vcc, exec, s[34:35]
	s_mov_b64 s[42:43], -1
	s_mov_b64 s[34:35], 0
	s_cbranch_vccz .LBB0_1246
	s_branch .Lpeel_exit8
.LBB0_1246:
	s_add_u32 s61, s30, s60
	s_addc_u32 s66, s31, 0
	s_add_u32 s64, s61, 0x100
	s_addc_u32 s65, s66, 0
	s_and_b64 s[62:63], s[42:43], exec
	s_cselect_b32 s63, s21, s65
	s_cselect_b32 s62, s55, s64
	s_add_u32 s60, s28, s60
	s_addc_u32 s64, s29, 0
	s_add_u32 s60, s60, 0x100
	s_addc_u32 s64, s64, 0
	s_and_b64 s[42:43], s[42:43], exec
	s_cselect_b32 s65, s19, s64
	s_cselect_b32 s64, s86, s60
	s_add_u32 s68, s61, 0x10080
	ds_read_b128 v[148:151], v145
	ds_read_b128 v[152:155], v145 offset:1024
	ds_read_b128 v[156:159], v145 offset:2048
	ds_read_b128 v[160:163], v145 offset:3072
	ds_read_b128 v[164:167], v146
	ds_read_b128 v[168:171], v146 offset:1024
	ds_read_b128 v[172:175], v146 offset:2048
	ds_read_b128 v[176:179], v146 offset:3072
	s_addc_u32 s69, s66, 0
	s_add_i32 s96, s81, s73
	s_add_i32 m0, s27, 0xc000
	s_add_i32 s97, s27, 0xe000
	s_add_i32 s93, s96, 0x2000
	s_add_u32 s66, s64, 0x10000
	s_addc_u32 s67, s65, 0
	s_add_i32 s95, s82, s73
	s_add_i32 s94, s95, 0x2000
	s_add_i32 s92, 0, 0x18000
	s_add_i32 s91, 0, 0x1c000
	s_add_u32 s60, s62, 0x10000
	s_addc_u32 s61, s63, 0
	s_add_i32 s90, s92, s73
	s_add_i32 s88, s90, 0x2000
	s_add_u32 s42, s64, 0x10080
	s_addc_u32 s43, s65, 0
	s_add_i32 s89, s91, s73
	s_add_i32 s87, s89, 0x2000
	ds_read_b128 v[180:183], v147
	ds_read_b128 v[184:187], v147 offset:1024
	ds_read_b128 v[192:195], v147 offset:2048
	ds_read_b128 v[196:199], v147 offset:3072
	ds_read_b128 v[200:203], v147 offset:4096
	ds_read_b128 v[204:207], v147 offset:5120
	ds_read_b128 v[208:211], v147 offset:6144
	ds_read_b128 v[212:215], v147 offset:7168
	global_load_lds_dwordx4 v128, s[68:69]
	s_mov_b32 m0, s97
	s_nop 0
	global_load_lds_dwordx4 v132, s[68:69]
	s_waitcnt vmcnt(8)
	s_waitcnt lgkmcnt(0)
	s_barrier
	v_mfma_f32_16x16x32_bf16 v[124:127], v[148:151], v[180:183], v[124:127]
	v_mfma_f32_16x16x32_bf16 v[120:123], v[156:159], v[180:183], v[120:123]
	v_mfma_f32_16x16x32_bf16 v[116:119], v[148:151], v[192:195], v[116:119]
	v_mfma_f32_16x16x32_bf16 v[108:111], v[156:159], v[192:195], v[108:111]
	v_mfma_f32_16x16x32_bf16 v[100:103], v[148:151], v[200:203], v[100:103]
	v_mfma_f32_16x16x32_bf16 v[92:95], v[156:159], v[200:203], v[92:95]
	v_mfma_f32_16x16x32_bf16 v[84:87], v[148:151], v[208:211], v[84:87]
	v_mfma_f32_16x16x32_bf16 v[76:79], v[156:159], v[208:211], v[76:79]
	v_mfma_f32_16x16x32_bf16 v[124:127], v[152:155], v[184:187], v[124:127]
	v_mfma_f32_16x16x32_bf16 v[120:123], v[160:163], v[184:187], v[120:123]
	v_mfma_f32_16x16x32_bf16 v[116:119], v[152:155], v[196:199], v[116:119]
	v_mfma_f32_16x16x32_bf16 v[108:111], v[160:163], v[196:199], v[108:111]
	v_mfma_f32_16x16x32_bf16 v[100:103], v[152:155], v[204:207], v[100:103]
	v_mfma_f32_16x16x32_bf16 v[92:95], v[160:163], v[204:207], v[92:95]
	v_mfma_f32_16x16x32_bf16 v[84:87], v[152:155], v[212:215], v[84:87]
	v_mfma_f32_16x16x32_bf16 v[76:79], v[160:163], v[212:215], v[76:79]
	v_mfma_f32_16x16x32_bf16 v[112:115], v[164:167], v[180:183], v[112:115]
	v_mfma_f32_16x16x32_bf16 v[104:107], v[172:175], v[180:183], v[104:107]
	v_mfma_f32_16x16x32_bf16 v[96:99], v[164:167], v[192:195], v[96:99]
	v_mfma_f32_16x16x32_bf16 v[88:91], v[172:175], v[192:195], v[88:91]
	v_mfma_f32_16x16x32_bf16 v[80:83], v[164:167], v[200:203], v[80:83]
	v_mfma_f32_16x16x32_bf16 v[72:75], v[172:175], v[200:203], v[72:75]
	v_mfma_f32_16x16x32_bf16 v[68:71], v[164:167], v[208:211], v[68:71]
	v_mfma_f32_16x16x32_bf16 v[64:67], v[172:175], v[208:211], v[64:67]
	v_mfma_f32_16x16x32_bf16 v[112:115], v[168:171], v[184:187], v[112:115]
	v_mfma_f32_16x16x32_bf16 v[104:107], v[176:179], v[184:187], v[104:107]
	v_mfma_f32_16x16x32_bf16 v[96:99], v[168:171], v[196:199], v[96:99]
	v_mfma_f32_16x16x32_bf16 v[88:91], v[176:179], v[196:199], v[88:91]
	v_mfma_f32_16x16x32_bf16 v[80:83], v[168:171], v[204:207], v[80:83]
	v_mfma_f32_16x16x32_bf16 v[72:75], v[176:179], v[204:207], v[72:75]
	v_mfma_f32_16x16x32_bf16 v[68:71], v[168:171], v[212:215], v[68:71]
	v_mfma_f32_16x16x32_bf16 v[64:67], v[176:179], v[212:215], v[64:67]
	s_barrier
	s_mov_b32 m0, s96
	v_lshl_add_u64 v[140:141], s[64:65], 0, v[130:131]
	ds_read_b128 v[180:183], v147 offset:16384
	ds_read_b128 v[184:187], v147 offset:17408
	ds_read_b128 v[192:195], v147 offset:18432
	ds_read_b128 v[196:199], v147 offset:19456
	ds_read_b128 v[200:203], v147 offset:20480
	ds_read_b128 v[204:207], v147 offset:21504
	ds_read_b128 v[208:211], v147 offset:22528
	ds_read_b128 v[212:215], v147 offset:23552
	global_load_lds_dwordx4 v[140:141], off
	s_mov_b32 m0, s93
	v_lshl_add_u64 v[188:189], s[64:65], 0, v[134:135]
	global_load_lds_dwordx4 v[188:189], off
	s_mov_b32 m0, s95
	v_lshl_add_u64 v[218:219], s[62:63], 0, v[132:133]
	global_load_lds_dwordx4 v130, s[66:67]
	s_mov_b32 m0, s94
	v_lshl_add_u64 v[216:217], s[62:63], 0, v[128:129]
	global_load_lds_dwordx4 v134, s[66:67]
	s_mov_b32 m0, s27
	s_nop 0
	global_load_lds_dwordx4 v[216:217], off
	s_mov_b32 m0, s33
	s_nop 0
	global_load_lds_dwordx4 v[218:219], off
	s_waitcnt vmcnt(8)
	s_waitcnt lgkmcnt(0)
	s_barrier
	v_mfma_f32_16x16x32_bf16 v[60:63], v[148:151], v[180:183], v[60:63]
	v_mfma_f32_16x16x32_bf16 v[56:59], v[156:159], v[180:183], v[56:59]
	v_mfma_f32_16x16x32_bf16 v[52:55], v[148:151], v[192:195], v[52:55]
	v_mfma_f32_16x16x32_bf16 v[44:47], v[156:159], v[192:195], v[44:47]
	v_mfma_f32_16x16x32_bf16 v[36:39], v[148:151], v[200:203], v[36:39]
	v_mfma_f32_16x16x32_bf16 v[28:31], v[156:159], v[200:203], v[28:31]
	v_mfma_f32_16x16x32_bf16 v[20:23], v[148:151], v[208:211], v[20:23]
	v_mfma_f32_16x16x32_bf16 v[12:15], v[156:159], v[208:211], v[12:15]
	v_mfma_f32_16x16x32_bf16 v[60:63], v[152:155], v[184:187], v[60:63]
	v_mfma_f32_16x16x32_bf16 v[56:59], v[160:163], v[184:187], v[56:59]
	v_mfma_f32_16x16x32_bf16 v[52:55], v[152:155], v[196:199], v[52:55]
	v_mfma_f32_16x16x32_bf16 v[44:47], v[160:163], v[196:199], v[44:47]
	v_mfma_f32_16x16x32_bf16 v[36:39], v[152:155], v[204:207], v[36:39]
	v_mfma_f32_16x16x32_bf16 v[28:31], v[160:163], v[204:207], v[28:31]
	v_mfma_f32_16x16x32_bf16 v[20:23], v[152:155], v[212:215], v[20:23]
	v_mfma_f32_16x16x32_bf16 v[12:15], v[160:163], v[212:215], v[12:15]
	v_mfma_f32_16x16x32_bf16 v[48:51], v[164:167], v[180:183], v[48:51]
	v_mfma_f32_16x16x32_bf16 v[40:43], v[172:175], v[180:183], v[40:43]
	v_mfma_f32_16x16x32_bf16 v[32:35], v[164:167], v[192:195], v[32:35]
	v_mfma_f32_16x16x32_bf16 v[24:27], v[172:175], v[192:195], v[24:27]
	v_mfma_f32_16x16x32_bf16 v[16:19], v[164:167], v[200:203], v[16:19]
	v_mfma_f32_16x16x32_bf16 v[8:11], v[172:175], v[200:203], v[8:11]
	v_mfma_f32_16x16x32_bf16 v[4:7], v[164:167], v[208:211], v[4:7]
	v_mfma_f32_16x16x32_bf16 v[0:3], v[172:175], v[208:211], v[0:3]
	v_mfma_f32_16x16x32_bf16 v[48:51], v[168:171], v[184:187], v[48:51]
	v_mfma_f32_16x16x32_bf16 v[40:43], v[176:179], v[184:187], v[40:43]
	v_mfma_f32_16x16x32_bf16 v[32:35], v[168:171], v[196:199], v[32:35]
	v_mfma_f32_16x16x32_bf16 v[24:27], v[176:179], v[196:199], v[24:27]
	v_mfma_f32_16x16x32_bf16 v[16:19], v[168:171], v[204:207], v[16:19]
	v_mfma_f32_16x16x32_bf16 v[8:11], v[176:179], v[204:207], v[8:11]
	v_mfma_f32_16x16x32_bf16 v[4:7], v[168:171], v[212:215], v[4:7]
	v_mfma_f32_16x16x32_bf16 v[0:3], v[176:179], v[212:215], v[0:3]
	s_barrier
	v_add_u32_e32 v160, s92, v143
	v_add_u32_e32 v176, s91, v143
	ds_read_b128 v[148:151], v160
	ds_read_b128 v[152:155], v160 offset:1024
	ds_read_b128 v[156:159], v160 offset:2048
	ds_read_b128 v[160:163], v160 offset:3072
	ds_read_b128 v[164:167], v176
	ds_read_b128 v[168:171], v176 offset:1024
	ds_read_b128 v[172:175], v176 offset:2048
	ds_read_b128 v[176:179], v176 offset:3072
	s_mov_b32 m0, s74
	ds_read_b128 v[180:183], v147 offset:32768
	ds_read_b128 v[184:187], v147 offset:33792
	ds_read_b128 v[192:195], v147 offset:34816
	ds_read_b128 v[196:199], v147 offset:35840
	ds_read_b128 v[200:203], v147 offset:36864
	ds_read_b128 v[204:207], v147 offset:37888
	ds_read_b128 v[208:211], v147 offset:38912
	ds_read_b128 v[212:215], v147 offset:39936
	global_load_lds_dwordx4 v128, s[60:61]
	s_mov_b32 m0, s75
	s_nop 0
	global_load_lds_dwordx4 v132, s[60:61]
	s_waitcnt vmcnt(8)
	s_waitcnt lgkmcnt(0)
	s_barrier
	v_mfma_f32_16x16x32_bf16 v[124:127], v[148:151], v[180:183], v[124:127]
	v_mfma_f32_16x16x32_bf16 v[120:123], v[156:159], v[180:183], v[120:123]
	v_mfma_f32_16x16x32_bf16 v[116:119], v[148:151], v[192:195], v[116:119]
	v_mfma_f32_16x16x32_bf16 v[108:111], v[156:159], v[192:195], v[108:111]
	v_mfma_f32_16x16x32_bf16 v[100:103], v[148:151], v[200:203], v[100:103]
	v_mfma_f32_16x16x32_bf16 v[92:95], v[156:159], v[200:203], v[92:95]
	v_mfma_f32_16x16x32_bf16 v[84:87], v[148:151], v[208:211], v[84:87]
	v_mfma_f32_16x16x32_bf16 v[76:79], v[156:159], v[208:211], v[76:79]
	v_mfma_f32_16x16x32_bf16 v[124:127], v[152:155], v[184:187], v[124:127]
	v_mfma_f32_16x16x32_bf16 v[120:123], v[160:163], v[184:187], v[120:123]
	v_mfma_f32_16x16x32_bf16 v[116:119], v[152:155], v[196:199], v[116:119]
	v_mfma_f32_16x16x32_bf16 v[108:111], v[160:163], v[196:199], v[108:111]
	v_mfma_f32_16x16x32_bf16 v[100:103], v[152:155], v[204:207], v[100:103]
	v_mfma_f32_16x16x32_bf16 v[92:95], v[160:163], v[204:207], v[92:95]
	v_mfma_f32_16x16x32_bf16 v[84:87], v[152:155], v[212:215], v[84:87]
	v_mfma_f32_16x16x32_bf16 v[76:79], v[160:163], v[212:215], v[76:79]
	v_mfma_f32_16x16x32_bf16 v[112:115], v[164:167], v[180:183], v[112:115]
	v_mfma_f32_16x16x32_bf16 v[104:107], v[172:175], v[180:183], v[104:107]
	v_mfma_f32_16x16x32_bf16 v[96:99], v[164:167], v[192:195], v[96:99]
	v_mfma_f32_16x16x32_bf16 v[88:91], v[172:175], v[192:195], v[88:91]
	v_mfma_f32_16x16x32_bf16 v[80:83], v[164:167], v[200:203], v[80:83]
	v_mfma_f32_16x16x32_bf16 v[72:75], v[172:175], v[200:203], v[72:75]
	v_mfma_f32_16x16x32_bf16 v[68:71], v[164:167], v[208:211], v[68:71]
	v_mfma_f32_16x16x32_bf16 v[64:67], v[172:175], v[208:211], v[64:67]
	v_mfma_f32_16x16x32_bf16 v[112:115], v[168:171], v[184:187], v[112:115]
	v_mfma_f32_16x16x32_bf16 v[104:107], v[176:179], v[184:187], v[104:107]
	v_mfma_f32_16x16x32_bf16 v[96:99], v[168:171], v[196:199], v[96:99]
	v_mfma_f32_16x16x32_bf16 v[88:91], v[176:179], v[196:199], v[88:91]
	v_mfma_f32_16x16x32_bf16 v[80:83], v[168:171], v[204:207], v[80:83]
	v_mfma_f32_16x16x32_bf16 v[72:75], v[176:179], v[204:207], v[72:75]
	v_mfma_f32_16x16x32_bf16 v[68:71], v[168:171], v[212:215], v[68:71]
	v_mfma_f32_16x16x32_bf16 v[64:67], v[176:179], v[212:215], v[64:67]
	s_barrier
	s_mov_b32 m0, s90
	v_lshl_add_u64 v[140:141], v[140:141], 0, s[10:11]
	ds_read_b128 v[180:183], v147 offset:49152
	ds_read_b128 v[184:187], v147 offset:50176
	ds_read_b128 v[192:195], v147 offset:51200
	ds_read_b128 v[196:199], v147 offset:52224
	ds_read_b128 v[200:203], v147 offset:53248
	ds_read_b128 v[204:207], v147 offset:54272
	ds_read_b128 v[208:211], v147 offset:55296
	ds_read_b128 v[212:215], v147 offset:56320
	global_load_lds_dwordx4 v[140:141], off
	s_mov_b32 m0, s88
	v_lshl_add_u64 v[140:141], v[188:189], 0, s[10:11]
	global_load_lds_dwordx4 v[140:141], off
	s_mov_b32 m0, s89
	s_nop 0
	global_load_lds_dwordx4 v130, s[42:43]
	s_mov_b32 m0, s87
	v_lshl_add_u64 v[140:141], v[216:217], 0, s[10:11]
	global_load_lds_dwordx4 v134, s[42:43]
	s_mov_b32 m0, s77
	s_nop 0
	global_load_lds_dwordx4 v[140:141], off
	s_mov_b32 m0, s79
	v_lshl_add_u64 v[140:141], v[218:219], 0, s[10:11]
	global_load_lds_dwordx4 v[140:141], off
	s_waitcnt vmcnt(8)
	s_waitcnt lgkmcnt(0)
	s_barrier
	v_mfma_f32_16x16x32_bf16 v[60:63], v[148:151], v[180:183], v[60:63]
	v_mfma_f32_16x16x32_bf16 v[56:59], v[156:159], v[180:183], v[56:59]
	v_mfma_f32_16x16x32_bf16 v[52:55], v[148:151], v[192:195], v[52:55]
	v_mfma_f32_16x16x32_bf16 v[44:47], v[156:159], v[192:195], v[44:47]
	v_mfma_f32_16x16x32_bf16 v[36:39], v[148:151], v[200:203], v[36:39]
	v_mfma_f32_16x16x32_bf16 v[28:31], v[156:159], v[200:203], v[28:31]
	v_mfma_f32_16x16x32_bf16 v[20:23], v[148:151], v[208:211], v[20:23]
	v_mfma_f32_16x16x32_bf16 v[12:15], v[156:159], v[208:211], v[12:15]
	v_mfma_f32_16x16x32_bf16 v[60:63], v[152:155], v[184:187], v[60:63]
	v_mfma_f32_16x16x32_bf16 v[56:59], v[160:163], v[184:187], v[56:59]
	v_mfma_f32_16x16x32_bf16 v[52:55], v[152:155], v[196:199], v[52:55]
	v_mfma_f32_16x16x32_bf16 v[44:47], v[160:163], v[196:199], v[44:47]
	v_mfma_f32_16x16x32_bf16 v[36:39], v[152:155], v[204:207], v[36:39]
	v_mfma_f32_16x16x32_bf16 v[28:31], v[160:163], v[204:207], v[28:31]
	v_mfma_f32_16x16x32_bf16 v[20:23], v[152:155], v[212:215], v[20:23]
	v_mfma_f32_16x16x32_bf16 v[12:15], v[160:163], v[212:215], v[12:15]
	v_mfma_f32_16x16x32_bf16 v[48:51], v[164:167], v[180:183], v[48:51]
	v_mfma_f32_16x16x32_bf16 v[40:43], v[172:175], v[180:183], v[40:43]
	v_mfma_f32_16x16x32_bf16 v[32:35], v[164:167], v[192:195], v[32:35]
	v_mfma_f32_16x16x32_bf16 v[24:27], v[172:175], v[192:195], v[24:27]
	v_mfma_f32_16x16x32_bf16 v[16:19], v[164:167], v[200:203], v[16:19]
	v_mfma_f32_16x16x32_bf16 v[8:11], v[172:175], v[200:203], v[8:11]
	v_mfma_f32_16x16x32_bf16 v[4:7], v[164:167], v[208:211], v[4:7]
	v_mfma_f32_16x16x32_bf16 v[0:3], v[172:175], v[208:211], v[0:3]
	v_mfma_f32_16x16x32_bf16 v[48:51], v[168:171], v[184:187], v[48:51]
	v_mfma_f32_16x16x32_bf16 v[40:43], v[176:179], v[184:187], v[40:43]
	v_mfma_f32_16x16x32_bf16 v[32:35], v[168:171], v[196:199], v[32:35]
	v_mfma_f32_16x16x32_bf16 v[24:27], v[176:179], v[196:199], v[24:27]
	v_mfma_f32_16x16x32_bf16 v[16:19], v[168:171], v[204:207], v[16:19]
	v_mfma_f32_16x16x32_bf16 v[8:11], v[176:179], v[204:207], v[8:11]
	v_mfma_f32_16x16x32_bf16 v[4:7], v[168:171], v[212:215], v[4:7]
	v_mfma_f32_16x16x32_bf16 v[0:3], v[176:179], v[212:215], v[0:3]
	s_barrier
	s_movk_i32 s60, 0x100
	s_andn2_b64 vcc, exec, s[34:35]
	s_mov_b64 s[42:43], -1
	s_mov_b64 s[34:35], 0
	s_cbranch_vccz .LBB0_1246

.LBB0_1265:
	s_add_u32 s65, s18, 0x100
	s_addc_u32 s66, s19, 0
	s_mov_b32 s67, -2
	ds_read_b128 v[144:147], v151
	ds_read_b128 v[154:157], v151 offset:1024
	ds_read_b128 v[158:161], v151 offset:2048
	ds_read_b128 v[162:165], v151 offset:3072
	ds_read_b128 v[166:169], v152
	ds_read_b128 v[170:173], v152 offset:1024
	ds_read_b128 v[174:177], v152 offset:2048
	ds_read_b128 v[178:181], v152 offset:3072
	s_add_u32 s18, s16, 0x100
	s_addc_u32 s19, s17, 0
	s_cmp_eq_u32 s67, 2
	s_cselect_b32 s23, s5, s19
	s_cselect_b32 s22, s4, s18
	s_cselect_b32 s21, s15, s66
	s_cselect_b32 s20, s14, s65
	v_lshl_add_u64 v[216:217], s[16:17], 0, v[136:137]
	s_add_i32 m0, s31, 0xc000
	ds_read_b128 v[182:185], v153
	ds_read_b128 v[186:189], v153 offset:1024
	ds_read_b128 v[192:195], v153 offset:2048
	ds_read_b128 v[196:199], v153 offset:3072
	ds_read_b128 v[200:203], v153 offset:4096
	ds_read_b128 v[204:207], v153 offset:5120
	ds_read_b128 v[208:211], v153 offset:6144
	ds_read_b128 v[212:215], v153 offset:7168
	global_load_lds_dwordx4 v[216:217], off
	s_add_i32 m0, s31, 0xe000
	v_lshl_add_u64 v[216:217], s[16:17], 0, v[138:139]
	global_load_lds_dwordx4 v[216:217], off
	s_waitcnt vmcnt(8)
	s_waitcnt lgkmcnt(0)
	s_barrier
	v_mfma_f32_16x16x32_bf16 v[124:127], v[144:147], v[182:185], 0
	v_mfma_f32_16x16x32_bf16 v[120:123], v[158:161], v[182:185], 0
	v_mfma_f32_16x16x32_bf16 v[116:119], v[144:147], v[192:195], 0
	v_mfma_f32_16x16x32_bf16 v[108:111], v[158:161], v[192:195], 0
	v_mfma_f32_16x16x32_bf16 v[100:103], v[144:147], v[200:203], 0
	v_mfma_f32_16x16x32_bf16 v[92:95], v[158:161], v[200:203], 0
	v_mfma_f32_16x16x32_bf16 v[84:87], v[144:147], v[208:211], 0
	v_mfma_f32_16x16x32_bf16 v[76:79], v[158:161], v[208:211], 0
	v_mfma_f32_16x16x32_bf16 v[124:127], v[154:157], v[186:189], v[124:127]
	v_mfma_f32_16x16x32_bf16 v[120:123], v[162:165], v[186:189], v[120:123]
	v_mfma_f32_16x16x32_bf16 v[116:119], v[154:157], v[196:199], v[116:119]
	v_mfma_f32_16x16x32_bf16 v[108:111], v[162:165], v[196:199], v[108:111]
	v_mfma_f32_16x16x32_bf16 v[100:103], v[154:157], v[204:207], v[100:103]
	v_mfma_f32_16x16x32_bf16 v[92:95], v[162:165], v[204:207], v[92:95]
	v_mfma_f32_16x16x32_bf16 v[84:87], v[154:157], v[212:215], v[84:87]
	v_mfma_f32_16x16x32_bf16 v[76:79], v[162:165], v[212:215], v[76:79]
	v_mfma_f32_16x16x32_bf16 v[112:115], v[166:169], v[182:185], 0
	v_mfma_f32_16x16x32_bf16 v[104:107], v[174:177], v[182:185], 0
	v_mfma_f32_16x16x32_bf16 v[96:99], v[166:169], v[192:195], 0
	v_mfma_f32_16x16x32_bf16 v[88:91], v[174:177], v[192:195], 0
	v_mfma_f32_16x16x32_bf16 v[80:83], v[166:169], v[200:203], 0
	v_mfma_f32_16x16x32_bf16 v[72:75], v[174:177], v[200:203], 0
	v_mfma_f32_16x16x32_bf16 v[68:71], v[166:169], v[208:211], 0
	v_mfma_f32_16x16x32_bf16 v[64:67], v[174:177], v[208:211], 0
	v_mfma_f32_16x16x32_bf16 v[112:115], v[170:173], v[186:189], v[112:115]
	v_mfma_f32_16x16x32_bf16 v[104:107], v[178:181], v[186:189], v[104:107]
	v_mfma_f32_16x16x32_bf16 v[96:99], v[170:173], v[196:199], v[96:99]
	v_mfma_f32_16x16x32_bf16 v[88:91], v[178:181], v[196:199], v[88:91]
	v_mfma_f32_16x16x32_bf16 v[80:83], v[170:173], v[204:207], v[80:83]
	v_mfma_f32_16x16x32_bf16 v[72:75], v[178:181], v[204:207], v[72:75]
	v_mfma_f32_16x16x32_bf16 v[68:71], v[170:173], v[212:215], v[68:71]
	v_mfma_f32_16x16x32_bf16 v[64:67], v[178:181], v[212:215], v[64:67]
	s_barrier
	s_add_i32 s16, s60, s28
	v_lshl_add_u64 v[216:217], s[20:21], 0, v[132:133]
	s_mov_b32 m0, s16
	ds_read_b128 v[182:185], v153 offset:16384
	ds_read_b128 v[186:189], v153 offset:17408
	ds_read_b128 v[192:195], v153 offset:18432
	ds_read_b128 v[196:199], v153 offset:19456
	ds_read_b128 v[200:203], v153 offset:20480
	ds_read_b128 v[204:207], v153 offset:21504
	ds_read_b128 v[208:211], v153 offset:22528
	ds_read_b128 v[212:215], v153 offset:23552
	global_load_lds_dwordx4 v[216:217], off
	s_add_i32 m0, s16, 0x2000
	s_add_u32 s16, s20, 0x18000
	v_lshl_add_u64 v[218:219], s[20:21], 0, v[128:129]
	s_addc_u32 s17, s21, 0
	s_add_i32 s68, s61, s28
	global_load_lds_dwordx4 v[218:219], off
	s_mov_b32 m0, s68
	v_lshl_add_u64 v[222:223], s[22:23], 0, v[130:131]
	global_load_lds_dwordx4 v132, s[16:17]
	s_add_i32 m0, s68, 0x2000
	v_lshl_add_u64 v[220:221], s[22:23], 0, v[134:135]
	global_load_lds_dwordx4 v128, s[16:17]
	s_mov_b32 m0, s31
	s_nop 0
	global_load_lds_dwordx4 v[220:221], off
	s_mov_b32 m0, s33
	s_nop 0
	global_load_lds_dwordx4 v[222:223], off
	s_waitcnt vmcnt(8)
	s_waitcnt lgkmcnt(0)
	s_barrier
	v_mfma_f32_16x16x32_bf16 v[60:63], v[144:147], v[182:185], 0
	v_mfma_f32_16x16x32_bf16 v[56:59], v[158:161], v[182:185], 0
	v_mfma_f32_16x16x32_bf16 v[52:55], v[144:147], v[192:195], 0
	v_mfma_f32_16x16x32_bf16 v[44:47], v[158:161], v[192:195], 0
	v_mfma_f32_16x16x32_bf16 v[36:39], v[144:147], v[200:203], 0
	v_mfma_f32_16x16x32_bf16 v[28:31], v[158:161], v[200:203], 0
	v_mfma_f32_16x16x32_bf16 v[20:23], v[144:147], v[208:211], 0
	v_mfma_f32_16x16x32_bf16 v[12:15], v[158:161], v[208:211], 0
	v_mfma_f32_16x16x32_bf16 v[60:63], v[154:157], v[186:189], v[60:63]
	v_mfma_f32_16x16x32_bf16 v[56:59], v[162:165], v[186:189], v[56:59]
	v_mfma_f32_16x16x32_bf16 v[52:55], v[154:157], v[196:199], v[52:55]
	v_mfma_f32_16x16x32_bf16 v[44:47], v[162:165], v[196:199], v[44:47]
	v_mfma_f32_16x16x32_bf16 v[36:39], v[154:157], v[204:207], v[36:39]
	v_mfma_f32_16x16x32_bf16 v[28:31], v[162:165], v[204:207], v[28:31]
	v_mfma_f32_16x16x32_bf16 v[20:23], v[154:157], v[212:215], v[20:23]
	v_mfma_f32_16x16x32_bf16 v[12:15], v[162:165], v[212:215], v[12:15]
	v_mfma_f32_16x16x32_bf16 v[48:51], v[166:169], v[182:185], 0
	v_mfma_f32_16x16x32_bf16 v[40:43], v[174:177], v[182:185], 0
	v_mfma_f32_16x16x32_bf16 v[32:35], v[166:169], v[192:195], 0
	v_mfma_f32_16x16x32_bf16 v[24:27], v[174:177], v[192:195], 0
	v_mfma_f32_16x16x32_bf16 v[16:19], v[166:169], v[200:203], 0
	v_mfma_f32_16x16x32_bf16 v[8:11], v[174:177], v[200:203], 0
	v_mfma_f32_16x16x32_bf16 v[4:7], v[166:169], v[208:211], 0
	v_mfma_f32_16x16x32_bf16 v[0:3], v[174:177], v[208:211], 0
	v_mfma_f32_16x16x32_bf16 v[48:51], v[170:173], v[186:189], v[48:51]
	v_mfma_f32_16x16x32_bf16 v[40:43], v[178:181], v[186:189], v[40:43]
	v_mfma_f32_16x16x32_bf16 v[32:35], v[170:173], v[196:199], v[32:35]
	v_mfma_f32_16x16x32_bf16 v[24:27], v[178:181], v[196:199], v[24:27]
	v_mfma_f32_16x16x32_bf16 v[16:19], v[170:173], v[204:207], v[16:19]
	v_mfma_f32_16x16x32_bf16 v[8:11], v[178:181], v[204:207], v[8:11]
	v_mfma_f32_16x16x32_bf16 v[4:7], v[170:173], v[212:215], v[4:7]
	v_mfma_f32_16x16x32_bf16 v[0:3], v[178:181], v[212:215], v[0:3]
	s_barrier
	s_add_i32 s68, 0, 0x18000
	s_add_i32 s69, 0, 0x1c000
	v_add_u32_e32 v162, s68, v149
	v_add_u32_e32 v178, s69, v149
	ds_read_b128 v[144:147], v162
	ds_read_b128 v[154:157], v162 offset:1024
	ds_read_b128 v[158:161], v162 offset:2048
	ds_read_b128 v[162:165], v162 offset:3072
	ds_read_b128 v[166:169], v178
	ds_read_b128 v[170:173], v178 offset:1024
	ds_read_b128 v[174:177], v178 offset:2048
	ds_read_b128 v[178:181], v178 offset:3072
	s_add_u32 s16, s22, 0x18000
	s_addc_u32 s17, s23, 0
	s_mov_b32 m0, s34
	ds_read_b128 v[182:185], v153 offset:32768
	ds_read_b128 v[186:189], v153 offset:33792
	ds_read_b128 v[192:195], v153 offset:34816
	ds_read_b128 v[196:199], v153 offset:35840
	ds_read_b128 v[200:203], v153 offset:36864
	ds_read_b128 v[204:207], v153 offset:37888
	ds_read_b128 v[208:211], v153 offset:38912
	ds_read_b128 v[212:215], v153 offset:39936
	global_load_lds_dwordx4 v134, s[16:17]
	s_mov_b32 m0, s35
	s_nop 0
	global_load_lds_dwordx4 v130, s[16:17]
	s_waitcnt vmcnt(8)
	s_waitcnt lgkmcnt(0)
	s_barrier
	v_mfma_f32_16x16x32_bf16 v[124:127], v[144:147], v[182:185], v[124:127]
	v_mfma_f32_16x16x32_bf16 v[120:123], v[158:161], v[182:185], v[120:123]
	v_mfma_f32_16x16x32_bf16 v[116:119], v[144:147], v[192:195], v[116:119]
	v_mfma_f32_16x16x32_bf16 v[108:111], v[158:161], v[192:195], v[108:111]
	v_mfma_f32_16x16x32_bf16 v[100:103], v[144:147], v[200:203], v[100:103]
	v_mfma_f32_16x16x32_bf16 v[92:95], v[158:161], v[200:203], v[92:95]
	v_mfma_f32_16x16x32_bf16 v[84:87], v[144:147], v[208:211], v[84:87]
	v_mfma_f32_16x16x32_bf16 v[76:79], v[158:161], v[208:211], v[76:79]
	v_mfma_f32_16x16x32_bf16 v[124:127], v[154:157], v[186:189], v[124:127]
	v_mfma_f32_16x16x32_bf16 v[120:123], v[162:165], v[186:189], v[120:123]
	v_mfma_f32_16x16x32_bf16 v[116:119], v[154:157], v[196:199], v[116:119]
	v_mfma_f32_16x16x32_bf16 v[108:111], v[162:165], v[196:199], v[108:111]
	v_mfma_f32_16x16x32_bf16 v[100:103], v[154:157], v[204:207], v[100:103]
	v_mfma_f32_16x16x32_bf16 v[92:95], v[162:165], v[204:207], v[92:95]
	v_mfma_f32_16x16x32_bf16 v[84:87], v[154:157], v[212:215], v[84:87]
	v_mfma_f32_16x16x32_bf16 v[76:79], v[162:165], v[212:215], v[76:79]
	v_mfma_f32_16x16x32_bf16 v[112:115], v[166:169], v[182:185], v[112:115]
	v_mfma_f32_16x16x32_bf16 v[104:107], v[174:177], v[182:185], v[104:107]
	v_mfma_f32_16x16x32_bf16 v[96:99], v[166:169], v[192:195], v[96:99]
	v_mfma_f32_16x16x32_bf16 v[88:91], v[174:177], v[192:195], v[88:91]
	v_mfma_f32_16x16x32_bf16 v[80:83], v[166:169], v[200:203], v[80:83]
	v_mfma_f32_16x16x32_bf16 v[72:75], v[174:177], v[200:203], v[72:75]
	v_mfma_f32_16x16x32_bf16 v[68:71], v[166:169], v[208:211], v[68:71]
	v_mfma_f32_16x16x32_bf16 v[64:67], v[174:177], v[208:211], v[64:67]
	v_mfma_f32_16x16x32_bf16 v[112:115], v[170:173], v[186:189], v[112:115]
	v_mfma_f32_16x16x32_bf16 v[104:107], v[178:181], v[186:189], v[104:107]
	v_mfma_f32_16x16x32_bf16 v[96:99], v[170:173], v[196:199], v[96:99]
	v_mfma_f32_16x16x32_bf16 v[88:91], v[178:181], v[196:199], v[88:91]
	v_mfma_f32_16x16x32_bf16 v[80:83], v[170:173], v[204:207], v[80:83]
	v_mfma_f32_16x16x32_bf16 v[72:75], v[178:181], v[204:207], v[72:75]
	v_mfma_f32_16x16x32_bf16 v[68:71], v[170:173], v[212:215], v[68:71]
	v_mfma_f32_16x16x32_bf16 v[64:67], v[178:181], v[212:215], v[64:67]
	s_barrier
	s_add_i32 s16, s68, s28
	v_lshl_add_u64 v[216:217], v[216:217], 0, s[10:11]
	s_mov_b32 m0, s16
	ds_read_b128 v[182:185], v153 offset:49152
	ds_read_b128 v[186:189], v153 offset:50176
	ds_read_b128 v[192:195], v153 offset:51200
	ds_read_b128 v[196:199], v153 offset:52224
	ds_read_b128 v[200:203], v153 offset:53248
	ds_read_b128 v[204:207], v153 offset:54272
	ds_read_b128 v[208:211], v153 offset:55296
	ds_read_b128 v[212:215], v153 offset:56320
	global_load_lds_dwordx4 v[216:217], off
	s_add_i32 m0, s16, 0x2000
	s_add_u32 s16, s20, 0x18080
	v_lshl_add_u64 v[216:217], v[218:219], 0, s[10:11]
	s_addc_u32 s17, s21, 0
	s_add_i32 s20, s69, s28
	global_load_lds_dwordx4 v[216:217], off
	s_mov_b32 m0, s20
	s_nop 0
	global_load_lds_dwordx4 v132, s[16:17]
	s_add_i32 m0, s20, 0x2000
	v_lshl_add_u64 v[216:217], v[220:221], 0, s[10:11]
	global_load_lds_dwordx4 v128, s[16:17]
	s_mov_b32 m0, s43
	s_nop 0
	global_load_lds_dwordx4 v[216:217], off
	s_mov_b32 m0, s52
	v_lshl_add_u64 v[216:217], v[222:223], 0, s[10:11]
	global_load_lds_dwordx4 v[216:217], off
	s_waitcnt vmcnt(8)
	s_waitcnt lgkmcnt(0)
	s_barrier
	v_mfma_f32_16x16x32_bf16 v[60:63], v[144:147], v[182:185], v[60:63]
	v_mfma_f32_16x16x32_bf16 v[56:59], v[158:161], v[182:185], v[56:59]
	v_mfma_f32_16x16x32_bf16 v[52:55], v[144:147], v[192:195], v[52:55]
	v_mfma_f32_16x16x32_bf16 v[44:47], v[158:161], v[192:195], v[44:47]
	v_mfma_f32_16x16x32_bf16 v[36:39], v[144:147], v[200:203], v[36:39]
	v_mfma_f32_16x16x32_bf16 v[28:31], v[158:161], v[200:203], v[28:31]
	v_mfma_f32_16x16x32_bf16 v[20:23], v[144:147], v[208:211], v[20:23]
	v_mfma_f32_16x16x32_bf16 v[12:15], v[158:161], v[208:211], v[12:15]
	v_mfma_f32_16x16x32_bf16 v[60:63], v[154:157], v[186:189], v[60:63]
	v_mfma_f32_16x16x32_bf16 v[56:59], v[162:165], v[186:189], v[56:59]
	v_mfma_f32_16x16x32_bf16 v[52:55], v[154:157], v[196:199], v[52:55]
	v_mfma_f32_16x16x32_bf16 v[44:47], v[162:165], v[196:199], v[44:47]
	v_mfma_f32_16x16x32_bf16 v[36:39], v[154:157], v[204:207], v[36:39]
	v_mfma_f32_16x16x32_bf16 v[28:31], v[162:165], v[204:207], v[28:31]
	v_mfma_f32_16x16x32_bf16 v[20:23], v[154:157], v[212:215], v[20:23]
	v_mfma_f32_16x16x32_bf16 v[12:15], v[162:165], v[212:215], v[12:15]
	v_mfma_f32_16x16x32_bf16 v[48:51], v[166:169], v[182:185], v[48:51]
	v_mfma_f32_16x16x32_bf16 v[40:43], v[174:177], v[182:185], v[40:43]
	v_mfma_f32_16x16x32_bf16 v[32:35], v[166:169], v[192:195], v[32:35]
	v_mfma_f32_16x16x32_bf16 v[24:27], v[174:177], v[192:195], v[24:27]
	v_mfma_f32_16x16x32_bf16 v[16:19], v[166:169], v[200:203], v[16:19]
	v_mfma_f32_16x16x32_bf16 v[8:11], v[174:177], v[200:203], v[8:11]
	v_mfma_f32_16x16x32_bf16 v[4:7], v[166:169], v[208:211], v[4:7]
	v_mfma_f32_16x16x32_bf16 v[0:3], v[174:177], v[208:211], v[0:3]
	v_mfma_f32_16x16x32_bf16 v[48:51], v[170:173], v[186:189], v[48:51]
	v_mfma_f32_16x16x32_bf16 v[40:43], v[178:181], v[186:189], v[40:43]
	v_mfma_f32_16x16x32_bf16 v[32:35], v[170:173], v[196:199], v[32:35]
	v_mfma_f32_16x16x32_bf16 v[24:27], v[178:181], v[196:199], v[24:27]
	v_mfma_f32_16x16x32_bf16 v[16:19], v[170:173], v[204:207], v[16:19]
	v_mfma_f32_16x16x32_bf16 v[8:11], v[178:181], v[204:207], v[8:11]
	v_mfma_f32_16x16x32_bf16 v[4:7], v[170:173], v[212:215], v[4:7]
	v_mfma_f32_16x16x32_bf16 v[0:3], v[178:181], v[212:215], v[0:3]
	s_barrier
	s_add_i32 s67, s67, 2
	s_add_u32 s65, s65, 0x100
	s_addc_u32 s66, s66, 0
	s_cmp_gt_u32 s67, 3
	s_mov_b64 s[16:17], s[18:19]
	s_cbranch_scc0 .LBB0_1266
	s_branch .Lpeel_exit9
.LBB0_1266:
	ds_read_b128 v[144:147], v151
	ds_read_b128 v[154:157], v151 offset:1024
	ds_read_b128 v[158:161], v151 offset:2048
	ds_read_b128 v[162:165], v151 offset:3072
	ds_read_b128 v[166:169], v152
	ds_read_b128 v[170:173], v152 offset:1024
	ds_read_b128 v[174:177], v152 offset:2048
	ds_read_b128 v[178:181], v152 offset:3072
	s_add_u32 s18, s16, 0x100
	s_addc_u32 s19, s17, 0
	s_cmp_eq_u32 s67, 2
	s_cselect_b32 s23, s5, s19
	s_cselect_b32 s22, s4, s18
	s_cselect_b32 s21, s15, s66
	s_cselect_b32 s20, s14, s65
	v_lshl_add_u64 v[216:217], s[16:17], 0, v[136:137]
	s_add_i32 m0, s31, 0xc000
	ds_read_b128 v[182:185], v153
	ds_read_b128 v[186:189], v153 offset:1024
	ds_read_b128 v[192:195], v153 offset:2048
	ds_read_b128 v[196:199], v153 offset:3072
	ds_read_b128 v[200:203], v153 offset:4096
	ds_read_b128 v[204:207], v153 offset:5120
	ds_read_b128 v[208:211], v153 offset:6144
	ds_read_b128 v[212:215], v153 offset:7168
	global_load_lds_dwordx4 v[216:217], off
	s_add_i32 m0, s31, 0xe000
	v_lshl_add_u64 v[216:217], s[16:17], 0, v[138:139]
	global_load_lds_dwordx4 v[216:217], off
	s_waitcnt vmcnt(8)
	s_waitcnt lgkmcnt(0)
	s_barrier
	v_mfma_f32_16x16x32_bf16 v[124:127], v[144:147], v[182:185], v[124:127]
	v_mfma_f32_16x16x32_bf16 v[120:123], v[158:161], v[182:185], v[120:123]
	v_mfma_f32_16x16x32_bf16 v[116:119], v[144:147], v[192:195], v[116:119]
	v_mfma_f32_16x16x32_bf16 v[108:111], v[158:161], v[192:195], v[108:111]
	v_mfma_f32_16x16x32_bf16 v[100:103], v[144:147], v[200:203], v[100:103]
	v_mfma_f32_16x16x32_bf16 v[92:95], v[158:161], v[200:203], v[92:95]
	v_mfma_f32_16x16x32_bf16 v[84:87], v[144:147], v[208:211], v[84:87]
	v_mfma_f32_16x16x32_bf16 v[76:79], v[158:161], v[208:211], v[76:79]
	v_mfma_f32_16x16x32_bf16 v[124:127], v[154:157], v[186:189], v[124:127]
	v_mfma_f32_16x16x32_bf16 v[120:123], v[162:165], v[186:189], v[120:123]
	v_mfma_f32_16x16x32_bf16 v[116:119], v[154:157], v[196:199], v[116:119]
	v_mfma_f32_16x16x32_bf16 v[108:111], v[162:165], v[196:199], v[108:111]
	v_mfma_f32_16x16x32_bf16 v[100:103], v[154:157], v[204:207], v[100:103]
	v_mfma_f32_16x16x32_bf16 v[92:95], v[162:165], v[204:207], v[92:95]
	v_mfma_f32_16x16x32_bf16 v[84:87], v[154:157], v[212:215], v[84:87]
	v_mfma_f32_16x16x32_bf16 v[76:79], v[162:165], v[212:215], v[76:79]
	v_mfma_f32_16x16x32_bf16 v[112:115], v[166:169], v[182:185], v[112:115]
	v_mfma_f32_16x16x32_bf16 v[104:107], v[174:177], v[182:185], v[104:107]
	v_mfma_f32_16x16x32_bf16 v[96:99], v[166:169], v[192:195], v[96:99]
	v_mfma_f32_16x16x32_bf16 v[88:91], v[174:177], v[192:195], v[88:91]
	v_mfma_f32_16x16x32_bf16 v[80:83], v[166:169], v[200:203], v[80:83]
	v_mfma_f32_16x16x32_bf16 v[72:75], v[174:177], v[200:203], v[72:75]
	v_mfma_f32_16x16x32_bf16 v[68:71], v[166:169], v[208:211], v[68:71]
	v_mfma_f32_16x16x32_bf16 v[64:67], v[174:177], v[208:211], v[64:67]
	v_mfma_f32_16x16x32_bf16 v[112:115], v[170:173], v[186:189], v[112:115]
	v_mfma_f32_16x16x32_bf16 v[104:107], v[178:181], v[186:189], v[104:107]
	v_mfma_f32_16x16x32_bf16 v[96:99], v[170:173], v[196:199], v[96:99]
	v_mfma_f32_16x16x32_bf16 v[88:91], v[178:181], v[196:199], v[88:91]
	v_mfma_f32_16x16x32_bf16 v[80:83], v[170:173], v[204:207], v[80:83]
	v_mfma_f32_16x16x32_bf16 v[72:75], v[178:181], v[204:207], v[72:75]
	v_mfma_f32_16x16x32_bf16 v[68:71], v[170:173], v[212:215], v[68:71]
	v_mfma_f32_16x16x32_bf16 v[64:67], v[178:181], v[212:215], v[64:67]
	s_barrier
	s_add_i32 s16, s60, s28
	v_lshl_add_u64 v[216:217], s[20:21], 0, v[132:133]
	s_mov_b32 m0, s16
	ds_read_b128 v[182:185], v153 offset:16384
	ds_read_b128 v[186:189], v153 offset:17408
	ds_read_b128 v[192:195], v153 offset:18432
	ds_read_b128 v[196:199], v153 offset:19456
	ds_read_b128 v[200:203], v153 offset:20480
	ds_read_b128 v[204:207], v153 offset:21504
	ds_read_b128 v[208:211], v153 offset:22528
	ds_read_b128 v[212:215], v153 offset:23552
	global_load_lds_dwordx4 v[216:217], off
	s_add_i32 m0, s16, 0x2000
	s_add_u32 s16, s20, 0x18000
	v_lshl_add_u64 v[218:219], s[20:21], 0, v[128:129]
	s_addc_u32 s17, s21, 0
	s_add_i32 s68, s61, s28
	global_load_lds_dwordx4 v[218:219], off
	s_mov_b32 m0, s68
	v_lshl_add_u64 v[222:223], s[22:23], 0, v[130:131]
	global_load_lds_dwordx4 v132, s[16:17]
	s_add_i32 m0, s68, 0x2000
	v_lshl_add_u64 v[220:221], s[22:23], 0, v[134:135]
	global_load_lds_dwordx4 v128, s[16:17]
	s_mov_b32 m0, s31
	s_nop 0
	global_load_lds_dwordx4 v[220:221], off
	s_mov_b32 m0, s33
	s_nop 0
	global_load_lds_dwordx4 v[222:223], off
	s_waitcnt vmcnt(8)
	s_waitcnt lgkmcnt(0)
	s_barrier
	v_mfma_f32_16x16x32_bf16 v[60:63], v[144:147], v[182:185], v[60:63]
	v_mfma_f32_16x16x32_bf16 v[56:59], v[158:161], v[182:185], v[56:59]
	v_mfma_f32_16x16x32_bf16 v[52:55], v[144:147], v[192:195], v[52:55]
	v_mfma_f32_16x16x32_bf16 v[44:47], v[158:161], v[192:195], v[44:47]
	v_mfma_f32_16x16x32_bf16 v[36:39], v[144:147], v[200:203], v[36:39]
	v_mfma_f32_16x16x32_bf16 v[28:31], v[158:161], v[200:203], v[28:31]
	v_mfma_f32_16x16x32_bf16 v[20:23], v[144:147], v[208:211], v[20:23]
	v_mfma_f32_16x16x32_bf16 v[12:15], v[158:161], v[208:211], v[12:15]
	v_mfma_f32_16x16x32_bf16 v[60:63], v[154:157], v[186:189], v[60:63]
	v_mfma_f32_16x16x32_bf16 v[56:59], v[162:165], v[186:189], v[56:59]
	v_mfma_f32_16x16x32_bf16 v[52:55], v[154:157], v[196:199], v[52:55]
	v_mfma_f32_16x16x32_bf16 v[44:47], v[162:165], v[196:199], v[44:47]
	v_mfma_f32_16x16x32_bf16 v[36:39], v[154:157], v[204:207], v[36:39]
	v_mfma_f32_16x16x32_bf16 v[28:31], v[162:165], v[204:207], v[28:31]
	v_mfma_f32_16x16x32_bf16 v[20:23], v[154:157], v[212:215], v[20:23]
	v_mfma_f32_16x16x32_bf16 v[12:15], v[162:165], v[212:215], v[12:15]
	v_mfma_f32_16x16x32_bf16 v[48:51], v[166:169], v[182:185], v[48:51]
	v_mfma_f32_16x16x32_bf16 v[40:43], v[174:177], v[182:185], v[40:43]
	v_mfma_f32_16x16x32_bf16 v[32:35], v[166:169], v[192:195], v[32:35]
	v_mfma_f32_16x16x32_bf16 v[24:27], v[174:177], v[192:195], v[24:27]
	v_mfma_f32_16x16x32_bf16 v[16:19], v[166:169], v[200:203], v[16:19]
	v_mfma_f32_16x16x32_bf16 v[8:11], v[174:177], v[200:203], v[8:11]
	v_mfma_f32_16x16x32_bf16 v[4:7], v[166:169], v[208:211], v[4:7]
	v_mfma_f32_16x16x32_bf16 v[0:3], v[174:177], v[208:211], v[0:3]
	v_mfma_f32_16x16x32_bf16 v[48:51], v[170:173], v[186:189], v[48:51]
	v_mfma_f32_16x16x32_bf16 v[40:43], v[178:181], v[186:189], v[40:43]
	v_mfma_f32_16x16x32_bf16 v[32:35], v[170:173], v[196:199], v[32:35]
	v_mfma_f32_16x16x32_bf16 v[24:27], v[178:181], v[196:199], v[24:27]
	v_mfma_f32_16x16x32_bf16 v[16:19], v[170:173], v[204:207], v[16:19]
	v_mfma_f32_16x16x32_bf16 v[8:11], v[178:181], v[204:207], v[8:11]
	v_mfma_f32_16x16x32_bf16 v[4:7], v[170:173], v[212:215], v[4:7]
	v_mfma_f32_16x16x32_bf16 v[0:3], v[178:181], v[212:215], v[0:3]
	s_barrier
	s_add_i32 s68, 0, 0x18000
	s_add_i32 s69, 0, 0x1c000
	v_add_u32_e32 v162, s68, v149
	v_add_u32_e32 v178, s69, v149
	ds_read_b128 v[144:147], v162
	ds_read_b128 v[154:157], v162 offset:1024
	ds_read_b128 v[158:161], v162 offset:2048
	ds_read_b128 v[162:165], v162 offset:3072
	ds_read_b128 v[166:169], v178
	ds_read_b128 v[170:173], v178 offset:1024
	ds_read_b128 v[174:177], v178 offset:2048
	ds_read_b128 v[178:181], v178 offset:3072
	s_add_u32 s16, s22, 0x18000
	s_addc_u32 s17, s23, 0
	s_mov_b32 m0, s34
	ds_read_b128 v[182:185], v153 offset:32768
	ds_read_b128 v[186:189], v153 offset:33792
	ds_read_b128 v[192:195], v153 offset:34816
	ds_read_b128 v[196:199], v153 offset:35840
	ds_read_b128 v[200:203], v153 offset:36864
	ds_read_b128 v[204:207], v153 offset:37888
	ds_read_b128 v[208:211], v153 offset:38912
	ds_read_b128 v[212:215], v153 offset:39936
	global_load_lds_dwordx4 v134, s[16:17]
	s_mov_b32 m0, s35
	s_nop 0
	global_load_lds_dwordx4 v130, s[16:17]
	s_waitcnt vmcnt(8)
	s_waitcnt lgkmcnt(0)
	s_barrier
	v_mfma_f32_16x16x32_bf16 v[124:127], v[144:147], v[182:185], v[124:127]
	v_mfma_f32_16x16x32_bf16 v[120:123], v[158:161], v[182:185], v[120:123]
	v_mfma_f32_16x16x32_bf16 v[116:119], v[144:147], v[192:195], v[116:119]
	v_mfma_f32_16x16x32_bf16 v[108:111], v[158:161], v[192:195], v[108:111]
	v_mfma_f32_16x16x32_bf16 v[100:103], v[144:147], v[200:203], v[100:103]
	v_mfma_f32_16x16x32_bf16 v[92:95], v[158:161], v[200:203], v[92:95]
	v_mfma_f32_16x16x32_bf16 v[84:87], v[144:147], v[208:211], v[84:87]
	v_mfma_f32_16x16x32_bf16 v[76:79], v[158:161], v[208:211], v[76:79]
	v_mfma_f32_16x16x32_bf16 v[124:127], v[154:157], v[186:189], v[124:127]
	v_mfma_f32_16x16x32_bf16 v[120:123], v[162:165], v[186:189], v[120:123]
	v_mfma_f32_16x16x32_bf16 v[116:119], v[154:157], v[196:199], v[116:119]
	v_mfma_f32_16x16x32_bf16 v[108:111], v[162:165], v[196:199], v[108:111]
	v_mfma_f32_16x16x32_bf16 v[100:103], v[154:157], v[204:207], v[100:103]
	v_mfma_f32_16x16x32_bf16 v[92:95], v[162:165], v[204:207], v[92:95]
	v_mfma_f32_16x16x32_bf16 v[84:87], v[154:157], v[212:215], v[84:87]
	v_mfma_f32_16x16x32_bf16 v[76:79], v[162:165], v[212:215], v[76:79]
	v_mfma_f32_16x16x32_bf16 v[112:115], v[166:169], v[182:185], v[112:115]
	v_mfma_f32_16x16x32_bf16 v[104:107], v[174:177], v[182:185], v[104:107]
	v_mfma_f32_16x16x32_bf16 v[96:99], v[166:169], v[192:195], v[96:99]
	v_mfma_f32_16x16x32_bf16 v[88:91], v[174:177], v[192:195], v[88:91]
	v_mfma_f32_16x16x32_bf16 v[80:83], v[166:169], v[200:203], v[80:83]
	v_mfma_f32_16x16x32_bf16 v[72:75], v[174:177], v[200:203], v[72:75]
	v_mfma_f32_16x16x32_bf16 v[68:71], v[166:169], v[208:211], v[68:71]
	v_mfma_f32_16x16x32_bf16 v[64:67], v[174:177], v[208:211], v[64:67]
	v_mfma_f32_16x16x32_bf16 v[112:115], v[170:173], v[186:189], v[112:115]
	v_mfma_f32_16x16x32_bf16 v[104:107], v[178:181], v[186:189], v[104:107]
	v_mfma_f32_16x16x32_bf16 v[96:99], v[170:173], v[196:199], v[96:99]
	v_mfma_f32_16x16x32_bf16 v[88:91], v[178:181], v[196:199], v[88:91]
	v_mfma_f32_16x16x32_bf16 v[80:83], v[170:173], v[204:207], v[80:83]
	v_mfma_f32_16x16x32_bf16 v[72:75], v[178:181], v[204:207], v[72:75]
	v_mfma_f32_16x16x32_bf16 v[68:71], v[170:173], v[212:215], v[68:71]
	v_mfma_f32_16x16x32_bf16 v[64:67], v[178:181], v[212:215], v[64:67]
	s_barrier
	s_add_i32 s16, s68, s28
	v_lshl_add_u64 v[216:217], v[216:217], 0, s[10:11]
	s_mov_b32 m0, s16
	ds_read_b128 v[182:185], v153 offset:49152
	ds_read_b128 v[186:189], v153 offset:50176
	ds_read_b128 v[192:195], v153 offset:51200
	ds_read_b128 v[196:199], v153 offset:52224
	ds_read_b128 v[200:203], v153 offset:53248
	ds_read_b128 v[204:207], v153 offset:54272
	ds_read_b128 v[208:211], v153 offset:55296
	ds_read_b128 v[212:215], v153 offset:56320
	global_load_lds_dwordx4 v[216:217], off
	s_add_i32 m0, s16, 0x2000
	s_add_u32 s16, s20, 0x18080
	v_lshl_add_u64 v[216:217], v[218:219], 0, s[10:11]
	s_addc_u32 s17, s21, 0
	s_add_i32 s20, s69, s28
	global_load_lds_dwordx4 v[216:217], off
	s_mov_b32 m0, s20
	s_nop 0
	global_load_lds_dwordx4 v132, s[16:17]
	s_add_i32 m0, s20, 0x2000
	v_lshl_add_u64 v[216:217], v[220:221], 0, s[10:11]
	global_load_lds_dwordx4 v128, s[16:17]
	s_mov_b32 m0, s43
	s_nop 0
	global_load_lds_dwordx4 v[216:217], off
	s_mov_b32 m0, s52
	v_lshl_add_u64 v[216:217], v[222:223], 0, s[10:11]
	global_load_lds_dwordx4 v[216:217], off
	s_waitcnt vmcnt(8)
	s_waitcnt lgkmcnt(0)
	s_barrier
	v_mfma_f32_16x16x32_bf16 v[60:63], v[144:147], v[182:185], v[60:63]
	v_mfma_f32_16x16x32_bf16 v[56:59], v[158:161], v[182:185], v[56:59]
	v_mfma_f32_16x16x32_bf16 v[52:55], v[144:147], v[192:195], v[52:55]
	v_mfma_f32_16x16x32_bf16 v[44:47], v[158:161], v[192:195], v[44:47]
	v_mfma_f32_16x16x32_bf16 v[36:39], v[144:147], v[200:203], v[36:39]
	v_mfma_f32_16x16x32_bf16 v[28:31], v[158:161], v[200:203], v[28:31]
	v_mfma_f32_16x16x32_bf16 v[20:23], v[144:147], v[208:211], v[20:23]
	v_mfma_f32_16x16x32_bf16 v[12:15], v[158:161], v[208:211], v[12:15]
	v_mfma_f32_16x16x32_bf16 v[60:63], v[154:157], v[186:189], v[60:63]
	v_mfma_f32_16x16x32_bf16 v[56:59], v[162:165], v[186:189], v[56:59]
	v_mfma_f32_16x16x32_bf16 v[52:55], v[154:157], v[196:199], v[52:55]
	v_mfma_f32_16x16x32_bf16 v[44:47], v[162:165], v[196:199], v[44:47]
	v_mfma_f32_16x16x32_bf16 v[36:39], v[154:157], v[204:207], v[36:39]
	v_mfma_f32_16x16x32_bf16 v[28:31], v[162:165], v[204:207], v[28:31]
	v_mfma_f32_16x16x32_bf16 v[20:23], v[154:157], v[212:215], v[20:23]
	v_mfma_f32_16x16x32_bf16 v[12:15], v[162:165], v[212:215], v[12:15]
	v_mfma_f32_16x16x32_bf16 v[48:51], v[166:169], v[182:185], v[48:51]
	v_mfma_f32_16x16x32_bf16 v[40:43], v[174:177], v[182:185], v[40:43]
	v_mfma_f32_16x16x32_bf16 v[32:35], v[166:169], v[192:195], v[32:35]
	v_mfma_f32_16x16x32_bf16 v[24:27], v[174:177], v[192:195], v[24:27]
	v_mfma_f32_16x16x32_bf16 v[16:19], v[166:169], v[200:203], v[16:19]
	v_mfma_f32_16x16x32_bf16 v[8:11], v[174:177], v[200:203], v[8:11]
	v_mfma_f32_16x16x32_bf16 v[4:7], v[166:169], v[208:211], v[4:7]
	v_mfma_f32_16x16x32_bf16 v[0:3], v[174:177], v[208:211], v[0:3]
	v_mfma_f32_16x16x32_bf16 v[48:51], v[170:173], v[186:189], v[48:51]
	v_mfma_f32_16x16x32_bf16 v[40:43], v[178:181], v[186:189], v[40:43]
	v_mfma_f32_16x16x32_bf16 v[32:35], v[170:173], v[196:199], v[32:35]
	v_mfma_f32_16x16x32_bf16 v[24:27], v[178:181], v[196:199], v[24:27]
	v_mfma_f32_16x16x32_bf16 v[16:19], v[170:173], v[204:207], v[16:19]
	v_mfma_f32_16x16x32_bf16 v[8:11], v[178:181], v[204:207], v[8:11]
	v_mfma_f32_16x16x32_bf16 v[4:7], v[170:173], v[212:215], v[4:7]
	v_mfma_f32_16x16x32_bf16 v[0:3], v[178:181], v[212:215], v[0:3]
	s_barrier
	s_add_i32 s67, s67, 2
	s_add_u32 s65, s65, 0x100
	s_addc_u32 s66, s66, 0
	s_cmp_gt_u32 s67, 3
	s_mov_b64 s[16:17], s[18:19]
	s_cbranch_scc0 .LBB0_1266

.LBB0_1433:
	s_ashr_i32 s23, s22, 31
	s_lshl_b64 s[24:25], s[22:23], 19
	s_add_u32 s24, s56, s24
	s_addc_u32 s25, s57, s25
	s_and_b64 s[26:27], s[0:1], exec
	s_cselect_b32 s23, s25, s31
	s_cselect_b32 s55, s24, s30
	s_ashr_i32 s21, s20, 31
	s_lshl_b64 s[26:27], s[20:21], 19
	s_add_u32 s26, s53, s26
	s_addc_u32 s27, s60, s27
	s_and_b64 s[42:43], s[0:1], exec
	s_cselect_b32 s21, s27, s35
	s_cselect_b32 s74, s26, s34
	s_add_u32 s30, s30, 0x40080
	s_addc_u32 s31, s31, 0
	s_add_u32 s75, s34, 0x100
	s_addc_u32 s76, s35, 0
	s_mov_b32 s77, -2
	ds_read_b128 v[152:155], v149
	ds_read_b128 v[156:159], v149 offset:1024
	ds_read_b128 v[160:163], v149 offset:2048
	ds_read_b128 v[164:167], v149 offset:3072
	ds_read_b128 v[168:171], v150
	ds_read_b128 v[172:175], v150 offset:1024
	ds_read_b128 v[176:179], v150 offset:2048
	ds_read_b128 v[180:183], v150 offset:3072
	s_add_u32 s34, s30, 0xfffc0080
	s_addc_u32 s35, s31, -1
	s_cmp_eq_u32 s77, 12
	s_cselect_b32 s43, s23, s35
	s_cselect_b32 s42, s55, s34
	s_cselect_b32 s35, s21, s76
	s_cselect_b32 s34, s74, s75
	s_add_i32 m0, s29, 0xc000
	ds_read_b128 v[184:187], v151
	ds_read_b128 v[192:195], v151 offset:1024
	ds_read_b128 v[196:199], v151 offset:2048
	ds_read_b128 v[200:203], v151 offset:3072
	ds_read_b128 v[204:207], v151 offset:4096
	ds_read_b128 v[208:211], v151 offset:5120
	ds_read_b128 v[212:215], v151 offset:6144
	ds_read_b128 v[216:219], v151 offset:7168
	global_load_lds_dwordx4 v136, s[30:31]
	s_add_i32 m0, s29, 0xe000
	s_nop 0
	global_load_lds_dwordx4 v138, s[30:31]
	s_waitcnt vmcnt(8)
	s_waitcnt lgkmcnt(0)
	s_barrier
	v_mfma_f32_16x16x32_bf16 v[124:127], v[152:155], v[184:187], 0
	v_mfma_f32_16x16x32_bf16 v[120:123], v[160:163], v[184:187], 0
	v_mfma_f32_16x16x32_bf16 v[116:119], v[152:155], v[196:199], 0
	v_mfma_f32_16x16x32_bf16 v[108:111], v[160:163], v[196:199], 0
	v_mfma_f32_16x16x32_bf16 v[100:103], v[152:155], v[204:207], 0
	v_mfma_f32_16x16x32_bf16 v[92:95], v[160:163], v[204:207], 0
	v_mfma_f32_16x16x32_bf16 v[84:87], v[152:155], v[212:215], 0
	v_mfma_f32_16x16x32_bf16 v[76:79], v[160:163], v[212:215], 0
	v_mfma_f32_16x16x32_bf16 v[124:127], v[156:159], v[192:195], v[124:127]
	v_mfma_f32_16x16x32_bf16 v[120:123], v[164:167], v[192:195], v[120:123]
	v_mfma_f32_16x16x32_bf16 v[116:119], v[156:159], v[200:203], v[116:119]
	v_mfma_f32_16x16x32_bf16 v[108:111], v[164:167], v[200:203], v[108:111]
	v_mfma_f32_16x16x32_bf16 v[100:103], v[156:159], v[208:211], v[100:103]
	v_mfma_f32_16x16x32_bf16 v[92:95], v[164:167], v[208:211], v[92:95]
	v_mfma_f32_16x16x32_bf16 v[84:87], v[156:159], v[216:219], v[84:87]
	v_mfma_f32_16x16x32_bf16 v[76:79], v[164:167], v[216:219], v[76:79]
	v_mfma_f32_16x16x32_bf16 v[112:115], v[168:171], v[184:187], 0
	v_mfma_f32_16x16x32_bf16 v[104:107], v[176:179], v[184:187], 0
	v_mfma_f32_16x16x32_bf16 v[96:99], v[168:171], v[196:199], 0
	v_mfma_f32_16x16x32_bf16 v[88:91], v[176:179], v[196:199], 0
	v_mfma_f32_16x16x32_bf16 v[80:83], v[168:171], v[204:207], 0
	v_mfma_f32_16x16x32_bf16 v[72:75], v[176:179], v[204:207], 0
	v_mfma_f32_16x16x32_bf16 v[68:71], v[168:171], v[212:215], 0
	v_mfma_f32_16x16x32_bf16 v[64:67], v[176:179], v[212:215], 0
	v_mfma_f32_16x16x32_bf16 v[112:115], v[172:175], v[192:195], v[112:115]
	v_mfma_f32_16x16x32_bf16 v[104:107], v[180:183], v[192:195], v[104:107]
	v_mfma_f32_16x16x32_bf16 v[96:99], v[172:175], v[200:203], v[96:99]
	v_mfma_f32_16x16x32_bf16 v[88:91], v[180:183], v[200:203], v[88:91]
	v_mfma_f32_16x16x32_bf16 v[80:83], v[172:175], v[208:211], v[80:83]
	v_mfma_f32_16x16x32_bf16 v[72:75], v[180:183], v[208:211], v[72:75]
	v_mfma_f32_16x16x32_bf16 v[68:71], v[172:175], v[216:219], v[68:71]
	v_mfma_f32_16x16x32_bf16 v[64:67], v[180:183], v[216:219], v[64:67]
	s_barrier
	s_add_i32 s79, s68, s61
	v_lshl_add_u64 v[144:145], s[34:35], 0, v[130:131]
	s_mov_b32 m0, s79
	ds_read_b128 v[184:187], v151 offset:16384
	ds_read_b128 v[192:195], v151 offset:17408
	ds_read_b128 v[196:199], v151 offset:18432
	ds_read_b128 v[200:203], v151 offset:19456
	ds_read_b128 v[204:207], v151 offset:20480
	ds_read_b128 v[208:211], v151 offset:21504
	ds_read_b128 v[212:215], v151 offset:22528
	ds_read_b128 v[216:219], v151 offset:23552
	global_load_lds_dwordx4 v[144:145], off
	s_add_i32 m0, s79, 0x2000
	s_add_u32 s80, s34, 0x40000
	v_lshl_add_u64 v[188:189], s[34:35], 0, v[134:135]
	s_addc_u32 s81, s35, 0
	s_add_i32 s79, s69, s61
	global_load_lds_dwordx4 v[188:189], off
	s_mov_b32 m0, s79
	v_lshl_add_u64 v[222:223], s[42:43], 0, v[132:133]
	global_load_lds_dwordx4 v130, s[80:81]
	s_add_i32 m0, s79, 0x2000
	v_lshl_add_u64 v[220:221], s[42:43], 0, v[128:129]
	global_load_lds_dwordx4 v134, s[80:81]
	s_mov_b32 m0, s29
	s_nop 0
	global_load_lds_dwordx4 v[220:221], off
	s_mov_b32 m0, s33
	s_nop 0
	global_load_lds_dwordx4 v[222:223], off
	s_waitcnt vmcnt(8)
	s_waitcnt lgkmcnt(0)
	s_barrier
	v_mfma_f32_16x16x32_bf16 v[60:63], v[152:155], v[184:187], 0
	v_mfma_f32_16x16x32_bf16 v[56:59], v[160:163], v[184:187], 0
	v_mfma_f32_16x16x32_bf16 v[52:55], v[152:155], v[196:199], 0
	v_mfma_f32_16x16x32_bf16 v[44:47], v[160:163], v[196:199], 0
	v_mfma_f32_16x16x32_bf16 v[36:39], v[152:155], v[204:207], 0
	v_mfma_f32_16x16x32_bf16 v[28:31], v[160:163], v[204:207], 0
	v_mfma_f32_16x16x32_bf16 v[20:23], v[152:155], v[212:215], 0
	v_mfma_f32_16x16x32_bf16 v[12:15], v[160:163], v[212:215], 0
	v_mfma_f32_16x16x32_bf16 v[60:63], v[156:159], v[192:195], v[60:63]
	v_mfma_f32_16x16x32_bf16 v[56:59], v[164:167], v[192:195], v[56:59]
	v_mfma_f32_16x16x32_bf16 v[52:55], v[156:159], v[200:203], v[52:55]
	v_mfma_f32_16x16x32_bf16 v[44:47], v[164:167], v[200:203], v[44:47]
	v_mfma_f32_16x16x32_bf16 v[36:39], v[156:159], v[208:211], v[36:39]
	v_mfma_f32_16x16x32_bf16 v[28:31], v[164:167], v[208:211], v[28:31]
	v_mfma_f32_16x16x32_bf16 v[20:23], v[156:159], v[216:219], v[20:23]
	v_mfma_f32_16x16x32_bf16 v[12:15], v[164:167], v[216:219], v[12:15]
	v_mfma_f32_16x16x32_bf16 v[48:51], v[168:171], v[184:187], 0
	v_mfma_f32_16x16x32_bf16 v[40:43], v[176:179], v[184:187], 0
	v_mfma_f32_16x16x32_bf16 v[32:35], v[168:171], v[196:199], 0
	v_mfma_f32_16x16x32_bf16 v[24:27], v[176:179], v[196:199], 0
	v_mfma_f32_16x16x32_bf16 v[16:19], v[168:171], v[204:207], 0
	v_mfma_f32_16x16x32_bf16 v[8:11], v[176:179], v[204:207], 0
	v_mfma_f32_16x16x32_bf16 v[4:7], v[168:171], v[212:215], 0
	v_mfma_f32_16x16x32_bf16 v[0:3], v[176:179], v[212:215], 0
	v_mfma_f32_16x16x32_bf16 v[48:51], v[172:175], v[192:195], v[48:51]
	v_mfma_f32_16x16x32_bf16 v[40:43], v[180:183], v[192:195], v[40:43]
	v_mfma_f32_16x16x32_bf16 v[32:35], v[172:175], v[200:203], v[32:35]
	v_mfma_f32_16x16x32_bf16 v[24:27], v[180:183], v[200:203], v[24:27]
	v_mfma_f32_16x16x32_bf16 v[16:19], v[172:175], v[208:211], v[16:19]
	v_mfma_f32_16x16x32_bf16 v[8:11], v[180:183], v[208:211], v[8:11]
	v_mfma_f32_16x16x32_bf16 v[4:7], v[172:175], v[216:219], v[4:7]
	v_mfma_f32_16x16x32_bf16 v[0:3], v[180:183], v[216:219], v[0:3]
	s_barrier
	s_add_i32 s79, 0, 0x18000
	s_add_i32 s80, 0, 0x1c000
	v_add_u32_e32 v164, s79, v147
	v_add_u32_e32 v180, s80, v147
	ds_read_b128 v[152:155], v164
	ds_read_b128 v[156:159], v164 offset:1024
	ds_read_b128 v[160:163], v164 offset:2048
	ds_read_b128 v[164:167], v164 offset:3072
	ds_read_b128 v[168:171], v180
	ds_read_b128 v[172:175], v180 offset:1024
	ds_read_b128 v[176:179], v180 offset:2048
	ds_read_b128 v[180:183], v180 offset:3072
	s_add_u32 s42, s42, 0x40000
	s_addc_u32 s43, s43, 0
	s_mov_b32 m0, s62
	ds_read_b128 v[184:187], v151 offset:32768
	ds_read_b128 v[192:195], v151 offset:33792
	ds_read_b128 v[196:199], v151 offset:34816
	ds_read_b128 v[200:203], v151 offset:35840
	ds_read_b128 v[204:207], v151 offset:36864
	ds_read_b128 v[208:211], v151 offset:37888
	ds_read_b128 v[212:215], v151 offset:38912
	ds_read_b128 v[216:219], v151 offset:39936
	global_load_lds_dwordx4 v128, s[42:43]
	s_mov_b32 m0, s63
	s_nop 0
	global_load_lds_dwordx4 v132, s[42:43]
	s_waitcnt vmcnt(8)
	s_waitcnt lgkmcnt(0)
	s_barrier
	v_mfma_f32_16x16x32_bf16 v[124:127], v[152:155], v[184:187], v[124:127]
	v_mfma_f32_16x16x32_bf16 v[120:123], v[160:163], v[184:187], v[120:123]
	v_mfma_f32_16x16x32_bf16 v[116:119], v[152:155], v[196:199], v[116:119]
	v_mfma_f32_16x16x32_bf16 v[108:111], v[160:163], v[196:199], v[108:111]
	v_mfma_f32_16x16x32_bf16 v[100:103], v[152:155], v[204:207], v[100:103]
	v_mfma_f32_16x16x32_bf16 v[92:95], v[160:163], v[204:207], v[92:95]
	v_mfma_f32_16x16x32_bf16 v[84:87], v[152:155], v[212:215], v[84:87]
	v_mfma_f32_16x16x32_bf16 v[76:79], v[160:163], v[212:215], v[76:79]
	v_mfma_f32_16x16x32_bf16 v[124:127], v[156:159], v[192:195], v[124:127]
	v_mfma_f32_16x16x32_bf16 v[120:123], v[164:167], v[192:195], v[120:123]
	v_mfma_f32_16x16x32_bf16 v[116:119], v[156:159], v[200:203], v[116:119]
	v_mfma_f32_16x16x32_bf16 v[108:111], v[164:167], v[200:203], v[108:111]
	v_mfma_f32_16x16x32_bf16 v[100:103], v[156:159], v[208:211], v[100:103]
	v_mfma_f32_16x16x32_bf16 v[92:95], v[164:167], v[208:211], v[92:95]
	v_mfma_f32_16x16x32_bf16 v[84:87], v[156:159], v[216:219], v[84:87]
	v_mfma_f32_16x16x32_bf16 v[76:79], v[164:167], v[216:219], v[76:79]
	v_mfma_f32_16x16x32_bf16 v[112:115], v[168:171], v[184:187], v[112:115]
	v_mfma_f32_16x16x32_bf16 v[104:107], v[176:179], v[184:187], v[104:107]
	v_mfma_f32_16x16x32_bf16 v[96:99], v[168:171], v[196:199], v[96:99]
	v_mfma_f32_16x16x32_bf16 v[88:91], v[176:179], v[196:199], v[88:91]
	v_mfma_f32_16x16x32_bf16 v[80:83], v[168:171], v[204:207], v[80:83]
	v_mfma_f32_16x16x32_bf16 v[72:75], v[176:179], v[204:207], v[72:75]
	v_mfma_f32_16x16x32_bf16 v[68:71], v[168:171], v[212:215], v[68:71]
	v_mfma_f32_16x16x32_bf16 v[64:67], v[176:179], v[212:215], v[64:67]
	v_mfma_f32_16x16x32_bf16 v[112:115], v[172:175], v[192:195], v[112:115]
	v_mfma_f32_16x16x32_bf16 v[104:107], v[180:183], v[192:195], v[104:107]
	v_mfma_f32_16x16x32_bf16 v[96:99], v[172:175], v[200:203], v[96:99]
	v_mfma_f32_16x16x32_bf16 v[88:91], v[180:183], v[200:203], v[88:91]
	v_mfma_f32_16x16x32_bf16 v[80:83], v[172:175], v[208:211], v[80:83]
	v_mfma_f32_16x16x32_bf16 v[72:75], v[180:183], v[208:211], v[72:75]
	v_mfma_f32_16x16x32_bf16 v[68:71], v[172:175], v[216:219], v[68:71]
	v_mfma_f32_16x16x32_bf16 v[64:67], v[180:183], v[216:219], v[64:67]
	s_barrier
	s_add_i32 s42, s79, s61
	v_lshl_add_u64 v[144:145], v[144:145], 0, s[10:11]
	s_mov_b32 m0, s42
	ds_read_b128 v[184:187], v151 offset:49152
	ds_read_b128 v[192:195], v151 offset:50176
	ds_read_b128 v[196:199], v151 offset:51200
	ds_read_b128 v[200:203], v151 offset:52224
	ds_read_b128 v[204:207], v151 offset:53248
	ds_read_b128 v[208:211], v151 offset:54272
	ds_read_b128 v[212:215], v151 offset:55296
	ds_read_b128 v[216:219], v151 offset:56320
	global_load_lds_dwordx4 v[144:145], off
	s_add_i32 m0, s42, 0x2000
	s_add_u32 s34, s34, 0x40080
	v_lshl_add_u64 v[144:145], v[188:189], 0, s[10:11]
	s_addc_u32 s35, s35, 0
	s_add_i32 s42, s80, s61
	global_load_lds_dwordx4 v[144:145], off
	s_mov_b32 m0, s42
	s_nop 0
	global_load_lds_dwordx4 v130, s[34:35]
	s_add_i32 m0, s42, 0x2000
	v_lshl_add_u64 v[144:145], v[220:221], 0, s[10:11]
	global_load_lds_dwordx4 v134, s[34:35]
	s_mov_b32 m0, s65
	s_nop 0
	global_load_lds_dwordx4 v[144:145], off
	s_mov_b32 m0, s66
	v_lshl_add_u64 v[144:145], v[222:223], 0, s[10:11]
	global_load_lds_dwordx4 v[144:145], off
	s_waitcnt vmcnt(8)
	s_waitcnt lgkmcnt(0)
	s_barrier
	v_mfma_f32_16x16x32_bf16 v[60:63], v[152:155], v[184:187], v[60:63]
	v_mfma_f32_16x16x32_bf16 v[56:59], v[160:163], v[184:187], v[56:59]
	v_mfma_f32_16x16x32_bf16 v[52:55], v[152:155], v[196:199], v[52:55]
	v_mfma_f32_16x16x32_bf16 v[44:47], v[160:163], v[196:199], v[44:47]
	v_mfma_f32_16x16x32_bf16 v[36:39], v[152:155], v[204:207], v[36:39]
	v_mfma_f32_16x16x32_bf16 v[28:31], v[160:163], v[204:207], v[28:31]
	v_mfma_f32_16x16x32_bf16 v[20:23], v[152:155], v[212:215], v[20:23]
	v_mfma_f32_16x16x32_bf16 v[12:15], v[160:163], v[212:215], v[12:15]
	v_mfma_f32_16x16x32_bf16 v[60:63], v[156:159], v[192:195], v[60:63]
	v_mfma_f32_16x16x32_bf16 v[56:59], v[164:167], v[192:195], v[56:59]
	v_mfma_f32_16x16x32_bf16 v[52:55], v[156:159], v[200:203], v[52:55]
	v_mfma_f32_16x16x32_bf16 v[44:47], v[164:167], v[200:203], v[44:47]
	v_mfma_f32_16x16x32_bf16 v[36:39], v[156:159], v[208:211], v[36:39]
	v_mfma_f32_16x16x32_bf16 v[28:31], v[164:167], v[208:211], v[28:31]
	v_mfma_f32_16x16x32_bf16 v[20:23], v[156:159], v[216:219], v[20:23]
	v_mfma_f32_16x16x32_bf16 v[12:15], v[164:167], v[216:219], v[12:15]
	v_mfma_f32_16x16x32_bf16 v[48:51], v[168:171], v[184:187], v[48:51]
	v_mfma_f32_16x16x32_bf16 v[40:43], v[176:179], v[184:187], v[40:43]
	v_mfma_f32_16x16x32_bf16 v[32:35], v[168:171], v[196:199], v[32:35]
	v_mfma_f32_16x16x32_bf16 v[24:27], v[176:179], v[196:199], v[24:27]
	v_mfma_f32_16x16x32_bf16 v[16:19], v[168:171], v[204:207], v[16:19]
	v_mfma_f32_16x16x32_bf16 v[8:11], v[176:179], v[204:207], v[8:11]
	v_mfma_f32_16x16x32_bf16 v[4:7], v[168:171], v[212:215], v[4:7]
	v_mfma_f32_16x16x32_bf16 v[0:3], v[176:179], v[212:215], v[0:3]
	v_mfma_f32_16x16x32_bf16 v[48:51], v[172:175], v[192:195], v[48:51]
	v_mfma_f32_16x16x32_bf16 v[40:43], v[180:183], v[192:195], v[40:43]
	v_mfma_f32_16x16x32_bf16 v[32:35], v[172:175], v[200:203], v[32:35]
	v_mfma_f32_16x16x32_bf16 v[24:27], v[180:183], v[200:203], v[24:27]
	v_mfma_f32_16x16x32_bf16 v[16:19], v[172:175], v[208:211], v[16:19]
	v_mfma_f32_16x16x32_bf16 v[8:11], v[180:183], v[208:211], v[8:11]
	v_mfma_f32_16x16x32_bf16 v[4:7], v[172:175], v[216:219], v[4:7]
	v_mfma_f32_16x16x32_bf16 v[0:3], v[180:183], v[216:219], v[0:3]
	s_barrier
	s_add_i32 s77, s77, 2
	s_add_u32 s30, s30, 0x100
	s_addc_u32 s31, s31, 0
	s_add_u32 s75, s75, 0x100
	s_addc_u32 s76, s76, 0
	s_cmp_gt_u32 s77, 13
	s_cbranch_scc0 .LBB0_1434
	s_branch .Lpeel_exit10
.LBB0_1434:
	ds_read_b128 v[152:155], v149
	ds_read_b128 v[156:159], v149 offset:1024
	ds_read_b128 v[160:163], v149 offset:2048
	ds_read_b128 v[164:167], v149 offset:3072
	ds_read_b128 v[168:171], v150
	ds_read_b128 v[172:175], v150 offset:1024
	ds_read_b128 v[176:179], v150 offset:2048
	ds_read_b128 v[180:183], v150 offset:3072
	s_add_u32 s34, s30, 0xfffc0080
	s_addc_u32 s35, s31, -1
	s_cmp_eq_u32 s77, 12
	s_cselect_b32 s43, s23, s35
	s_cselect_b32 s42, s55, s34
	s_cselect_b32 s35, s21, s76
	s_cselect_b32 s34, s74, s75
	s_add_i32 m0, s29, 0xc000
	ds_read_b128 v[184:187], v151
	ds_read_b128 v[192:195], v151 offset:1024
	ds_read_b128 v[196:199], v151 offset:2048
	ds_read_b128 v[200:203], v151 offset:3072
	ds_read_b128 v[204:207], v151 offset:4096
	ds_read_b128 v[208:211], v151 offset:5120
	ds_read_b128 v[212:215], v151 offset:6144
	ds_read_b128 v[216:219], v151 offset:7168
	global_load_lds_dwordx4 v136, s[30:31]
	s_add_i32 m0, s29, 0xe000
	s_nop 0
	global_load_lds_dwordx4 v138, s[30:31]
	s_waitcnt vmcnt(8)
	s_waitcnt lgkmcnt(0)
	s_barrier
	v_mfma_f32_16x16x32_bf16 v[124:127], v[152:155], v[184:187], v[124:127]
	v_mfma_f32_16x16x32_bf16 v[120:123], v[160:163], v[184:187], v[120:123]
	v_mfma_f32_16x16x32_bf16 v[116:119], v[152:155], v[196:199], v[116:119]
	v_mfma_f32_16x16x32_bf16 v[108:111], v[160:163], v[196:199], v[108:111]
	v_mfma_f32_16x16x32_bf16 v[100:103], v[152:155], v[204:207], v[100:103]
	v_mfma_f32_16x16x32_bf16 v[92:95], v[160:163], v[204:207], v[92:95]
	v_mfma_f32_16x16x32_bf16 v[84:87], v[152:155], v[212:215], v[84:87]
	v_mfma_f32_16x16x32_bf16 v[76:79], v[160:163], v[212:215], v[76:79]
	v_mfma_f32_16x16x32_bf16 v[124:127], v[156:159], v[192:195], v[124:127]
	v_mfma_f32_16x16x32_bf16 v[120:123], v[164:167], v[192:195], v[120:123]
	v_mfma_f32_16x16x32_bf16 v[116:119], v[156:159], v[200:203], v[116:119]
	v_mfma_f32_16x16x32_bf16 v[108:111], v[164:167], v[200:203], v[108:111]
	v_mfma_f32_16x16x32_bf16 v[100:103], v[156:159], v[208:211], v[100:103]
	v_mfma_f32_16x16x32_bf16 v[92:95], v[164:167], v[208:211], v[92:95]
	v_mfma_f32_16x16x32_bf16 v[84:87], v[156:159], v[216:219], v[84:87]
	v_mfma_f32_16x16x32_bf16 v[76:79], v[164:167], v[216:219], v[76:79]
	v_mfma_f32_16x16x32_bf16 v[112:115], v[168:171], v[184:187], v[112:115]
	v_mfma_f32_16x16x32_bf16 v[104:107], v[176:179], v[184:187], v[104:107]
	v_mfma_f32_16x16x32_bf16 v[96:99], v[168:171], v[196:199], v[96:99]
	v_mfma_f32_16x16x32_bf16 v[88:91], v[176:179], v[196:199], v[88:91]
	v_mfma_f32_16x16x32_bf16 v[80:83], v[168:171], v[204:207], v[80:83]
	v_mfma_f32_16x16x32_bf16 v[72:75], v[176:179], v[204:207], v[72:75]
	v_mfma_f32_16x16x32_bf16 v[68:71], v[168:171], v[212:215], v[68:71]
	v_mfma_f32_16x16x32_bf16 v[64:67], v[176:179], v[212:215], v[64:67]
	v_mfma_f32_16x16x32_bf16 v[112:115], v[172:175], v[192:195], v[112:115]
	v_mfma_f32_16x16x32_bf16 v[104:107], v[180:183], v[192:195], v[104:107]
	v_mfma_f32_16x16x32_bf16 v[96:99], v[172:175], v[200:203], v[96:99]
	v_mfma_f32_16x16x32_bf16 v[88:91], v[180:183], v[200:203], v[88:91]
	v_mfma_f32_16x16x32_bf16 v[80:83], v[172:175], v[208:211], v[80:83]
	v_mfma_f32_16x16x32_bf16 v[72:75], v[180:183], v[208:211], v[72:75]
	v_mfma_f32_16x16x32_bf16 v[68:71], v[172:175], v[216:219], v[68:71]
	v_mfma_f32_16x16x32_bf16 v[64:67], v[180:183], v[216:219], v[64:67]
	s_barrier
	s_add_i32 s79, s68, s61
	v_lshl_add_u64 v[144:145], s[34:35], 0, v[130:131]
	s_mov_b32 m0, s79
	ds_read_b128 v[184:187], v151 offset:16384
	ds_read_b128 v[192:195], v151 offset:17408
	ds_read_b128 v[196:199], v151 offset:18432
	ds_read_b128 v[200:203], v151 offset:19456
	ds_read_b128 v[204:207], v151 offset:20480
	ds_read_b128 v[208:211], v151 offset:21504
	ds_read_b128 v[212:215], v151 offset:22528
	ds_read_b128 v[216:219], v151 offset:23552
	global_load_lds_dwordx4 v[144:145], off
	s_add_i32 m0, s79, 0x2000
	s_add_u32 s80, s34, 0x40000
	v_lshl_add_u64 v[188:189], s[34:35], 0, v[134:135]
	s_addc_u32 s81, s35, 0
	s_add_i32 s79, s69, s61
	global_load_lds_dwordx4 v[188:189], off
	s_mov_b32 m0, s79
	v_lshl_add_u64 v[222:223], s[42:43], 0, v[132:133]
	global_load_lds_dwordx4 v130, s[80:81]
	s_add_i32 m0, s79, 0x2000
	v_lshl_add_u64 v[220:221], s[42:43], 0, v[128:129]
	global_load_lds_dwordx4 v134, s[80:81]
	s_mov_b32 m0, s29
	s_nop 0
	global_load_lds_dwordx4 v[220:221], off
	s_mov_b32 m0, s33
	s_nop 0
	global_load_lds_dwordx4 v[222:223], off
	s_waitcnt vmcnt(8)
	s_waitcnt lgkmcnt(0)
	s_barrier
	v_mfma_f32_16x16x32_bf16 v[60:63], v[152:155], v[184:187], v[60:63]
	v_mfma_f32_16x16x32_bf16 v[56:59], v[160:163], v[184:187], v[56:59]
	v_mfma_f32_16x16x32_bf16 v[52:55], v[152:155], v[196:199], v[52:55]
	v_mfma_f32_16x16x32_bf16 v[44:47], v[160:163], v[196:199], v[44:47]
	v_mfma_f32_16x16x32_bf16 v[36:39], v[152:155], v[204:207], v[36:39]
	v_mfma_f32_16x16x32_bf16 v[28:31], v[160:163], v[204:207], v[28:31]
	v_mfma_f32_16x16x32_bf16 v[20:23], v[152:155], v[212:215], v[20:23]
	v_mfma_f32_16x16x32_bf16 v[12:15], v[160:163], v[212:215], v[12:15]
	v_mfma_f32_16x16x32_bf16 v[60:63], v[156:159], v[192:195], v[60:63]
	v_mfma_f32_16x16x32_bf16 v[56:59], v[164:167], v[192:195], v[56:59]
	v_mfma_f32_16x16x32_bf16 v[52:55], v[156:159], v[200:203], v[52:55]
	v_mfma_f32_16x16x32_bf16 v[44:47], v[164:167], v[200:203], v[44:47]
	v_mfma_f32_16x16x32_bf16 v[36:39], v[156:159], v[208:211], v[36:39]
	v_mfma_f32_16x16x32_bf16 v[28:31], v[164:167], v[208:211], v[28:31]
	v_mfma_f32_16x16x32_bf16 v[20:23], v[156:159], v[216:219], v[20:23]
	v_mfma_f32_16x16x32_bf16 v[12:15], v[164:167], v[216:219], v[12:15]
	v_mfma_f32_16x16x32_bf16 v[48:51], v[168:171], v[184:187], v[48:51]
	v_mfma_f32_16x16x32_bf16 v[40:43], v[176:179], v[184:187], v[40:43]
	v_mfma_f32_16x16x32_bf16 v[32:35], v[168:171], v[196:199], v[32:35]
	v_mfma_f32_16x16x32_bf16 v[24:27], v[176:179], v[196:199], v[24:27]
	v_mfma_f32_16x16x32_bf16 v[16:19], v[168:171], v[204:207], v[16:19]
	v_mfma_f32_16x16x32_bf16 v[8:11], v[176:179], v[204:207], v[8:11]
	v_mfma_f32_16x16x32_bf16 v[4:7], v[168:171], v[212:215], v[4:7]
	v_mfma_f32_16x16x32_bf16 v[0:3], v[176:179], v[212:215], v[0:3]
	v_mfma_f32_16x16x32_bf16 v[48:51], v[172:175], v[192:195], v[48:51]
	v_mfma_f32_16x16x32_bf16 v[40:43], v[180:183], v[192:195], v[40:43]
	v_mfma_f32_16x16x32_bf16 v[32:35], v[172:175], v[200:203], v[32:35]
	v_mfma_f32_16x16x32_bf16 v[24:27], v[180:183], v[200:203], v[24:27]
	v_mfma_f32_16x16x32_bf16 v[16:19], v[172:175], v[208:211], v[16:19]
	v_mfma_f32_16x16x32_bf16 v[8:11], v[180:183], v[208:211], v[8:11]
	v_mfma_f32_16x16x32_bf16 v[4:7], v[172:175], v[216:219], v[4:7]
	v_mfma_f32_16x16x32_bf16 v[0:3], v[180:183], v[216:219], v[0:3]
	s_barrier
	s_add_i32 s79, 0, 0x18000
	s_add_i32 s80, 0, 0x1c000
	v_add_u32_e32 v164, s79, v147
	v_add_u32_e32 v180, s80, v147
	ds_read_b128 v[152:155], v164
	ds_read_b128 v[156:159], v164 offset:1024
	ds_read_b128 v[160:163], v164 offset:2048
	ds_read_b128 v[164:167], v164 offset:3072
	ds_read_b128 v[168:171], v180
	ds_read_b128 v[172:175], v180 offset:1024
	ds_read_b128 v[176:179], v180 offset:2048
	ds_read_b128 v[180:183], v180 offset:3072
	s_add_u32 s42, s42, 0x40000
	s_addc_u32 s43, s43, 0
	s_mov_b32 m0, s62
	ds_read_b128 v[184:187], v151 offset:32768
	ds_read_b128 v[192:195], v151 offset:33792
	ds_read_b128 v[196:199], v151 offset:34816
	ds_read_b128 v[200:203], v151 offset:35840
	ds_read_b128 v[204:207], v151 offset:36864
	ds_read_b128 v[208:211], v151 offset:37888
	ds_read_b128 v[212:215], v151 offset:38912
	ds_read_b128 v[216:219], v151 offset:39936
	global_load_lds_dwordx4 v128, s[42:43]
	s_mov_b32 m0, s63
	s_nop 0
	global_load_lds_dwordx4 v132, s[42:43]
	s_waitcnt vmcnt(8)
	s_waitcnt lgkmcnt(0)
	s_barrier
	v_mfma_f32_16x16x32_bf16 v[124:127], v[152:155], v[184:187], v[124:127]
	v_mfma_f32_16x16x32_bf16 v[120:123], v[160:163], v[184:187], v[120:123]
	v_mfma_f32_16x16x32_bf16 v[116:119], v[152:155], v[196:199], v[116:119]
	v_mfma_f32_16x16x32_bf16 v[108:111], v[160:163], v[196:199], v[108:111]
	v_mfma_f32_16x16x32_bf16 v[100:103], v[152:155], v[204:207], v[100:103]
	v_mfma_f32_16x16x32_bf16 v[92:95], v[160:163], v[204:207], v[92:95]
	v_mfma_f32_16x16x32_bf16 v[84:87], v[152:155], v[212:215], v[84:87]
	v_mfma_f32_16x16x32_bf16 v[76:79], v[160:163], v[212:215], v[76:79]
	v_mfma_f32_16x16x32_bf16 v[124:127], v[156:159], v[192:195], v[124:127]
	v_mfma_f32_16x16x32_bf16 v[120:123], v[164:167], v[192:195], v[120:123]
	v_mfma_f32_16x16x32_bf16 v[116:119], v[156:159], v[200:203], v[116:119]
	v_mfma_f32_16x16x32_bf16 v[108:111], v[164:167], v[200:203], v[108:111]
	v_mfma_f32_16x16x32_bf16 v[100:103], v[156:159], v[208:211], v[100:103]
	v_mfma_f32_16x16x32_bf16 v[92:95], v[164:167], v[208:211], v[92:95]
	v_mfma_f32_16x16x32_bf16 v[84:87], v[156:159], v[216:219], v[84:87]
	v_mfma_f32_16x16x32_bf16 v[76:79], v[164:167], v[216:219], v[76:79]
	v_mfma_f32_16x16x32_bf16 v[112:115], v[168:171], v[184:187], v[112:115]
	v_mfma_f32_16x16x32_bf16 v[104:107], v[176:179], v[184:187], v[104:107]
	v_mfma_f32_16x16x32_bf16 v[96:99], v[168:171], v[196:199], v[96:99]
	v_mfma_f32_16x16x32_bf16 v[88:91], v[176:179], v[196:199], v[88:91]
	v_mfma_f32_16x16x32_bf16 v[80:83], v[168:171], v[204:207], v[80:83]
	v_mfma_f32_16x16x32_bf16 v[72:75], v[176:179], v[204:207], v[72:75]
	v_mfma_f32_16x16x32_bf16 v[68:71], v[168:171], v[212:215], v[68:71]
	v_mfma_f32_16x16x32_bf16 v[64:67], v[176:179], v[212:215], v[64:67]
	v_mfma_f32_16x16x32_bf16 v[112:115], v[172:175], v[192:195], v[112:115]
	v_mfma_f32_16x16x32_bf16 v[104:107], v[180:183], v[192:195], v[104:107]
	v_mfma_f32_16x16x32_bf16 v[96:99], v[172:175], v[200:203], v[96:99]
	v_mfma_f32_16x16x32_bf16 v[88:91], v[180:183], v[200:203], v[88:91]
	v_mfma_f32_16x16x32_bf16 v[80:83], v[172:175], v[208:211], v[80:83]
	v_mfma_f32_16x16x32_bf16 v[72:75], v[180:183], v[208:211], v[72:75]
	v_mfma_f32_16x16x32_bf16 v[68:71], v[172:175], v[216:219], v[68:71]
	v_mfma_f32_16x16x32_bf16 v[64:67], v[180:183], v[216:219], v[64:67]
	s_barrier
	s_add_i32 s42, s79, s61
	v_lshl_add_u64 v[144:145], v[144:145], 0, s[10:11]
	s_mov_b32 m0, s42
	ds_read_b128 v[184:187], v151 offset:49152
	ds_read_b128 v[192:195], v151 offset:50176
	ds_read_b128 v[196:199], v151 offset:51200
	ds_read_b128 v[200:203], v151 offset:52224
	ds_read_b128 v[204:207], v151 offset:53248
	ds_read_b128 v[208:211], v151 offset:54272
	ds_read_b128 v[212:215], v151 offset:55296
	ds_read_b128 v[216:219], v151 offset:56320
	global_load_lds_dwordx4 v[144:145], off
	s_add_i32 m0, s42, 0x2000
	s_add_u32 s34, s34, 0x40080
	v_lshl_add_u64 v[144:145], v[188:189], 0, s[10:11]
	s_addc_u32 s35, s35, 0
	s_add_i32 s42, s80, s61
	global_load_lds_dwordx4 v[144:145], off
	s_mov_b32 m0, s42
	s_nop 0
	global_load_lds_dwordx4 v130, s[34:35]
	s_add_i32 m0, s42, 0x2000
	v_lshl_add_u64 v[144:145], v[220:221], 0, s[10:11]
	global_load_lds_dwordx4 v134, s[34:35]
	s_mov_b32 m0, s65
	s_nop 0
	global_load_lds_dwordx4 v[144:145], off
	s_mov_b32 m0, s66
	v_lshl_add_u64 v[144:145], v[222:223], 0, s[10:11]
	global_load_lds_dwordx4 v[144:145], off
	s_waitcnt vmcnt(8)
	s_waitcnt lgkmcnt(0)
	s_barrier
	v_mfma_f32_16x16x32_bf16 v[60:63], v[152:155], v[184:187], v[60:63]
	v_mfma_f32_16x16x32_bf16 v[56:59], v[160:163], v[184:187], v[56:59]
	v_mfma_f32_16x16x32_bf16 v[52:55], v[152:155], v[196:199], v[52:55]
	v_mfma_f32_16x16x32_bf16 v[44:47], v[160:163], v[196:199], v[44:47]
	v_mfma_f32_16x16x32_bf16 v[36:39], v[152:155], v[204:207], v[36:39]
	v_mfma_f32_16x16x32_bf16 v[28:31], v[160:163], v[204:207], v[28:31]
	v_mfma_f32_16x16x32_bf16 v[20:23], v[152:155], v[212:215], v[20:23]
	v_mfma_f32_16x16x32_bf16 v[12:15], v[160:163], v[212:215], v[12:15]
	v_mfma_f32_16x16x32_bf16 v[60:63], v[156:159], v[192:195], v[60:63]
	v_mfma_f32_16x16x32_bf16 v[56:59], v[164:167], v[192:195], v[56:59]
	v_mfma_f32_16x16x32_bf16 v[52:55], v[156:159], v[200:203], v[52:55]
	v_mfma_f32_16x16x32_bf16 v[44:47], v[164:167], v[200:203], v[44:47]
	v_mfma_f32_16x16x32_bf16 v[36:39], v[156:159], v[208:211], v[36:39]
	v_mfma_f32_16x16x32_bf16 v[28:31], v[164:167], v[208:211], v[28:31]
	v_mfma_f32_16x16x32_bf16 v[20:23], v[156:159], v[216:219], v[20:23]
	v_mfma_f32_16x16x32_bf16 v[12:15], v[164:167], v[216:219], v[12:15]
	v_mfma_f32_16x16x32_bf16 v[48:51], v[168:171], v[184:187], v[48:51]
	v_mfma_f32_16x16x32_bf16 v[40:43], v[176:179], v[184:187], v[40:43]
	v_mfma_f32_16x16x32_bf16 v[32:35], v[168:171], v[196:199], v[32:35]
	v_mfma_f32_16x16x32_bf16 v[24:27], v[176:179], v[196:199], v[24:27]
	v_mfma_f32_16x16x32_bf16 v[16:19], v[168:171], v[204:207], v[16:19]
	v_mfma_f32_16x16x32_bf16 v[8:11], v[176:179], v[204:207], v[8:11]
	v_mfma_f32_16x16x32_bf16 v[4:7], v[168:171], v[212:215], v[4:7]
	v_mfma_f32_16x16x32_bf16 v[0:3], v[176:179], v[212:215], v[0:3]
	v_mfma_f32_16x16x32_bf16 v[48:51], v[172:175], v[192:195], v[48:51]
	v_mfma_f32_16x16x32_bf16 v[40:43], v[180:183], v[192:195], v[40:43]
	v_mfma_f32_16x16x32_bf16 v[32:35], v[172:175], v[200:203], v[32:35]
	v_mfma_f32_16x16x32_bf16 v[24:27], v[180:183], v[200:203], v[24:27]
	v_mfma_f32_16x16x32_bf16 v[16:19], v[172:175], v[208:211], v[16:19]
	v_mfma_f32_16x16x32_bf16 v[8:11], v[180:183], v[208:211], v[8:11]
	v_mfma_f32_16x16x32_bf16 v[4:7], v[172:175], v[216:219], v[4:7]
	v_mfma_f32_16x16x32_bf16 v[0:3], v[180:183], v[216:219], v[0:3]
	s_barrier
	s_add_i32 s77, s77, 2
	s_add_u32 s30, s30, 0x100
	s_addc_u32 s31, s31, 0
	s_add_u32 s75, s75, 0x100
	s_addc_u32 s76, s76, 0
	s_cmp_gt_u32 s77, 13
	s_cbranch_scc0 .LBB0_1434

.LBB0_1570:
	s_ashr_i32 s23, s22, 31
	s_lshl_b64 s[24:25], s[22:23], 19
	s_add_u32 s24, s58, s24
	s_addc_u32 s25, s59, s25
	s_and_b64 s[26:27], s[0:1], exec
	s_cselect_b32 s23, s25, s31
	s_cselect_b32 s54, s24, s30
	s_ashr_i32 s21, s20, 31
	s_lshl_b64 s[26:27], s[20:21], 19
	s_add_u32 s26, s61, s26
	s_addc_u32 s27, s62, s27
	s_and_b64 s[42:43], s[0:1], exec
	s_cselect_b32 s21, s27, s35
	s_cselect_b32 s55, s26, s34
	s_add_u32 s30, s30, 0x40080
	s_addc_u32 s31, s31, 0
	s_add_u32 s75, s34, 0x100
	s_addc_u32 s76, s35, 0
	s_mov_b32 s77, -2
	ds_read_b128 v[152:155], v149
	ds_read_b128 v[156:159], v149 offset:1024
	ds_read_b128 v[160:163], v149 offset:2048
	ds_read_b128 v[164:167], v149 offset:3072
	ds_read_b128 v[168:171], v150
	ds_read_b128 v[172:175], v150 offset:1024
	ds_read_b128 v[176:179], v150 offset:2048
	ds_read_b128 v[180:183], v150 offset:3072
	s_add_u32 s34, s30, 0xfffc0080
	s_addc_u32 s35, s31, -1
	s_cmp_eq_u32 s77, 12
	s_cselect_b32 s43, s23, s35
	s_cselect_b32 s42, s54, s34
	s_cselect_b32 s35, s21, s76
	s_cselect_b32 s34, s55, s75
	s_add_i32 m0, s29, 0xc000
	ds_read_b128 v[184:187], v151
	ds_read_b128 v[192:195], v151 offset:1024
	ds_read_b128 v[196:199], v151 offset:2048
	ds_read_b128 v[200:203], v151 offset:3072
	ds_read_b128 v[204:207], v151 offset:4096
	ds_read_b128 v[208:211], v151 offset:5120
	ds_read_b128 v[212:215], v151 offset:6144
	ds_read_b128 v[216:219], v151 offset:7168
	global_load_lds_dwordx4 v136, s[30:31]
	s_add_i32 m0, s29, 0xe000
	s_nop 0
	global_load_lds_dwordx4 v138, s[30:31]
	s_waitcnt vmcnt(8)
	s_waitcnt lgkmcnt(0)
	s_barrier
	v_mfma_f32_16x16x32_bf16 v[124:127], v[152:155], v[184:187], 0
	v_mfma_f32_16x16x32_bf16 v[120:123], v[160:163], v[184:187], 0
	v_mfma_f32_16x16x32_bf16 v[108:111], v[152:155], v[196:199], 0
	v_mfma_f32_16x16x32_bf16 v[104:107], v[160:163], v[196:199], 0
	v_mfma_f32_16x16x32_bf16 v[92:95], v[152:155], v[204:207], 0
	v_mfma_f32_16x16x32_bf16 v[88:91], v[160:163], v[204:207], 0
	v_mfma_f32_16x16x32_bf16 v[76:79], v[152:155], v[212:215], 0
	v_mfma_f32_16x16x32_bf16 v[72:75], v[160:163], v[212:215], 0
	v_mfma_f32_16x16x32_bf16 v[124:127], v[156:159], v[192:195], v[124:127]
	v_mfma_f32_16x16x32_bf16 v[120:123], v[164:167], v[192:195], v[120:123]
	v_mfma_f32_16x16x32_bf16 v[108:111], v[156:159], v[200:203], v[108:111]
	v_mfma_f32_16x16x32_bf16 v[104:107], v[164:167], v[200:203], v[104:107]
	v_mfma_f32_16x16x32_bf16 v[92:95], v[156:159], v[208:211], v[92:95]
	v_mfma_f32_16x16x32_bf16 v[88:91], v[164:167], v[208:211], v[88:91]
	v_mfma_f32_16x16x32_bf16 v[76:79], v[156:159], v[216:219], v[76:79]
	v_mfma_f32_16x16x32_bf16 v[72:75], v[164:167], v[216:219], v[72:75]
	v_mfma_f32_16x16x32_bf16 v[116:119], v[168:171], v[184:187], 0
	v_mfma_f32_16x16x32_bf16 v[112:115], v[176:179], v[184:187], 0
	v_mfma_f32_16x16x32_bf16 v[100:103], v[168:171], v[196:199], 0
	v_mfma_f32_16x16x32_bf16 v[96:99], v[176:179], v[196:199], 0
	v_mfma_f32_16x16x32_bf16 v[84:87], v[168:171], v[204:207], 0
	v_mfma_f32_16x16x32_bf16 v[80:83], v[176:179], v[204:207], 0
	v_mfma_f32_16x16x32_bf16 v[68:71], v[168:171], v[212:215], 0
	v_mfma_f32_16x16x32_bf16 v[64:67], v[176:179], v[212:215], 0
	v_mfma_f32_16x16x32_bf16 v[116:119], v[172:175], v[192:195], v[116:119]
	v_mfma_f32_16x16x32_bf16 v[112:115], v[180:183], v[192:195], v[112:115]
	v_mfma_f32_16x16x32_bf16 v[100:103], v[172:175], v[200:203], v[100:103]
	v_mfma_f32_16x16x32_bf16 v[96:99], v[180:183], v[200:203], v[96:99]
	v_mfma_f32_16x16x32_bf16 v[84:87], v[172:175], v[208:211], v[84:87]
	v_mfma_f32_16x16x32_bf16 v[80:83], v[180:183], v[208:211], v[80:83]
	v_mfma_f32_16x16x32_bf16 v[68:71], v[172:175], v[216:219], v[68:71]
	v_mfma_f32_16x16x32_bf16 v[64:67], v[180:183], v[216:219], v[64:67]
	s_barrier
	s_add_i32 s79, s69, s63
	v_lshl_add_u64 v[144:145], s[34:35], 0, v[130:131]
	s_mov_b32 m0, s79
	ds_read_b128 v[184:187], v151 offset:16384
	ds_read_b128 v[192:195], v151 offset:17408
	ds_read_b128 v[196:199], v151 offset:18432
	ds_read_b128 v[200:203], v151 offset:19456
	ds_read_b128 v[204:207], v151 offset:20480
	ds_read_b128 v[208:211], v151 offset:21504
	ds_read_b128 v[212:215], v151 offset:22528
	ds_read_b128 v[216:219], v151 offset:23552
	global_load_lds_dwordx4 v[144:145], off
	s_add_i32 m0, s79, 0x2000
	s_add_u32 s80, s34, 0x40000
	v_lshl_add_u64 v[188:189], s[34:35], 0, v[134:135]
	s_addc_u32 s81, s35, 0
	s_add_i32 s79, s70, s63
	global_load_lds_dwordx4 v[188:189], off
	s_mov_b32 m0, s79
	v_lshl_add_u64 v[222:223], s[42:43], 0, v[132:133]
	global_load_lds_dwordx4 v130, s[80:81]
	s_add_i32 m0, s79, 0x2000
	v_lshl_add_u64 v[220:221], s[42:43], 0, v[128:129]
	global_load_lds_dwordx4 v134, s[80:81]
	s_mov_b32 m0, s29
	s_nop 0
	global_load_lds_dwordx4 v[220:221], off
	s_mov_b32 m0, s64
	s_nop 0
	global_load_lds_dwordx4 v[222:223], off
	s_waitcnt vmcnt(8)
	s_waitcnt lgkmcnt(0)
	s_barrier
	v_mfma_f32_16x16x32_bf16 v[60:63], v[152:155], v[184:187], 0
	v_mfma_f32_16x16x32_bf16 v[56:59], v[160:163], v[184:187], 0
	v_mfma_f32_16x16x32_bf16 v[44:47], v[152:155], v[196:199], 0
	v_mfma_f32_16x16x32_bf16 v[40:43], v[160:163], v[196:199], 0
	v_mfma_f32_16x16x32_bf16 v[28:31], v[152:155], v[204:207], 0
	v_mfma_f32_16x16x32_bf16 v[24:27], v[160:163], v[204:207], 0
	v_mfma_f32_16x16x32_bf16 v[12:15], v[152:155], v[212:215], 0
	v_mfma_f32_16x16x32_bf16 v[8:11], v[160:163], v[212:215], 0
	v_mfma_f32_16x16x32_bf16 v[60:63], v[156:159], v[192:195], v[60:63]
	v_mfma_f32_16x16x32_bf16 v[56:59], v[164:167], v[192:195], v[56:59]
	v_mfma_f32_16x16x32_bf16 v[44:47], v[156:159], v[200:203], v[44:47]
	v_mfma_f32_16x16x32_bf16 v[40:43], v[164:167], v[200:203], v[40:43]
	v_mfma_f32_16x16x32_bf16 v[28:31], v[156:159], v[208:211], v[28:31]
	v_mfma_f32_16x16x32_bf16 v[24:27], v[164:167], v[208:211], v[24:27]
	v_mfma_f32_16x16x32_bf16 v[12:15], v[156:159], v[216:219], v[12:15]
	v_mfma_f32_16x16x32_bf16 v[8:11], v[164:167], v[216:219], v[8:11]
	v_mfma_f32_16x16x32_bf16 v[52:55], v[168:171], v[184:187], 0
	v_mfma_f32_16x16x32_bf16 v[48:51], v[176:179], v[184:187], 0
	v_mfma_f32_16x16x32_bf16 v[36:39], v[168:171], v[196:199], 0
	v_mfma_f32_16x16x32_bf16 v[32:35], v[176:179], v[196:199], 0
	v_mfma_f32_16x16x32_bf16 v[20:23], v[168:171], v[204:207], 0
	v_mfma_f32_16x16x32_bf16 v[16:19], v[176:179], v[204:207], 0
	v_mfma_f32_16x16x32_bf16 v[4:7], v[168:171], v[212:215], 0
	v_mfma_f32_16x16x32_bf16 v[0:3], v[176:179], v[212:215], 0
	v_mfma_f32_16x16x32_bf16 v[52:55], v[172:175], v[192:195], v[52:55]
	v_mfma_f32_16x16x32_bf16 v[48:51], v[180:183], v[192:195], v[48:51]
	v_mfma_f32_16x16x32_bf16 v[36:39], v[172:175], v[200:203], v[36:39]
	v_mfma_f32_16x16x32_bf16 v[32:35], v[180:183], v[200:203], v[32:35]
	v_mfma_f32_16x16x32_bf16 v[20:23], v[172:175], v[208:211], v[20:23]
	v_mfma_f32_16x16x32_bf16 v[16:19], v[180:183], v[208:211], v[16:19]
	v_mfma_f32_16x16x32_bf16 v[4:7], v[172:175], v[216:219], v[4:7]
	v_mfma_f32_16x16x32_bf16 v[0:3], v[180:183], v[216:219], v[0:3]
	s_barrier
	s_add_i32 s79, 0, 0x18000
	s_add_i32 s80, 0, 0x1c000
	v_add_u32_e32 v164, s79, v147
	v_add_u32_e32 v180, s80, v147
	ds_read_b128 v[152:155], v164
	ds_read_b128 v[156:159], v164 offset:1024
	ds_read_b128 v[160:163], v164 offset:2048
	ds_read_b128 v[164:167], v164 offset:3072
	ds_read_b128 v[168:171], v180
	ds_read_b128 v[172:175], v180 offset:1024
	ds_read_b128 v[176:179], v180 offset:2048
	ds_read_b128 v[180:183], v180 offset:3072
	s_add_u32 s42, s42, 0x40000
	s_addc_u32 s43, s43, 0
	s_mov_b32 m0, s65
	ds_read_b128 v[184:187], v151 offset:32768
	ds_read_b128 v[192:195], v151 offset:33792
	ds_read_b128 v[196:199], v151 offset:34816
	ds_read_b128 v[200:203], v151 offset:35840
	ds_read_b128 v[204:207], v151 offset:36864
	ds_read_b128 v[208:211], v151 offset:37888
	ds_read_b128 v[212:215], v151 offset:38912
	ds_read_b128 v[216:219], v151 offset:39936
	global_load_lds_dwordx4 v128, s[42:43]
	s_mov_b32 m0, s66
	s_nop 0
	global_load_lds_dwordx4 v132, s[42:43]
	s_waitcnt vmcnt(8)
	s_waitcnt lgkmcnt(0)
	s_barrier
	v_mfma_f32_16x16x32_bf16 v[124:127], v[152:155], v[184:187], v[124:127]
	v_mfma_f32_16x16x32_bf16 v[120:123], v[160:163], v[184:187], v[120:123]
	v_mfma_f32_16x16x32_bf16 v[108:111], v[152:155], v[196:199], v[108:111]
	v_mfma_f32_16x16x32_bf16 v[104:107], v[160:163], v[196:199], v[104:107]
	v_mfma_f32_16x16x32_bf16 v[92:95], v[152:155], v[204:207], v[92:95]
	v_mfma_f32_16x16x32_bf16 v[88:91], v[160:163], v[204:207], v[88:91]
	v_mfma_f32_16x16x32_bf16 v[76:79], v[152:155], v[212:215], v[76:79]
	v_mfma_f32_16x16x32_bf16 v[72:75], v[160:163], v[212:215], v[72:75]
	v_mfma_f32_16x16x32_bf16 v[124:127], v[156:159], v[192:195], v[124:127]
	v_mfma_f32_16x16x32_bf16 v[120:123], v[164:167], v[192:195], v[120:123]
	v_mfma_f32_16x16x32_bf16 v[108:111], v[156:159], v[200:203], v[108:111]
	v_mfma_f32_16x16x32_bf16 v[104:107], v[164:167], v[200:203], v[104:107]
	v_mfma_f32_16x16x32_bf16 v[92:95], v[156:159], v[208:211], v[92:95]
	v_mfma_f32_16x16x32_bf16 v[88:91], v[164:167], v[208:211], v[88:91]
	v_mfma_f32_16x16x32_bf16 v[76:79], v[156:159], v[216:219], v[76:79]
	v_mfma_f32_16x16x32_bf16 v[72:75], v[164:167], v[216:219], v[72:75]
	v_mfma_f32_16x16x32_bf16 v[116:119], v[168:171], v[184:187], v[116:119]
	v_mfma_f32_16x16x32_bf16 v[112:115], v[176:179], v[184:187], v[112:115]
	v_mfma_f32_16x16x32_bf16 v[100:103], v[168:171], v[196:199], v[100:103]
	v_mfma_f32_16x16x32_bf16 v[96:99], v[176:179], v[196:199], v[96:99]
	v_mfma_f32_16x16x32_bf16 v[84:87], v[168:171], v[204:207], v[84:87]
	v_mfma_f32_16x16x32_bf16 v[80:83], v[176:179], v[204:207], v[80:83]
	v_mfma_f32_16x16x32_bf16 v[68:71], v[168:171], v[212:215], v[68:71]
	v_mfma_f32_16x16x32_bf16 v[64:67], v[176:179], v[212:215], v[64:67]
	v_mfma_f32_16x16x32_bf16 v[116:119], v[172:175], v[192:195], v[116:119]
	v_mfma_f32_16x16x32_bf16 v[112:115], v[180:183], v[192:195], v[112:115]
	v_mfma_f32_16x16x32_bf16 v[100:103], v[172:175], v[200:203], v[100:103]
	v_mfma_f32_16x16x32_bf16 v[96:99], v[180:183], v[200:203], v[96:99]
	v_mfma_f32_16x16x32_bf16 v[84:87], v[172:175], v[208:211], v[84:87]
	v_mfma_f32_16x16x32_bf16 v[80:83], v[180:183], v[208:211], v[80:83]
	v_mfma_f32_16x16x32_bf16 v[68:71], v[172:175], v[216:219], v[68:71]
	v_mfma_f32_16x16x32_bf16 v[64:67], v[180:183], v[216:219], v[64:67]
	s_barrier
	s_add_i32 s42, s79, s63
	v_lshl_add_u64 v[144:145], v[144:145], 0, s[8:9]
	s_mov_b32 m0, s42
	ds_read_b128 v[184:187], v151 offset:49152
	ds_read_b128 v[192:195], v151 offset:50176
	ds_read_b128 v[196:199], v151 offset:51200
	ds_read_b128 v[200:203], v151 offset:52224
	ds_read_b128 v[204:207], v151 offset:53248
	ds_read_b128 v[208:211], v151 offset:54272
	ds_read_b128 v[212:215], v151 offset:55296
	ds_read_b128 v[216:219], v151 offset:56320
	global_load_lds_dwordx4 v[144:145], off
	s_add_i32 m0, s42, 0x2000
	s_add_u32 s34, s34, 0x40080
	v_lshl_add_u64 v[144:145], v[188:189], 0, s[8:9]
	s_addc_u32 s35, s35, 0
	s_add_i32 s42, s80, s63
	global_load_lds_dwordx4 v[144:145], off
	s_mov_b32 m0, s42
	s_nop 0
	global_load_lds_dwordx4 v130, s[34:35]
	s_add_i32 m0, s42, 0x2000
	v_lshl_add_u64 v[144:145], v[220:221], 0, s[8:9]
	global_load_lds_dwordx4 v134, s[34:35]
	s_mov_b32 m0, s52
	s_nop 0
	global_load_lds_dwordx4 v[144:145], off
	s_mov_b32 m0, s53
	v_lshl_add_u64 v[144:145], v[222:223], 0, s[8:9]
	global_load_lds_dwordx4 v[144:145], off
	s_waitcnt vmcnt(8)
	s_waitcnt lgkmcnt(0)
	s_barrier
	v_mfma_f32_16x16x32_bf16 v[60:63], v[152:155], v[184:187], v[60:63]
	v_mfma_f32_16x16x32_bf16 v[56:59], v[160:163], v[184:187], v[56:59]
	v_mfma_f32_16x16x32_bf16 v[44:47], v[152:155], v[196:199], v[44:47]
	v_mfma_f32_16x16x32_bf16 v[40:43], v[160:163], v[196:199], v[40:43]
	v_mfma_f32_16x16x32_bf16 v[28:31], v[152:155], v[204:207], v[28:31]
	v_mfma_f32_16x16x32_bf16 v[24:27], v[160:163], v[204:207], v[24:27]
	v_mfma_f32_16x16x32_bf16 v[12:15], v[152:155], v[212:215], v[12:15]
	v_mfma_f32_16x16x32_bf16 v[8:11], v[160:163], v[212:215], v[8:11]
	v_mfma_f32_16x16x32_bf16 v[60:63], v[156:159], v[192:195], v[60:63]
	v_mfma_f32_16x16x32_bf16 v[56:59], v[164:167], v[192:195], v[56:59]
	v_mfma_f32_16x16x32_bf16 v[44:47], v[156:159], v[200:203], v[44:47]
	v_mfma_f32_16x16x32_bf16 v[40:43], v[164:167], v[200:203], v[40:43]
	v_mfma_f32_16x16x32_bf16 v[28:31], v[156:159], v[208:211], v[28:31]
	v_mfma_f32_16x16x32_bf16 v[24:27], v[164:167], v[208:211], v[24:27]
	v_mfma_f32_16x16x32_bf16 v[12:15], v[156:159], v[216:219], v[12:15]
	v_mfma_f32_16x16x32_bf16 v[8:11], v[164:167], v[216:219], v[8:11]
	v_mfma_f32_16x16x32_bf16 v[52:55], v[168:171], v[184:187], v[52:55]
	v_mfma_f32_16x16x32_bf16 v[48:51], v[176:179], v[184:187], v[48:51]
	v_mfma_f32_16x16x32_bf16 v[36:39], v[168:171], v[196:199], v[36:39]
	v_mfma_f32_16x16x32_bf16 v[32:35], v[176:179], v[196:199], v[32:35]
	v_mfma_f32_16x16x32_bf16 v[20:23], v[168:171], v[204:207], v[20:23]
	v_mfma_f32_16x16x32_bf16 v[16:19], v[176:179], v[204:207], v[16:19]
	v_mfma_f32_16x16x32_bf16 v[4:7], v[168:171], v[212:215], v[4:7]
	v_mfma_f32_16x16x32_bf16 v[0:3], v[176:179], v[212:215], v[0:3]
	v_mfma_f32_16x16x32_bf16 v[52:55], v[172:175], v[192:195], v[52:55]
	v_mfma_f32_16x16x32_bf16 v[48:51], v[180:183], v[192:195], v[48:51]
	v_mfma_f32_16x16x32_bf16 v[36:39], v[172:175], v[200:203], v[36:39]
	v_mfma_f32_16x16x32_bf16 v[32:35], v[180:183], v[200:203], v[32:35]
	v_mfma_f32_16x16x32_bf16 v[20:23], v[172:175], v[208:211], v[20:23]
	v_mfma_f32_16x16x32_bf16 v[16:19], v[180:183], v[208:211], v[16:19]
	v_mfma_f32_16x16x32_bf16 v[4:7], v[172:175], v[216:219], v[4:7]
	v_mfma_f32_16x16x32_bf16 v[0:3], v[180:183], v[216:219], v[0:3]
	s_barrier
	s_add_i32 s77, s77, 2
	s_add_u32 s30, s30, 0x100
	s_addc_u32 s31, s31, 0
	s_add_u32 s75, s75, 0x100
	s_addc_u32 s76, s76, 0
	s_cmp_gt_u32 s77, 13
	s_cbranch_scc0 .LBB0_1571
	s_branch .Lpeel_exit11
.LBB0_1571:
	ds_read_b128 v[152:155], v149
	ds_read_b128 v[156:159], v149 offset:1024
	ds_read_b128 v[160:163], v149 offset:2048
	ds_read_b128 v[164:167], v149 offset:3072
	ds_read_b128 v[168:171], v150
	ds_read_b128 v[172:175], v150 offset:1024
	ds_read_b128 v[176:179], v150 offset:2048
	ds_read_b128 v[180:183], v150 offset:3072
	s_add_u32 s34, s30, 0xfffc0080
	s_addc_u32 s35, s31, -1
	s_cmp_eq_u32 s77, 12
	s_cselect_b32 s43, s23, s35
	s_cselect_b32 s42, s54, s34
	s_cselect_b32 s35, s21, s76
	s_cselect_b32 s34, s55, s75
	s_add_i32 m0, s29, 0xc000
	ds_read_b128 v[184:187], v151
	ds_read_b128 v[192:195], v151 offset:1024
	ds_read_b128 v[196:199], v151 offset:2048
	ds_read_b128 v[200:203], v151 offset:3072
	ds_read_b128 v[204:207], v151 offset:4096
	ds_read_b128 v[208:211], v151 offset:5120
	ds_read_b128 v[212:215], v151 offset:6144
	ds_read_b128 v[216:219], v151 offset:7168
	global_load_lds_dwordx4 v136, s[30:31]
	s_add_i32 m0, s29, 0xe000
	s_nop 0
	global_load_lds_dwordx4 v138, s[30:31]
	s_waitcnt vmcnt(8)
	s_waitcnt lgkmcnt(0)
	s_barrier
	v_mfma_f32_16x16x32_bf16 v[124:127], v[152:155], v[184:187], v[124:127]
	v_mfma_f32_16x16x32_bf16 v[120:123], v[160:163], v[184:187], v[120:123]
	v_mfma_f32_16x16x32_bf16 v[108:111], v[152:155], v[196:199], v[108:111]
	v_mfma_f32_16x16x32_bf16 v[104:107], v[160:163], v[196:199], v[104:107]
	v_mfma_f32_16x16x32_bf16 v[92:95], v[152:155], v[204:207], v[92:95]
	v_mfma_f32_16x16x32_bf16 v[88:91], v[160:163], v[204:207], v[88:91]
	v_mfma_f32_16x16x32_bf16 v[76:79], v[152:155], v[212:215], v[76:79]
	v_mfma_f32_16x16x32_bf16 v[72:75], v[160:163], v[212:215], v[72:75]
	v_mfma_f32_16x16x32_bf16 v[124:127], v[156:159], v[192:195], v[124:127]
	v_mfma_f32_16x16x32_bf16 v[120:123], v[164:167], v[192:195], v[120:123]
	v_mfma_f32_16x16x32_bf16 v[108:111], v[156:159], v[200:203], v[108:111]
	v_mfma_f32_16x16x32_bf16 v[104:107], v[164:167], v[200:203], v[104:107]
	v_mfma_f32_16x16x32_bf16 v[92:95], v[156:159], v[208:211], v[92:95]
	v_mfma_f32_16x16x32_bf16 v[88:91], v[164:167], v[208:211], v[88:91]
	v_mfma_f32_16x16x32_bf16 v[76:79], v[156:159], v[216:219], v[76:79]
	v_mfma_f32_16x16x32_bf16 v[72:75], v[164:167], v[216:219], v[72:75]
	v_mfma_f32_16x16x32_bf16 v[116:119], v[168:171], v[184:187], v[116:119]
	v_mfma_f32_16x16x32_bf16 v[112:115], v[176:179], v[184:187], v[112:115]
	v_mfma_f32_16x16x32_bf16 v[100:103], v[168:171], v[196:199], v[100:103]
	v_mfma_f32_16x16x32_bf16 v[96:99], v[176:179], v[196:199], v[96:99]
	v_mfma_f32_16x16x32_bf16 v[84:87], v[168:171], v[204:207], v[84:87]
	v_mfma_f32_16x16x32_bf16 v[80:83], v[176:179], v[204:207], v[80:83]
	v_mfma_f32_16x16x32_bf16 v[68:71], v[168:171], v[212:215], v[68:71]
	v_mfma_f32_16x16x32_bf16 v[64:67], v[176:179], v[212:215], v[64:67]
	v_mfma_f32_16x16x32_bf16 v[116:119], v[172:175], v[192:195], v[116:119]
	v_mfma_f32_16x16x32_bf16 v[112:115], v[180:183], v[192:195], v[112:115]
	v_mfma_f32_16x16x32_bf16 v[100:103], v[172:175], v[200:203], v[100:103]
	v_mfma_f32_16x16x32_bf16 v[96:99], v[180:183], v[200:203], v[96:99]
	v_mfma_f32_16x16x32_bf16 v[84:87], v[172:175], v[208:211], v[84:87]
	v_mfma_f32_16x16x32_bf16 v[80:83], v[180:183], v[208:211], v[80:83]
	v_mfma_f32_16x16x32_bf16 v[68:71], v[172:175], v[216:219], v[68:71]
	v_mfma_f32_16x16x32_bf16 v[64:67], v[180:183], v[216:219], v[64:67]
	s_barrier
	s_add_i32 s79, s69, s63
	v_lshl_add_u64 v[144:145], s[34:35], 0, v[130:131]
	s_mov_b32 m0, s79
	ds_read_b128 v[184:187], v151 offset:16384
	ds_read_b128 v[192:195], v151 offset:17408
	ds_read_b128 v[196:199], v151 offset:18432
	ds_read_b128 v[200:203], v151 offset:19456
	ds_read_b128 v[204:207], v151 offset:20480
	ds_read_b128 v[208:211], v151 offset:21504
	ds_read_b128 v[212:215], v151 offset:22528
	ds_read_b128 v[216:219], v151 offset:23552
	global_load_lds_dwordx4 v[144:145], off
	s_add_i32 m0, s79, 0x2000
	s_add_u32 s80, s34, 0x40000
	v_lshl_add_u64 v[188:189], s[34:35], 0, v[134:135]
	s_addc_u32 s81, s35, 0
	s_add_i32 s79, s70, s63
	global_load_lds_dwordx4 v[188:189], off
	s_mov_b32 m0, s79
	v_lshl_add_u64 v[222:223], s[42:43], 0, v[132:133]
	global_load_lds_dwordx4 v130, s[80:81]
	s_add_i32 m0, s79, 0x2000
	v_lshl_add_u64 v[220:221], s[42:43], 0, v[128:129]
	global_load_lds_dwordx4 v134, s[80:81]
	s_mov_b32 m0, s29
	s_nop 0
	global_load_lds_dwordx4 v[220:221], off
	s_mov_b32 m0, s64
	s_nop 0
	global_load_lds_dwordx4 v[222:223], off
	s_waitcnt vmcnt(8)
	s_waitcnt lgkmcnt(0)
	s_barrier
	v_mfma_f32_16x16x32_bf16 v[60:63], v[152:155], v[184:187], v[60:63]
	v_mfma_f32_16x16x32_bf16 v[56:59], v[160:163], v[184:187], v[56:59]
	v_mfma_f32_16x16x32_bf16 v[44:47], v[152:155], v[196:199], v[44:47]
	v_mfma_f32_16x16x32_bf16 v[40:43], v[160:163], v[196:199], v[40:43]
	v_mfma_f32_16x16x32_bf16 v[28:31], v[152:155], v[204:207], v[28:31]
	v_mfma_f32_16x16x32_bf16 v[24:27], v[160:163], v[204:207], v[24:27]
	v_mfma_f32_16x16x32_bf16 v[12:15], v[152:155], v[212:215], v[12:15]
	v_mfma_f32_16x16x32_bf16 v[8:11], v[160:163], v[212:215], v[8:11]
	v_mfma_f32_16x16x32_bf16 v[60:63], v[156:159], v[192:195], v[60:63]
	v_mfma_f32_16x16x32_bf16 v[56:59], v[164:167], v[192:195], v[56:59]
	v_mfma_f32_16x16x32_bf16 v[44:47], v[156:159], v[200:203], v[44:47]
	v_mfma_f32_16x16x32_bf16 v[40:43], v[164:167], v[200:203], v[40:43]
	v_mfma_f32_16x16x32_bf16 v[28:31], v[156:159], v[208:211], v[28:31]
	v_mfma_f32_16x16x32_bf16 v[24:27], v[164:167], v[208:211], v[24:27]
	v_mfma_f32_16x16x32_bf16 v[12:15], v[156:159], v[216:219], v[12:15]
	v_mfma_f32_16x16x32_bf16 v[8:11], v[164:167], v[216:219], v[8:11]
	v_mfma_f32_16x16x32_bf16 v[52:55], v[168:171], v[184:187], v[52:55]
	v_mfma_f32_16x16x32_bf16 v[48:51], v[176:179], v[184:187], v[48:51]
	v_mfma_f32_16x16x32_bf16 v[36:39], v[168:171], v[196:199], v[36:39]
	v_mfma_f32_16x16x32_bf16 v[32:35], v[176:179], v[196:199], v[32:35]
	v_mfma_f32_16x16x32_bf16 v[20:23], v[168:171], v[204:207], v[20:23]
	v_mfma_f32_16x16x32_bf16 v[16:19], v[176:179], v[204:207], v[16:19]
	v_mfma_f32_16x16x32_bf16 v[4:7], v[168:171], v[212:215], v[4:7]
	v_mfma_f32_16x16x32_bf16 v[0:3], v[176:179], v[212:215], v[0:3]
	v_mfma_f32_16x16x32_bf16 v[52:55], v[172:175], v[192:195], v[52:55]
	v_mfma_f32_16x16x32_bf16 v[48:51], v[180:183], v[192:195], v[48:51]
	v_mfma_f32_16x16x32_bf16 v[36:39], v[172:175], v[200:203], v[36:39]
	v_mfma_f32_16x16x32_bf16 v[32:35], v[180:183], v[200:203], v[32:35]
	v_mfma_f32_16x16x32_bf16 v[20:23], v[172:175], v[208:211], v[20:23]
	v_mfma_f32_16x16x32_bf16 v[16:19], v[180:183], v[208:211], v[16:19]
	v_mfma_f32_16x16x32_bf16 v[4:7], v[172:175], v[216:219], v[4:7]
	v_mfma_f32_16x16x32_bf16 v[0:3], v[180:183], v[216:219], v[0:3]
	s_barrier
	s_add_i32 s79, 0, 0x18000
	s_add_i32 s80, 0, 0x1c000
	v_add_u32_e32 v164, s79, v147
	v_add_u32_e32 v180, s80, v147
	ds_read_b128 v[152:155], v164
	ds_read_b128 v[156:159], v164 offset:1024
	ds_read_b128 v[160:163], v164 offset:2048
	ds_read_b128 v[164:167], v164 offset:3072
	ds_read_b128 v[168:171], v180
	ds_read_b128 v[172:175], v180 offset:1024
	ds_read_b128 v[176:179], v180 offset:2048
	ds_read_b128 v[180:183], v180 offset:3072
	s_add_u32 s42, s42, 0x40000
	s_addc_u32 s43, s43, 0
	s_mov_b32 m0, s65
	ds_read_b128 v[184:187], v151 offset:32768
	ds_read_b128 v[192:195], v151 offset:33792
	ds_read_b128 v[196:199], v151 offset:34816
	ds_read_b128 v[200:203], v151 offset:35840
	ds_read_b128 v[204:207], v151 offset:36864
	ds_read_b128 v[208:211], v151 offset:37888
	ds_read_b128 v[212:215], v151 offset:38912
	ds_read_b128 v[216:219], v151 offset:39936
	global_load_lds_dwordx4 v128, s[42:43]
	s_mov_b32 m0, s66
	s_nop 0
	global_load_lds_dwordx4 v132, s[42:43]
	s_waitcnt vmcnt(8)
	s_waitcnt lgkmcnt(0)
	s_barrier
	v_mfma_f32_16x16x32_bf16 v[124:127], v[152:155], v[184:187], v[124:127]
	v_mfma_f32_16x16x32_bf16 v[120:123], v[160:163], v[184:187], v[120:123]
	v_mfma_f32_16x16x32_bf16 v[108:111], v[152:155], v[196:199], v[108:111]
	v_mfma_f32_16x16x32_bf16 v[104:107], v[160:163], v[196:199], v[104:107]
	v_mfma_f32_16x16x32_bf16 v[92:95], v[152:155], v[204:207], v[92:95]
	v_mfma_f32_16x16x32_bf16 v[88:91], v[160:163], v[204:207], v[88:91]
	v_mfma_f32_16x16x32_bf16 v[76:79], v[152:155], v[212:215], v[76:79]
	v_mfma_f32_16x16x32_bf16 v[72:75], v[160:163], v[212:215], v[72:75]
	v_mfma_f32_16x16x32_bf16 v[124:127], v[156:159], v[192:195], v[124:127]
	v_mfma_f32_16x16x32_bf16 v[120:123], v[164:167], v[192:195], v[120:123]
	v_mfma_f32_16x16x32_bf16 v[108:111], v[156:159], v[200:203], v[108:111]
	v_mfma_f32_16x16x32_bf16 v[104:107], v[164:167], v[200:203], v[104:107]
	v_mfma_f32_16x16x32_bf16 v[92:95], v[156:159], v[208:211], v[92:95]
	v_mfma_f32_16x16x32_bf16 v[88:91], v[164:167], v[208:211], v[88:91]
	v_mfma_f32_16x16x32_bf16 v[76:79], v[156:159], v[216:219], v[76:79]
	v_mfma_f32_16x16x32_bf16 v[72:75], v[164:167], v[216:219], v[72:75]
	v_mfma_f32_16x16x32_bf16 v[116:119], v[168:171], v[184:187], v[116:119]
	v_mfma_f32_16x16x32_bf16 v[112:115], v[176:179], v[184:187], v[112:115]
	v_mfma_f32_16x16x32_bf16 v[100:103], v[168:171], v[196:199], v[100:103]
	v_mfma_f32_16x16x32_bf16 v[96:99], v[176:179], v[196:199], v[96:99]
	v_mfma_f32_16x16x32_bf16 v[84:87], v[168:171], v[204:207], v[84:87]
	v_mfma_f32_16x16x32_bf16 v[80:83], v[176:179], v[204:207], v[80:83]
	v_mfma_f32_16x16x32_bf16 v[68:71], v[168:171], v[212:215], v[68:71]
	v_mfma_f32_16x16x32_bf16 v[64:67], v[176:179], v[212:215], v[64:67]
	v_mfma_f32_16x16x32_bf16 v[116:119], v[172:175], v[192:195], v[116:119]
	v_mfma_f32_16x16x32_bf16 v[112:115], v[180:183], v[192:195], v[112:115]
	v_mfma_f32_16x16x32_bf16 v[100:103], v[172:175], v[200:203], v[100:103]
	v_mfma_f32_16x16x32_bf16 v[96:99], v[180:183], v[200:203], v[96:99]
	v_mfma_f32_16x16x32_bf16 v[84:87], v[172:175], v[208:211], v[84:87]
	v_mfma_f32_16x16x32_bf16 v[80:83], v[180:183], v[208:211], v[80:83]
	v_mfma_f32_16x16x32_bf16 v[68:71], v[172:175], v[216:219], v[68:71]
	v_mfma_f32_16x16x32_bf16 v[64:67], v[180:183], v[216:219], v[64:67]
	s_barrier
	s_add_i32 s42, s79, s63
	v_lshl_add_u64 v[144:145], v[144:145], 0, s[8:9]
	s_mov_b32 m0, s42
	ds_read_b128 v[184:187], v151 offset:49152
	ds_read_b128 v[192:195], v151 offset:50176
	ds_read_b128 v[196:199], v151 offset:51200
	ds_read_b128 v[200:203], v151 offset:52224
	ds_read_b128 v[204:207], v151 offset:53248
	ds_read_b128 v[208:211], v151 offset:54272
	ds_read_b128 v[212:215], v151 offset:55296
	ds_read_b128 v[216:219], v151 offset:56320
	global_load_lds_dwordx4 v[144:145], off
	s_add_i32 m0, s42, 0x2000
	s_add_u32 s34, s34, 0x40080
	v_lshl_add_u64 v[144:145], v[188:189], 0, s[8:9]
	s_addc_u32 s35, s35, 0
	s_add_i32 s42, s80, s63
	global_load_lds_dwordx4 v[144:145], off
	s_mov_b32 m0, s42
	s_nop 0
	global_load_lds_dwordx4 v130, s[34:35]
	s_add_i32 m0, s42, 0x2000
	v_lshl_add_u64 v[144:145], v[220:221], 0, s[8:9]
	global_load_lds_dwordx4 v134, s[34:35]
	s_mov_b32 m0, s52
	s_nop 0
	global_load_lds_dwordx4 v[144:145], off
	s_mov_b32 m0, s53
	v_lshl_add_u64 v[144:145], v[222:223], 0, s[8:9]
	global_load_lds_dwordx4 v[144:145], off
	s_waitcnt vmcnt(8)
	s_waitcnt lgkmcnt(0)
	s_barrier
	v_mfma_f32_16x16x32_bf16 v[60:63], v[152:155], v[184:187], v[60:63]
	v_mfma_f32_16x16x32_bf16 v[56:59], v[160:163], v[184:187], v[56:59]
	v_mfma_f32_16x16x32_bf16 v[44:47], v[152:155], v[196:199], v[44:47]
	v_mfma_f32_16x16x32_bf16 v[40:43], v[160:163], v[196:199], v[40:43]
	v_mfma_f32_16x16x32_bf16 v[28:31], v[152:155], v[204:207], v[28:31]
	v_mfma_f32_16x16x32_bf16 v[24:27], v[160:163], v[204:207], v[24:27]
	v_mfma_f32_16x16x32_bf16 v[12:15], v[152:155], v[212:215], v[12:15]
	v_mfma_f32_16x16x32_bf16 v[8:11], v[160:163], v[212:215], v[8:11]
	v_mfma_f32_16x16x32_bf16 v[60:63], v[156:159], v[192:195], v[60:63]
	v_mfma_f32_16x16x32_bf16 v[56:59], v[164:167], v[192:195], v[56:59]
	v_mfma_f32_16x16x32_bf16 v[44:47], v[156:159], v[200:203], v[44:47]
	v_mfma_f32_16x16x32_bf16 v[40:43], v[164:167], v[200:203], v[40:43]
	v_mfma_f32_16x16x32_bf16 v[28:31], v[156:159], v[208:211], v[28:31]
	v_mfma_f32_16x16x32_bf16 v[24:27], v[164:167], v[208:211], v[24:27]
	v_mfma_f32_16x16x32_bf16 v[12:15], v[156:159], v[216:219], v[12:15]
	v_mfma_f32_16x16x32_bf16 v[8:11], v[164:167], v[216:219], v[8:11]
	v_mfma_f32_16x16x32_bf16 v[52:55], v[168:171], v[184:187], v[52:55]
	v_mfma_f32_16x16x32_bf16 v[48:51], v[176:179], v[184:187], v[48:51]
	v_mfma_f32_16x16x32_bf16 v[36:39], v[168:171], v[196:199], v[36:39]
	v_mfma_f32_16x16x32_bf16 v[32:35], v[176:179], v[196:199], v[32:35]
	v_mfma_f32_16x16x32_bf16 v[20:23], v[168:171], v[204:207], v[20:23]
	v_mfma_f32_16x16x32_bf16 v[16:19], v[176:179], v[204:207], v[16:19]
	v_mfma_f32_16x16x32_bf16 v[4:7], v[168:171], v[212:215], v[4:7]
	v_mfma_f32_16x16x32_bf16 v[0:3], v[176:179], v[212:215], v[0:3]
	v_mfma_f32_16x16x32_bf16 v[52:55], v[172:175], v[192:195], v[52:55]
	v_mfma_f32_16x16x32_bf16 v[48:51], v[180:183], v[192:195], v[48:51]
	v_mfma_f32_16x16x32_bf16 v[36:39], v[172:175], v[200:203], v[36:39]
	v_mfma_f32_16x16x32_bf16 v[32:35], v[180:183], v[200:203], v[32:35]
	v_mfma_f32_16x16x32_bf16 v[20:23], v[172:175], v[208:211], v[20:23]
	v_mfma_f32_16x16x32_bf16 v[16:19], v[180:183], v[208:211], v[16:19]
	v_mfma_f32_16x16x32_bf16 v[4:7], v[172:175], v[216:219], v[4:7]
	v_mfma_f32_16x16x32_bf16 v[0:3], v[180:183], v[216:219], v[0:3]
	s_barrier
	s_add_i32 s77, s77, 2
	s_add_u32 s30, s30, 0x100
	s_addc_u32 s31, s31, 0
	s_add_u32 s75, s75, 0x100
	s_addc_u32 s76, s76, 0
	s_cmp_gt_u32 s77, 13
	s_cbranch_scc0 .LBB0_1571

.LBB0_1649:
	s_ashr_i32 s23, s22, 31
	s_lshl_b64 s[24:25], s[22:23], 21
	s_add_u32 s24, s56, s24
	s_addc_u32 s25, s57, s25
	s_and_b64 s[26:27], s[0:1], exec
	s_cselect_b32 s23, s25, s31
	s_cselect_b32 s55, s24, s30
	s_ashr_i32 s21, s20, 31
	s_lshl_b64 s[26:27], s[20:21], 21
	s_add_u32 s26, s53, s26
	s_addc_u32 s27, s58, s27
	s_and_b64 s[42:43], s[0:1], exec
	s_cselect_b32 s21, s27, s35
	s_cselect_b32 s72, s26, s34
	s_add_u32 s30, s30, 0x100080
	s_addc_u32 s31, s31, 0
	s_add_u32 s73, s34, 0x100
	s_addc_u32 s74, s35, 0
	s_mov_b32 s75, -2
	ds_read_b128 v[152:155], v149
	ds_read_b128 v[156:159], v149 offset:1024
	ds_read_b128 v[160:163], v149 offset:2048
	ds_read_b128 v[164:167], v149 offset:3072
	ds_read_b128 v[168:171], v150
	ds_read_b128 v[172:175], v150 offset:1024
	ds_read_b128 v[176:179], v150 offset:2048
	ds_read_b128 v[180:183], v150 offset:3072
	s_add_u32 s34, s30, 0xfff00080
	s_addc_u32 s35, s31, -1
	s_cmp_eq_u32 s75, 60
	s_cselect_b32 s43, s23, s35
	s_cselect_b32 s42, s55, s34
	s_cselect_b32 s35, s21, s74
	s_cselect_b32 s34, s72, s73
	s_add_i32 m0, s29, 0xc000
	ds_read_b128 v[184:187], v151
	ds_read_b128 v[192:195], v151 offset:1024
	ds_read_b128 v[196:199], v151 offset:2048
	ds_read_b128 v[200:203], v151 offset:3072
	ds_read_b128 v[204:207], v151 offset:4096
	ds_read_b128 v[208:211], v151 offset:5120
	ds_read_b128 v[212:215], v151 offset:6144
	ds_read_b128 v[216:219], v151 offset:7168
	global_load_lds_dwordx4 v136, s[30:31]
	s_add_i32 m0, s29, 0xe000
	s_nop 0
	global_load_lds_dwordx4 v138, s[30:31]
	s_waitcnt vmcnt(8)
	s_waitcnt lgkmcnt(0)
	s_barrier
	v_mfma_f32_16x16x32_bf16 v[124:127], v[152:155], v[184:187], 0
	v_mfma_f32_16x16x32_bf16 v[120:123], v[160:163], v[184:187], 0
	v_mfma_f32_16x16x32_bf16 v[116:119], v[152:155], v[196:199], 0
	v_mfma_f32_16x16x32_bf16 v[108:111], v[160:163], v[196:199], 0
	v_mfma_f32_16x16x32_bf16 v[100:103], v[152:155], v[204:207], 0
	v_mfma_f32_16x16x32_bf16 v[92:95], v[160:163], v[204:207], 0
	v_mfma_f32_16x16x32_bf16 v[84:87], v[152:155], v[212:215], 0
	v_mfma_f32_16x16x32_bf16 v[76:79], v[160:163], v[212:215], 0
	v_mfma_f32_16x16x32_bf16 v[124:127], v[156:159], v[192:195], v[124:127]
	v_mfma_f32_16x16x32_bf16 v[120:123], v[164:167], v[192:195], v[120:123]
	v_mfma_f32_16x16x32_bf16 v[116:119], v[156:159], v[200:203], v[116:119]
	v_mfma_f32_16x16x32_bf16 v[108:111], v[164:167], v[200:203], v[108:111]
	v_mfma_f32_16x16x32_bf16 v[100:103], v[156:159], v[208:211], v[100:103]
	v_mfma_f32_16x16x32_bf16 v[92:95], v[164:167], v[208:211], v[92:95]
	v_mfma_f32_16x16x32_bf16 v[84:87], v[156:159], v[216:219], v[84:87]
	v_mfma_f32_16x16x32_bf16 v[76:79], v[164:167], v[216:219], v[76:79]
	v_mfma_f32_16x16x32_bf16 v[112:115], v[168:171], v[184:187], 0
	v_mfma_f32_16x16x32_bf16 v[104:107], v[176:179], v[184:187], 0
	v_mfma_f32_16x16x32_bf16 v[96:99], v[168:171], v[196:199], 0
	v_mfma_f32_16x16x32_bf16 v[88:91], v[176:179], v[196:199], 0
	v_mfma_f32_16x16x32_bf16 v[80:83], v[168:171], v[204:207], 0
	v_mfma_f32_16x16x32_bf16 v[72:75], v[176:179], v[204:207], 0
	v_mfma_f32_16x16x32_bf16 v[68:71], v[168:171], v[212:215], 0
	v_mfma_f32_16x16x32_bf16 v[64:67], v[176:179], v[212:215], 0
	v_mfma_f32_16x16x32_bf16 v[112:115], v[172:175], v[192:195], v[112:115]
	v_mfma_f32_16x16x32_bf16 v[104:107], v[180:183], v[192:195], v[104:107]
	v_mfma_f32_16x16x32_bf16 v[96:99], v[172:175], v[200:203], v[96:99]
	v_mfma_f32_16x16x32_bf16 v[88:91], v[180:183], v[200:203], v[88:91]
	v_mfma_f32_16x16x32_bf16 v[80:83], v[172:175], v[208:211], v[80:83]
	v_mfma_f32_16x16x32_bf16 v[72:75], v[180:183], v[208:211], v[72:75]
	v_mfma_f32_16x16x32_bf16 v[68:71], v[172:175], v[216:219], v[68:71]
	v_mfma_f32_16x16x32_bf16 v[64:67], v[180:183], v[216:219], v[64:67]
	s_barrier
	s_add_i32 s76, s66, s59
	v_lshl_add_u64 v[144:145], s[34:35], 0, v[130:131]
	s_mov_b32 m0, s76
	ds_read_b128 v[184:187], v151 offset:16384
	ds_read_b128 v[192:195], v151 offset:17408
	ds_read_b128 v[196:199], v151 offset:18432
	ds_read_b128 v[200:203], v151 offset:19456
	ds_read_b128 v[204:207], v151 offset:20480
	ds_read_b128 v[208:211], v151 offset:21504
	ds_read_b128 v[212:215], v151 offset:22528
	ds_read_b128 v[216:219], v151 offset:23552
	global_load_lds_dwordx4 v[144:145], off
	s_add_i32 m0, s76, 0x2000
	s_add_u32 s76, s34, 0x100000
	v_lshl_add_u64 v[188:189], s[34:35], 0, v[134:135]
	s_addc_u32 s77, s35, 0
	s_add_i32 s79, s67, s59
	global_load_lds_dwordx4 v[188:189], off
	s_mov_b32 m0, s79
	v_lshl_add_u64 v[222:223], s[42:43], 0, v[132:133]
	global_load_lds_dwordx4 v130, s[76:77]
	s_add_i32 m0, s79, 0x2000
	v_lshl_add_u64 v[220:221], s[42:43], 0, v[128:129]
	global_load_lds_dwordx4 v134, s[76:77]
	s_mov_b32 m0, s29
	s_nop 0
	global_load_lds_dwordx4 v[220:221], off
	s_mov_b32 m0, s33
	s_nop 0
	global_load_lds_dwordx4 v[222:223], off
	s_waitcnt vmcnt(8)
	s_waitcnt lgkmcnt(0)
	s_barrier
	v_mfma_f32_16x16x32_bf16 v[60:63], v[152:155], v[184:187], 0
	v_mfma_f32_16x16x32_bf16 v[56:59], v[160:163], v[184:187], 0
	v_mfma_f32_16x16x32_bf16 v[52:55], v[152:155], v[196:199], 0
	v_mfma_f32_16x16x32_bf16 v[44:47], v[160:163], v[196:199], 0
	v_mfma_f32_16x16x32_bf16 v[36:39], v[152:155], v[204:207], 0
	v_mfma_f32_16x16x32_bf16 v[28:31], v[160:163], v[204:207], 0
	v_mfma_f32_16x16x32_bf16 v[20:23], v[152:155], v[212:215], 0
	v_mfma_f32_16x16x32_bf16 v[12:15], v[160:163], v[212:215], 0
	v_mfma_f32_16x16x32_bf16 v[60:63], v[156:159], v[192:195], v[60:63]
	v_mfma_f32_16x16x32_bf16 v[56:59], v[164:167], v[192:195], v[56:59]
	v_mfma_f32_16x16x32_bf16 v[52:55], v[156:159], v[200:203], v[52:55]
	v_mfma_f32_16x16x32_bf16 v[44:47], v[164:167], v[200:203], v[44:47]
	v_mfma_f32_16x16x32_bf16 v[36:39], v[156:159], v[208:211], v[36:39]
	v_mfma_f32_16x16x32_bf16 v[28:31], v[164:167], v[208:211], v[28:31]
	v_mfma_f32_16x16x32_bf16 v[20:23], v[156:159], v[216:219], v[20:23]
	v_mfma_f32_16x16x32_bf16 v[12:15], v[164:167], v[216:219], v[12:15]
	v_mfma_f32_16x16x32_bf16 v[48:51], v[168:171], v[184:187], 0
	v_mfma_f32_16x16x32_bf16 v[40:43], v[176:179], v[184:187], 0
	v_mfma_f32_16x16x32_bf16 v[32:35], v[168:171], v[196:199], 0
	v_mfma_f32_16x16x32_bf16 v[24:27], v[176:179], v[196:199], 0
	v_mfma_f32_16x16x32_bf16 v[16:19], v[168:171], v[204:207], 0
	v_mfma_f32_16x16x32_bf16 v[8:11], v[176:179], v[204:207], 0
	v_mfma_f32_16x16x32_bf16 v[4:7], v[168:171], v[212:215], 0
	v_mfma_f32_16x16x32_bf16 v[0:3], v[176:179], v[212:215], 0
	v_mfma_f32_16x16x32_bf16 v[48:51], v[172:175], v[192:195], v[48:51]
	v_mfma_f32_16x16x32_bf16 v[40:43], v[180:183], v[192:195], v[40:43]
	v_mfma_f32_16x16x32_bf16 v[32:35], v[172:175], v[200:203], v[32:35]
	v_mfma_f32_16x16x32_bf16 v[24:27], v[180:183], v[200:203], v[24:27]
	v_mfma_f32_16x16x32_bf16 v[16:19], v[172:175], v[208:211], v[16:19]
	v_mfma_f32_16x16x32_bf16 v[8:11], v[180:183], v[208:211], v[8:11]
	v_mfma_f32_16x16x32_bf16 v[4:7], v[172:175], v[216:219], v[4:7]
	v_mfma_f32_16x16x32_bf16 v[0:3], v[180:183], v[216:219], v[0:3]
	s_barrier
	s_add_i32 s76, 0, 0x18000
	s_add_i32 s77, 0, 0x1c000
	v_add_u32_e32 v164, s76, v147
	v_add_u32_e32 v180, s77, v147
	ds_read_b128 v[152:155], v164
	ds_read_b128 v[156:159], v164 offset:1024
	ds_read_b128 v[160:163], v164 offset:2048
	ds_read_b128 v[164:167], v164 offset:3072
	ds_read_b128 v[168:171], v180
	ds_read_b128 v[172:175], v180 offset:1024
	ds_read_b128 v[176:179], v180 offset:2048
	ds_read_b128 v[180:183], v180 offset:3072
	s_add_u32 s42, s42, 0x100000
	s_addc_u32 s43, s43, 0
	s_mov_b32 m0, s60
	ds_read_b128 v[184:187], v151 offset:32768
	ds_read_b128 v[192:195], v151 offset:33792
	ds_read_b128 v[196:199], v151 offset:34816
	ds_read_b128 v[200:203], v151 offset:35840
	ds_read_b128 v[204:207], v151 offset:36864
	ds_read_b128 v[208:211], v151 offset:37888
	ds_read_b128 v[212:215], v151 offset:38912
	ds_read_b128 v[216:219], v151 offset:39936
	global_load_lds_dwordx4 v128, s[42:43]
	s_mov_b32 m0, s61
	s_nop 0
	global_load_lds_dwordx4 v132, s[42:43]
	s_waitcnt vmcnt(8)
	s_waitcnt lgkmcnt(0)
	s_barrier
	v_mfma_f32_16x16x32_bf16 v[124:127], v[152:155], v[184:187], v[124:127]
	v_mfma_f32_16x16x32_bf16 v[120:123], v[160:163], v[184:187], v[120:123]
	v_mfma_f32_16x16x32_bf16 v[116:119], v[152:155], v[196:199], v[116:119]
	v_mfma_f32_16x16x32_bf16 v[108:111], v[160:163], v[196:199], v[108:111]
	v_mfma_f32_16x16x32_bf16 v[100:103], v[152:155], v[204:207], v[100:103]
	v_mfma_f32_16x16x32_bf16 v[92:95], v[160:163], v[204:207], v[92:95]
	v_mfma_f32_16x16x32_bf16 v[84:87], v[152:155], v[212:215], v[84:87]
	v_mfma_f32_16x16x32_bf16 v[76:79], v[160:163], v[212:215], v[76:79]
	v_mfma_f32_16x16x32_bf16 v[124:127], v[156:159], v[192:195], v[124:127]
	v_mfma_f32_16x16x32_bf16 v[120:123], v[164:167], v[192:195], v[120:123]
	v_mfma_f32_16x16x32_bf16 v[116:119], v[156:159], v[200:203], v[116:119]
	v_mfma_f32_16x16x32_bf16 v[108:111], v[164:167], v[200:203], v[108:111]
	v_mfma_f32_16x16x32_bf16 v[100:103], v[156:159], v[208:211], v[100:103]
	v_mfma_f32_16x16x32_bf16 v[92:95], v[164:167], v[208:211], v[92:95]
	v_mfma_f32_16x16x32_bf16 v[84:87], v[156:159], v[216:219], v[84:87]
	v_mfma_f32_16x16x32_bf16 v[76:79], v[164:167], v[216:219], v[76:79]
	v_mfma_f32_16x16x32_bf16 v[112:115], v[168:171], v[184:187], v[112:115]
	v_mfma_f32_16x16x32_bf16 v[104:107], v[176:179], v[184:187], v[104:107]
	v_mfma_f32_16x16x32_bf16 v[96:99], v[168:171], v[196:199], v[96:99]
	v_mfma_f32_16x16x32_bf16 v[88:91], v[176:179], v[196:199], v[88:91]
	v_mfma_f32_16x16x32_bf16 v[80:83], v[168:171], v[204:207], v[80:83]
	v_mfma_f32_16x16x32_bf16 v[72:75], v[176:179], v[204:207], v[72:75]
	v_mfma_f32_16x16x32_bf16 v[68:71], v[168:171], v[212:215], v[68:71]
	v_mfma_f32_16x16x32_bf16 v[64:67], v[176:179], v[212:215], v[64:67]
	v_mfma_f32_16x16x32_bf16 v[112:115], v[172:175], v[192:195], v[112:115]
	v_mfma_f32_16x16x32_bf16 v[104:107], v[180:183], v[192:195], v[104:107]
	v_mfma_f32_16x16x32_bf16 v[96:99], v[172:175], v[200:203], v[96:99]
	v_mfma_f32_16x16x32_bf16 v[88:91], v[180:183], v[200:203], v[88:91]
	v_mfma_f32_16x16x32_bf16 v[80:83], v[172:175], v[208:211], v[80:83]
	v_mfma_f32_16x16x32_bf16 v[72:75], v[180:183], v[208:211], v[72:75]
	v_mfma_f32_16x16x32_bf16 v[68:71], v[172:175], v[216:219], v[68:71]
	v_mfma_f32_16x16x32_bf16 v[64:67], v[180:183], v[216:219], v[64:67]
	s_barrier
	s_add_i32 s42, s76, s59
	v_lshl_add_u64 v[144:145], v[144:145], 0, s[8:9]
	s_mov_b32 m0, s42
	ds_read_b128 v[184:187], v151 offset:49152
	ds_read_b128 v[192:195], v151 offset:50176
	ds_read_b128 v[196:199], v151 offset:51200
	ds_read_b128 v[200:203], v151 offset:52224
	ds_read_b128 v[204:207], v151 offset:53248
	ds_read_b128 v[208:211], v151 offset:54272
	ds_read_b128 v[212:215], v151 offset:55296
	ds_read_b128 v[216:219], v151 offset:56320
	global_load_lds_dwordx4 v[144:145], off
	s_add_i32 m0, s42, 0x2000
	s_add_u32 s34, s34, 0x100080
	v_lshl_add_u64 v[144:145], v[188:189], 0, s[8:9]
	s_addc_u32 s35, s35, 0
	s_add_i32 s42, s77, s59
	global_load_lds_dwordx4 v[144:145], off
	s_mov_b32 m0, s42
	s_nop 0
	global_load_lds_dwordx4 v130, s[34:35]
	s_add_i32 m0, s42, 0x2000
	v_lshl_add_u64 v[144:145], v[220:221], 0, s[8:9]
	global_load_lds_dwordx4 v134, s[34:35]
	s_mov_b32 m0, s63
	s_nop 0
	global_load_lds_dwordx4 v[144:145], off
	s_mov_b32 m0, s64
	v_lshl_add_u64 v[144:145], v[222:223], 0, s[8:9]
	global_load_lds_dwordx4 v[144:145], off
	s_waitcnt vmcnt(8)
	s_waitcnt lgkmcnt(0)
	s_barrier
	v_mfma_f32_16x16x32_bf16 v[60:63], v[152:155], v[184:187], v[60:63]
	v_mfma_f32_16x16x32_bf16 v[56:59], v[160:163], v[184:187], v[56:59]
	v_mfma_f32_16x16x32_bf16 v[52:55], v[152:155], v[196:199], v[52:55]
	v_mfma_f32_16x16x32_bf16 v[44:47], v[160:163], v[196:199], v[44:47]
	v_mfma_f32_16x16x32_bf16 v[36:39], v[152:155], v[204:207], v[36:39]
	v_mfma_f32_16x16x32_bf16 v[28:31], v[160:163], v[204:207], v[28:31]
	v_mfma_f32_16x16x32_bf16 v[20:23], v[152:155], v[212:215], v[20:23]
	v_mfma_f32_16x16x32_bf16 v[12:15], v[160:163], v[212:215], v[12:15]
	v_mfma_f32_16x16x32_bf16 v[60:63], v[156:159], v[192:195], v[60:63]
	v_mfma_f32_16x16x32_bf16 v[56:59], v[164:167], v[192:195], v[56:59]
	v_mfma_f32_16x16x32_bf16 v[52:55], v[156:159], v[200:203], v[52:55]
	v_mfma_f32_16x16x32_bf16 v[44:47], v[164:167], v[200:203], v[44:47]
	v_mfma_f32_16x16x32_bf16 v[36:39], v[156:159], v[208:211], v[36:39]
	v_mfma_f32_16x16x32_bf16 v[28:31], v[164:167], v[208:211], v[28:31]
	v_mfma_f32_16x16x32_bf16 v[20:23], v[156:159], v[216:219], v[20:23]
	v_mfma_f32_16x16x32_bf16 v[12:15], v[164:167], v[216:219], v[12:15]
	v_mfma_f32_16x16x32_bf16 v[48:51], v[168:171], v[184:187], v[48:51]
	v_mfma_f32_16x16x32_bf16 v[40:43], v[176:179], v[184:187], v[40:43]
	v_mfma_f32_16x16x32_bf16 v[32:35], v[168:171], v[196:199], v[32:35]
	v_mfma_f32_16x16x32_bf16 v[24:27], v[176:179], v[196:199], v[24:27]
	v_mfma_f32_16x16x32_bf16 v[16:19], v[168:171], v[204:207], v[16:19]
	v_mfma_f32_16x16x32_bf16 v[8:11], v[176:179], v[204:207], v[8:11]
	v_mfma_f32_16x16x32_bf16 v[4:7], v[168:171], v[212:215], v[4:7]
	v_mfma_f32_16x16x32_bf16 v[0:3], v[176:179], v[212:215], v[0:3]
	v_mfma_f32_16x16x32_bf16 v[48:51], v[172:175], v[192:195], v[48:51]
	v_mfma_f32_16x16x32_bf16 v[40:43], v[180:183], v[192:195], v[40:43]
	v_mfma_f32_16x16x32_bf16 v[32:35], v[172:175], v[200:203], v[32:35]
	v_mfma_f32_16x16x32_bf16 v[24:27], v[180:183], v[200:203], v[24:27]
	v_mfma_f32_16x16x32_bf16 v[16:19], v[172:175], v[208:211], v[16:19]
	v_mfma_f32_16x16x32_bf16 v[8:11], v[180:183], v[208:211], v[8:11]
	v_mfma_f32_16x16x32_bf16 v[4:7], v[172:175], v[216:219], v[4:7]
	v_mfma_f32_16x16x32_bf16 v[0:3], v[180:183], v[216:219], v[0:3]
	s_barrier
	s_add_i32 s75, s75, 2
	s_add_u32 s30, s30, 0x100
	s_addc_u32 s31, s31, 0
	s_add_u32 s73, s73, 0x100
	s_addc_u32 s74, s74, 0
	s_cmp_gt_u32 s75, 61
	s_cbranch_scc0 .LBB0_1650
	s_branch .Lpeel_exit12
.LBB0_1650:
	ds_read_b128 v[152:155], v149
	ds_read_b128 v[156:159], v149 offset:1024
	ds_read_b128 v[160:163], v149 offset:2048
	ds_read_b128 v[164:167], v149 offset:3072
	ds_read_b128 v[168:171], v150
	ds_read_b128 v[172:175], v150 offset:1024
	ds_read_b128 v[176:179], v150 offset:2048
	ds_read_b128 v[180:183], v150 offset:3072
	s_add_u32 s34, s30, 0xfff00080
	s_addc_u32 s35, s31, -1
	s_cmp_eq_u32 s75, 60
	s_cselect_b32 s43, s23, s35
	s_cselect_b32 s42, s55, s34
	s_cselect_b32 s35, s21, s74
	s_cselect_b32 s34, s72, s73
	s_add_i32 m0, s29, 0xc000
	ds_read_b128 v[184:187], v151
	ds_read_b128 v[192:195], v151 offset:1024
	ds_read_b128 v[196:199], v151 offset:2048
	ds_read_b128 v[200:203], v151 offset:3072
	ds_read_b128 v[204:207], v151 offset:4096
	ds_read_b128 v[208:211], v151 offset:5120
	ds_read_b128 v[212:215], v151 offset:6144
	ds_read_b128 v[216:219], v151 offset:7168
	global_load_lds_dwordx4 v136, s[30:31]
	s_add_i32 m0, s29, 0xe000
	s_nop 0
	global_load_lds_dwordx4 v138, s[30:31]
	s_waitcnt vmcnt(8)
	s_waitcnt lgkmcnt(0)
	s_barrier
	v_mfma_f32_16x16x32_bf16 v[124:127], v[152:155], v[184:187], v[124:127]
	v_mfma_f32_16x16x32_bf16 v[120:123], v[160:163], v[184:187], v[120:123]
	v_mfma_f32_16x16x32_bf16 v[116:119], v[152:155], v[196:199], v[116:119]
	v_mfma_f32_16x16x32_bf16 v[108:111], v[160:163], v[196:199], v[108:111]
	v_mfma_f32_16x16x32_bf16 v[100:103], v[152:155], v[204:207], v[100:103]
	v_mfma_f32_16x16x32_bf16 v[92:95], v[160:163], v[204:207], v[92:95]
	v_mfma_f32_16x16x32_bf16 v[84:87], v[152:155], v[212:215], v[84:87]
	v_mfma_f32_16x16x32_bf16 v[76:79], v[160:163], v[212:215], v[76:79]
	v_mfma_f32_16x16x32_bf16 v[124:127], v[156:159], v[192:195], v[124:127]
	v_mfma_f32_16x16x32_bf16 v[120:123], v[164:167], v[192:195], v[120:123]
	v_mfma_f32_16x16x32_bf16 v[116:119], v[156:159], v[200:203], v[116:119]
	v_mfma_f32_16x16x32_bf16 v[108:111], v[164:167], v[200:203], v[108:111]
	v_mfma_f32_16x16x32_bf16 v[100:103], v[156:159], v[208:211], v[100:103]
	v_mfma_f32_16x16x32_bf16 v[92:95], v[164:167], v[208:211], v[92:95]
	v_mfma_f32_16x16x32_bf16 v[84:87], v[156:159], v[216:219], v[84:87]
	v_mfma_f32_16x16x32_bf16 v[76:79], v[164:167], v[216:219], v[76:79]
	v_mfma_f32_16x16x32_bf16 v[112:115], v[168:171], v[184:187], v[112:115]
	v_mfma_f32_16x16x32_bf16 v[104:107], v[176:179], v[184:187], v[104:107]
	v_mfma_f32_16x16x32_bf16 v[96:99], v[168:171], v[196:199], v[96:99]
	v_mfma_f32_16x16x32_bf16 v[88:91], v[176:179], v[196:199], v[88:91]
	v_mfma_f32_16x16x32_bf16 v[80:83], v[168:171], v[204:207], v[80:83]
	v_mfma_f32_16x16x32_bf16 v[72:75], v[176:179], v[204:207], v[72:75]
	v_mfma_f32_16x16x32_bf16 v[68:71], v[168:171], v[212:215], v[68:71]
	v_mfma_f32_16x16x32_bf16 v[64:67], v[176:179], v[212:215], v[64:67]
	v_mfma_f32_16x16x32_bf16 v[112:115], v[172:175], v[192:195], v[112:115]
	v_mfma_f32_16x16x32_bf16 v[104:107], v[180:183], v[192:195], v[104:107]
	v_mfma_f32_16x16x32_bf16 v[96:99], v[172:175], v[200:203], v[96:99]
	v_mfma_f32_16x16x32_bf16 v[88:91], v[180:183], v[200:203], v[88:91]
	v_mfma_f32_16x16x32_bf16 v[80:83], v[172:175], v[208:211], v[80:83]
	v_mfma_f32_16x16x32_bf16 v[72:75], v[180:183], v[208:211], v[72:75]
	v_mfma_f32_16x16x32_bf16 v[68:71], v[172:175], v[216:219], v[68:71]
	v_mfma_f32_16x16x32_bf16 v[64:67], v[180:183], v[216:219], v[64:67]
	s_barrier
	s_add_i32 s76, s66, s59
	v_lshl_add_u64 v[144:145], s[34:35], 0, v[130:131]
	s_mov_b32 m0, s76
	ds_read_b128 v[184:187], v151 offset:16384
	ds_read_b128 v[192:195], v151 offset:17408
	ds_read_b128 v[196:199], v151 offset:18432
	ds_read_b128 v[200:203], v151 offset:19456
	ds_read_b128 v[204:207], v151 offset:20480
	ds_read_b128 v[208:211], v151 offset:21504
	ds_read_b128 v[212:215], v151 offset:22528
	ds_read_b128 v[216:219], v151 offset:23552
	global_load_lds_dwordx4 v[144:145], off
	s_add_i32 m0, s76, 0x2000
	s_add_u32 s76, s34, 0x100000
	v_lshl_add_u64 v[188:189], s[34:35], 0, v[134:135]
	s_addc_u32 s77, s35, 0
	s_add_i32 s79, s67, s59
	global_load_lds_dwordx4 v[188:189], off
	s_mov_b32 m0, s79
	v_lshl_add_u64 v[222:223], s[42:43], 0, v[132:133]
	global_load_lds_dwordx4 v130, s[76:77]
	s_add_i32 m0, s79, 0x2000
	v_lshl_add_u64 v[220:221], s[42:43], 0, v[128:129]
	global_load_lds_dwordx4 v134, s[76:77]
	s_mov_b32 m0, s29
	s_nop 0
	global_load_lds_dwordx4 v[220:221], off
	s_mov_b32 m0, s33
	s_nop 0
	global_load_lds_dwordx4 v[222:223], off
	s_waitcnt vmcnt(8)
	s_waitcnt lgkmcnt(0)
	s_barrier
	v_mfma_f32_16x16x32_bf16 v[60:63], v[152:155], v[184:187], v[60:63]
	v_mfma_f32_16x16x32_bf16 v[56:59], v[160:163], v[184:187], v[56:59]
	v_mfma_f32_16x16x32_bf16 v[52:55], v[152:155], v[196:199], v[52:55]
	v_mfma_f32_16x16x32_bf16 v[44:47], v[160:163], v[196:199], v[44:47]
	v_mfma_f32_16x16x32_bf16 v[36:39], v[152:155], v[204:207], v[36:39]
	v_mfma_f32_16x16x32_bf16 v[28:31], v[160:163], v[204:207], v[28:31]
	v_mfma_f32_16x16x32_bf16 v[20:23], v[152:155], v[212:215], v[20:23]
	v_mfma_f32_16x16x32_bf16 v[12:15], v[160:163], v[212:215], v[12:15]
	v_mfma_f32_16x16x32_bf16 v[60:63], v[156:159], v[192:195], v[60:63]
	v_mfma_f32_16x16x32_bf16 v[56:59], v[164:167], v[192:195], v[56:59]
	v_mfma_f32_16x16x32_bf16 v[52:55], v[156:159], v[200:203], v[52:55]
	v_mfma_f32_16x16x32_bf16 v[44:47], v[164:167], v[200:203], v[44:47]
	v_mfma_f32_16x16x32_bf16 v[36:39], v[156:159], v[208:211], v[36:39]
	v_mfma_f32_16x16x32_bf16 v[28:31], v[164:167], v[208:211], v[28:31]
	v_mfma_f32_16x16x32_bf16 v[20:23], v[156:159], v[216:219], v[20:23]
	v_mfma_f32_16x16x32_bf16 v[12:15], v[164:167], v[216:219], v[12:15]
	v_mfma_f32_16x16x32_bf16 v[48:51], v[168:171], v[184:187], v[48:51]
	v_mfma_f32_16x16x32_bf16 v[40:43], v[176:179], v[184:187], v[40:43]
	v_mfma_f32_16x16x32_bf16 v[32:35], v[168:171], v[196:199], v[32:35]
	v_mfma_f32_16x16x32_bf16 v[24:27], v[176:179], v[196:199], v[24:27]
	v_mfma_f32_16x16x32_bf16 v[16:19], v[168:171], v[204:207], v[16:19]
	v_mfma_f32_16x16x32_bf16 v[8:11], v[176:179], v[204:207], v[8:11]
	v_mfma_f32_16x16x32_bf16 v[4:7], v[168:171], v[212:215], v[4:7]
	v_mfma_f32_16x16x32_bf16 v[0:3], v[176:179], v[212:215], v[0:3]
	v_mfma_f32_16x16x32_bf16 v[48:51], v[172:175], v[192:195], v[48:51]
	v_mfma_f32_16x16x32_bf16 v[40:43], v[180:183], v[192:195], v[40:43]
	v_mfma_f32_16x16x32_bf16 v[32:35], v[172:175], v[200:203], v[32:35]
	v_mfma_f32_16x16x32_bf16 v[24:27], v[180:183], v[200:203], v[24:27]
	v_mfma_f32_16x16x32_bf16 v[16:19], v[172:175], v[208:211], v[16:19]
	v_mfma_f32_16x16x32_bf16 v[8:11], v[180:183], v[208:211], v[8:11]
	v_mfma_f32_16x16x32_bf16 v[4:7], v[172:175], v[216:219], v[4:7]
	v_mfma_f32_16x16x32_bf16 v[0:3], v[180:183], v[216:219], v[0:3]
	s_barrier
	s_add_i32 s76, 0, 0x18000
	s_add_i32 s77, 0, 0x1c000
	v_add_u32_e32 v164, s76, v147
	v_add_u32_e32 v180, s77, v147
	ds_read_b128 v[152:155], v164
	ds_read_b128 v[156:159], v164 offset:1024
	ds_read_b128 v[160:163], v164 offset:2048
	ds_read_b128 v[164:167], v164 offset:3072
	ds_read_b128 v[168:171], v180
	ds_read_b128 v[172:175], v180 offset:1024
	ds_read_b128 v[176:179], v180 offset:2048
	ds_read_b128 v[180:183], v180 offset:3072
	s_add_u32 s42, s42, 0x100000
	s_addc_u32 s43, s43, 0
	s_mov_b32 m0, s60
	ds_read_b128 v[184:187], v151 offset:32768
	ds_read_b128 v[192:195], v151 offset:33792
	ds_read_b128 v[196:199], v151 offset:34816
	ds_read_b128 v[200:203], v151 offset:35840
	ds_read_b128 v[204:207], v151 offset:36864
	ds_read_b128 v[208:211], v151 offset:37888
	ds_read_b128 v[212:215], v151 offset:38912
	ds_read_b128 v[216:219], v151 offset:39936
	global_load_lds_dwordx4 v128, s[42:43]
	s_mov_b32 m0, s61
	s_nop 0
	global_load_lds_dwordx4 v132, s[42:43]
	s_waitcnt vmcnt(8)
	s_waitcnt lgkmcnt(0)
	s_barrier
	v_mfma_f32_16x16x32_bf16 v[124:127], v[152:155], v[184:187], v[124:127]
	v_mfma_f32_16x16x32_bf16 v[120:123], v[160:163], v[184:187], v[120:123]
	v_mfma_f32_16x16x32_bf16 v[116:119], v[152:155], v[196:199], v[116:119]
	v_mfma_f32_16x16x32_bf16 v[108:111], v[160:163], v[196:199], v[108:111]
	v_mfma_f32_16x16x32_bf16 v[100:103], v[152:155], v[204:207], v[100:103]
	v_mfma_f32_16x16x32_bf16 v[92:95], v[160:163], v[204:207], v[92:95]
	v_mfma_f32_16x16x32_bf16 v[84:87], v[152:155], v[212:215], v[84:87]
	v_mfma_f32_16x16x32_bf16 v[76:79], v[160:163], v[212:215], v[76:79]
	v_mfma_f32_16x16x32_bf16 v[124:127], v[156:159], v[192:195], v[124:127]
	v_mfma_f32_16x16x32_bf16 v[120:123], v[164:167], v[192:195], v[120:123]
	v_mfma_f32_16x16x32_bf16 v[116:119], v[156:159], v[200:203], v[116:119]
	v_mfma_f32_16x16x32_bf16 v[108:111], v[164:167], v[200:203], v[108:111]
	v_mfma_f32_16x16x32_bf16 v[100:103], v[156:159], v[208:211], v[100:103]
	v_mfma_f32_16x16x32_bf16 v[92:95], v[164:167], v[208:211], v[92:95]
	v_mfma_f32_16x16x32_bf16 v[84:87], v[156:159], v[216:219], v[84:87]
	v_mfma_f32_16x16x32_bf16 v[76:79], v[164:167], v[216:219], v[76:79]
	v_mfma_f32_16x16x32_bf16 v[112:115], v[168:171], v[184:187], v[112:115]
	v_mfma_f32_16x16x32_bf16 v[104:107], v[176:179], v[184:187], v[104:107]
	v_mfma_f32_16x16x32_bf16 v[96:99], v[168:171], v[196:199], v[96:99]
	v_mfma_f32_16x16x32_bf16 v[88:91], v[176:179], v[196:199], v[88:91]
	v_mfma_f32_16x16x32_bf16 v[80:83], v[168:171], v[204:207], v[80:83]
	v_mfma_f32_16x16x32_bf16 v[72:75], v[176:179], v[204:207], v[72:75]
	v_mfma_f32_16x16x32_bf16 v[68:71], v[168:171], v[212:215], v[68:71]
	v_mfma_f32_16x16x32_bf16 v[64:67], v[176:179], v[212:215], v[64:67]
	v_mfma_f32_16x16x32_bf16 v[112:115], v[172:175], v[192:195], v[112:115]
	v_mfma_f32_16x16x32_bf16 v[104:107], v[180:183], v[192:195], v[104:107]
	v_mfma_f32_16x16x32_bf16 v[96:99], v[172:175], v[200:203], v[96:99]
	v_mfma_f32_16x16x32_bf16 v[88:91], v[180:183], v[200:203], v[88:91]
	v_mfma_f32_16x16x32_bf16 v[80:83], v[172:175], v[208:211], v[80:83]
	v_mfma_f32_16x16x32_bf16 v[72:75], v[180:183], v[208:211], v[72:75]
	v_mfma_f32_16x16x32_bf16 v[68:71], v[172:175], v[216:219], v[68:71]
	v_mfma_f32_16x16x32_bf16 v[64:67], v[180:183], v[216:219], v[64:67]
	s_barrier
	s_add_i32 s42, s76, s59
	v_lshl_add_u64 v[144:145], v[144:145], 0, s[8:9]
	s_mov_b32 m0, s42
	ds_read_b128 v[184:187], v151 offset:49152
	ds_read_b128 v[192:195], v151 offset:50176
	ds_read_b128 v[196:199], v151 offset:51200
	ds_read_b128 v[200:203], v151 offset:52224
	ds_read_b128 v[204:207], v151 offset:53248
	ds_read_b128 v[208:211], v151 offset:54272
	ds_read_b128 v[212:215], v151 offset:55296
	ds_read_b128 v[216:219], v151 offset:56320
	global_load_lds_dwordx4 v[144:145], off
	s_add_i32 m0, s42, 0x2000
	s_add_u32 s34, s34, 0x100080
	v_lshl_add_u64 v[144:145], v[188:189], 0, s[8:9]
	s_addc_u32 s35, s35, 0
	s_add_i32 s42, s77, s59
	global_load_lds_dwordx4 v[144:145], off
	s_mov_b32 m0, s42
	s_nop 0
	global_load_lds_dwordx4 v130, s[34:35]
	s_add_i32 m0, s42, 0x2000
	v_lshl_add_u64 v[144:145], v[220:221], 0, s[8:9]
	global_load_lds_dwordx4 v134, s[34:35]
	s_mov_b32 m0, s63
	s_nop 0
	global_load_lds_dwordx4 v[144:145], off
	s_mov_b32 m0, s64
	v_lshl_add_u64 v[144:145], v[222:223], 0, s[8:9]
	global_load_lds_dwordx4 v[144:145], off
	s_waitcnt vmcnt(8)
	s_waitcnt lgkmcnt(0)
	s_barrier
	v_mfma_f32_16x16x32_bf16 v[60:63], v[152:155], v[184:187], v[60:63]
	v_mfma_f32_16x16x32_bf16 v[56:59], v[160:163], v[184:187], v[56:59]
	v_mfma_f32_16x16x32_bf16 v[52:55], v[152:155], v[196:199], v[52:55]
	v_mfma_f32_16x16x32_bf16 v[44:47], v[160:163], v[196:199], v[44:47]
	v_mfma_f32_16x16x32_bf16 v[36:39], v[152:155], v[204:207], v[36:39]
	v_mfma_f32_16x16x32_bf16 v[28:31], v[160:163], v[204:207], v[28:31]
	v_mfma_f32_16x16x32_bf16 v[20:23], v[152:155], v[212:215], v[20:23]
	v_mfma_f32_16x16x32_bf16 v[12:15], v[160:163], v[212:215], v[12:15]
	v_mfma_f32_16x16x32_bf16 v[60:63], v[156:159], v[192:195], v[60:63]
	v_mfma_f32_16x16x32_bf16 v[56:59], v[164:167], v[192:195], v[56:59]
	v_mfma_f32_16x16x32_bf16 v[52:55], v[156:159], v[200:203], v[52:55]
	v_mfma_f32_16x16x32_bf16 v[44:47], v[164:167], v[200:203], v[44:47]
	v_mfma_f32_16x16x32_bf16 v[36:39], v[156:159], v[208:211], v[36:39]
	v_mfma_f32_16x16x32_bf16 v[28:31], v[164:167], v[208:211], v[28:31]
	v_mfma_f32_16x16x32_bf16 v[20:23], v[156:159], v[216:219], v[20:23]
	v_mfma_f32_16x16x32_bf16 v[12:15], v[164:167], v[216:219], v[12:15]
	v_mfma_f32_16x16x32_bf16 v[48:51], v[168:171], v[184:187], v[48:51]
	v_mfma_f32_16x16x32_bf16 v[40:43], v[176:179], v[184:187], v[40:43]
	v_mfma_f32_16x16x32_bf16 v[32:35], v[168:171], v[196:199], v[32:35]
	v_mfma_f32_16x16x32_bf16 v[24:27], v[176:179], v[196:199], v[24:27]
	v_mfma_f32_16x16x32_bf16 v[16:19], v[168:171], v[204:207], v[16:19]
	v_mfma_f32_16x16x32_bf16 v[8:11], v[176:179], v[204:207], v[8:11]
	v_mfma_f32_16x16x32_bf16 v[4:7], v[168:171], v[212:215], v[4:7]
	v_mfma_f32_16x16x32_bf16 v[0:3], v[176:179], v[212:215], v[0:3]
	v_mfma_f32_16x16x32_bf16 v[48:51], v[172:175], v[192:195], v[48:51]
	v_mfma_f32_16x16x32_bf16 v[40:43], v[180:183], v[192:195], v[40:43]
	v_mfma_f32_16x16x32_bf16 v[32:35], v[172:175], v[200:203], v[32:35]
	v_mfma_f32_16x16x32_bf16 v[24:27], v[180:183], v[200:203], v[24:27]
	v_mfma_f32_16x16x32_bf16 v[16:19], v[172:175], v[208:211], v[16:19]
	v_mfma_f32_16x16x32_bf16 v[8:11], v[180:183], v[208:211], v[8:11]
	v_mfma_f32_16x16x32_bf16 v[4:7], v[172:175], v[216:219], v[4:7]
	v_mfma_f32_16x16x32_bf16 v[0:3], v[180:183], v[216:219], v[0:3]
	s_barrier
	s_add_i32 s75, s75, 2
	s_add_u32 s30, s30, 0x100
	s_addc_u32 s31, s31, 0
	s_add_u32 s73, s73, 0x100
	s_addc_u32 s74, s74, 0
	s_cmp_gt_u32 s75, 61
	s_cbranch_scc0 .LBB0_1650
